# hand-scheduled K-loops (staging interleaved with MFMAs, 2-step lookahead in out-proj), de-serialised epilogues in out-proj/attention/RWKV-out, small LDS/load batching in RWKV precompute
# speedup vs baseline: 1.3783x; 1.0421x over previous
;     ...
;   const int srow = tid >> 3, skc = tid & 7;
;   const u16* Ag = A + (size_t)(m0 + srow) * K + skc * 8;
;   const u16* Bg[4];
; #pragma unroll
;   for (int i = 0; i < 4; ++i) { int n = n0 + srow + 64 * i; n = n < nmax ? n : nmax - 1; Bg[i] = Bt + (size_t)n * K + skc * 8; }
;   const int nk = nk_override ? nk_override : K / 64;
; #pragma unroll
;   for (int i = 0; i < 4; ++i) { ra[i] = *(const u32x4*)(Ag + (size_t)(64 * i) * K); rb[i] = *(const u32x4*)(Bg[i]); }
; #pragma unroll
;   for (int i = 0; i < 4; ++i) { *(u32x4*)(As0 + (srow + 64 * i) * LD + skc * 8) = ra[i]; *(u32x4*)(Bs0 + (srow + 64 * i) * LD + skc * 8) = rb[i]; }
;   if (nk > 1) {
; #pragma unroll
;     for (int i = 0; i < 4; ++i) { ra[i] = *(const u32x4*)(Ag + (size_t)(64 * i) * K + 64); rb[i] = *(const u32x4*)(Bg[i] + 64); }
;   }
;   for (int kt = 0; kt < nk; ++kt) {
;     __syncthreads();
;     if (kt + 1 < nk) {
;       u16* aw = As0 + ((kt + 1) & 1) * 256 * LD;
;       u16* bw = Bs0 + ((kt + 1) & 1) * 256 * LD;
; #pragma unroll
;       for (int i = 0; i < 4; ++i) { *(u32x4*)(aw + (srow + 64 * i) * LD + skc * 8) = ra[i]; *(u32x4*)(bw + (srow + 64 * i) * LD + skc * 8) = rb[i]; }
;     }
;     if (kt + 2 < nk) {
; #pragma unroll
;       for (int i = 0; i < 4; ++i) { ra[i] = *(const u32x4*)(Ag + (size_t)(64 * i) * K + (kt + 2) * 64); rb[i] = *(const u32x4*)(Bg[i] + (kt + 2) * 64); }
;     }
;     __builtin_amdgcn_sched_barrier(0);
;     const u16* as = As0 + (kt & 1) * 256 * LD + (wr * 128 + l31) * LD + h * 8;
;     const u16* bs = Bs0 + (kt & 1) * 256 * LD + (wc * 64 + l31) * LD + h * 8;
;     if (domma)
; #pragma unroll
;     for (int ks = 0; ks < 4; ++ks) {
;       bf16x8 wf[2], xf[4];
; #pragma unroll
;       for (int ct = 0; ct < 2; ++ct) wf[ct] = *(const bf16x8*)(bs + ct * 32 * LD + ks * 16);
; #pragma unroll
;       for (int tt = 0; tt < 4; ++tt) xf[tt] = *(const bf16x8*)(as + tt * 32 * LD + ks * 16);
; #pragma unroll
;       for (int ct = 0; ct < 2; ++ct)
; #pragma unroll
;         for (int tt = 0; tt < 4; ++tt) acc[ct][tt] = __builtin_amdgcn_mfma_f32_32x32x16_bf16(wf[ct], xf[tt], acc[ct][tt], 0, 0, 0);
;     ...
;   for (int Lx = jx; Lx < (NMT / 8) * NNT; Lx += nbx) {
;     const int grp = Lx / (2 * NNT), gi = Lx % (2 * NNT);
;     const int mt = xcd * (NMT / 8) + 2 * grp + (gi & 1), nt = gi >> 1;
.LBB0_107:
	s_lshl_b32 s34, s34, 1
	s_add_i32 s34, s34, s40
	s_and_b32 s30, s35, 1
	s_or_b32 s30, s34, s30
	s_lshl_b32 s59, s62, 8
	v_ashrrev_i32_e32 v42, 3, v227
	s_lshl_b32 s35, s30, 8
	s_waitcnt vmcnt(3)
	v_add_u32_e32 v10, s59, v42
	s_waitcnt vmcnt(0)
	v_add_u32_e32 v4, s35, v42
	v_lshlrev_b32_e32 v2, 4, v227
	v_min_i32_e32 v8, 0x107f, v10
	v_ashrrev_i32_e32 v5, 31, v4
	v_and_b32_e32 v2, 0x70, v2
	v_ashrrev_i32_e32 v9, 31, v8
	v_lshlrev_b64 v[4:5], 11, v[4:5]
	s_waitcnt lgkmcnt(0)
	v_lshl_add_u64 v[6:7], s[18:19], 0, v[2:3]
	v_lshlrev_b64 v[8:9], 11, v[8:9]
	v_lshl_add_u64 v[228:229], v[6:7], 0, v[8:9]
	v_min_i32_e32 v8, 0x103f, v10
	v_lshl_add_u64 v[4:5], s[16:17], 0, v[4:5]
	v_ashrrev_i32_e32 v9, 31, v8
	v_lshl_add_u64 v[230:231], v[4:5], 0, v[2:3]
	v_lshlrev_b64 v[8:9], 11, v[8:9]
	v_add_co_u32_e32 v232, vcc, s42, v230
	v_lshl_add_u64 v[36:37], v[6:7], 0, v[8:9]
	v_min_i32_e32 v8, 0xfff, v10
	v_addc_co_u32_e32 v233, vcc, 0, v231, vcc
	v_ashrrev_i32_e32 v9, 31, v8
	v_add_co_u32_e32 v16, vcc, s42, v36
	v_lshlrev_b64 v[8:9], 11, v[8:9]
	s_nop 0
	v_addc_co_u32_e32 v17, vcc, 0, v37, vcc
	v_lshl_add_u64 v[38:39], v[6:7], 0, v[8:9]
	v_min_i32_e32 v8, 0xfbf, v10
	v_add_co_u32_e32 v68, vcc, s43, v230
	v_ashrrev_i32_e32 v9, 31, v8
	s_nop 0
	v_addc_co_u32_e32 v69, vcc, 0, v231, vcc
	v_lshlrev_b64 v[8:9], 11, v[8:9]
	v_add_co_u32_e32 v24, vcc, s43, v38
	v_lshl_add_u64 v[40:41], v[6:7], 0, v[8:9]
	global_load_dwordx4 v[4:7], v[230:231], off
	global_load_dwordx4 v[8:11], v[228:229], off
	v_addc_co_u32_e32 v25, vcc, 0, v39, vcc
	global_load_dwordx4 v[16:19], v[16:17], off
	v_add_co_u32_e32 v28, vcc, s44, v40
	global_load_dwordx4 v[24:27], v[24:25], off
	s_nop 0
	v_addc_co_u32_e32 v29, vcc, 0, v41, vcc
	global_load_dwordx4 v[28:31], v[28:29], off
	v_add_co_u32_e32 v70, vcc, s44, v230
	global_load_dwordx4 v[12:15], v[232:233], off
	global_load_dwordx4 v[20:23], v[68:69], off
	v_addc_co_u32_e32 v71, vcc, 0, v231, vcc
	global_load_dwordx4 v[32:35], v[70:71], off
	v_mul_lo_u32 v42, v42, s46
	v_add3_u32 v251, s45, v2, v42
	v_add3_u32 v250, 0, v2, v42
	v_lshl_add_u64 v[238:239], v[36:37], 0, s[24:25]
	v_lshl_add_u64 v[234:235], v[38:39], 0, s[26:27]
	v_lshl_add_u64 v[236:237], v[40:41], 0, s[28:29]
	global_load_dwordx4 v[36:39], v[228:229], off offset:128
	global_load_dwordx4 v[40:43], v[238:239], off offset:128
	global_load_dwordx4 v[44:47], v[234:235], off offset:128
	global_load_dwordx4 v[48:51], v[236:237], off offset:128
	global_load_dwordx4 v[52:55], v[230:231], off offset:128
	global_load_dwordx4 v[56:59], v[232:233], off offset:128
	global_load_dwordx4 v[60:63], v[68:69], off offset:128
	global_load_dwordx4 v[64:67], v[70:71], off offset:128
	s_ashr_i32 s36, s60, 6
	s_bfe_u32 s37, s36, 0x10001
	s_ashr_i32 s38, s60, 8
	s_and_b64 s[30:31], s[6:7], exec
	s_cselect_b32 s37, s37, s38
	s_xor_b64 s[6:7], s[6:7], -1
	s_cmp_lt_i32 s36, 4
	v_and_b32_e32 v225, 31, v227
	s_cselect_b64 s[30:31], -1, 0
	s_lshl_b32 s36, s37, 7
	v_bfe_u32 v247, v227, 5, 1
	v_or_b32_e32 v2, s36, v225
	v_mul_lo_u32 v2, v2, s46
	v_lshlrev_b32_e32 v226, 4, v247
	s_lshl_b32 s61, s20, 6
	v_add3_u32 v248, 0, v2, v226
	v_or_b32_e32 v2, s61, v225
	v_mul_lo_u32 v2, v2, s46
	s_or_b64 s[30:31], s[6:7], s[30:31]
	v_add3_u32 v249, s45, v2, v226
	s_waitcnt vmcnt(14)
	ds_write_b128 v251, v[8:11]
	s_waitcnt vmcnt(13)
	ds_write_b128 v251, v[16:19] offset:9216
	s_waitcnt vmcnt(12)
	ds_write_b128 v251, v[24:27] offset:18432
	s_waitcnt vmcnt(11)
	ds_write_b128 v251, v[28:31] offset:27648
	ds_write_b128 v250, v[4:7]
	s_waitcnt vmcnt(10)
	ds_write_b128 v250, v[12:15] offset:9216
	s_waitcnt vmcnt(9)
	ds_write_b128 v250, v[20:23] offset:18432
	s_waitcnt vmcnt(8)
	ds_write_b128 v250, v[32:35] offset:27648
	s_waitcnt lgkmcnt(0)
	s_barrier
	s_cmp_eq_u32 s62, 16
	s_cbranch_scc1 .Lp1_orig_k
	v_mov_b64_e32 v[12:13], v[68:69]
	v_mov_b64_e32 v[14:15], v[70:71]
	global_load_dwordx4 v[146:149], v[230:231], off offset:256
	global_load_dwordx4 v[162:165], v[228:229], off offset:256
	global_load_dwordx4 v[150:153], v[232:233], off offset:256
	global_load_dwordx4 v[166:169], v[238:239], off offset:256
	global_load_dwordx4 v[154:157], v[12:13], off offset:256
	global_load_dwordx4 v[170:173], v[234:235], off offset:256
	global_load_dwordx4 v[158:161], v[14:15], off offset:256
	global_load_dwordx4 v[174:177], v[236:237], off offset:256
	s_waitcnt vmcnt(15)
	ds_write_b128 v251, v[36:39] offset:36864
	s_waitcnt vmcnt(14)
	ds_write_b128 v251, v[40:43] offset:46080
	s_waitcnt vmcnt(13)
	ds_write_b128 v251, v[44:47] offset:55296
	s_waitcnt vmcnt(12)
	ds_write_b128 v251, v[48:51] offset:64512
	s_waitcnt vmcnt(11)
	ds_write_b128 v250, v[52:55] offset:36864
	s_waitcnt vmcnt(10)
	ds_write_b128 v250, v[56:59] offset:46080
	s_waitcnt vmcnt(9)
	ds_write_b128 v250, v[60:63] offset:55296
	s_waitcnt vmcnt(8)
	ds_write_b128 v250, v[64:67] offset:64512
	ds_read_b128 v[178:181], v249
	ds_read_b128 v[194:197], v248
	ds_read_b128 v[182:185], v249 offset:4608
	ds_read_b128 v[198:201], v248 offset:4608
	ds_read_b128 v[202:205], v248 offset:9216
	ds_read_b128 v[206:209], v248 offset:13824
	s_waitcnt lgkmcnt(4)
	v_mfma_f32_32x32x16_bf16 v[114:129], v[178:181], v[194:197], 0
	s_waitcnt lgkmcnt(3)
	v_mfma_f32_32x32x16_bf16 v[130:145], v[182:185], v[194:197], 0
	s_waitcnt lgkmcnt(2)
	v_mfma_f32_32x32x16_bf16 v[82:97], v[178:181], v[198:201], 0
	ds_read_b128 v[186:189], v249 offset:32
	v_mfma_f32_32x32x16_bf16 v[98:113], v[182:185], v[198:201], 0
	ds_read_b128 v[210:213], v248 offset:32
	s_waitcnt lgkmcnt(3)
	v_mfma_f32_32x32x16_bf16 v[50:65], v[178:181], v[202:205], 0
	ds_read_b128 v[190:193], v249 offset:4640
	v_mfma_f32_32x32x16_bf16 v[66:81], v[182:185], v[202:205], 0
	ds_read_b128 v[214:217], v248 offset:4640
	s_waitcnt lgkmcnt(4)
;     ...
;   for (int kt = 0; kt < nk; ++kt) {
;     __syncthreads();
;     if (kt + 1 < nk) {
;       u16* aw = As0 + ((kt + 1) & 1) * 256 * LD;
;       u16* bw = Bs0 + ((kt + 1) & 1) * 256 * LD;
; #pragma unroll
;       for (int i = 0; i < 4; ++i) { *(u32x4*)(aw + (srow + 64 * i) * LD + skc * 8) = ra[i]; *(u32x4*)(bw + (srow + 64 * i) * LD + skc * 8) = rb[i]; }
;     }
;     if (kt + 2 < nk) {
; #pragma unroll
;       for (int i = 0; i < 4; ++i) { ra[i] = *(const u32x4*)(Ag + (size_t)(64 * i) * K + (kt + 2) * 64); rb[i] = *(const u32x4*)(Bg[i] + (kt + 2) * 64); }
;     }
;     __builtin_amdgcn_sched_barrier(0);
;     const u16* as = As0 + (kt & 1) * 256 * LD + (wr * 128 + l31) * LD + h * 8;
;     const u16* bs = Bs0 + (kt & 1) * 256 * LD + (wc * 64 + l31) * LD + h * 8;
;     if (domma)
; #pragma unroll
;     for (int ks = 0; ks < 4; ++ks) {
;       bf16x8 wf[2], xf[4];
; #pragma unroll
;       for (int ct = 0; ct < 2; ++ct) wf[ct] = *(const bf16x8*)(bs + ct * 32 * LD + ks * 16);
; #pragma unroll
;       for (int tt = 0; tt < 4; ++tt) xf[tt] = *(const bf16x8*)(as + tt * 32 * LD + ks * 16);
; #pragma unroll
;       for (int ct = 0; ct < 2; ++ct)
; #pragma unroll
;         for (int tt = 0; tt < 4; ++tt) acc[ct][tt] = __builtin_amdgcn_mfma_f32_32x32x16_bf16(wf[ct], xf[tt], acc[ct][tt], 0, 0, 0);
;     }
	v_mfma_f32_32x32x16_bf16 v[18:33], v[178:181], v[206:209], 0
	ds_read_b128 v[4:7], v248 offset:9248
	v_mfma_f32_32x32x16_bf16 v[34:49], v[182:185], v[206:209], 0
	ds_read_b128 v[8:11], v248 offset:13856
	s_waitcnt lgkmcnt(4)
	v_mfma_f32_32x32x16_bf16 v[114:129], v[186:189], v[210:213], v[114:129]
	s_waitcnt lgkmcnt(3)
	v_mfma_f32_32x32x16_bf16 v[130:145], v[190:193], v[210:213], v[130:145]
	s_waitcnt lgkmcnt(2)
	v_mfma_f32_32x32x16_bf16 v[82:97], v[186:189], v[214:217], v[82:97]
	ds_read_b128 v[178:181], v249 offset:64
	v_mfma_f32_32x32x16_bf16 v[98:113], v[190:193], v[214:217], v[98:113]
	ds_read_b128 v[194:197], v248 offset:64
	s_waitcnt lgkmcnt(3)
	v_mfma_f32_32x32x16_bf16 v[50:65], v[186:189], v[4:7], v[50:65]
	ds_read_b128 v[182:185], v249 offset:4672
	v_mfma_f32_32x32x16_bf16 v[66:81], v[190:193], v[4:7], v[66:81]
	ds_read_b128 v[198:201], v248 offset:4672
	s_waitcnt lgkmcnt(4)
	v_mfma_f32_32x32x16_bf16 v[18:33], v[186:189], v[8:11], v[18:33]
	ds_read_b128 v[202:205], v248 offset:9280
	v_mfma_f32_32x32x16_bf16 v[34:49], v[190:193], v[8:11], v[34:49]
	ds_read_b128 v[206:209], v248 offset:13888
	s_waitcnt lgkmcnt(4)
	v_mfma_f32_32x32x16_bf16 v[114:129], v[178:181], v[194:197], v[114:129]
	s_waitcnt lgkmcnt(3)
	v_mfma_f32_32x32x16_bf16 v[130:145], v[182:185], v[194:197], v[130:145]
	s_waitcnt lgkmcnt(2)
	v_mfma_f32_32x32x16_bf16 v[82:97], v[178:181], v[198:201], v[82:97]
	ds_read_b128 v[186:189], v249 offset:96
	v_mfma_f32_32x32x16_bf16 v[98:113], v[182:185], v[198:201], v[98:113]
	ds_read_b128 v[210:213], v248 offset:96
	s_waitcnt lgkmcnt(3)
	v_mfma_f32_32x32x16_bf16 v[50:65], v[178:181], v[202:205], v[50:65]
	ds_read_b128 v[190:193], v249 offset:4704
	v_mfma_f32_32x32x16_bf16 v[66:81], v[182:185], v[202:205], v[66:81]
	ds_read_b128 v[214:217], v248 offset:4704
	s_waitcnt lgkmcnt(4)
	v_mfma_f32_32x32x16_bf16 v[18:33], v[178:181], v[206:209], v[18:33]
	ds_read_b128 v[4:7], v248 offset:9312
	v_mfma_f32_32x32x16_bf16 v[34:49], v[182:185], v[206:209], v[34:49]
	ds_read_b128 v[8:11], v248 offset:13920
	s_waitcnt lgkmcnt(4)
	v_mfma_f32_32x32x16_bf16 v[114:129], v[186:189], v[210:213], v[114:129]
	s_waitcnt lgkmcnt(3)
	v_mfma_f32_32x32x16_bf16 v[130:145], v[190:193], v[210:213], v[130:145]
	s_waitcnt lgkmcnt(2)
	v_mfma_f32_32x32x16_bf16 v[82:97], v[186:189], v[214:217], v[82:97]
	v_mfma_f32_32x32x16_bf16 v[98:113], v[190:193], v[214:217], v[98:113]
	s_waitcnt lgkmcnt(1)
	v_mfma_f32_32x32x16_bf16 v[50:65], v[186:189], v[4:7], v[50:65]
	v_mfma_f32_32x32x16_bf16 v[66:81], v[190:193], v[4:7], v[66:81]
	s_waitcnt lgkmcnt(0)
	v_mfma_f32_32x32x16_bf16 v[18:33], v[186:189], v[8:11], v[18:33]
	v_mfma_f32_32x32x16_bf16 v[34:49], v[190:193], v[8:11], v[34:49]
	s_barrier
	ds_read_b128 v[178:181], v249 offset:36864
	ds_read_b128 v[194:197], v248 offset:36864
	ds_read_b128 v[182:185], v249 offset:41472
	ds_read_b128 v[198:201], v248 offset:41472
	ds_read_b128 v[202:205], v248 offset:46080
	ds_read_b128 v[206:209], v248 offset:50688
	s_waitcnt lgkmcnt(4)
	v_mfma_f32_32x32x16_bf16 v[114:129], v[178:181], v[194:197], v[114:129]
	s_waitcnt lgkmcnt(3)
	v_mfma_f32_32x32x16_bf16 v[130:145], v[182:185], v[194:197], v[130:145]
	s_waitcnt lgkmcnt(2)
	v_mfma_f32_32x32x16_bf16 v[82:97], v[178:181], v[198:201], v[82:97]
	ds_read_b128 v[186:189], v249 offset:36896
	v_mfma_f32_32x32x16_bf16 v[98:113], v[182:185], v[198:201], v[98:113]
	ds_read_b128 v[210:213], v248 offset:36896
	s_waitcnt vmcnt(7)
	ds_write_b128 v250, v[146:149]
	s_waitcnt lgkmcnt(4)
	v_mfma_f32_32x32x16_bf16 v[50:65], v[178:181], v[202:205], v[50:65]
	ds_read_b128 v[190:193], v249 offset:41504
	v_mfma_f32_32x32x16_bf16 v[66:81], v[182:185], v[202:205], v[66:81]
	ds_read_b128 v[214:217], v248 offset:41504
	global_load_dwordx4 v[146:149], v[230:231], off offset:384
	s_waitcnt lgkmcnt(5)
	v_mfma_f32_32x32x16_bf16 v[18:33], v[178:181], v[206:209], v[18:33]
	ds_read_b128 v[4:7], v248 offset:46112
	s_waitcnt vmcnt(7)
	ds_write_b128 v251, v[162:165]
	v_mfma_f32_32x32x16_bf16 v[34:49], v[182:185], v[206:209], v[34:49]
	ds_read_b128 v[8:11], v248 offset:50720
	s_waitcnt lgkmcnt(6)
	v_mfma_f32_32x32x16_bf16 v[114:129], v[186:189], v[210:213], v[114:129]
	global_load_dwordx4 v[162:165], v[228:229], off offset:384
	s_waitcnt lgkmcnt(4)
	v_mfma_f32_32x32x16_bf16 v[130:145], v[190:193], v[210:213], v[130:145]
	s_waitcnt vmcnt(7)
	ds_write_b128 v250, v[150:153] offset:9216
	s_waitcnt lgkmcnt(4)
	v_mfma_f32_32x32x16_bf16 v[82:97], v[186:189], v[214:217], v[82:97]
	ds_read_b128 v[178:181], v249 offset:36928
	v_mfma_f32_32x32x16_bf16 v[98:113], v[190:193], v[214:217], v[98:113]
	ds_read_b128 v[194:197], v248 offset:36928
	global_load_dwordx4 v[150:153], v[232:233], off offset:384
	s_waitcnt lgkmcnt(5)
	v_mfma_f32_32x32x16_bf16 v[50:65], v[186:189], v[4:7], v[50:65]
	ds_read_b128 v[182:185], v249 offset:41536
	s_waitcnt vmcnt(7)
	ds_write_b128 v251, v[166:169] offset:9216
	v_mfma_f32_32x32x16_bf16 v[66:81], v[190:193], v[4:7], v[66:81]
	ds_read_b128 v[198:201], v248 offset:41536
	s_waitcnt lgkmcnt(6)
	v_mfma_f32_32x32x16_bf16 v[18:33], v[186:189], v[8:11], v[18:33]
	ds_read_b128 v[202:205], v248 offset:46144
	global_load_dwordx4 v[166:169], v[238:239], off offset:384
	v_mfma_f32_32x32x16_bf16 v[34:49], v[190:193], v[8:11], v[34:49]
	ds_read_b128 v[206:209], v248 offset:50752
	s_waitcnt vmcnt(7)
	ds_write_b128 v250, v[154:157] offset:18432
	s_waitcnt lgkmcnt(6)
	v_mfma_f32_32x32x16_bf16 v[114:129], v[178:181], v[194:197], v[114:129]
	s_waitcnt lgkmcnt(5)
	v_mfma_f32_32x32x16_bf16 v[130:145], v[182:185], v[194:197], v[130:145]
	global_load_dwordx4 v[154:157], v[12:13], off offset:384
	s_waitcnt lgkmcnt(3)
;     ...
;   for (int kt = 0; kt < nk; ++kt) {
;     __syncthreads();
;     if (kt + 1 < nk) {
;       u16* aw = As0 + ((kt + 1) & 1) * 256 * LD;
;       u16* bw = Bs0 + ((kt + 1) & 1) * 256 * LD;
; #pragma unroll
;       for (int i = 0; i < 4; ++i) { *(u32x4*)(aw + (srow + 64 * i) * LD + skc * 8) = ra[i]; *(u32x4*)(bw + (srow + 64 * i) * LD + skc * 8) = rb[i]; }
;     }
;     if (kt + 2 < nk) {
; #pragma unroll
;       for (int i = 0; i < 4; ++i) { ra[i] = *(const u32x4*)(Ag + (size_t)(64 * i) * K + (kt + 2) * 64); rb[i] = *(const u32x4*)(Bg[i] + (kt + 2) * 64); }
;     }
;     __builtin_amdgcn_sched_barrier(0);
;     const u16* as = As0 + (kt & 1) * 256 * LD + (wr * 128 + l31) * LD + h * 8;
;     const u16* bs = Bs0 + (kt & 1) * 256 * LD + (wc * 64 + l31) * LD + h * 8;
;     if (domma)
; #pragma unroll
;     for (int ks = 0; ks < 4; ++ks) {
;       bf16x8 wf[2], xf[4];
; #pragma unroll
;       for (int ct = 0; ct < 2; ++ct) wf[ct] = *(const bf16x8*)(bs + ct * 32 * LD + ks * 16);
; #pragma unroll
;       for (int tt = 0; tt < 4; ++tt) xf[tt] = *(const bf16x8*)(as + tt * 32 * LD + ks * 16);
; #pragma unroll
;       for (int ct = 0; ct < 2; ++ct)
; #pragma unroll
;         for (int tt = 0; tt < 4; ++tt) acc[ct][tt] = __builtin_amdgcn_mfma_f32_32x32x16_bf16(wf[ct], xf[tt], acc[ct][tt], 0, 0, 0);
;     }
	v_mfma_f32_32x32x16_bf16 v[82:97], v[178:181], v[198:201], v[82:97]
	ds_read_b128 v[186:189], v249 offset:36960
	s_waitcnt vmcnt(7)
	ds_write_b128 v251, v[170:173] offset:18432
	v_mfma_f32_32x32x16_bf16 v[98:113], v[182:185], v[198:201], v[98:113]
	ds_read_b128 v[210:213], v248 offset:36960
	s_waitcnt lgkmcnt(5)
	v_mfma_f32_32x32x16_bf16 v[50:65], v[178:181], v[202:205], v[50:65]
	ds_read_b128 v[190:193], v249 offset:41568
	global_load_dwordx4 v[170:173], v[234:235], off offset:384
	v_mfma_f32_32x32x16_bf16 v[66:81], v[182:185], v[202:205], v[66:81]
	ds_read_b128 v[214:217], v248 offset:41568
	s_waitcnt vmcnt(7)
	ds_write_b128 v250, v[158:161] offset:27648
	s_waitcnt lgkmcnt(7)
	v_mfma_f32_32x32x16_bf16 v[18:33], v[178:181], v[206:209], v[18:33]
	ds_read_b128 v[4:7], v248 offset:46176
	v_mfma_f32_32x32x16_bf16 v[34:49], v[182:185], v[206:209], v[34:49]
	ds_read_b128 v[8:11], v248 offset:50784
	global_load_dwordx4 v[158:161], v[14:15], off offset:384
	s_waitcnt lgkmcnt(5)
	v_mfma_f32_32x32x16_bf16 v[114:129], v[186:189], v[210:213], v[114:129]
	s_waitcnt vmcnt(7)
	ds_write_b128 v251, v[174:177] offset:27648
	s_waitcnt lgkmcnt(5)
	v_mfma_f32_32x32x16_bf16 v[130:145], v[190:193], v[210:213], v[130:145]
	s_waitcnt lgkmcnt(4)
	v_mfma_f32_32x32x16_bf16 v[82:97], v[186:189], v[214:217], v[82:97]
	global_load_dwordx4 v[174:177], v[236:237], off offset:384
	v_mfma_f32_32x32x16_bf16 v[98:113], v[190:193], v[214:217], v[98:113]
	s_waitcnt lgkmcnt(2)
	v_mfma_f32_32x32x16_bf16 v[50:65], v[186:189], v[4:7], v[50:65]
	v_mfma_f32_32x32x16_bf16 v[66:81], v[190:193], v[4:7], v[66:81]
	s_waitcnt lgkmcnt(1)
	v_mfma_f32_32x32x16_bf16 v[18:33], v[186:189], v[8:11], v[18:33]
	v_mfma_f32_32x32x16_bf16 v[34:49], v[190:193], v[8:11], v[34:49]
	s_waitcnt lgkmcnt(0)
	s_barrier
	ds_read_b128 v[178:181], v249
	ds_read_b128 v[194:197], v248
	ds_read_b128 v[182:185], v249 offset:4608
	ds_read_b128 v[198:201], v248 offset:4608
	ds_read_b128 v[202:205], v248 offset:9216
	ds_read_b128 v[206:209], v248 offset:13824
	s_waitcnt lgkmcnt(4)
	v_mfma_f32_32x32x16_bf16 v[114:129], v[178:181], v[194:197], v[114:129]
	s_waitcnt lgkmcnt(3)
	v_mfma_f32_32x32x16_bf16 v[130:145], v[182:185], v[194:197], v[130:145]
	s_waitcnt lgkmcnt(2)
	v_mfma_f32_32x32x16_bf16 v[82:97], v[178:181], v[198:201], v[82:97]
	ds_read_b128 v[186:189], v249 offset:32
	v_mfma_f32_32x32x16_bf16 v[98:113], v[182:185], v[198:201], v[98:113]
	ds_read_b128 v[210:213], v248 offset:32
	s_waitcnt vmcnt(7)
	ds_write_b128 v250, v[146:149] offset:36864
	s_waitcnt lgkmcnt(4)
	v_mfma_f32_32x32x16_bf16 v[50:65], v[178:181], v[202:205], v[50:65]
	ds_read_b128 v[190:193], v249 offset:4640
	v_mfma_f32_32x32x16_bf16 v[66:81], v[182:185], v[202:205], v[66:81]
	ds_read_b128 v[214:217], v248 offset:4640
	global_load_dwordx4 v[146:149], v[230:231], off offset:512
	s_waitcnt lgkmcnt(5)
	v_mfma_f32_32x32x16_bf16 v[18:33], v[178:181], v[206:209], v[18:33]
	ds_read_b128 v[4:7], v248 offset:9248
	s_waitcnt vmcnt(7)
	ds_write_b128 v251, v[162:165] offset:36864
	v_mfma_f32_32x32x16_bf16 v[34:49], v[182:185], v[206:209], v[34:49]
	ds_read_b128 v[8:11], v248 offset:13856
	s_waitcnt lgkmcnt(6)
	v_mfma_f32_32x32x16_bf16 v[114:129], v[186:189], v[210:213], v[114:129]
	global_load_dwordx4 v[162:165], v[228:229], off offset:512
	s_waitcnt lgkmcnt(4)
	v_mfma_f32_32x32x16_bf16 v[130:145], v[190:193], v[210:213], v[130:145]
	s_waitcnt vmcnt(7)
	ds_write_b128 v250, v[150:153] offset:46080
	s_waitcnt lgkmcnt(4)
	v_mfma_f32_32x32x16_bf16 v[82:97], v[186:189], v[214:217], v[82:97]
	ds_read_b128 v[178:181], v249 offset:64
	v_mfma_f32_32x32x16_bf16 v[98:113], v[190:193], v[214:217], v[98:113]
	ds_read_b128 v[194:197], v248 offset:64
	global_load_dwordx4 v[150:153], v[232:233], off offset:512
	s_waitcnt lgkmcnt(5)
	v_mfma_f32_32x32x16_bf16 v[50:65], v[186:189], v[4:7], v[50:65]
	ds_read_b128 v[182:185], v249 offset:4672
	s_waitcnt vmcnt(7)
	ds_write_b128 v251, v[166:169] offset:46080
	v_mfma_f32_32x32x16_bf16 v[66:81], v[190:193], v[4:7], v[66:81]
	ds_read_b128 v[198:201], v248 offset:4672
	s_waitcnt lgkmcnt(6)
	v_mfma_f32_32x32x16_bf16 v[18:33], v[186:189], v[8:11], v[18:33]
	ds_read_b128 v[202:205], v248 offset:9280
	global_load_dwordx4 v[166:169], v[238:239], off offset:512
	v_mfma_f32_32x32x16_bf16 v[34:49], v[190:193], v[8:11], v[34:49]
	ds_read_b128 v[206:209], v248 offset:13888
	s_waitcnt vmcnt(7)
	ds_write_b128 v250, v[154:157] offset:55296
	s_waitcnt lgkmcnt(6)
	v_mfma_f32_32x32x16_bf16 v[114:129], v[178:181], v[194:197], v[114:129]
	s_waitcnt lgkmcnt(5)
	v_mfma_f32_32x32x16_bf16 v[130:145], v[182:185], v[194:197], v[130:145]
	global_load_dwordx4 v[154:157], v[12:13], off offset:512
	s_waitcnt lgkmcnt(3)
	v_mfma_f32_32x32x16_bf16 v[82:97], v[178:181], v[198:201], v[82:97]
	ds_read_b128 v[186:189], v249 offset:96
	s_waitcnt vmcnt(7)
	ds_write_b128 v251, v[170:173] offset:55296
	v_mfma_f32_32x32x16_bf16 v[98:113], v[182:185], v[198:201], v[98:113]
	ds_read_b128 v[210:213], v248 offset:96
	s_waitcnt lgkmcnt(5)
	v_mfma_f32_32x32x16_bf16 v[50:65], v[178:181], v[202:205], v[50:65]
	ds_read_b128 v[190:193], v249 offset:4704
	global_load_dwordx4 v[170:173], v[234:235], off offset:512
	v_mfma_f32_32x32x16_bf16 v[66:81], v[182:185], v[202:205], v[66:81]
	ds_read_b128 v[214:217], v248 offset:4704
	s_waitcnt vmcnt(7)
	ds_write_b128 v250, v[158:161] offset:64512
	s_waitcnt lgkmcnt(7)
	v_mfma_f32_32x32x16_bf16 v[18:33], v[178:181], v[206:209], v[18:33]
	ds_read_b128 v[4:7], v248 offset:9312
	v_mfma_f32_32x32x16_bf16 v[34:49], v[182:185], v[206:209], v[34:49]
	ds_read_b128 v[8:11], v248 offset:13920
	global_load_dwordx4 v[158:161], v[14:15], off offset:512
	s_waitcnt lgkmcnt(5)
	v_mfma_f32_32x32x16_bf16 v[114:129], v[186:189], v[210:213], v[114:129]
	s_waitcnt vmcnt(7)
	ds_write_b128 v251, v[174:177] offset:64512
	s_waitcnt lgkmcnt(5)
	v_mfma_f32_32x32x16_bf16 v[130:145], v[190:193], v[210:213], v[130:145]
	s_waitcnt lgkmcnt(4)
	v_mfma_f32_32x32x16_bf16 v[82:97], v[186:189], v[214:217], v[82:97]
	global_load_dwordx4 v[174:177], v[236:237], off offset:512
	v_mfma_f32_32x32x16_bf16 v[98:113], v[190:193], v[214:217], v[98:113]
	s_waitcnt lgkmcnt(2)
	v_mfma_f32_32x32x16_bf16 v[50:65], v[186:189], v[4:7], v[50:65]
	v_mfma_f32_32x32x16_bf16 v[66:81], v[190:193], v[4:7], v[66:81]
	s_waitcnt lgkmcnt(1)
	v_mfma_f32_32x32x16_bf16 v[18:33], v[186:189], v[8:11], v[18:33]
	v_mfma_f32_32x32x16_bf16 v[34:49], v[190:193], v[8:11], v[34:49]
	s_waitcnt lgkmcnt(0)
	s_barrier
;     ...
;   for (int kt = 0; kt < nk; ++kt) {
;     __syncthreads();
;     if (kt + 1 < nk) {
;       u16* aw = As0 + ((kt + 1) & 1) * 256 * LD;
;       u16* bw = Bs0 + ((kt + 1) & 1) * 256 * LD;
; #pragma unroll
;       for (int i = 0; i < 4; ++i) { *(u32x4*)(aw + (srow + 64 * i) * LD + skc * 8) = ra[i]; *(u32x4*)(bw + (srow + 64 * i) * LD + skc * 8) = rb[i]; }
;     }
;     if (kt + 2 < nk) {
; #pragma unroll
;       for (int i = 0; i < 4; ++i) { ra[i] = *(const u32x4*)(Ag + (size_t)(64 * i) * K + (kt + 2) * 64); rb[i] = *(const u32x4*)(Bg[i] + (kt + 2) * 64); }
;     }
;     __builtin_amdgcn_sched_barrier(0);
;     const u16* as = As0 + (kt & 1) * 256 * LD + (wr * 128 + l31) * LD + h * 8;
;     const u16* bs = Bs0 + (kt & 1) * 256 * LD + (wc * 64 + l31) * LD + h * 8;
;     if (domma)
; #pragma unroll
;     for (int ks = 0; ks < 4; ++ks) {
;       bf16x8 wf[2], xf[4];
; #pragma unroll
;       for (int ct = 0; ct < 2; ++ct) wf[ct] = *(const bf16x8*)(bs + ct * 32 * LD + ks * 16);
; #pragma unroll
;       for (int tt = 0; tt < 4; ++tt) xf[tt] = *(const bf16x8*)(as + tt * 32 * LD + ks * 16);
; #pragma unroll
;       for (int ct = 0; ct < 2; ++ct)
; #pragma unroll
;         for (int tt = 0; tt < 4; ++tt) acc[ct][tt] = __builtin_amdgcn_mfma_f32_32x32x16_bf16(wf[ct], xf[tt], acc[ct][tt], 0, 0, 0);
;     }
	ds_read_b128 v[178:181], v249 offset:36864
	ds_read_b128 v[194:197], v248 offset:36864
	ds_read_b128 v[182:185], v249 offset:41472
	ds_read_b128 v[198:201], v248 offset:41472
	ds_read_b128 v[202:205], v248 offset:46080
	ds_read_b128 v[206:209], v248 offset:50688
	s_waitcnt lgkmcnt(4)
	v_mfma_f32_32x32x16_bf16 v[114:129], v[178:181], v[194:197], v[114:129]
	s_waitcnt lgkmcnt(3)
	v_mfma_f32_32x32x16_bf16 v[130:145], v[182:185], v[194:197], v[130:145]
	s_waitcnt lgkmcnt(2)
	v_mfma_f32_32x32x16_bf16 v[82:97], v[178:181], v[198:201], v[82:97]
	ds_read_b128 v[186:189], v249 offset:36896
	v_mfma_f32_32x32x16_bf16 v[98:113], v[182:185], v[198:201], v[98:113]
	ds_read_b128 v[210:213], v248 offset:36896
	s_waitcnt vmcnt(7)
	ds_write_b128 v250, v[146:149]
	s_waitcnt lgkmcnt(4)
	v_mfma_f32_32x32x16_bf16 v[50:65], v[178:181], v[202:205], v[50:65]
	ds_read_b128 v[190:193], v249 offset:41504
	v_mfma_f32_32x32x16_bf16 v[66:81], v[182:185], v[202:205], v[66:81]
	ds_read_b128 v[214:217], v248 offset:41504
	global_load_dwordx4 v[146:149], v[230:231], off offset:640
	s_waitcnt lgkmcnt(5)
	v_mfma_f32_32x32x16_bf16 v[18:33], v[178:181], v[206:209], v[18:33]
	ds_read_b128 v[4:7], v248 offset:46112
	s_waitcnt vmcnt(7)
	ds_write_b128 v251, v[162:165]
	v_mfma_f32_32x32x16_bf16 v[34:49], v[182:185], v[206:209], v[34:49]
	ds_read_b128 v[8:11], v248 offset:50720
	s_waitcnt lgkmcnt(6)
	v_mfma_f32_32x32x16_bf16 v[114:129], v[186:189], v[210:213], v[114:129]
	global_load_dwordx4 v[162:165], v[228:229], off offset:640
	s_waitcnt lgkmcnt(4)
	v_mfma_f32_32x32x16_bf16 v[130:145], v[190:193], v[210:213], v[130:145]
	s_waitcnt vmcnt(7)
	ds_write_b128 v250, v[150:153] offset:9216
	s_waitcnt lgkmcnt(4)
	v_mfma_f32_32x32x16_bf16 v[82:97], v[186:189], v[214:217], v[82:97]
	ds_read_b128 v[178:181], v249 offset:36928
	v_mfma_f32_32x32x16_bf16 v[98:113], v[190:193], v[214:217], v[98:113]
	ds_read_b128 v[194:197], v248 offset:36928
	global_load_dwordx4 v[150:153], v[232:233], off offset:640
	s_waitcnt lgkmcnt(5)
	v_mfma_f32_32x32x16_bf16 v[50:65], v[186:189], v[4:7], v[50:65]
	ds_read_b128 v[182:185], v249 offset:41536
	s_waitcnt vmcnt(7)
	ds_write_b128 v251, v[166:169] offset:9216
	v_mfma_f32_32x32x16_bf16 v[66:81], v[190:193], v[4:7], v[66:81]
	ds_read_b128 v[198:201], v248 offset:41536
	s_waitcnt lgkmcnt(6)
	v_mfma_f32_32x32x16_bf16 v[18:33], v[186:189], v[8:11], v[18:33]
	ds_read_b128 v[202:205], v248 offset:46144
	global_load_dwordx4 v[166:169], v[238:239], off offset:640
	v_mfma_f32_32x32x16_bf16 v[34:49], v[190:193], v[8:11], v[34:49]
	ds_read_b128 v[206:209], v248 offset:50752
	s_waitcnt vmcnt(7)
	ds_write_b128 v250, v[154:157] offset:18432
	s_waitcnt lgkmcnt(6)
	v_mfma_f32_32x32x16_bf16 v[114:129], v[178:181], v[194:197], v[114:129]
	s_waitcnt lgkmcnt(5)
	v_mfma_f32_32x32x16_bf16 v[130:145], v[182:185], v[194:197], v[130:145]
	global_load_dwordx4 v[154:157], v[12:13], off offset:640
	s_waitcnt lgkmcnt(3)
	v_mfma_f32_32x32x16_bf16 v[82:97], v[178:181], v[198:201], v[82:97]
	ds_read_b128 v[186:189], v249 offset:36960
	s_waitcnt vmcnt(7)
	ds_write_b128 v251, v[170:173] offset:18432
	v_mfma_f32_32x32x16_bf16 v[98:113], v[182:185], v[198:201], v[98:113]
	ds_read_b128 v[210:213], v248 offset:36960
	s_waitcnt lgkmcnt(5)
	v_mfma_f32_32x32x16_bf16 v[50:65], v[178:181], v[202:205], v[50:65]
	ds_read_b128 v[190:193], v249 offset:41568
	global_load_dwordx4 v[170:173], v[234:235], off offset:640
	v_mfma_f32_32x32x16_bf16 v[66:81], v[182:185], v[202:205], v[66:81]
	ds_read_b128 v[214:217], v248 offset:41568
	s_waitcnt vmcnt(7)
	ds_write_b128 v250, v[158:161] offset:27648
	s_waitcnt lgkmcnt(7)
	v_mfma_f32_32x32x16_bf16 v[18:33], v[178:181], v[206:209], v[18:33]
	ds_read_b128 v[4:7], v248 offset:46176
	v_mfma_f32_32x32x16_bf16 v[34:49], v[182:185], v[206:209], v[34:49]
	ds_read_b128 v[8:11], v248 offset:50784
	global_load_dwordx4 v[158:161], v[14:15], off offset:640
	s_waitcnt lgkmcnt(5)
	v_mfma_f32_32x32x16_bf16 v[114:129], v[186:189], v[210:213], v[114:129]
	s_waitcnt vmcnt(7)
	ds_write_b128 v251, v[174:177] offset:27648
	s_waitcnt lgkmcnt(5)
	v_mfma_f32_32x32x16_bf16 v[130:145], v[190:193], v[210:213], v[130:145]
	s_waitcnt lgkmcnt(4)
	v_mfma_f32_32x32x16_bf16 v[82:97], v[186:189], v[214:217], v[82:97]
	global_load_dwordx4 v[174:177], v[236:237], off offset:640
	v_mfma_f32_32x32x16_bf16 v[98:113], v[190:193], v[214:217], v[98:113]
	s_waitcnt lgkmcnt(2)
	v_mfma_f32_32x32x16_bf16 v[50:65], v[186:189], v[4:7], v[50:65]
	v_mfma_f32_32x32x16_bf16 v[66:81], v[190:193], v[4:7], v[66:81]
	s_waitcnt lgkmcnt(1)
	v_mfma_f32_32x32x16_bf16 v[18:33], v[186:189], v[8:11], v[18:33]
	v_mfma_f32_32x32x16_bf16 v[34:49], v[190:193], v[8:11], v[34:49]
	s_waitcnt lgkmcnt(0)
	s_barrier
;     ...
;   for (int kt = 0; kt < nk; ++kt) {
;     __syncthreads();
;     if (kt + 1 < nk) {
;       u16* aw = As0 + ((kt + 1) & 1) * 256 * LD;
;       u16* bw = Bs0 + ((kt + 1) & 1) * 256 * LD;
; #pragma unroll
;       for (int i = 0; i < 4; ++i) { *(u32x4*)(aw + (srow + 64 * i) * LD + skc * 8) = ra[i]; *(u32x4*)(bw + (srow + 64 * i) * LD + skc * 8) = rb[i]; }
;     }
;     if (kt + 2 < nk) {
; #pragma unroll
;       for (int i = 0; i < 4; ++i) { ra[i] = *(const u32x4*)(Ag + (size_t)(64 * i) * K + (kt + 2) * 64); rb[i] = *(const u32x4*)(Bg[i] + (kt + 2) * 64); }
;     }
;     __builtin_amdgcn_sched_barrier(0);
;     const u16* as = As0 + (kt & 1) * 256 * LD + (wr * 128 + l31) * LD + h * 8;
;     const u16* bs = Bs0 + (kt & 1) * 256 * LD + (wc * 64 + l31) * LD + h * 8;
;     if (domma)
; #pragma unroll
;     for (int ks = 0; ks < 4; ++ks) {
;       bf16x8 wf[2], xf[4];
; #pragma unroll
;       for (int ct = 0; ct < 2; ++ct) wf[ct] = *(const bf16x8*)(bs + ct * 32 * LD + ks * 16);
; #pragma unroll
;       for (int tt = 0; tt < 4; ++tt) xf[tt] = *(const bf16x8*)(as + tt * 32 * LD + ks * 16);
; #pragma unroll
;       for (int ct = 0; ct < 2; ++ct)
; #pragma unroll
;         for (int tt = 0; tt < 4; ++tt) acc[ct][tt] = __builtin_amdgcn_mfma_f32_32x32x16_bf16(wf[ct], xf[tt], acc[ct][tt], 0, 0, 0);
;     }
	ds_read_b128 v[178:181], v249
	ds_read_b128 v[194:197], v248
	ds_read_b128 v[182:185], v249 offset:4608
	ds_read_b128 v[198:201], v248 offset:4608
	ds_read_b128 v[202:205], v248 offset:9216
	ds_read_b128 v[206:209], v248 offset:13824
	s_waitcnt lgkmcnt(4)
	v_mfma_f32_32x32x16_bf16 v[114:129], v[178:181], v[194:197], v[114:129]
	s_waitcnt lgkmcnt(3)
	v_mfma_f32_32x32x16_bf16 v[130:145], v[182:185], v[194:197], v[130:145]
	s_waitcnt lgkmcnt(2)
	v_mfma_f32_32x32x16_bf16 v[82:97], v[178:181], v[198:201], v[82:97]
	ds_read_b128 v[186:189], v249 offset:32
	v_mfma_f32_32x32x16_bf16 v[98:113], v[182:185], v[198:201], v[98:113]
	ds_read_b128 v[210:213], v248 offset:32
	s_waitcnt vmcnt(7)
	ds_write_b128 v250, v[146:149] offset:36864
	s_waitcnt lgkmcnt(4)
	v_mfma_f32_32x32x16_bf16 v[50:65], v[178:181], v[202:205], v[50:65]
	ds_read_b128 v[190:193], v249 offset:4640
	v_mfma_f32_32x32x16_bf16 v[66:81], v[182:185], v[202:205], v[66:81]
	ds_read_b128 v[214:217], v248 offset:4640
	global_load_dwordx4 v[146:149], v[230:231], off offset:768
	s_waitcnt lgkmcnt(5)
	v_mfma_f32_32x32x16_bf16 v[18:33], v[178:181], v[206:209], v[18:33]
	ds_read_b128 v[4:7], v248 offset:9248
	s_waitcnt vmcnt(7)
	ds_write_b128 v251, v[162:165] offset:36864
	v_mfma_f32_32x32x16_bf16 v[34:49], v[182:185], v[206:209], v[34:49]
	ds_read_b128 v[8:11], v248 offset:13856
	s_waitcnt lgkmcnt(6)
	v_mfma_f32_32x32x16_bf16 v[114:129], v[186:189], v[210:213], v[114:129]
	global_load_dwordx4 v[162:165], v[228:229], off offset:768
	s_waitcnt lgkmcnt(4)
	v_mfma_f32_32x32x16_bf16 v[130:145], v[190:193], v[210:213], v[130:145]
	s_waitcnt vmcnt(7)
	ds_write_b128 v250, v[150:153] offset:46080
	s_waitcnt lgkmcnt(4)
	v_mfma_f32_32x32x16_bf16 v[82:97], v[186:189], v[214:217], v[82:97]
	ds_read_b128 v[178:181], v249 offset:64
	v_mfma_f32_32x32x16_bf16 v[98:113], v[190:193], v[214:217], v[98:113]
	ds_read_b128 v[194:197], v248 offset:64
	global_load_dwordx4 v[150:153], v[232:233], off offset:768
	s_waitcnt lgkmcnt(5)
	v_mfma_f32_32x32x16_bf16 v[50:65], v[186:189], v[4:7], v[50:65]
	ds_read_b128 v[182:185], v249 offset:4672
	s_waitcnt vmcnt(7)
	ds_write_b128 v251, v[166:169] offset:46080
	v_mfma_f32_32x32x16_bf16 v[66:81], v[190:193], v[4:7], v[66:81]
	ds_read_b128 v[198:201], v248 offset:4672
	s_waitcnt lgkmcnt(6)
	v_mfma_f32_32x32x16_bf16 v[18:33], v[186:189], v[8:11], v[18:33]
	ds_read_b128 v[202:205], v248 offset:9280
	global_load_dwordx4 v[166:169], v[238:239], off offset:768
	v_mfma_f32_32x32x16_bf16 v[34:49], v[190:193], v[8:11], v[34:49]
	ds_read_b128 v[206:209], v248 offset:13888
	s_waitcnt vmcnt(7)
	ds_write_b128 v250, v[154:157] offset:55296
	s_waitcnt lgkmcnt(6)
	v_mfma_f32_32x32x16_bf16 v[114:129], v[178:181], v[194:197], v[114:129]
	s_waitcnt lgkmcnt(5)
	v_mfma_f32_32x32x16_bf16 v[130:145], v[182:185], v[194:197], v[130:145]
	global_load_dwordx4 v[154:157], v[12:13], off offset:768
	s_waitcnt lgkmcnt(3)
	v_mfma_f32_32x32x16_bf16 v[82:97], v[178:181], v[198:201], v[82:97]
	ds_read_b128 v[186:189], v249 offset:96
	s_waitcnt vmcnt(7)
	ds_write_b128 v251, v[170:173] offset:55296
	v_mfma_f32_32x32x16_bf16 v[98:113], v[182:185], v[198:201], v[98:113]
	ds_read_b128 v[210:213], v248 offset:96
	s_waitcnt lgkmcnt(5)
	v_mfma_f32_32x32x16_bf16 v[50:65], v[178:181], v[202:205], v[50:65]
	ds_read_b128 v[190:193], v249 offset:4704
	global_load_dwordx4 v[170:173], v[234:235], off offset:768
	v_mfma_f32_32x32x16_bf16 v[66:81], v[182:185], v[202:205], v[66:81]
	ds_read_b128 v[214:217], v248 offset:4704
	s_waitcnt vmcnt(7)
	ds_write_b128 v250, v[158:161] offset:64512
	s_waitcnt lgkmcnt(7)
	v_mfma_f32_32x32x16_bf16 v[18:33], v[178:181], v[206:209], v[18:33]
	ds_read_b128 v[4:7], v248 offset:9312
	v_mfma_f32_32x32x16_bf16 v[34:49], v[182:185], v[206:209], v[34:49]
	ds_read_b128 v[8:11], v248 offset:13920
	global_load_dwordx4 v[158:161], v[14:15], off offset:768
	s_waitcnt lgkmcnt(5)
	v_mfma_f32_32x32x16_bf16 v[114:129], v[186:189], v[210:213], v[114:129]
	s_waitcnt vmcnt(7)
	ds_write_b128 v251, v[174:177] offset:64512
	s_waitcnt lgkmcnt(5)
	v_mfma_f32_32x32x16_bf16 v[130:145], v[190:193], v[210:213], v[130:145]
	s_waitcnt lgkmcnt(4)
	v_mfma_f32_32x32x16_bf16 v[82:97], v[186:189], v[214:217], v[82:97]
	global_load_dwordx4 v[174:177], v[236:237], off offset:768
	v_mfma_f32_32x32x16_bf16 v[98:113], v[190:193], v[214:217], v[98:113]
	s_waitcnt lgkmcnt(2)
	v_mfma_f32_32x32x16_bf16 v[50:65], v[186:189], v[4:7], v[50:65]
	v_mfma_f32_32x32x16_bf16 v[66:81], v[190:193], v[4:7], v[66:81]
	s_waitcnt lgkmcnt(1)
	v_mfma_f32_32x32x16_bf16 v[18:33], v[186:189], v[8:11], v[18:33]
	v_mfma_f32_32x32x16_bf16 v[34:49], v[190:193], v[8:11], v[34:49]
	s_waitcnt lgkmcnt(0)
	s_barrier
;     ...
;   for (int kt = 0; kt < nk; ++kt) {
;     __syncthreads();
;     if (kt + 1 < nk) {
;       u16* aw = As0 + ((kt + 1) & 1) * 256 * LD;
;       u16* bw = Bs0 + ((kt + 1) & 1) * 256 * LD;
; #pragma unroll
;       for (int i = 0; i < 4; ++i) { *(u32x4*)(aw + (srow + 64 * i) * LD + skc * 8) = ra[i]; *(u32x4*)(bw + (srow + 64 * i) * LD + skc * 8) = rb[i]; }
;     }
;     if (kt + 2 < nk) {
; #pragma unroll
;       for (int i = 0; i < 4; ++i) { ra[i] = *(const u32x4*)(Ag + (size_t)(64 * i) * K + (kt + 2) * 64); rb[i] = *(const u32x4*)(Bg[i] + (kt + 2) * 64); }
;     }
;     __builtin_amdgcn_sched_barrier(0);
;     const u16* as = As0 + (kt & 1) * 256 * LD + (wr * 128 + l31) * LD + h * 8;
;     const u16* bs = Bs0 + (kt & 1) * 256 * LD + (wc * 64 + l31) * LD + h * 8;
;     if (domma)
; #pragma unroll
;     for (int ks = 0; ks < 4; ++ks) {
;       bf16x8 wf[2], xf[4];
; #pragma unroll
;       for (int ct = 0; ct < 2; ++ct) wf[ct] = *(const bf16x8*)(bs + ct * 32 * LD + ks * 16);
; #pragma unroll
;       for (int tt = 0; tt < 4; ++tt) xf[tt] = *(const bf16x8*)(as + tt * 32 * LD + ks * 16);
; #pragma unroll
;       for (int ct = 0; ct < 2; ++ct)
; #pragma unroll
;         for (int tt = 0; tt < 4; ++tt) acc[ct][tt] = __builtin_amdgcn_mfma_f32_32x32x16_bf16(wf[ct], xf[tt], acc[ct][tt], 0, 0, 0);
;     }
	ds_read_b128 v[178:181], v249 offset:36864
	ds_read_b128 v[194:197], v248 offset:36864
	ds_read_b128 v[182:185], v249 offset:41472
	ds_read_b128 v[198:201], v248 offset:41472
	ds_read_b128 v[202:205], v248 offset:46080
	ds_read_b128 v[206:209], v248 offset:50688
	s_waitcnt lgkmcnt(4)
	v_mfma_f32_32x32x16_bf16 v[114:129], v[178:181], v[194:197], v[114:129]
	s_waitcnt lgkmcnt(3)
	v_mfma_f32_32x32x16_bf16 v[130:145], v[182:185], v[194:197], v[130:145]
	s_waitcnt lgkmcnt(2)
	v_mfma_f32_32x32x16_bf16 v[82:97], v[178:181], v[198:201], v[82:97]
	ds_read_b128 v[186:189], v249 offset:36896
	v_mfma_f32_32x32x16_bf16 v[98:113], v[182:185], v[198:201], v[98:113]
	ds_read_b128 v[210:213], v248 offset:36896
	s_waitcnt vmcnt(7)
	ds_write_b128 v250, v[146:149]
	s_waitcnt lgkmcnt(4)
	v_mfma_f32_32x32x16_bf16 v[50:65], v[178:181], v[202:205], v[50:65]
	ds_read_b128 v[190:193], v249 offset:41504
	v_mfma_f32_32x32x16_bf16 v[66:81], v[182:185], v[202:205], v[66:81]
	ds_read_b128 v[214:217], v248 offset:41504
	global_load_dwordx4 v[146:149], v[230:231], off offset:896
	s_waitcnt lgkmcnt(5)
	v_mfma_f32_32x32x16_bf16 v[18:33], v[178:181], v[206:209], v[18:33]
	ds_read_b128 v[4:7], v248 offset:46112
	s_waitcnt vmcnt(7)
	ds_write_b128 v251, v[162:165]
	v_mfma_f32_32x32x16_bf16 v[34:49], v[182:185], v[206:209], v[34:49]
	ds_read_b128 v[8:11], v248 offset:50720
	s_waitcnt lgkmcnt(6)
	v_mfma_f32_32x32x16_bf16 v[114:129], v[186:189], v[210:213], v[114:129]
	global_load_dwordx4 v[162:165], v[228:229], off offset:896
	s_waitcnt lgkmcnt(4)
	v_mfma_f32_32x32x16_bf16 v[130:145], v[190:193], v[210:213], v[130:145]
	s_waitcnt vmcnt(7)
	ds_write_b128 v250, v[150:153] offset:9216
	s_waitcnt lgkmcnt(4)
	v_mfma_f32_32x32x16_bf16 v[82:97], v[186:189], v[214:217], v[82:97]
	ds_read_b128 v[178:181], v249 offset:36928
	v_mfma_f32_32x32x16_bf16 v[98:113], v[190:193], v[214:217], v[98:113]
	ds_read_b128 v[194:197], v248 offset:36928
	global_load_dwordx4 v[150:153], v[232:233], off offset:896
	s_waitcnt lgkmcnt(5)
	v_mfma_f32_32x32x16_bf16 v[50:65], v[186:189], v[4:7], v[50:65]
	ds_read_b128 v[182:185], v249 offset:41536
	s_waitcnt vmcnt(7)
	ds_write_b128 v251, v[166:169] offset:9216
	v_mfma_f32_32x32x16_bf16 v[66:81], v[190:193], v[4:7], v[66:81]
	ds_read_b128 v[198:201], v248 offset:41536
	s_waitcnt lgkmcnt(6)
	v_mfma_f32_32x32x16_bf16 v[18:33], v[186:189], v[8:11], v[18:33]
	ds_read_b128 v[202:205], v248 offset:46144
	global_load_dwordx4 v[166:169], v[238:239], off offset:896
	v_mfma_f32_32x32x16_bf16 v[34:49], v[190:193], v[8:11], v[34:49]
	ds_read_b128 v[206:209], v248 offset:50752
	s_waitcnt vmcnt(7)
	ds_write_b128 v250, v[154:157] offset:18432
	s_waitcnt lgkmcnt(6)
	v_mfma_f32_32x32x16_bf16 v[114:129], v[178:181], v[194:197], v[114:129]
	s_waitcnt lgkmcnt(5)
	v_mfma_f32_32x32x16_bf16 v[130:145], v[182:185], v[194:197], v[130:145]
	global_load_dwordx4 v[154:157], v[12:13], off offset:896
	s_waitcnt lgkmcnt(3)
	v_mfma_f32_32x32x16_bf16 v[82:97], v[178:181], v[198:201], v[82:97]
	ds_read_b128 v[186:189], v249 offset:36960
	s_waitcnt vmcnt(7)
	ds_write_b128 v251, v[170:173] offset:18432
	v_mfma_f32_32x32x16_bf16 v[98:113], v[182:185], v[198:201], v[98:113]
	ds_read_b128 v[210:213], v248 offset:36960
	s_waitcnt lgkmcnt(5)
	v_mfma_f32_32x32x16_bf16 v[50:65], v[178:181], v[202:205], v[50:65]
	ds_read_b128 v[190:193], v249 offset:41568
	global_load_dwordx4 v[170:173], v[234:235], off offset:896
	v_mfma_f32_32x32x16_bf16 v[66:81], v[182:185], v[202:205], v[66:81]
	ds_read_b128 v[214:217], v248 offset:41568
	s_waitcnt vmcnt(7)
	ds_write_b128 v250, v[158:161] offset:27648
	s_waitcnt lgkmcnt(7)
	v_mfma_f32_32x32x16_bf16 v[18:33], v[178:181], v[206:209], v[18:33]
	ds_read_b128 v[4:7], v248 offset:46176
	v_mfma_f32_32x32x16_bf16 v[34:49], v[182:185], v[206:209], v[34:49]
	ds_read_b128 v[8:11], v248 offset:50784
	global_load_dwordx4 v[158:161], v[14:15], off offset:896
	s_waitcnt lgkmcnt(5)
	v_mfma_f32_32x32x16_bf16 v[114:129], v[186:189], v[210:213], v[114:129]
	s_waitcnt vmcnt(7)
	ds_write_b128 v251, v[174:177] offset:27648
	s_waitcnt lgkmcnt(5)
	v_mfma_f32_32x32x16_bf16 v[130:145], v[190:193], v[210:213], v[130:145]
	s_waitcnt lgkmcnt(4)
	v_mfma_f32_32x32x16_bf16 v[82:97], v[186:189], v[214:217], v[82:97]
	global_load_dwordx4 v[174:177], v[236:237], off offset:896
	v_mfma_f32_32x32x16_bf16 v[98:113], v[190:193], v[214:217], v[98:113]
	s_waitcnt lgkmcnt(2)
	v_mfma_f32_32x32x16_bf16 v[50:65], v[186:189], v[4:7], v[50:65]
	v_mfma_f32_32x32x16_bf16 v[66:81], v[190:193], v[4:7], v[66:81]
	s_waitcnt lgkmcnt(1)
	v_mfma_f32_32x32x16_bf16 v[18:33], v[186:189], v[8:11], v[18:33]
	v_mfma_f32_32x32x16_bf16 v[34:49], v[190:193], v[8:11], v[34:49]
	s_waitcnt lgkmcnt(0)
	s_barrier
;     ...
;   for (int kt = 0; kt < nk; ++kt) {
;     __syncthreads();
;     if (kt + 1 < nk) {
;       u16* aw = As0 + ((kt + 1) & 1) * 256 * LD;
;       u16* bw = Bs0 + ((kt + 1) & 1) * 256 * LD;
; #pragma unroll
;       for (int i = 0; i < 4; ++i) { *(u32x4*)(aw + (srow + 64 * i) * LD + skc * 8) = ra[i]; *(u32x4*)(bw + (srow + 64 * i) * LD + skc * 8) = rb[i]; }
;     }
;     if (kt + 2 < nk) {
; #pragma unroll
;       for (int i = 0; i < 4; ++i) { ra[i] = *(const u32x4*)(Ag + (size_t)(64 * i) * K + (kt + 2) * 64); rb[i] = *(const u32x4*)(Bg[i] + (kt + 2) * 64); }
;     }
;     __builtin_amdgcn_sched_barrier(0);
;     const u16* as = As0 + (kt & 1) * 256 * LD + (wr * 128 + l31) * LD + h * 8;
;     const u16* bs = Bs0 + (kt & 1) * 256 * LD + (wc * 64 + l31) * LD + h * 8;
;     if (domma)
; #pragma unroll
;     for (int ks = 0; ks < 4; ++ks) {
;       bf16x8 wf[2], xf[4];
; #pragma unroll
;       for (int ct = 0; ct < 2; ++ct) wf[ct] = *(const bf16x8*)(bs + ct * 32 * LD + ks * 16);
; #pragma unroll
;       for (int tt = 0; tt < 4; ++tt) xf[tt] = *(const bf16x8*)(as + tt * 32 * LD + ks * 16);
; #pragma unroll
;       for (int ct = 0; ct < 2; ++ct)
; #pragma unroll
;         for (int tt = 0; tt < 4; ++tt) acc[ct][tt] = __builtin_amdgcn_mfma_f32_32x32x16_bf16(wf[ct], xf[tt], acc[ct][tt], 0, 0, 0);
;     }
	ds_read_b128 v[178:181], v249
	ds_read_b128 v[194:197], v248
	ds_read_b128 v[182:185], v249 offset:4608
	ds_read_b128 v[198:201], v248 offset:4608
	ds_read_b128 v[202:205], v248 offset:9216
	ds_read_b128 v[206:209], v248 offset:13824
	s_waitcnt lgkmcnt(4)
	v_mfma_f32_32x32x16_bf16 v[114:129], v[178:181], v[194:197], v[114:129]
	s_waitcnt lgkmcnt(3)
	v_mfma_f32_32x32x16_bf16 v[130:145], v[182:185], v[194:197], v[130:145]
	s_waitcnt lgkmcnt(2)
	v_mfma_f32_32x32x16_bf16 v[82:97], v[178:181], v[198:201], v[82:97]
	ds_read_b128 v[186:189], v249 offset:32
	v_mfma_f32_32x32x16_bf16 v[98:113], v[182:185], v[198:201], v[98:113]
	ds_read_b128 v[210:213], v248 offset:32
	s_waitcnt vmcnt(7)
	ds_write_b128 v250, v[146:149] offset:36864
	s_waitcnt lgkmcnt(4)
	v_mfma_f32_32x32x16_bf16 v[50:65], v[178:181], v[202:205], v[50:65]
	ds_read_b128 v[190:193], v249 offset:4640
	v_mfma_f32_32x32x16_bf16 v[66:81], v[182:185], v[202:205], v[66:81]
	ds_read_b128 v[214:217], v248 offset:4640
	global_load_dwordx4 v[146:149], v[230:231], off offset:1024
	s_waitcnt lgkmcnt(5)
	v_mfma_f32_32x32x16_bf16 v[18:33], v[178:181], v[206:209], v[18:33]
	ds_read_b128 v[4:7], v248 offset:9248
	s_waitcnt vmcnt(7)
	ds_write_b128 v251, v[162:165] offset:36864
	v_mfma_f32_32x32x16_bf16 v[34:49], v[182:185], v[206:209], v[34:49]
	ds_read_b128 v[8:11], v248 offset:13856
	s_waitcnt lgkmcnt(6)
	v_mfma_f32_32x32x16_bf16 v[114:129], v[186:189], v[210:213], v[114:129]
	global_load_dwordx4 v[162:165], v[228:229], off offset:1024
	s_waitcnt lgkmcnt(4)
	v_mfma_f32_32x32x16_bf16 v[130:145], v[190:193], v[210:213], v[130:145]
	s_waitcnt vmcnt(7)
	ds_write_b128 v250, v[150:153] offset:46080
	s_waitcnt lgkmcnt(4)
	v_mfma_f32_32x32x16_bf16 v[82:97], v[186:189], v[214:217], v[82:97]
	ds_read_b128 v[178:181], v249 offset:64
	v_mfma_f32_32x32x16_bf16 v[98:113], v[190:193], v[214:217], v[98:113]
	ds_read_b128 v[194:197], v248 offset:64
	global_load_dwordx4 v[150:153], v[232:233], off offset:1024
	s_waitcnt lgkmcnt(5)
	v_mfma_f32_32x32x16_bf16 v[50:65], v[186:189], v[4:7], v[50:65]
	ds_read_b128 v[182:185], v249 offset:4672
	s_waitcnt vmcnt(7)
	ds_write_b128 v251, v[166:169] offset:46080
	v_mfma_f32_32x32x16_bf16 v[66:81], v[190:193], v[4:7], v[66:81]
	ds_read_b128 v[198:201], v248 offset:4672
	s_waitcnt lgkmcnt(6)
	v_mfma_f32_32x32x16_bf16 v[18:33], v[186:189], v[8:11], v[18:33]
	ds_read_b128 v[202:205], v248 offset:9280
	global_load_dwordx4 v[166:169], v[238:239], off offset:1024
	v_mfma_f32_32x32x16_bf16 v[34:49], v[190:193], v[8:11], v[34:49]
	ds_read_b128 v[206:209], v248 offset:13888
	s_waitcnt vmcnt(7)
	ds_write_b128 v250, v[154:157] offset:55296
	s_waitcnt lgkmcnt(6)
	v_mfma_f32_32x32x16_bf16 v[114:129], v[178:181], v[194:197], v[114:129]
	s_waitcnt lgkmcnt(5)
	v_mfma_f32_32x32x16_bf16 v[130:145], v[182:185], v[194:197], v[130:145]
	global_load_dwordx4 v[154:157], v[12:13], off offset:1024
	s_waitcnt lgkmcnt(3)
	v_mfma_f32_32x32x16_bf16 v[82:97], v[178:181], v[198:201], v[82:97]
	ds_read_b128 v[186:189], v249 offset:96
	s_waitcnt vmcnt(7)
	ds_write_b128 v251, v[170:173] offset:55296
	v_mfma_f32_32x32x16_bf16 v[98:113], v[182:185], v[198:201], v[98:113]
	ds_read_b128 v[210:213], v248 offset:96
	s_waitcnt lgkmcnt(5)
	v_mfma_f32_32x32x16_bf16 v[50:65], v[178:181], v[202:205], v[50:65]
	ds_read_b128 v[190:193], v249 offset:4704
	global_load_dwordx4 v[170:173], v[234:235], off offset:1024
	v_mfma_f32_32x32x16_bf16 v[66:81], v[182:185], v[202:205], v[66:81]
	ds_read_b128 v[214:217], v248 offset:4704
	s_waitcnt vmcnt(7)
	ds_write_b128 v250, v[158:161] offset:64512
	s_waitcnt lgkmcnt(7)
	v_mfma_f32_32x32x16_bf16 v[18:33], v[178:181], v[206:209], v[18:33]
	ds_read_b128 v[4:7], v248 offset:9312
	v_mfma_f32_32x32x16_bf16 v[34:49], v[182:185], v[206:209], v[34:49]
	ds_read_b128 v[8:11], v248 offset:13920
	global_load_dwordx4 v[158:161], v[14:15], off offset:1024
	s_waitcnt lgkmcnt(5)
	v_mfma_f32_32x32x16_bf16 v[114:129], v[186:189], v[210:213], v[114:129]
	s_waitcnt vmcnt(7)
	ds_write_b128 v251, v[174:177] offset:64512
	s_waitcnt lgkmcnt(5)
	v_mfma_f32_32x32x16_bf16 v[130:145], v[190:193], v[210:213], v[130:145]
	s_waitcnt lgkmcnt(4)
	v_mfma_f32_32x32x16_bf16 v[82:97], v[186:189], v[214:217], v[82:97]
	global_load_dwordx4 v[174:177], v[236:237], off offset:1024
	v_mfma_f32_32x32x16_bf16 v[98:113], v[190:193], v[214:217], v[98:113]
	s_waitcnt lgkmcnt(2)
	v_mfma_f32_32x32x16_bf16 v[50:65], v[186:189], v[4:7], v[50:65]
	v_mfma_f32_32x32x16_bf16 v[66:81], v[190:193], v[4:7], v[66:81]
	s_waitcnt lgkmcnt(1)
	v_mfma_f32_32x32x16_bf16 v[18:33], v[186:189], v[8:11], v[18:33]
	v_mfma_f32_32x32x16_bf16 v[34:49], v[190:193], v[8:11], v[34:49]
	s_waitcnt lgkmcnt(0)
	s_barrier
;     ...
;   for (int kt = 0; kt < nk; ++kt) {
;     __syncthreads();
;     if (kt + 1 < nk) {
;       u16* aw = As0 + ((kt + 1) & 1) * 256 * LD;
;       u16* bw = Bs0 + ((kt + 1) & 1) * 256 * LD;
; #pragma unroll
;       for (int i = 0; i < 4; ++i) { *(u32x4*)(aw + (srow + 64 * i) * LD + skc * 8) = ra[i]; *(u32x4*)(bw + (srow + 64 * i) * LD + skc * 8) = rb[i]; }
;     }
;     if (kt + 2 < nk) {
; #pragma unroll
;       for (int i = 0; i < 4; ++i) { ra[i] = *(const u32x4*)(Ag + (size_t)(64 * i) * K + (kt + 2) * 64); rb[i] = *(const u32x4*)(Bg[i] + (kt + 2) * 64); }
;     }
;     __builtin_amdgcn_sched_barrier(0);
;     const u16* as = As0 + (kt & 1) * 256 * LD + (wr * 128 + l31) * LD + h * 8;
;     const u16* bs = Bs0 + (kt & 1) * 256 * LD + (wc * 64 + l31) * LD + h * 8;
;     if (domma)
; #pragma unroll
;     for (int ks = 0; ks < 4; ++ks) {
;       bf16x8 wf[2], xf[4];
; #pragma unroll
;       for (int ct = 0; ct < 2; ++ct) wf[ct] = *(const bf16x8*)(bs + ct * 32 * LD + ks * 16);
; #pragma unroll
;       for (int tt = 0; tt < 4; ++tt) xf[tt] = *(const bf16x8*)(as + tt * 32 * LD + ks * 16);
; #pragma unroll
;       for (int ct = 0; ct < 2; ++ct)
; #pragma unroll
;         for (int tt = 0; tt < 4; ++tt) acc[ct][tt] = __builtin_amdgcn_mfma_f32_32x32x16_bf16(wf[ct], xf[tt], acc[ct][tt], 0, 0, 0);
;     }
	ds_read_b128 v[178:181], v249 offset:36864
	ds_read_b128 v[194:197], v248 offset:36864
	ds_read_b128 v[182:185], v249 offset:41472
	ds_read_b128 v[198:201], v248 offset:41472
	ds_read_b128 v[202:205], v248 offset:46080
	ds_read_b128 v[206:209], v248 offset:50688
	s_waitcnt lgkmcnt(4)
	v_mfma_f32_32x32x16_bf16 v[114:129], v[178:181], v[194:197], v[114:129]
	s_waitcnt lgkmcnt(3)
	v_mfma_f32_32x32x16_bf16 v[130:145], v[182:185], v[194:197], v[130:145]
	s_waitcnt lgkmcnt(2)
	v_mfma_f32_32x32x16_bf16 v[82:97], v[178:181], v[198:201], v[82:97]
	ds_read_b128 v[186:189], v249 offset:36896
	v_mfma_f32_32x32x16_bf16 v[98:113], v[182:185], v[198:201], v[98:113]
	ds_read_b128 v[210:213], v248 offset:36896
	s_waitcnt vmcnt(7)
	ds_write_b128 v250, v[146:149]
	s_waitcnt lgkmcnt(4)
	v_mfma_f32_32x32x16_bf16 v[50:65], v[178:181], v[202:205], v[50:65]
	ds_read_b128 v[190:193], v249 offset:41504
	v_mfma_f32_32x32x16_bf16 v[66:81], v[182:185], v[202:205], v[66:81]
	ds_read_b128 v[214:217], v248 offset:41504
	global_load_dwordx4 v[146:149], v[230:231], off offset:1152
	s_waitcnt lgkmcnt(5)
	v_mfma_f32_32x32x16_bf16 v[18:33], v[178:181], v[206:209], v[18:33]
	ds_read_b128 v[4:7], v248 offset:46112
	s_waitcnt vmcnt(7)
	ds_write_b128 v251, v[162:165]
	v_mfma_f32_32x32x16_bf16 v[34:49], v[182:185], v[206:209], v[34:49]
	ds_read_b128 v[8:11], v248 offset:50720
	s_waitcnt lgkmcnt(6)
	v_mfma_f32_32x32x16_bf16 v[114:129], v[186:189], v[210:213], v[114:129]
	global_load_dwordx4 v[162:165], v[228:229], off offset:1152
	s_waitcnt lgkmcnt(4)
	v_mfma_f32_32x32x16_bf16 v[130:145], v[190:193], v[210:213], v[130:145]
	s_waitcnt vmcnt(7)
	ds_write_b128 v250, v[150:153] offset:9216
	s_waitcnt lgkmcnt(4)
	v_mfma_f32_32x32x16_bf16 v[82:97], v[186:189], v[214:217], v[82:97]
	ds_read_b128 v[178:181], v249 offset:36928
	v_mfma_f32_32x32x16_bf16 v[98:113], v[190:193], v[214:217], v[98:113]
	ds_read_b128 v[194:197], v248 offset:36928
	global_load_dwordx4 v[150:153], v[232:233], off offset:1152
	s_waitcnt lgkmcnt(5)
	v_mfma_f32_32x32x16_bf16 v[50:65], v[186:189], v[4:7], v[50:65]
	ds_read_b128 v[182:185], v249 offset:41536
	s_waitcnt vmcnt(7)
	ds_write_b128 v251, v[166:169] offset:9216
	v_mfma_f32_32x32x16_bf16 v[66:81], v[190:193], v[4:7], v[66:81]
	ds_read_b128 v[198:201], v248 offset:41536
	s_waitcnt lgkmcnt(6)
	v_mfma_f32_32x32x16_bf16 v[18:33], v[186:189], v[8:11], v[18:33]
	ds_read_b128 v[202:205], v248 offset:46144
	global_load_dwordx4 v[166:169], v[238:239], off offset:1152
	v_mfma_f32_32x32x16_bf16 v[34:49], v[190:193], v[8:11], v[34:49]
	ds_read_b128 v[206:209], v248 offset:50752
	s_waitcnt vmcnt(7)
	ds_write_b128 v250, v[154:157] offset:18432
	s_waitcnt lgkmcnt(6)
	v_mfma_f32_32x32x16_bf16 v[114:129], v[178:181], v[194:197], v[114:129]
	s_waitcnt lgkmcnt(5)
	v_mfma_f32_32x32x16_bf16 v[130:145], v[182:185], v[194:197], v[130:145]
	global_load_dwordx4 v[154:157], v[12:13], off offset:1152
	s_waitcnt lgkmcnt(3)
	v_mfma_f32_32x32x16_bf16 v[82:97], v[178:181], v[198:201], v[82:97]
	ds_read_b128 v[186:189], v249 offset:36960
	s_waitcnt vmcnt(7)
	ds_write_b128 v251, v[170:173] offset:18432
	v_mfma_f32_32x32x16_bf16 v[98:113], v[182:185], v[198:201], v[98:113]
	ds_read_b128 v[210:213], v248 offset:36960
	s_waitcnt lgkmcnt(5)
	v_mfma_f32_32x32x16_bf16 v[50:65], v[178:181], v[202:205], v[50:65]
	ds_read_b128 v[190:193], v249 offset:41568
	global_load_dwordx4 v[170:173], v[234:235], off offset:1152
	v_mfma_f32_32x32x16_bf16 v[66:81], v[182:185], v[202:205], v[66:81]
	ds_read_b128 v[214:217], v248 offset:41568
	s_waitcnt vmcnt(7)
	ds_write_b128 v250, v[158:161] offset:27648
	s_waitcnt lgkmcnt(7)
	v_mfma_f32_32x32x16_bf16 v[18:33], v[178:181], v[206:209], v[18:33]
	ds_read_b128 v[4:7], v248 offset:46176
	v_mfma_f32_32x32x16_bf16 v[34:49], v[182:185], v[206:209], v[34:49]
	ds_read_b128 v[8:11], v248 offset:50784
	global_load_dwordx4 v[158:161], v[14:15], off offset:1152
	s_waitcnt lgkmcnt(5)
	v_mfma_f32_32x32x16_bf16 v[114:129], v[186:189], v[210:213], v[114:129]
	s_waitcnt vmcnt(7)
	ds_write_b128 v251, v[174:177] offset:27648
	s_waitcnt lgkmcnt(5)
	v_mfma_f32_32x32x16_bf16 v[130:145], v[190:193], v[210:213], v[130:145]
	s_waitcnt lgkmcnt(4)
	v_mfma_f32_32x32x16_bf16 v[82:97], v[186:189], v[214:217], v[82:97]
	global_load_dwordx4 v[174:177], v[236:237], off offset:1152
	v_mfma_f32_32x32x16_bf16 v[98:113], v[190:193], v[214:217], v[98:113]
	s_waitcnt lgkmcnt(2)
	v_mfma_f32_32x32x16_bf16 v[50:65], v[186:189], v[4:7], v[50:65]
	v_mfma_f32_32x32x16_bf16 v[66:81], v[190:193], v[4:7], v[66:81]
	s_waitcnt lgkmcnt(1)
	v_mfma_f32_32x32x16_bf16 v[18:33], v[186:189], v[8:11], v[18:33]
	v_mfma_f32_32x32x16_bf16 v[34:49], v[190:193], v[8:11], v[34:49]
	s_waitcnt lgkmcnt(0)
	s_barrier
;     ...
;   for (int kt = 0; kt < nk; ++kt) {
;     __syncthreads();
;     if (kt + 1 < nk) {
;       u16* aw = As0 + ((kt + 1) & 1) * 256 * LD;
;       u16* bw = Bs0 + ((kt + 1) & 1) * 256 * LD;
; #pragma unroll
;       for (int i = 0; i < 4; ++i) { *(u32x4*)(aw + (srow + 64 * i) * LD + skc * 8) = ra[i]; *(u32x4*)(bw + (srow + 64 * i) * LD + skc * 8) = rb[i]; }
;     }
;     if (kt + 2 < nk) {
; #pragma unroll
;       for (int i = 0; i < 4; ++i) { ra[i] = *(const u32x4*)(Ag + (size_t)(64 * i) * K + (kt + 2) * 64); rb[i] = *(const u32x4*)(Bg[i] + (kt + 2) * 64); }
;     }
;     __builtin_amdgcn_sched_barrier(0);
;     const u16* as = As0 + (kt & 1) * 256 * LD + (wr * 128 + l31) * LD + h * 8;
;     const u16* bs = Bs0 + (kt & 1) * 256 * LD + (wc * 64 + l31) * LD + h * 8;
;     if (domma)
; #pragma unroll
;     for (int ks = 0; ks < 4; ++ks) {
;       bf16x8 wf[2], xf[4];
; #pragma unroll
;       for (int ct = 0; ct < 2; ++ct) wf[ct] = *(const bf16x8*)(bs + ct * 32 * LD + ks * 16);
; #pragma unroll
;       for (int tt = 0; tt < 4; ++tt) xf[tt] = *(const bf16x8*)(as + tt * 32 * LD + ks * 16);
; #pragma unroll
;       for (int ct = 0; ct < 2; ++ct)
; #pragma unroll
;         for (int tt = 0; tt < 4; ++tt) acc[ct][tt] = __builtin_amdgcn_mfma_f32_32x32x16_bf16(wf[ct], xf[tt], acc[ct][tt], 0, 0, 0);
;     }
	ds_read_b128 v[178:181], v249
	ds_read_b128 v[194:197], v248
	ds_read_b128 v[182:185], v249 offset:4608
	ds_read_b128 v[198:201], v248 offset:4608
	ds_read_b128 v[202:205], v248 offset:9216
	ds_read_b128 v[206:209], v248 offset:13824
	s_waitcnt lgkmcnt(4)
	v_mfma_f32_32x32x16_bf16 v[114:129], v[178:181], v[194:197], v[114:129]
	s_waitcnt lgkmcnt(3)
	v_mfma_f32_32x32x16_bf16 v[130:145], v[182:185], v[194:197], v[130:145]
	s_waitcnt lgkmcnt(2)
	v_mfma_f32_32x32x16_bf16 v[82:97], v[178:181], v[198:201], v[82:97]
	ds_read_b128 v[186:189], v249 offset:32
	v_mfma_f32_32x32x16_bf16 v[98:113], v[182:185], v[198:201], v[98:113]
	ds_read_b128 v[210:213], v248 offset:32
	s_waitcnt vmcnt(7)
	ds_write_b128 v250, v[146:149] offset:36864
	s_waitcnt lgkmcnt(4)
	v_mfma_f32_32x32x16_bf16 v[50:65], v[178:181], v[202:205], v[50:65]
	ds_read_b128 v[190:193], v249 offset:4640
	v_mfma_f32_32x32x16_bf16 v[66:81], v[182:185], v[202:205], v[66:81]
	ds_read_b128 v[214:217], v248 offset:4640
	global_load_dwordx4 v[146:149], v[230:231], off offset:1280
	s_waitcnt lgkmcnt(5)
	v_mfma_f32_32x32x16_bf16 v[18:33], v[178:181], v[206:209], v[18:33]
	ds_read_b128 v[4:7], v248 offset:9248
	s_waitcnt vmcnt(7)
	ds_write_b128 v251, v[162:165] offset:36864
	v_mfma_f32_32x32x16_bf16 v[34:49], v[182:185], v[206:209], v[34:49]
	ds_read_b128 v[8:11], v248 offset:13856
	s_waitcnt lgkmcnt(6)
	v_mfma_f32_32x32x16_bf16 v[114:129], v[186:189], v[210:213], v[114:129]
	global_load_dwordx4 v[162:165], v[228:229], off offset:1280
	s_waitcnt lgkmcnt(4)
	v_mfma_f32_32x32x16_bf16 v[130:145], v[190:193], v[210:213], v[130:145]
	s_waitcnt vmcnt(7)
	ds_write_b128 v250, v[150:153] offset:46080
	s_waitcnt lgkmcnt(4)
	v_mfma_f32_32x32x16_bf16 v[82:97], v[186:189], v[214:217], v[82:97]
	ds_read_b128 v[178:181], v249 offset:64
	v_mfma_f32_32x32x16_bf16 v[98:113], v[190:193], v[214:217], v[98:113]
	ds_read_b128 v[194:197], v248 offset:64
	global_load_dwordx4 v[150:153], v[232:233], off offset:1280
	s_waitcnt lgkmcnt(5)
	v_mfma_f32_32x32x16_bf16 v[50:65], v[186:189], v[4:7], v[50:65]
	ds_read_b128 v[182:185], v249 offset:4672
	s_waitcnt vmcnt(7)
	ds_write_b128 v251, v[166:169] offset:46080
	v_mfma_f32_32x32x16_bf16 v[66:81], v[190:193], v[4:7], v[66:81]
	ds_read_b128 v[198:201], v248 offset:4672
	s_waitcnt lgkmcnt(6)
	v_mfma_f32_32x32x16_bf16 v[18:33], v[186:189], v[8:11], v[18:33]
	ds_read_b128 v[202:205], v248 offset:9280
	global_load_dwordx4 v[166:169], v[238:239], off offset:1280
	v_mfma_f32_32x32x16_bf16 v[34:49], v[190:193], v[8:11], v[34:49]
	ds_read_b128 v[206:209], v248 offset:13888
	s_waitcnt vmcnt(7)
	ds_write_b128 v250, v[154:157] offset:55296
	s_waitcnt lgkmcnt(6)
	v_mfma_f32_32x32x16_bf16 v[114:129], v[178:181], v[194:197], v[114:129]
	s_waitcnt lgkmcnt(5)
	v_mfma_f32_32x32x16_bf16 v[130:145], v[182:185], v[194:197], v[130:145]
	global_load_dwordx4 v[154:157], v[12:13], off offset:1280
	s_waitcnt lgkmcnt(3)
	v_mfma_f32_32x32x16_bf16 v[82:97], v[178:181], v[198:201], v[82:97]
	ds_read_b128 v[186:189], v249 offset:96
	s_waitcnt vmcnt(7)
	ds_write_b128 v251, v[170:173] offset:55296
	v_mfma_f32_32x32x16_bf16 v[98:113], v[182:185], v[198:201], v[98:113]
	ds_read_b128 v[210:213], v248 offset:96
	s_waitcnt lgkmcnt(5)
	v_mfma_f32_32x32x16_bf16 v[50:65], v[178:181], v[202:205], v[50:65]
	ds_read_b128 v[190:193], v249 offset:4704
	global_load_dwordx4 v[170:173], v[234:235], off offset:1280
	v_mfma_f32_32x32x16_bf16 v[66:81], v[182:185], v[202:205], v[66:81]
	ds_read_b128 v[214:217], v248 offset:4704
	s_waitcnt vmcnt(7)
	ds_write_b128 v250, v[158:161] offset:64512
	s_waitcnt lgkmcnt(7)
	v_mfma_f32_32x32x16_bf16 v[18:33], v[178:181], v[206:209], v[18:33]
	ds_read_b128 v[4:7], v248 offset:9312
	v_mfma_f32_32x32x16_bf16 v[34:49], v[182:185], v[206:209], v[34:49]
	ds_read_b128 v[8:11], v248 offset:13920
	global_load_dwordx4 v[158:161], v[14:15], off offset:1280
	s_waitcnt lgkmcnt(5)
	v_mfma_f32_32x32x16_bf16 v[114:129], v[186:189], v[210:213], v[114:129]
	s_waitcnt vmcnt(7)
	ds_write_b128 v251, v[174:177] offset:64512
	s_waitcnt lgkmcnt(5)
	v_mfma_f32_32x32x16_bf16 v[130:145], v[190:193], v[210:213], v[130:145]
	s_waitcnt lgkmcnt(4)
	v_mfma_f32_32x32x16_bf16 v[82:97], v[186:189], v[214:217], v[82:97]
	global_load_dwordx4 v[174:177], v[236:237], off offset:1280
	v_mfma_f32_32x32x16_bf16 v[98:113], v[190:193], v[214:217], v[98:113]
	s_waitcnt lgkmcnt(2)
	v_mfma_f32_32x32x16_bf16 v[50:65], v[186:189], v[4:7], v[50:65]
	v_mfma_f32_32x32x16_bf16 v[66:81], v[190:193], v[4:7], v[66:81]
	s_waitcnt lgkmcnt(1)
	v_mfma_f32_32x32x16_bf16 v[18:33], v[186:189], v[8:11], v[18:33]
	v_mfma_f32_32x32x16_bf16 v[34:49], v[190:193], v[8:11], v[34:49]
	s_waitcnt lgkmcnt(0)
	s_barrier
;     ...
;   for (int kt = 0; kt < nk; ++kt) {
;     __syncthreads();
;     if (kt + 1 < nk) {
;       u16* aw = As0 + ((kt + 1) & 1) * 256 * LD;
;       u16* bw = Bs0 + ((kt + 1) & 1) * 256 * LD;
; #pragma unroll
;       for (int i = 0; i < 4; ++i) { *(u32x4*)(aw + (srow + 64 * i) * LD + skc * 8) = ra[i]; *(u32x4*)(bw + (srow + 64 * i) * LD + skc * 8) = rb[i]; }
;     }
;     if (kt + 2 < nk) {
; #pragma unroll
;       for (int i = 0; i < 4; ++i) { ra[i] = *(const u32x4*)(Ag + (size_t)(64 * i) * K + (kt + 2) * 64); rb[i] = *(const u32x4*)(Bg[i] + (kt + 2) * 64); }
;     }
;     __builtin_amdgcn_sched_barrier(0);
;     const u16* as = As0 + (kt & 1) * 256 * LD + (wr * 128 + l31) * LD + h * 8;
;     const u16* bs = Bs0 + (kt & 1) * 256 * LD + (wc * 64 + l31) * LD + h * 8;
;     if (domma)
; #pragma unroll
;     for (int ks = 0; ks < 4; ++ks) {
;       bf16x8 wf[2], xf[4];
; #pragma unroll
;       for (int ct = 0; ct < 2; ++ct) wf[ct] = *(const bf16x8*)(bs + ct * 32 * LD + ks * 16);
; #pragma unroll
;       for (int tt = 0; tt < 4; ++tt) xf[tt] = *(const bf16x8*)(as + tt * 32 * LD + ks * 16);
; #pragma unroll
;       for (int ct = 0; ct < 2; ++ct)
; #pragma unroll
;         for (int tt = 0; tt < 4; ++tt) acc[ct][tt] = __builtin_amdgcn_mfma_f32_32x32x16_bf16(wf[ct], xf[tt], acc[ct][tt], 0, 0, 0);
;     }
	ds_read_b128 v[178:181], v249 offset:36864
	ds_read_b128 v[194:197], v248 offset:36864
	ds_read_b128 v[182:185], v249 offset:41472
	ds_read_b128 v[198:201], v248 offset:41472
	ds_read_b128 v[202:205], v248 offset:46080
	ds_read_b128 v[206:209], v248 offset:50688
	s_waitcnt lgkmcnt(4)
	v_mfma_f32_32x32x16_bf16 v[114:129], v[178:181], v[194:197], v[114:129]
	s_waitcnt lgkmcnt(3)
	v_mfma_f32_32x32x16_bf16 v[130:145], v[182:185], v[194:197], v[130:145]
	s_waitcnt lgkmcnt(2)
	v_mfma_f32_32x32x16_bf16 v[82:97], v[178:181], v[198:201], v[82:97]
	ds_read_b128 v[186:189], v249 offset:36896
	v_mfma_f32_32x32x16_bf16 v[98:113], v[182:185], v[198:201], v[98:113]
	ds_read_b128 v[210:213], v248 offset:36896
	s_waitcnt vmcnt(7)
	ds_write_b128 v250, v[146:149]
	s_waitcnt lgkmcnt(4)
	v_mfma_f32_32x32x16_bf16 v[50:65], v[178:181], v[202:205], v[50:65]
	ds_read_b128 v[190:193], v249 offset:41504
	v_mfma_f32_32x32x16_bf16 v[66:81], v[182:185], v[202:205], v[66:81]
	ds_read_b128 v[214:217], v248 offset:41504
	global_load_dwordx4 v[146:149], v[230:231], off offset:1408
	s_waitcnt lgkmcnt(5)
	v_mfma_f32_32x32x16_bf16 v[18:33], v[178:181], v[206:209], v[18:33]
	ds_read_b128 v[4:7], v248 offset:46112
	s_waitcnt vmcnt(7)
	ds_write_b128 v251, v[162:165]
	v_mfma_f32_32x32x16_bf16 v[34:49], v[182:185], v[206:209], v[34:49]
	ds_read_b128 v[8:11], v248 offset:50720
	s_waitcnt lgkmcnt(6)
	v_mfma_f32_32x32x16_bf16 v[114:129], v[186:189], v[210:213], v[114:129]
	global_load_dwordx4 v[162:165], v[228:229], off offset:1408
	s_waitcnt lgkmcnt(4)
	v_mfma_f32_32x32x16_bf16 v[130:145], v[190:193], v[210:213], v[130:145]
	s_waitcnt vmcnt(7)
	ds_write_b128 v250, v[150:153] offset:9216
	s_waitcnt lgkmcnt(4)
	v_mfma_f32_32x32x16_bf16 v[82:97], v[186:189], v[214:217], v[82:97]
	ds_read_b128 v[178:181], v249 offset:36928
	v_mfma_f32_32x32x16_bf16 v[98:113], v[190:193], v[214:217], v[98:113]
	ds_read_b128 v[194:197], v248 offset:36928
	global_load_dwordx4 v[150:153], v[232:233], off offset:1408
	s_waitcnt lgkmcnt(5)
	v_mfma_f32_32x32x16_bf16 v[50:65], v[186:189], v[4:7], v[50:65]
	ds_read_b128 v[182:185], v249 offset:41536
	s_waitcnt vmcnt(7)
	ds_write_b128 v251, v[166:169] offset:9216
	v_mfma_f32_32x32x16_bf16 v[66:81], v[190:193], v[4:7], v[66:81]
	ds_read_b128 v[198:201], v248 offset:41536
	s_waitcnt lgkmcnt(6)
	v_mfma_f32_32x32x16_bf16 v[18:33], v[186:189], v[8:11], v[18:33]
	ds_read_b128 v[202:205], v248 offset:46144
	global_load_dwordx4 v[166:169], v[238:239], off offset:1408
	v_mfma_f32_32x32x16_bf16 v[34:49], v[190:193], v[8:11], v[34:49]
	ds_read_b128 v[206:209], v248 offset:50752
	s_waitcnt vmcnt(7)
	ds_write_b128 v250, v[154:157] offset:18432
	s_waitcnt lgkmcnt(6)
	v_mfma_f32_32x32x16_bf16 v[114:129], v[178:181], v[194:197], v[114:129]
	s_waitcnt lgkmcnt(5)
	v_mfma_f32_32x32x16_bf16 v[130:145], v[182:185], v[194:197], v[130:145]
	global_load_dwordx4 v[154:157], v[12:13], off offset:1408
	s_waitcnt lgkmcnt(3)
	v_mfma_f32_32x32x16_bf16 v[82:97], v[178:181], v[198:201], v[82:97]
	ds_read_b128 v[186:189], v249 offset:36960
	s_waitcnt vmcnt(7)
	ds_write_b128 v251, v[170:173] offset:18432
	v_mfma_f32_32x32x16_bf16 v[98:113], v[182:185], v[198:201], v[98:113]
	ds_read_b128 v[210:213], v248 offset:36960
	s_waitcnt lgkmcnt(5)
	v_mfma_f32_32x32x16_bf16 v[50:65], v[178:181], v[202:205], v[50:65]
	ds_read_b128 v[190:193], v249 offset:41568
	global_load_dwordx4 v[170:173], v[234:235], off offset:1408
	v_mfma_f32_32x32x16_bf16 v[66:81], v[182:185], v[202:205], v[66:81]
	ds_read_b128 v[214:217], v248 offset:41568
	s_waitcnt vmcnt(7)
	ds_write_b128 v250, v[158:161] offset:27648
	s_waitcnt lgkmcnt(7)
	v_mfma_f32_32x32x16_bf16 v[18:33], v[178:181], v[206:209], v[18:33]
	ds_read_b128 v[4:7], v248 offset:46176
	v_mfma_f32_32x32x16_bf16 v[34:49], v[182:185], v[206:209], v[34:49]
	ds_read_b128 v[8:11], v248 offset:50784
	global_load_dwordx4 v[158:161], v[14:15], off offset:1408
	s_waitcnt lgkmcnt(5)
	v_mfma_f32_32x32x16_bf16 v[114:129], v[186:189], v[210:213], v[114:129]
	s_waitcnt vmcnt(7)
	ds_write_b128 v251, v[174:177] offset:27648
	s_waitcnt lgkmcnt(5)
	v_mfma_f32_32x32x16_bf16 v[130:145], v[190:193], v[210:213], v[130:145]
	s_waitcnt lgkmcnt(4)
	v_mfma_f32_32x32x16_bf16 v[82:97], v[186:189], v[214:217], v[82:97]
	global_load_dwordx4 v[174:177], v[236:237], off offset:1408
	v_mfma_f32_32x32x16_bf16 v[98:113], v[190:193], v[214:217], v[98:113]
	s_waitcnt lgkmcnt(2)
	v_mfma_f32_32x32x16_bf16 v[50:65], v[186:189], v[4:7], v[50:65]
	v_mfma_f32_32x32x16_bf16 v[66:81], v[190:193], v[4:7], v[66:81]
	s_waitcnt lgkmcnt(1)
	v_mfma_f32_32x32x16_bf16 v[18:33], v[186:189], v[8:11], v[18:33]
	v_mfma_f32_32x32x16_bf16 v[34:49], v[190:193], v[8:11], v[34:49]
	s_waitcnt lgkmcnt(0)
	s_barrier
;     ...
;   for (int kt = 0; kt < nk; ++kt) {
;     __syncthreads();
;     if (kt + 1 < nk) {
;       u16* aw = As0 + ((kt + 1) & 1) * 256 * LD;
;       u16* bw = Bs0 + ((kt + 1) & 1) * 256 * LD;
; #pragma unroll
;       for (int i = 0; i < 4; ++i) { *(u32x4*)(aw + (srow + 64 * i) * LD + skc * 8) = ra[i]; *(u32x4*)(bw + (srow + 64 * i) * LD + skc * 8) = rb[i]; }
;     }
;     if (kt + 2 < nk) {
; #pragma unroll
;       for (int i = 0; i < 4; ++i) { ra[i] = *(const u32x4*)(Ag + (size_t)(64 * i) * K + (kt + 2) * 64); rb[i] = *(const u32x4*)(Bg[i] + (kt + 2) * 64); }
;     }
;     __builtin_amdgcn_sched_barrier(0);
;     const u16* as = As0 + (kt & 1) * 256 * LD + (wr * 128 + l31) * LD + h * 8;
;     const u16* bs = Bs0 + (kt & 1) * 256 * LD + (wc * 64 + l31) * LD + h * 8;
;     if (domma)
; #pragma unroll
;     for (int ks = 0; ks < 4; ++ks) {
;       bf16x8 wf[2], xf[4];
; #pragma unroll
;       for (int ct = 0; ct < 2; ++ct) wf[ct] = *(const bf16x8*)(bs + ct * 32 * LD + ks * 16);
; #pragma unroll
;       for (int tt = 0; tt < 4; ++tt) xf[tt] = *(const bf16x8*)(as + tt * 32 * LD + ks * 16);
; #pragma unroll
;       for (int ct = 0; ct < 2; ++ct)
; #pragma unroll
;         for (int tt = 0; tt < 4; ++tt) acc[ct][tt] = __builtin_amdgcn_mfma_f32_32x32x16_bf16(wf[ct], xf[tt], acc[ct][tt], 0, 0, 0);
;     }
	ds_read_b128 v[178:181], v249
	ds_read_b128 v[194:197], v248
	ds_read_b128 v[182:185], v249 offset:4608
	ds_read_b128 v[198:201], v248 offset:4608
	ds_read_b128 v[202:205], v248 offset:9216
	ds_read_b128 v[206:209], v248 offset:13824
	s_waitcnt lgkmcnt(4)
	v_mfma_f32_32x32x16_bf16 v[114:129], v[178:181], v[194:197], v[114:129]
	s_waitcnt lgkmcnt(3)
	v_mfma_f32_32x32x16_bf16 v[130:145], v[182:185], v[194:197], v[130:145]
	s_waitcnt lgkmcnt(2)
	v_mfma_f32_32x32x16_bf16 v[82:97], v[178:181], v[198:201], v[82:97]
	ds_read_b128 v[186:189], v249 offset:32
	v_mfma_f32_32x32x16_bf16 v[98:113], v[182:185], v[198:201], v[98:113]
	ds_read_b128 v[210:213], v248 offset:32
	s_waitcnt vmcnt(7)
	ds_write_b128 v250, v[146:149] offset:36864
	s_waitcnt lgkmcnt(4)
	v_mfma_f32_32x32x16_bf16 v[50:65], v[178:181], v[202:205], v[50:65]
	ds_read_b128 v[190:193], v249 offset:4640
	v_mfma_f32_32x32x16_bf16 v[66:81], v[182:185], v[202:205], v[66:81]
	ds_read_b128 v[214:217], v248 offset:4640
	global_load_dwordx4 v[146:149], v[230:231], off offset:1536
	s_waitcnt lgkmcnt(5)
	v_mfma_f32_32x32x16_bf16 v[18:33], v[178:181], v[206:209], v[18:33]
	ds_read_b128 v[4:7], v248 offset:9248
	s_waitcnt vmcnt(7)
	ds_write_b128 v251, v[162:165] offset:36864
	v_mfma_f32_32x32x16_bf16 v[34:49], v[182:185], v[206:209], v[34:49]
	ds_read_b128 v[8:11], v248 offset:13856
	s_waitcnt lgkmcnt(6)
	v_mfma_f32_32x32x16_bf16 v[114:129], v[186:189], v[210:213], v[114:129]
	global_load_dwordx4 v[162:165], v[228:229], off offset:1536
	s_waitcnt lgkmcnt(4)
	v_mfma_f32_32x32x16_bf16 v[130:145], v[190:193], v[210:213], v[130:145]
	s_waitcnt vmcnt(7)
	ds_write_b128 v250, v[150:153] offset:46080
	s_waitcnt lgkmcnt(4)
	v_mfma_f32_32x32x16_bf16 v[82:97], v[186:189], v[214:217], v[82:97]
	ds_read_b128 v[178:181], v249 offset:64
	v_mfma_f32_32x32x16_bf16 v[98:113], v[190:193], v[214:217], v[98:113]
	ds_read_b128 v[194:197], v248 offset:64
	global_load_dwordx4 v[150:153], v[232:233], off offset:1536
	s_waitcnt lgkmcnt(5)
	v_mfma_f32_32x32x16_bf16 v[50:65], v[186:189], v[4:7], v[50:65]
	ds_read_b128 v[182:185], v249 offset:4672
	s_waitcnt vmcnt(7)
	ds_write_b128 v251, v[166:169] offset:46080
	v_mfma_f32_32x32x16_bf16 v[66:81], v[190:193], v[4:7], v[66:81]
	ds_read_b128 v[198:201], v248 offset:4672
	s_waitcnt lgkmcnt(6)
	v_mfma_f32_32x32x16_bf16 v[18:33], v[186:189], v[8:11], v[18:33]
	ds_read_b128 v[202:205], v248 offset:9280
	global_load_dwordx4 v[166:169], v[238:239], off offset:1536
	v_mfma_f32_32x32x16_bf16 v[34:49], v[190:193], v[8:11], v[34:49]
	ds_read_b128 v[206:209], v248 offset:13888
	s_waitcnt vmcnt(7)
	ds_write_b128 v250, v[154:157] offset:55296
	s_waitcnt lgkmcnt(6)
	v_mfma_f32_32x32x16_bf16 v[114:129], v[178:181], v[194:197], v[114:129]
	s_waitcnt lgkmcnt(5)
	v_mfma_f32_32x32x16_bf16 v[130:145], v[182:185], v[194:197], v[130:145]
	global_load_dwordx4 v[154:157], v[12:13], off offset:1536
	s_waitcnt lgkmcnt(3)
	v_mfma_f32_32x32x16_bf16 v[82:97], v[178:181], v[198:201], v[82:97]
	ds_read_b128 v[186:189], v249 offset:96
	s_waitcnt vmcnt(7)
	ds_write_b128 v251, v[170:173] offset:55296
	v_mfma_f32_32x32x16_bf16 v[98:113], v[182:185], v[198:201], v[98:113]
	ds_read_b128 v[210:213], v248 offset:96
	s_waitcnt lgkmcnt(5)
	v_mfma_f32_32x32x16_bf16 v[50:65], v[178:181], v[202:205], v[50:65]
	ds_read_b128 v[190:193], v249 offset:4704
	global_load_dwordx4 v[170:173], v[234:235], off offset:1536
	v_mfma_f32_32x32x16_bf16 v[66:81], v[182:185], v[202:205], v[66:81]
	ds_read_b128 v[214:217], v248 offset:4704
	s_waitcnt vmcnt(7)
	ds_write_b128 v250, v[158:161] offset:64512
	s_waitcnt lgkmcnt(7)
	v_mfma_f32_32x32x16_bf16 v[18:33], v[178:181], v[206:209], v[18:33]
	ds_read_b128 v[4:7], v248 offset:9312
	v_mfma_f32_32x32x16_bf16 v[34:49], v[182:185], v[206:209], v[34:49]
	ds_read_b128 v[8:11], v248 offset:13920
	global_load_dwordx4 v[158:161], v[14:15], off offset:1536
	s_waitcnt lgkmcnt(5)
	v_mfma_f32_32x32x16_bf16 v[114:129], v[186:189], v[210:213], v[114:129]
	s_waitcnt vmcnt(7)
	ds_write_b128 v251, v[174:177] offset:64512
	s_waitcnt lgkmcnt(5)
	v_mfma_f32_32x32x16_bf16 v[130:145], v[190:193], v[210:213], v[130:145]
	s_waitcnt lgkmcnt(4)
	v_mfma_f32_32x32x16_bf16 v[82:97], v[186:189], v[214:217], v[82:97]
	global_load_dwordx4 v[174:177], v[236:237], off offset:1536
	v_mfma_f32_32x32x16_bf16 v[98:113], v[190:193], v[214:217], v[98:113]
	s_waitcnt lgkmcnt(2)
	v_mfma_f32_32x32x16_bf16 v[50:65], v[186:189], v[4:7], v[50:65]
	v_mfma_f32_32x32x16_bf16 v[66:81], v[190:193], v[4:7], v[66:81]
	s_waitcnt lgkmcnt(1)
	v_mfma_f32_32x32x16_bf16 v[18:33], v[186:189], v[8:11], v[18:33]
	v_mfma_f32_32x32x16_bf16 v[34:49], v[190:193], v[8:11], v[34:49]
	s_waitcnt lgkmcnt(0)
	s_barrier
;     ...
;   for (int kt = 0; kt < nk; ++kt) {
;     __syncthreads();
;     if (kt + 1 < nk) {
;       u16* aw = As0 + ((kt + 1) & 1) * 256 * LD;
;       u16* bw = Bs0 + ((kt + 1) & 1) * 256 * LD;
; #pragma unroll
;       for (int i = 0; i < 4; ++i) { *(u32x4*)(aw + (srow + 64 * i) * LD + skc * 8) = ra[i]; *(u32x4*)(bw + (srow + 64 * i) * LD + skc * 8) = rb[i]; }
;     }
;     if (kt + 2 < nk) {
; #pragma unroll
;       for (int i = 0; i < 4; ++i) { ra[i] = *(const u32x4*)(Ag + (size_t)(64 * i) * K + (kt + 2) * 64); rb[i] = *(const u32x4*)(Bg[i] + (kt + 2) * 64); }
;     }
;     __builtin_amdgcn_sched_barrier(0);
;     const u16* as = As0 + (kt & 1) * 256 * LD + (wr * 128 + l31) * LD + h * 8;
;     const u16* bs = Bs0 + (kt & 1) * 256 * LD + (wc * 64 + l31) * LD + h * 8;
;     if (domma)
; #pragma unroll
;     for (int ks = 0; ks < 4; ++ks) {
;       bf16x8 wf[2], xf[4];
; #pragma unroll
;       for (int ct = 0; ct < 2; ++ct) wf[ct] = *(const bf16x8*)(bs + ct * 32 * LD + ks * 16);
; #pragma unroll
;       for (int tt = 0; tt < 4; ++tt) xf[tt] = *(const bf16x8*)(as + tt * 32 * LD + ks * 16);
; #pragma unroll
;       for (int ct = 0; ct < 2; ++ct)
; #pragma unroll
;         for (int tt = 0; tt < 4; ++tt) acc[ct][tt] = __builtin_amdgcn_mfma_f32_32x32x16_bf16(wf[ct], xf[tt], acc[ct][tt], 0, 0, 0);
;     }
	ds_read_b128 v[178:181], v249 offset:36864
	ds_read_b128 v[194:197], v248 offset:36864
	ds_read_b128 v[182:185], v249 offset:41472
	ds_read_b128 v[198:201], v248 offset:41472
	ds_read_b128 v[202:205], v248 offset:46080
	ds_read_b128 v[206:209], v248 offset:50688
	s_waitcnt lgkmcnt(4)
	v_mfma_f32_32x32x16_bf16 v[114:129], v[178:181], v[194:197], v[114:129]
	s_waitcnt lgkmcnt(3)
	v_mfma_f32_32x32x16_bf16 v[130:145], v[182:185], v[194:197], v[130:145]
	s_waitcnt lgkmcnt(2)
	v_mfma_f32_32x32x16_bf16 v[82:97], v[178:181], v[198:201], v[82:97]
	ds_read_b128 v[186:189], v249 offset:36896
	v_mfma_f32_32x32x16_bf16 v[98:113], v[182:185], v[198:201], v[98:113]
	ds_read_b128 v[210:213], v248 offset:36896
	s_waitcnt vmcnt(7)
	ds_write_b128 v250, v[146:149]
	s_waitcnt lgkmcnt(4)
	v_mfma_f32_32x32x16_bf16 v[50:65], v[178:181], v[202:205], v[50:65]
	ds_read_b128 v[190:193], v249 offset:41504
	v_mfma_f32_32x32x16_bf16 v[66:81], v[182:185], v[202:205], v[66:81]
	ds_read_b128 v[214:217], v248 offset:41504
	global_load_dwordx4 v[146:149], v[230:231], off offset:1664
	s_waitcnt lgkmcnt(5)
	v_mfma_f32_32x32x16_bf16 v[18:33], v[178:181], v[206:209], v[18:33]
	ds_read_b128 v[4:7], v248 offset:46112
	s_waitcnt vmcnt(7)
	ds_write_b128 v251, v[162:165]
	v_mfma_f32_32x32x16_bf16 v[34:49], v[182:185], v[206:209], v[34:49]
	ds_read_b128 v[8:11], v248 offset:50720
	s_waitcnt lgkmcnt(6)
	v_mfma_f32_32x32x16_bf16 v[114:129], v[186:189], v[210:213], v[114:129]
	global_load_dwordx4 v[162:165], v[228:229], off offset:1664
	s_waitcnt lgkmcnt(4)
	v_mfma_f32_32x32x16_bf16 v[130:145], v[190:193], v[210:213], v[130:145]
	s_waitcnt vmcnt(7)
	ds_write_b128 v250, v[150:153] offset:9216
	s_waitcnt lgkmcnt(4)
	v_mfma_f32_32x32x16_bf16 v[82:97], v[186:189], v[214:217], v[82:97]
	ds_read_b128 v[178:181], v249 offset:36928
	v_mfma_f32_32x32x16_bf16 v[98:113], v[190:193], v[214:217], v[98:113]
	ds_read_b128 v[194:197], v248 offset:36928
	global_load_dwordx4 v[150:153], v[232:233], off offset:1664
	s_waitcnt lgkmcnt(5)
	v_mfma_f32_32x32x16_bf16 v[50:65], v[186:189], v[4:7], v[50:65]
	ds_read_b128 v[182:185], v249 offset:41536
	s_waitcnt vmcnt(7)
	ds_write_b128 v251, v[166:169] offset:9216
	v_mfma_f32_32x32x16_bf16 v[66:81], v[190:193], v[4:7], v[66:81]
	ds_read_b128 v[198:201], v248 offset:41536
	s_waitcnt lgkmcnt(6)
	v_mfma_f32_32x32x16_bf16 v[18:33], v[186:189], v[8:11], v[18:33]
	ds_read_b128 v[202:205], v248 offset:46144
	global_load_dwordx4 v[166:169], v[238:239], off offset:1664
	v_mfma_f32_32x32x16_bf16 v[34:49], v[190:193], v[8:11], v[34:49]
	ds_read_b128 v[206:209], v248 offset:50752
	s_waitcnt vmcnt(7)
	ds_write_b128 v250, v[154:157] offset:18432
	s_waitcnt lgkmcnt(6)
	v_mfma_f32_32x32x16_bf16 v[114:129], v[178:181], v[194:197], v[114:129]
	s_waitcnt lgkmcnt(5)
	v_mfma_f32_32x32x16_bf16 v[130:145], v[182:185], v[194:197], v[130:145]
	global_load_dwordx4 v[154:157], v[12:13], off offset:1664
	s_waitcnt lgkmcnt(3)
	v_mfma_f32_32x32x16_bf16 v[82:97], v[178:181], v[198:201], v[82:97]
	ds_read_b128 v[186:189], v249 offset:36960
	s_waitcnt vmcnt(7)
	ds_write_b128 v251, v[170:173] offset:18432
	v_mfma_f32_32x32x16_bf16 v[98:113], v[182:185], v[198:201], v[98:113]
	ds_read_b128 v[210:213], v248 offset:36960
	s_waitcnt lgkmcnt(5)
	v_mfma_f32_32x32x16_bf16 v[50:65], v[178:181], v[202:205], v[50:65]
	ds_read_b128 v[190:193], v249 offset:41568
	global_load_dwordx4 v[170:173], v[234:235], off offset:1664
	v_mfma_f32_32x32x16_bf16 v[66:81], v[182:185], v[202:205], v[66:81]
	ds_read_b128 v[214:217], v248 offset:41568
	s_waitcnt vmcnt(7)
	ds_write_b128 v250, v[158:161] offset:27648
	s_waitcnt lgkmcnt(7)
	v_mfma_f32_32x32x16_bf16 v[18:33], v[178:181], v[206:209], v[18:33]
	ds_read_b128 v[4:7], v248 offset:46176
	v_mfma_f32_32x32x16_bf16 v[34:49], v[182:185], v[206:209], v[34:49]
	ds_read_b128 v[8:11], v248 offset:50784
	global_load_dwordx4 v[158:161], v[14:15], off offset:1664
	s_waitcnt lgkmcnt(5)
	v_mfma_f32_32x32x16_bf16 v[114:129], v[186:189], v[210:213], v[114:129]
	s_waitcnt vmcnt(7)
	ds_write_b128 v251, v[174:177] offset:27648
	s_waitcnt lgkmcnt(5)
	v_mfma_f32_32x32x16_bf16 v[130:145], v[190:193], v[210:213], v[130:145]
	s_waitcnt lgkmcnt(4)
	v_mfma_f32_32x32x16_bf16 v[82:97], v[186:189], v[214:217], v[82:97]
	global_load_dwordx4 v[174:177], v[236:237], off offset:1664
	v_mfma_f32_32x32x16_bf16 v[98:113], v[190:193], v[214:217], v[98:113]
	s_waitcnt lgkmcnt(2)
	v_mfma_f32_32x32x16_bf16 v[50:65], v[186:189], v[4:7], v[50:65]
	v_mfma_f32_32x32x16_bf16 v[66:81], v[190:193], v[4:7], v[66:81]
	s_waitcnt lgkmcnt(1)
	v_mfma_f32_32x32x16_bf16 v[18:33], v[186:189], v[8:11], v[18:33]
	v_mfma_f32_32x32x16_bf16 v[34:49], v[190:193], v[8:11], v[34:49]
	s_waitcnt lgkmcnt(0)
	s_barrier
;     ...
;   for (int kt = 0; kt < nk; ++kt) {
;     __syncthreads();
;     if (kt + 1 < nk) {
;       u16* aw = As0 + ((kt + 1) & 1) * 256 * LD;
;       u16* bw = Bs0 + ((kt + 1) & 1) * 256 * LD;
; #pragma unroll
;       for (int i = 0; i < 4; ++i) { *(u32x4*)(aw + (srow + 64 * i) * LD + skc * 8) = ra[i]; *(u32x4*)(bw + (srow + 64 * i) * LD + skc * 8) = rb[i]; }
;     }
;     if (kt + 2 < nk) {
; #pragma unroll
;       for (int i = 0; i < 4; ++i) { ra[i] = *(const u32x4*)(Ag + (size_t)(64 * i) * K + (kt + 2) * 64); rb[i] = *(const u32x4*)(Bg[i] + (kt + 2) * 64); }
;     }
;     __builtin_amdgcn_sched_barrier(0);
;     const u16* as = As0 + (kt & 1) * 256 * LD + (wr * 128 + l31) * LD + h * 8;
;     const u16* bs = Bs0 + (kt & 1) * 256 * LD + (wc * 64 + l31) * LD + h * 8;
;     if (domma)
; #pragma unroll
;     for (int ks = 0; ks < 4; ++ks) {
;       bf16x8 wf[2], xf[4];
; #pragma unroll
;       for (int ct = 0; ct < 2; ++ct) wf[ct] = *(const bf16x8*)(bs + ct * 32 * LD + ks * 16);
; #pragma unroll
;       for (int tt = 0; tt < 4; ++tt) xf[tt] = *(const bf16x8*)(as + tt * 32 * LD + ks * 16);
; #pragma unroll
;       for (int ct = 0; ct < 2; ++ct)
; #pragma unroll
;         for (int tt = 0; tt < 4; ++tt) acc[ct][tt] = __builtin_amdgcn_mfma_f32_32x32x16_bf16(wf[ct], xf[tt], acc[ct][tt], 0, 0, 0);
;     }
	ds_read_b128 v[178:181], v249
	ds_read_b128 v[194:197], v248
	ds_read_b128 v[182:185], v249 offset:4608
	ds_read_b128 v[198:201], v248 offset:4608
	ds_read_b128 v[202:205], v248 offset:9216
	ds_read_b128 v[206:209], v248 offset:13824
	s_waitcnt lgkmcnt(4)
	v_mfma_f32_32x32x16_bf16 v[114:129], v[178:181], v[194:197], v[114:129]
	s_waitcnt lgkmcnt(3)
	v_mfma_f32_32x32x16_bf16 v[130:145], v[182:185], v[194:197], v[130:145]
	s_waitcnt lgkmcnt(2)
	v_mfma_f32_32x32x16_bf16 v[82:97], v[178:181], v[198:201], v[82:97]
	ds_read_b128 v[186:189], v249 offset:32
	v_mfma_f32_32x32x16_bf16 v[98:113], v[182:185], v[198:201], v[98:113]
	ds_read_b128 v[210:213], v248 offset:32
	s_waitcnt vmcnt(7)
	ds_write_b128 v250, v[146:149] offset:36864
	s_waitcnt lgkmcnt(4)
	v_mfma_f32_32x32x16_bf16 v[50:65], v[178:181], v[202:205], v[50:65]
	ds_read_b128 v[190:193], v249 offset:4640
	v_mfma_f32_32x32x16_bf16 v[66:81], v[182:185], v[202:205], v[66:81]
	ds_read_b128 v[214:217], v248 offset:4640
	global_load_dwordx4 v[146:149], v[230:231], off offset:1792
	s_waitcnt lgkmcnt(5)
	v_mfma_f32_32x32x16_bf16 v[18:33], v[178:181], v[206:209], v[18:33]
	ds_read_b128 v[4:7], v248 offset:9248
	s_waitcnt vmcnt(7)
	ds_write_b128 v251, v[162:165] offset:36864
	v_mfma_f32_32x32x16_bf16 v[34:49], v[182:185], v[206:209], v[34:49]
	ds_read_b128 v[8:11], v248 offset:13856
	s_waitcnt lgkmcnt(6)
	v_mfma_f32_32x32x16_bf16 v[114:129], v[186:189], v[210:213], v[114:129]
	global_load_dwordx4 v[162:165], v[228:229], off offset:1792
	s_waitcnt lgkmcnt(4)
	v_mfma_f32_32x32x16_bf16 v[130:145], v[190:193], v[210:213], v[130:145]
	s_waitcnt vmcnt(7)
	ds_write_b128 v250, v[150:153] offset:46080
	s_waitcnt lgkmcnt(4)
	v_mfma_f32_32x32x16_bf16 v[82:97], v[186:189], v[214:217], v[82:97]
	ds_read_b128 v[178:181], v249 offset:64
	v_mfma_f32_32x32x16_bf16 v[98:113], v[190:193], v[214:217], v[98:113]
	ds_read_b128 v[194:197], v248 offset:64
	global_load_dwordx4 v[150:153], v[232:233], off offset:1792
	s_waitcnt lgkmcnt(5)
	v_mfma_f32_32x32x16_bf16 v[50:65], v[186:189], v[4:7], v[50:65]
	ds_read_b128 v[182:185], v249 offset:4672
	s_waitcnt vmcnt(7)
	ds_write_b128 v251, v[166:169] offset:46080
	v_mfma_f32_32x32x16_bf16 v[66:81], v[190:193], v[4:7], v[66:81]
	ds_read_b128 v[198:201], v248 offset:4672
	s_waitcnt lgkmcnt(6)
	v_mfma_f32_32x32x16_bf16 v[18:33], v[186:189], v[8:11], v[18:33]
	ds_read_b128 v[202:205], v248 offset:9280
	global_load_dwordx4 v[166:169], v[238:239], off offset:1792
	v_mfma_f32_32x32x16_bf16 v[34:49], v[190:193], v[8:11], v[34:49]
	ds_read_b128 v[206:209], v248 offset:13888
	s_waitcnt vmcnt(7)
	ds_write_b128 v250, v[154:157] offset:55296
	s_waitcnt lgkmcnt(6)
	v_mfma_f32_32x32x16_bf16 v[114:129], v[178:181], v[194:197], v[114:129]
	s_waitcnt lgkmcnt(5)
	v_mfma_f32_32x32x16_bf16 v[130:145], v[182:185], v[194:197], v[130:145]
	global_load_dwordx4 v[154:157], v[12:13], off offset:1792
	s_waitcnt lgkmcnt(3)
	v_mfma_f32_32x32x16_bf16 v[82:97], v[178:181], v[198:201], v[82:97]
	ds_read_b128 v[186:189], v249 offset:96
	s_waitcnt vmcnt(7)
	ds_write_b128 v251, v[170:173] offset:55296
	v_mfma_f32_32x32x16_bf16 v[98:113], v[182:185], v[198:201], v[98:113]
	ds_read_b128 v[210:213], v248 offset:96
	s_waitcnt lgkmcnt(5)
	v_mfma_f32_32x32x16_bf16 v[50:65], v[178:181], v[202:205], v[50:65]
	ds_read_b128 v[190:193], v249 offset:4704
	global_load_dwordx4 v[170:173], v[234:235], off offset:1792
	v_mfma_f32_32x32x16_bf16 v[66:81], v[182:185], v[202:205], v[66:81]
	ds_read_b128 v[214:217], v248 offset:4704
	s_waitcnt vmcnt(7)
	ds_write_b128 v250, v[158:161] offset:64512
	s_waitcnt lgkmcnt(7)
	v_mfma_f32_32x32x16_bf16 v[18:33], v[178:181], v[206:209], v[18:33]
	ds_read_b128 v[4:7], v248 offset:9312
	v_mfma_f32_32x32x16_bf16 v[34:49], v[182:185], v[206:209], v[34:49]
	ds_read_b128 v[8:11], v248 offset:13920
	global_load_dwordx4 v[158:161], v[14:15], off offset:1792
	s_waitcnt lgkmcnt(5)
	v_mfma_f32_32x32x16_bf16 v[114:129], v[186:189], v[210:213], v[114:129]
	s_waitcnt vmcnt(7)
	ds_write_b128 v251, v[174:177] offset:64512
	s_waitcnt lgkmcnt(5)
	v_mfma_f32_32x32x16_bf16 v[130:145], v[190:193], v[210:213], v[130:145]
	s_waitcnt lgkmcnt(4)
	v_mfma_f32_32x32x16_bf16 v[82:97], v[186:189], v[214:217], v[82:97]
	global_load_dwordx4 v[174:177], v[236:237], off offset:1792
	v_mfma_f32_32x32x16_bf16 v[98:113], v[190:193], v[214:217], v[98:113]
	s_waitcnt lgkmcnt(2)
	v_mfma_f32_32x32x16_bf16 v[50:65], v[186:189], v[4:7], v[50:65]
	v_mfma_f32_32x32x16_bf16 v[66:81], v[190:193], v[4:7], v[66:81]
	s_waitcnt lgkmcnt(1)
	v_mfma_f32_32x32x16_bf16 v[18:33], v[186:189], v[8:11], v[18:33]
	v_mfma_f32_32x32x16_bf16 v[34:49], v[190:193], v[8:11], v[34:49]
	s_waitcnt lgkmcnt(0)
	s_barrier
;     ...
;   for (int kt = 0; kt < nk; ++kt) {
;     __syncthreads();
;     if (kt + 1 < nk) {
;       u16* aw = As0 + ((kt + 1) & 1) * 256 * LD;
;       u16* bw = Bs0 + ((kt + 1) & 1) * 256 * LD;
; #pragma unroll
;       for (int i = 0; i < 4; ++i) { *(u32x4*)(aw + (srow + 64 * i) * LD + skc * 8) = ra[i]; *(u32x4*)(bw + (srow + 64 * i) * LD + skc * 8) = rb[i]; }
;     }
;     if (kt + 2 < nk) {
; #pragma unroll
;       for (int i = 0; i < 4; ++i) { ra[i] = *(const u32x4*)(Ag + (size_t)(64 * i) * K + (kt + 2) * 64); rb[i] = *(const u32x4*)(Bg[i] + (kt + 2) * 64); }
;     }
;     __builtin_amdgcn_sched_barrier(0);
;     const u16* as = As0 + (kt & 1) * 256 * LD + (wr * 128 + l31) * LD + h * 8;
;     const u16* bs = Bs0 + (kt & 1) * 256 * LD + (wc * 64 + l31) * LD + h * 8;
;     if (domma)
; #pragma unroll
;     for (int ks = 0; ks < 4; ++ks) {
;       bf16x8 wf[2], xf[4];
; #pragma unroll
;       for (int ct = 0; ct < 2; ++ct) wf[ct] = *(const bf16x8*)(bs + ct * 32 * LD + ks * 16);
; #pragma unroll
;       for (int tt = 0; tt < 4; ++tt) xf[tt] = *(const bf16x8*)(as + tt * 32 * LD + ks * 16);
; #pragma unroll
;       for (int ct = 0; ct < 2; ++ct)
; #pragma unroll
;         for (int tt = 0; tt < 4; ++tt) acc[ct][tt] = __builtin_amdgcn_mfma_f32_32x32x16_bf16(wf[ct], xf[tt], acc[ct][tt], 0, 0, 0);
;     }
	ds_read_b128 v[178:181], v249 offset:36864
	ds_read_b128 v[194:197], v248 offset:36864
	ds_read_b128 v[182:185], v249 offset:41472
	ds_read_b128 v[198:201], v248 offset:41472
	ds_read_b128 v[202:205], v248 offset:46080
	ds_read_b128 v[206:209], v248 offset:50688
	s_waitcnt lgkmcnt(4)
	v_mfma_f32_32x32x16_bf16 v[114:129], v[178:181], v[194:197], v[114:129]
	s_waitcnt lgkmcnt(3)
	v_mfma_f32_32x32x16_bf16 v[130:145], v[182:185], v[194:197], v[130:145]
	s_waitcnt lgkmcnt(2)
	v_mfma_f32_32x32x16_bf16 v[82:97], v[178:181], v[198:201], v[82:97]
	ds_read_b128 v[186:189], v249 offset:36896
	v_mfma_f32_32x32x16_bf16 v[98:113], v[182:185], v[198:201], v[98:113]
	ds_read_b128 v[210:213], v248 offset:36896
	s_waitcnt vmcnt(7)
	ds_write_b128 v250, v[146:149]
	s_waitcnt lgkmcnt(4)
	v_mfma_f32_32x32x16_bf16 v[50:65], v[178:181], v[202:205], v[50:65]
	ds_read_b128 v[190:193], v249 offset:41504
	v_mfma_f32_32x32x16_bf16 v[66:81], v[182:185], v[202:205], v[66:81]
	ds_read_b128 v[214:217], v248 offset:41504
	global_load_dwordx4 v[146:149], v[230:231], off offset:1920
	s_waitcnt lgkmcnt(5)
	v_mfma_f32_32x32x16_bf16 v[18:33], v[178:181], v[206:209], v[18:33]
	ds_read_b128 v[4:7], v248 offset:46112
	s_waitcnt vmcnt(7)
	ds_write_b128 v251, v[162:165]
	v_mfma_f32_32x32x16_bf16 v[34:49], v[182:185], v[206:209], v[34:49]
	ds_read_b128 v[8:11], v248 offset:50720
	s_waitcnt lgkmcnt(6)
	v_mfma_f32_32x32x16_bf16 v[114:129], v[186:189], v[210:213], v[114:129]
	global_load_dwordx4 v[162:165], v[228:229], off offset:1920
	s_waitcnt lgkmcnt(4)
	v_mfma_f32_32x32x16_bf16 v[130:145], v[190:193], v[210:213], v[130:145]
	s_waitcnt vmcnt(7)
	ds_write_b128 v250, v[150:153] offset:9216
	s_waitcnt lgkmcnt(4)
	v_mfma_f32_32x32x16_bf16 v[82:97], v[186:189], v[214:217], v[82:97]
	ds_read_b128 v[178:181], v249 offset:36928
	v_mfma_f32_32x32x16_bf16 v[98:113], v[190:193], v[214:217], v[98:113]
	ds_read_b128 v[194:197], v248 offset:36928
	global_load_dwordx4 v[150:153], v[232:233], off offset:1920
	s_waitcnt lgkmcnt(5)
	v_mfma_f32_32x32x16_bf16 v[50:65], v[186:189], v[4:7], v[50:65]
	ds_read_b128 v[182:185], v249 offset:41536
	s_waitcnt vmcnt(7)
	ds_write_b128 v251, v[166:169] offset:9216
	v_mfma_f32_32x32x16_bf16 v[66:81], v[190:193], v[4:7], v[66:81]
	ds_read_b128 v[198:201], v248 offset:41536
	s_waitcnt lgkmcnt(6)
	v_mfma_f32_32x32x16_bf16 v[18:33], v[186:189], v[8:11], v[18:33]
	ds_read_b128 v[202:205], v248 offset:46144
	global_load_dwordx4 v[166:169], v[238:239], off offset:1920
	v_mfma_f32_32x32x16_bf16 v[34:49], v[190:193], v[8:11], v[34:49]
	ds_read_b128 v[206:209], v248 offset:50752
	s_waitcnt vmcnt(7)
	ds_write_b128 v250, v[154:157] offset:18432
	s_waitcnt lgkmcnt(6)
	v_mfma_f32_32x32x16_bf16 v[114:129], v[178:181], v[194:197], v[114:129]
	s_waitcnt lgkmcnt(5)
	v_mfma_f32_32x32x16_bf16 v[130:145], v[182:185], v[194:197], v[130:145]
	global_load_dwordx4 v[154:157], v[12:13], off offset:1920
	s_waitcnt lgkmcnt(3)
	v_mfma_f32_32x32x16_bf16 v[82:97], v[178:181], v[198:201], v[82:97]
	ds_read_b128 v[186:189], v249 offset:36960
	s_waitcnt vmcnt(7)
	ds_write_b128 v251, v[170:173] offset:18432
	v_mfma_f32_32x32x16_bf16 v[98:113], v[182:185], v[198:201], v[98:113]
	ds_read_b128 v[210:213], v248 offset:36960
	s_waitcnt lgkmcnt(5)
	v_mfma_f32_32x32x16_bf16 v[50:65], v[178:181], v[202:205], v[50:65]
	ds_read_b128 v[190:193], v249 offset:41568
	global_load_dwordx4 v[170:173], v[234:235], off offset:1920
	v_mfma_f32_32x32x16_bf16 v[66:81], v[182:185], v[202:205], v[66:81]
	ds_read_b128 v[214:217], v248 offset:41568
	s_waitcnt vmcnt(7)
	ds_write_b128 v250, v[158:161] offset:27648
	s_waitcnt lgkmcnt(7)
	v_mfma_f32_32x32x16_bf16 v[18:33], v[178:181], v[206:209], v[18:33]
	ds_read_b128 v[4:7], v248 offset:46176
	v_mfma_f32_32x32x16_bf16 v[34:49], v[182:185], v[206:209], v[34:49]
	ds_read_b128 v[8:11], v248 offset:50784
	global_load_dwordx4 v[158:161], v[14:15], off offset:1920
	s_waitcnt lgkmcnt(5)
	v_mfma_f32_32x32x16_bf16 v[114:129], v[186:189], v[210:213], v[114:129]
	s_waitcnt vmcnt(7)
	ds_write_b128 v251, v[174:177] offset:27648
	s_waitcnt lgkmcnt(5)
	v_mfma_f32_32x32x16_bf16 v[130:145], v[190:193], v[210:213], v[130:145]
	s_waitcnt lgkmcnt(4)
	v_mfma_f32_32x32x16_bf16 v[82:97], v[186:189], v[214:217], v[82:97]
	global_load_dwordx4 v[174:177], v[236:237], off offset:1920
	v_mfma_f32_32x32x16_bf16 v[98:113], v[190:193], v[214:217], v[98:113]
	s_waitcnt lgkmcnt(2)
	v_mfma_f32_32x32x16_bf16 v[50:65], v[186:189], v[4:7], v[50:65]
	v_mfma_f32_32x32x16_bf16 v[66:81], v[190:193], v[4:7], v[66:81]
	s_waitcnt lgkmcnt(1)
	v_mfma_f32_32x32x16_bf16 v[18:33], v[186:189], v[8:11], v[18:33]
	v_mfma_f32_32x32x16_bf16 v[34:49], v[190:193], v[8:11], v[34:49]
	s_waitcnt lgkmcnt(0)
	s_barrier
;     ...
;   for (int kt = 0; kt < nk; ++kt) {
;     __syncthreads();
;     if (kt + 1 < nk) {
;       u16* aw = As0 + ((kt + 1) & 1) * 256 * LD;
;       u16* bw = Bs0 + ((kt + 1) & 1) * 256 * LD;
; #pragma unroll
;       for (int i = 0; i < 4; ++i) { *(u32x4*)(aw + (srow + 64 * i) * LD + skc * 8) = ra[i]; *(u32x4*)(bw + (srow + 64 * i) * LD + skc * 8) = rb[i]; }
;     }
;     if (kt + 2 < nk) {
; #pragma unroll
;       for (int i = 0; i < 4; ++i) { ra[i] = *(const u32x4*)(Ag + (size_t)(64 * i) * K + (kt + 2) * 64); rb[i] = *(const u32x4*)(Bg[i] + (kt + 2) * 64); }
;     }
;     __builtin_amdgcn_sched_barrier(0);
;     const u16* as = As0 + (kt & 1) * 256 * LD + (wr * 128 + l31) * LD + h * 8;
;     const u16* bs = Bs0 + (kt & 1) * 256 * LD + (wc * 64 + l31) * LD + h * 8;
;     if (domma)
; #pragma unroll
;     for (int ks = 0; ks < 4; ++ks) {
;       bf16x8 wf[2], xf[4];
; #pragma unroll
;       for (int ct = 0; ct < 2; ++ct) wf[ct] = *(const bf16x8*)(bs + ct * 32 * LD + ks * 16);
; #pragma unroll
;       for (int tt = 0; tt < 4; ++tt) xf[tt] = *(const bf16x8*)(as + tt * 32 * LD + ks * 16);
; #pragma unroll
;       for (int ct = 0; ct < 2; ++ct)
; #pragma unroll
;         for (int tt = 0; tt < 4; ++tt) acc[ct][tt] = __builtin_amdgcn_mfma_f32_32x32x16_bf16(wf[ct], xf[tt], acc[ct][tt], 0, 0, 0);
;     }
	ds_read_b128 v[178:181], v249
	ds_read_b128 v[194:197], v248
	ds_read_b128 v[182:185], v249 offset:4608
	ds_read_b128 v[198:201], v248 offset:4608
	ds_read_b128 v[202:205], v248 offset:9216
	ds_read_b128 v[206:209], v248 offset:13824
	s_waitcnt lgkmcnt(4)
	v_mfma_f32_32x32x16_bf16 v[114:129], v[178:181], v[194:197], v[114:129]
	s_waitcnt lgkmcnt(3)
	v_mfma_f32_32x32x16_bf16 v[130:145], v[182:185], v[194:197], v[130:145]
	s_waitcnt lgkmcnt(2)
	v_mfma_f32_32x32x16_bf16 v[82:97], v[178:181], v[198:201], v[82:97]
	ds_read_b128 v[186:189], v249 offset:32
	v_mfma_f32_32x32x16_bf16 v[98:113], v[182:185], v[198:201], v[98:113]
	ds_read_b128 v[210:213], v248 offset:32
	s_waitcnt vmcnt(7)
	ds_write_b128 v250, v[146:149] offset:36864
	s_waitcnt lgkmcnt(4)
	v_mfma_f32_32x32x16_bf16 v[50:65], v[178:181], v[202:205], v[50:65]
	ds_read_b128 v[190:193], v249 offset:4640
	v_mfma_f32_32x32x16_bf16 v[66:81], v[182:185], v[202:205], v[66:81]
	ds_read_b128 v[214:217], v248 offset:4640
	s_waitcnt lgkmcnt(5)
	v_mfma_f32_32x32x16_bf16 v[18:33], v[178:181], v[206:209], v[18:33]
	ds_read_b128 v[4:7], v248 offset:9248
	s_waitcnt vmcnt(6)
	ds_write_b128 v251, v[162:165] offset:36864
	v_mfma_f32_32x32x16_bf16 v[34:49], v[182:185], v[206:209], v[34:49]
	ds_read_b128 v[8:11], v248 offset:13856
	s_waitcnt lgkmcnt(6)
	v_mfma_f32_32x32x16_bf16 v[114:129], v[186:189], v[210:213], v[114:129]
	s_waitcnt lgkmcnt(4)
	v_mfma_f32_32x32x16_bf16 v[130:145], v[190:193], v[210:213], v[130:145]
	s_waitcnt vmcnt(5)
	ds_write_b128 v250, v[150:153] offset:46080
	s_waitcnt lgkmcnt(4)
	v_mfma_f32_32x32x16_bf16 v[82:97], v[186:189], v[214:217], v[82:97]
	ds_read_b128 v[178:181], v249 offset:64
	v_mfma_f32_32x32x16_bf16 v[98:113], v[190:193], v[214:217], v[98:113]
	ds_read_b128 v[194:197], v248 offset:64
	s_waitcnt lgkmcnt(5)
	v_mfma_f32_32x32x16_bf16 v[50:65], v[186:189], v[4:7], v[50:65]
	ds_read_b128 v[182:185], v249 offset:4672
	s_waitcnt vmcnt(4)
	ds_write_b128 v251, v[166:169] offset:46080
	v_mfma_f32_32x32x16_bf16 v[66:81], v[190:193], v[4:7], v[66:81]
	ds_read_b128 v[198:201], v248 offset:4672
	s_waitcnt lgkmcnt(6)
	v_mfma_f32_32x32x16_bf16 v[18:33], v[186:189], v[8:11], v[18:33]
	ds_read_b128 v[202:205], v248 offset:9280
	v_mfma_f32_32x32x16_bf16 v[34:49], v[190:193], v[8:11], v[34:49]
	ds_read_b128 v[206:209], v248 offset:13888
	s_waitcnt vmcnt(3)
	ds_write_b128 v250, v[154:157] offset:55296
	s_waitcnt lgkmcnt(6)
	v_mfma_f32_32x32x16_bf16 v[114:129], v[178:181], v[194:197], v[114:129]
	s_waitcnt lgkmcnt(5)
	v_mfma_f32_32x32x16_bf16 v[130:145], v[182:185], v[194:197], v[130:145]
	s_waitcnt lgkmcnt(3)
	v_mfma_f32_32x32x16_bf16 v[82:97], v[178:181], v[198:201], v[82:97]
	ds_read_b128 v[186:189], v249 offset:96
	s_waitcnt vmcnt(2)
	ds_write_b128 v251, v[170:173] offset:55296
	v_mfma_f32_32x32x16_bf16 v[98:113], v[182:185], v[198:201], v[98:113]
	ds_read_b128 v[210:213], v248 offset:96
	s_waitcnt lgkmcnt(5)
	v_mfma_f32_32x32x16_bf16 v[50:65], v[178:181], v[202:205], v[50:65]
	ds_read_b128 v[190:193], v249 offset:4704
	v_mfma_f32_32x32x16_bf16 v[66:81], v[182:185], v[202:205], v[66:81]
	ds_read_b128 v[214:217], v248 offset:4704
	s_waitcnt vmcnt(1)
	ds_write_b128 v250, v[158:161] offset:64512
	s_waitcnt lgkmcnt(7)
	v_mfma_f32_32x32x16_bf16 v[18:33], v[178:181], v[206:209], v[18:33]
	ds_read_b128 v[4:7], v248 offset:9312
	v_mfma_f32_32x32x16_bf16 v[34:49], v[182:185], v[206:209], v[34:49]
	ds_read_b128 v[8:11], v248 offset:13920
	s_waitcnt lgkmcnt(5)
	v_mfma_f32_32x32x16_bf16 v[114:129], v[186:189], v[210:213], v[114:129]
	s_waitcnt vmcnt(0)
	ds_write_b128 v251, v[174:177] offset:64512
	s_waitcnt lgkmcnt(5)
	v_mfma_f32_32x32x16_bf16 v[130:145], v[190:193], v[210:213], v[130:145]
	s_waitcnt lgkmcnt(4)
	v_mfma_f32_32x32x16_bf16 v[82:97], v[186:189], v[214:217], v[82:97]
	v_mfma_f32_32x32x16_bf16 v[98:113], v[190:193], v[214:217], v[98:113]
	s_waitcnt lgkmcnt(2)
	v_mfma_f32_32x32x16_bf16 v[50:65], v[186:189], v[4:7], v[50:65]
	v_mfma_f32_32x32x16_bf16 v[66:81], v[190:193], v[4:7], v[66:81]
	s_waitcnt lgkmcnt(1)
	v_mfma_f32_32x32x16_bf16 v[18:33], v[186:189], v[8:11], v[18:33]
	v_mfma_f32_32x32x16_bf16 v[34:49], v[190:193], v[8:11], v[34:49]
	s_waitcnt lgkmcnt(0)
	s_barrier
	ds_read_b128 v[178:181], v249 offset:36864
	ds_read_b128 v[194:197], v248 offset:36864
	ds_read_b128 v[182:185], v249 offset:41472
	ds_read_b128 v[198:201], v248 offset:41472
	ds_read_b128 v[202:205], v248 offset:46080
	ds_read_b128 v[206:209], v248 offset:50688
	s_waitcnt lgkmcnt(4)
	v_mfma_f32_32x32x16_bf16 v[114:129], v[178:181], v[194:197], v[114:129]
	s_waitcnt lgkmcnt(3)
	v_mfma_f32_32x32x16_bf16 v[130:145], v[182:185], v[194:197], v[130:145]
	s_waitcnt lgkmcnt(2)
	v_mfma_f32_32x32x16_bf16 v[82:97], v[178:181], v[198:201], v[82:97]
	ds_read_b128 v[186:189], v249 offset:36896
	v_mfma_f32_32x32x16_bf16 v[98:113], v[182:185], v[198:201], v[98:113]
	ds_read_b128 v[210:213], v248 offset:36896
	s_waitcnt lgkmcnt(3)
	v_mfma_f32_32x32x16_bf16 v[50:65], v[178:181], v[202:205], v[50:65]
	ds_read_b128 v[190:193], v249 offset:41504
	v_mfma_f32_32x32x16_bf16 v[66:81], v[182:185], v[202:205], v[66:81]
	ds_read_b128 v[214:217], v248 offset:41504
	s_waitcnt lgkmcnt(4)
	v_mfma_f32_32x32x16_bf16 v[18:33], v[178:181], v[206:209], v[18:33]
	ds_read_b128 v[4:7], v248 offset:46112
	v_mfma_f32_32x32x16_bf16 v[34:49], v[182:185], v[206:209], v[34:49]
	ds_read_b128 v[8:11], v248 offset:50720
	s_waitcnt lgkmcnt(4)
	v_mfma_f32_32x32x16_bf16 v[114:129], v[186:189], v[210:213], v[114:129]
	s_waitcnt lgkmcnt(3)
	v_mfma_f32_32x32x16_bf16 v[130:145], v[190:193], v[210:213], v[130:145]
	s_waitcnt lgkmcnt(2)
;     ...
;     const u16* as = As0 + (kt & 1) * 256 * LD + (wr * 128 + l31) * LD + h * 8;
;     const u16* bs = Bs0 + (kt & 1) * 256 * LD + (wc * 64 + l31) * LD + h * 8;
;     if (domma)
; #pragma unroll
;     for (int ks = 0; ks < 4; ++ks) {
;       bf16x8 wf[2], xf[4];
; #pragma unroll
;       for (int ct = 0; ct < 2; ++ct) wf[ct] = *(const bf16x8*)(bs + ct * 32 * LD + ks * 16);
; #pragma unroll
;       for (int tt = 0; tt < 4; ++tt) xf[tt] = *(const bf16x8*)(as + tt * 32 * LD + ks * 16);
; #pragma unroll
;       for (int ct = 0; ct < 2; ++ct)
; #pragma unroll
;         for (int tt = 0; tt < 4; ++tt) acc[ct][tt] = __builtin_amdgcn_mfma_f32_32x32x16_bf16(wf[ct], xf[tt], acc[ct][tt], 0, 0, 0);
;     }
;     __builtin_amdgcn_sched_barrier(0);
;   }
	v_mfma_f32_32x32x16_bf16 v[82:97], v[186:189], v[214:217], v[82:97]
	ds_read_b128 v[178:181], v249 offset:36928
	v_mfma_f32_32x32x16_bf16 v[98:113], v[190:193], v[214:217], v[98:113]
	ds_read_b128 v[194:197], v248 offset:36928
	s_waitcnt lgkmcnt(3)
	v_mfma_f32_32x32x16_bf16 v[50:65], v[186:189], v[4:7], v[50:65]
	ds_read_b128 v[182:185], v249 offset:41536
	v_mfma_f32_32x32x16_bf16 v[66:81], v[190:193], v[4:7], v[66:81]
	ds_read_b128 v[198:201], v248 offset:41536
	s_waitcnt lgkmcnt(4)
	v_mfma_f32_32x32x16_bf16 v[18:33], v[186:189], v[8:11], v[18:33]
	ds_read_b128 v[202:205], v248 offset:46144
	v_mfma_f32_32x32x16_bf16 v[34:49], v[190:193], v[8:11], v[34:49]
	ds_read_b128 v[206:209], v248 offset:50752
	s_waitcnt lgkmcnt(4)
	v_mfma_f32_32x32x16_bf16 v[114:129], v[178:181], v[194:197], v[114:129]
	s_waitcnt lgkmcnt(3)
	v_mfma_f32_32x32x16_bf16 v[130:145], v[182:185], v[194:197], v[130:145]
	s_waitcnt lgkmcnt(2)
	v_mfma_f32_32x32x16_bf16 v[82:97], v[178:181], v[198:201], v[82:97]
	ds_read_b128 v[186:189], v249 offset:36960
	v_mfma_f32_32x32x16_bf16 v[98:113], v[182:185], v[198:201], v[98:113]
	ds_read_b128 v[210:213], v248 offset:36960
	s_waitcnt lgkmcnt(3)
	v_mfma_f32_32x32x16_bf16 v[50:65], v[178:181], v[202:205], v[50:65]
	ds_read_b128 v[190:193], v249 offset:41568
	v_mfma_f32_32x32x16_bf16 v[66:81], v[182:185], v[202:205], v[66:81]
	ds_read_b128 v[214:217], v248 offset:41568
	s_waitcnt lgkmcnt(4)
	v_mfma_f32_32x32x16_bf16 v[18:33], v[178:181], v[206:209], v[18:33]
	ds_read_b128 v[4:7], v248 offset:46176
	v_mfma_f32_32x32x16_bf16 v[34:49], v[182:185], v[206:209], v[34:49]
	ds_read_b128 v[8:11], v248 offset:50784
	s_waitcnt lgkmcnt(4)
	v_mfma_f32_32x32x16_bf16 v[114:129], v[186:189], v[210:213], v[114:129]
	s_waitcnt lgkmcnt(3)
	v_mfma_f32_32x32x16_bf16 v[130:145], v[190:193], v[210:213], v[130:145]
	s_waitcnt lgkmcnt(2)
	v_mfma_f32_32x32x16_bf16 v[82:97], v[186:189], v[214:217], v[82:97]
	v_mfma_f32_32x32x16_bf16 v[98:113], v[190:193], v[214:217], v[98:113]
	s_waitcnt lgkmcnt(1)
	v_mfma_f32_32x32x16_bf16 v[50:65], v[186:189], v[4:7], v[50:65]
	v_mfma_f32_32x32x16_bf16 v[66:81], v[190:193], v[4:7], v[66:81]
	s_waitcnt lgkmcnt(0)
	v_mfma_f32_32x32x16_bf16 v[18:33], v[186:189], v[8:11], v[18:33]
	v_mfma_f32_32x32x16_bf16 v[34:49], v[190:193], v[8:11], v[34:49]
	s_waitcnt lgkmcnt(0)
	s_branch .LBB0_139
;     ...
; #pragma unroll
;   for (int a = 0; a < 2; ++a)
; #pragma unroll
;     for (int b = 0; b < 4; ++b)
; #pragma unroll
;       for (int r = 0; r < 16; ++r) acc[a][b][r] = 0.f;
;   u32x4 ra[4], rb[4];
;   const int srow = tid >> 3, skc = tid & 7;
;   const u16* Ag = A + (size_t)(m0 + srow) * K + skc * 8;
;   const u16* Bg[4];
; #pragma unroll
;   for (int i = 0; i < 4; ++i) { int n = n0 + srow + 64 * i; n = n < nmax ? n : nmax - 1; Bg[i] = Bt + (size_t)n * K + skc * 8; }
;   const int nk = nk_override ? nk_override : K / 64;
; #pragma unroll
;   for (int i = 0; i < 4; ++i) { ra[i] = *(const u32x4*)(Ag + (size_t)(64 * i) * K); rb[i] = *(const u32x4*)(Bg[i]); }
; #pragma unroll
;   for (int i = 0; i < 4; ++i) { *(u32x4*)(As0 + (srow + 64 * i) * LD + skc * 8) = ra[i]; *(u32x4*)(Bs0 + (srow + 64 * i) * LD + skc * 8) = rb[i]; }
;   if (nk > 1) {
; #pragma unroll
;     for (int i = 0; i < 4; ++i) { ra[i] = *(const u32x4*)(Ag + (size_t)(64 * i) * K + 64); rb[i] = *(const u32x4*)(Bg[i] + 64); }
;   }
;   for (int kt = 0; kt < nk; ++kt) {
;     __syncthreads();
;     if (kt + 1 < nk) {
;       u16* aw = As0 + ((kt + 1) & 1) * 256 * LD;
;       u16* bw = Bs0 + ((kt + 1) & 1) * 256 * LD;
; #pragma unroll
;       for (int i = 0; i < 4; ++i) { *(u32x4*)(aw + (srow + 64 * i) * LD + skc * 8) = ra[i]; *(u32x4*)(bw + (srow + 64 * i) * LD + skc * 8) = rb[i]; }
;     }
;     if (kt + 2 < nk) {
; #pragma unroll
;       for (int i = 0; i < 4; ++i) { ra[i] = *(const u32x4*)(Ag + (size_t)(64 * i) * K + (kt + 2) * 64); rb[i] = *(const u32x4*)(Bg[i] + (kt + 2) * 64); }
;     }
;     __builtin_amdgcn_sched_barrier(0);
;     const u16* as = As0 + (kt & 1) * 256 * LD + (wr * 128 + l31) * LD + h * 8;
;     const u16* bs = Bs0 + (kt & 1) * 256 * LD + (wc * 64 + l31) * LD + h * 8;
;     if (domma)
; #pragma unroll
;     for (int ks = 0; ks < 4; ++ks) {
;       bf16x8 wf[2], xf[4];
; #pragma unroll
;       for (int ct = 0; ct < 2; ++ct) wf[ct] = *(const bf16x8*)(bs + ct * 32 * LD + ks * 16);
; #pragma unroll
;       for (int tt = 0; tt < 4; ++tt) xf[tt] = *(const bf16x8*)(as + tt * 32 * LD + ks * 16);
; #pragma unroll
;       for (int ct = 0; ct < 2; ++ct)
; #pragma unroll
;         for (int tt = 0; tt < 4; ++tt) acc[ct][tt] = __builtin_amdgcn_mfma_f32_32x32x16_bf16(wf[ct], xf[tt], acc[ct][tt], 0, 0, 0);
;     }
.Lp1_orig_k:
	global_load_dwordx4 v[146:149], v[228:229], off offset:256
	global_load_dwordx4 v[150:153], v[238:239], off offset:256
	global_load_dwordx4 v[166:169], v[230:231], off offset:256
	global_load_dwordx4 v[154:157], v[68:69], off offset:256
	global_load_dwordx4 v[170:173], v[232:233], off offset:256
	global_load_dwordx4 v[158:161], v[70:71], off offset:256
	global_load_dwordx4 v[174:177], v[234:235], off offset:256
	global_load_dwordx4 v[162:165], v[236:237], off offset:256
	s_waitcnt vmcnt(11)
	ds_write_b128 v250, v[52:55] offset:36864
	ds_write_b128 v251, v[36:39] offset:36864
	s_waitcnt vmcnt(10)
	ds_write_b128 v250, v[56:59] offset:46080
	ds_write_b128 v251, v[40:43] offset:46080
	s_waitcnt vmcnt(9)
	ds_write_b128 v250, v[60:63] offset:55296
	ds_write_b128 v251, v[44:47] offset:55296
	s_waitcnt vmcnt(8)
	ds_write_b128 v250, v[64:67] offset:64512
	ds_write_b128 v251, v[48:51] offset:64512
	v_mov_b32_e32 v16, v3
	v_mov_b32_e32 v17, v3
	v_mov_b32_e32 v2, v3
	v_mov_b32_e32 v4, v3
	v_mov_b32_e32 v5, v3
	v_mov_b32_e32 v6, v3
	v_mov_b32_e32 v7, v3
	v_mov_b32_e32 v8, v3
	v_mov_b32_e32 v9, v3
	v_mov_b32_e32 v10, v3
	v_mov_b32_e32 v11, v3
	v_mov_b32_e32 v12, v3
	v_mov_b32_e32 v13, v3
	v_mov_b32_e32 v14, v3
	v_mov_b32_e32 v15, v3
	v_mov_b64_e32 v[32:33], v[16:17]
	v_mov_b64_e32 v[64:65], v[16:17]
	v_mov_b64_e32 v[96:97], v[16:17]
	v_mov_b64_e32 v[128:129], v[16:17]
	v_mov_b64_e32 v[144:145], v[16:17]
	v_mov_b64_e32 v[112:113], v[16:17]
	v_mov_b64_e32 v[80:81], v[16:17]
	v_mov_b64_e32 v[48:49], v[16:17]
	s_and_b64 vcc, exec, s[30:31]
	v_mov_b64_e32 v[30:31], v[14:15]
	v_mov_b64_e32 v[28:29], v[12:13]
	v_mov_b64_e32 v[26:27], v[10:11]
	v_mov_b64_e32 v[24:25], v[8:9]
	v_mov_b64_e32 v[22:23], v[6:7]
	v_mov_b64_e32 v[20:21], v[4:5]
	v_mov_b64_e32 v[18:19], v[2:3]
	v_mov_b64_e32 v[62:63], v[14:15]
	v_mov_b64_e32 v[60:61], v[12:13]
	v_mov_b64_e32 v[58:59], v[10:11]
	v_mov_b64_e32 v[56:57], v[8:9]
	v_mov_b64_e32 v[54:55], v[6:7]
	v_mov_b64_e32 v[52:53], v[4:5]
	v_mov_b64_e32 v[50:51], v[2:3]
	v_mov_b64_e32 v[94:95], v[14:15]
	v_mov_b64_e32 v[92:93], v[12:13]
	v_mov_b64_e32 v[90:91], v[10:11]
	v_mov_b64_e32 v[88:89], v[8:9]
	v_mov_b64_e32 v[86:87], v[6:7]
	v_mov_b64_e32 v[84:85], v[4:5]
	v_mov_b64_e32 v[82:83], v[2:3]
	v_mov_b64_e32 v[126:127], v[14:15]
	v_mov_b64_e32 v[124:125], v[12:13]
	v_mov_b64_e32 v[122:123], v[10:11]
	v_mov_b64_e32 v[120:121], v[8:9]
	v_mov_b64_e32 v[118:119], v[6:7]
	v_mov_b64_e32 v[116:117], v[4:5]
	v_mov_b64_e32 v[114:115], v[2:3]
	v_mov_b64_e32 v[142:143], v[14:15]
	v_mov_b64_e32 v[140:141], v[12:13]
	v_mov_b64_e32 v[138:139], v[10:11]
	v_mov_b64_e32 v[136:137], v[8:9]
	v_mov_b64_e32 v[134:135], v[6:7]
	v_mov_b64_e32 v[132:133], v[4:5]
	v_mov_b64_e32 v[130:131], v[2:3]
	v_mov_b64_e32 v[110:111], v[14:15]
	v_mov_b64_e32 v[108:109], v[12:13]
	v_mov_b64_e32 v[106:107], v[10:11]
	v_mov_b64_e32 v[104:105], v[8:9]
	v_mov_b64_e32 v[102:103], v[6:7]
	v_mov_b64_e32 v[100:101], v[4:5]
	v_mov_b64_e32 v[98:99], v[2:3]
	v_mov_b64_e32 v[78:79], v[14:15]
	v_mov_b64_e32 v[76:77], v[12:13]
	v_mov_b64_e32 v[74:75], v[10:11]
	v_mov_b64_e32 v[72:73], v[8:9]
	v_mov_b64_e32 v[70:71], v[6:7]
	v_mov_b64_e32 v[68:69], v[4:5]
	v_mov_b64_e32 v[66:67], v[2:3]
	v_mov_b64_e32 v[46:47], v[14:15]
	v_mov_b64_e32 v[44:45], v[12:13]
	v_mov_b64_e32 v[42:43], v[10:11]
	v_mov_b64_e32 v[40:41], v[8:9]
	v_mov_b64_e32 v[38:39], v[6:7]
	v_mov_b64_e32 v[36:37], v[4:5]
	v_mov_b64_e32 v[34:35], v[2:3]
	s_cbranch_vccz .LBB0_109
	ds_read_b128 v[4:7], v249
	ds_read_b128 v[8:11], v248
	ds_read_b128 v[12:15], v249 offset:32
	ds_read_b128 v[178:181], v248 offset:32
	ds_read_b128 v[34:37], v248 offset:4608
	ds_read_b128 v[182:185], v248 offset:4640
	ds_read_b128 v[38:41], v248 offset:9216
	ds_read_b128 v[186:189], v248 offset:9248
	ds_read_b128 v[42:45], v248 offset:13824
	ds_read_b128 v[190:193], v248 offset:13856
	s_waitcnt lgkmcnt(8)
	v_mfma_f32_32x32x16_bf16 v[114:129], v[4:7], v[8:11], 0
	s_waitcnt lgkmcnt(5)
	v_mfma_f32_32x32x16_bf16 v[82:97], v[4:7], v[34:37], 0
	s_waitcnt lgkmcnt(3)
	v_mfma_f32_32x32x16_bf16 v[50:65], v[4:7], v[38:41], 0
	s_waitcnt lgkmcnt(1)
	v_mfma_f32_32x32x16_bf16 v[18:33], v[4:7], v[42:45], 0
	ds_read_b128 v[4:7], v249 offset:4608
	ds_read_b128 v[194:197], v249 offset:4640
	s_waitcnt lgkmcnt(1)
	v_mfma_f32_32x32x16_bf16 v[130:145], v[4:7], v[8:11], 0
	v_mfma_f32_32x32x16_bf16 v[98:113], v[4:7], v[34:37], 0
	v_mfma_f32_32x32x16_bf16 v[66:81], v[4:7], v[38:41], 0
	v_mfma_f32_32x32x16_bf16 v[34:49], v[4:7], v[42:45], 0
	v_mfma_f32_32x32x16_bf16 v[114:129], v[12:15], v[178:181], v[114:129]
	v_mfma_f32_32x32x16_bf16 v[82:97], v[12:15], v[182:185], v[82:97]
	v_mfma_f32_32x32x16_bf16 v[50:65], v[12:15], v[186:189], v[50:65]
	v_mfma_f32_32x32x16_bf16 v[18:33], v[12:15], v[190:193], v[18:33]
	s_waitcnt lgkmcnt(0)
	v_mfma_f32_32x32x16_bf16 v[130:145], v[194:197], v[178:181], v[130:145]
	ds_read_b128 v[4:7], v249 offset:64
	ds_read_b128 v[8:11], v248 offset:64
	ds_read_b128 v[12:15], v249 offset:96
	ds_read_b128 v[178:181], v248 offset:96
	v_mfma_f32_32x32x16_bf16 v[98:113], v[194:197], v[182:185], v[98:113]
	v_mfma_f32_32x32x16_bf16 v[66:81], v[194:197], v[186:189], v[66:81]
	ds_read_b128 v[182:185], v248 offset:4672
	ds_read_b128 v[186:189], v248 offset:4704
	v_mfma_f32_32x32x16_bf16 v[34:49], v[194:197], v[190:193], v[34:49]
	ds_read_b128 v[190:193], v248 offset:9280
	ds_read_b128 v[194:197], v248 offset:9312
	ds_read_b128 v[198:201], v248 offset:13888
	ds_read_b128 v[202:205], v248 offset:13920
	s_waitcnt lgkmcnt(8)
	v_mfma_f32_32x32x16_bf16 v[114:129], v[4:7], v[8:11], v[114:129]
	s_waitcnt lgkmcnt(5)
	v_mfma_f32_32x32x16_bf16 v[82:97], v[4:7], v[182:185], v[82:97]
	s_waitcnt lgkmcnt(3)
	v_mfma_f32_32x32x16_bf16 v[50:65], v[4:7], v[190:193], v[50:65]
	s_waitcnt lgkmcnt(1)
	v_mfma_f32_32x32x16_bf16 v[18:33], v[4:7], v[198:201], v[18:33]
	ds_read_b128 v[4:7], v249 offset:4672
	ds_read_b128 v[206:209], v249 offset:4704
	s_waitcnt lgkmcnt(1)
	v_mfma_f32_32x32x16_bf16 v[130:145], v[4:7], v[8:11], v[130:145]
	v_mfma_f32_32x32x16_bf16 v[98:113], v[4:7], v[182:185], v[98:113]
	v_mfma_f32_32x32x16_bf16 v[66:81], v[4:7], v[190:193], v[66:81]
	v_mfma_f32_32x32x16_bf16 v[34:49], v[4:7], v[198:201], v[34:49]
	v_mfma_f32_32x32x16_bf16 v[114:129], v[12:15], v[178:181], v[114:129]
	v_mfma_f32_32x32x16_bf16 v[82:97], v[12:15], v[186:189], v[82:97]
	v_mfma_f32_32x32x16_bf16 v[50:65], v[12:15], v[194:197], v[50:65]
	v_mfma_f32_32x32x16_bf16 v[18:33], v[12:15], v[202:205], v[18:33]
	s_waitcnt lgkmcnt(0)
	v_mfma_f32_32x32x16_bf16 v[130:145], v[206:209], v[178:181], v[130:145]
	v_mfma_f32_32x32x16_bf16 v[98:113], v[206:209], v[186:189], v[98:113]
	v_mfma_f32_32x32x16_bf16 v[66:81], v[206:209], v[194:197], v[66:81]
	v_mfma_f32_32x32x16_bf16 v[34:49], v[206:209], v[202:205], v[34:49]

; __device__ void rwkv_prep_item(const Params& p, char* lds_, int item, PrepRaw& raw, int next_item) {
;     ...
;   {
;     const int cbp = hd * 64 + cg8;
; #pragma unroll
;     for (int q = 0; q < 2; ++q) {
;       pdb[q] = *(const f32x4*)(p.decay_bias + cbp + 4 * q); pib[q] = *(const f32x4*)(p.iclr_bias + cbp + 4 * q);
;       pkk[q] = *(const f32x4*)(p.k_k + cbp + 4 * q); pka[q] = *(const f32x4*)(p.k_a + cbp + 4 * q); prk[q] = *(const f32x4*)(p.r_k + cbp + 4 * q);
;     }
;   }
;     ...
;     *(u32x4*)(DUs + t * LD + cg8) = *(const u32x4*)(p.DUt + (size_t)(hd * 64 + t) * 64 + cg8);
;     *(u32x4*)(IUs + t * LD + cg8) = *(const u32x4*)(p.IUt + (size_t)(hd * 64 + t) * 64 + cg8);
.LBB0_277:
	s_and_b32 s55, s54, 0x1c0
	v_or_b32_e32 v23, s55, v116
	v_lshlrev_b32_e32 v22, 2, v23
	global_load_dwordx4 v[34:37], v22, s[62:63] offset:16
	global_load_dwordx4 v[38:41], v22, s[62:63]
	global_load_dwordx4 v[54:57], v22, s[80:81] offset:16
	global_load_dwordx4 v[70:73], v22, s[80:81]
	global_load_dwordx4 v[46:49], v22, s[64:65] offset:16
	global_load_dwordx4 v[50:53], v22, s[66:67] offset:16
	global_load_dwordx4 v[66:69], v22, s[64:65]
	global_load_dwordx4 v[62:65], v22, s[66:67]
	global_load_dwordx4 v[42:45], v22, s[82:83] offset:16
	global_load_dwordx4 v[58:61], v22, s[82:83]
	v_add_lshl_u32 v192, s55, v240, 7
	v_mov_b32_e32 v193, 0
	v_lshl_add_u64 v[192:193], v[136:137], 0, v[192:193]
	global_load_dwordx4 v[192:195], v[192:193], off
	s_lshl_b32 s57, s54, 6
	s_ashr_i32 s56, s54, 9
	s_and_b32 s57, s57, 0xfc0
	v_add_u32_e32 v118, s57, v240
	s_ashr_i32 s57, s56, 31
	s_lshl_b64 s[56:57], s[56:57], 12
	v_lshl_add_u64 v[24:25], s[56:57], 0, v[118:119]
	v_mov_b64_e32 v[26:27], s[78:79]
	v_mad_u64_u32 v[156:157], s[56:57], v24, s53, v[26:27]
	v_mad_i32_i24 v157, v25, s53, v157
	v_cmp_ne_u32_e32 vcc, 0, v118
	v_lshlrev_b32_e32 v118, 1, v23
	v_mov_b32_e32 v78, 0
	v_mov_b32_e32 v79, 0
	v_mov_b32_e32 v80, 0
	v_mov_b32_e32 v81, 0
	s_barrier
	s_and_saveexec_b64 s[56:57], vcc
	s_cbranch_execz .LBB0_279
	v_lshl_add_u64 v[24:25], v[156:157], 0, v[118:119]
	global_load_dwordx4 v[78:81], v[24:25], off offset:-3328

; __device__ __forceinline__ unsigned pk2(float lo, float hi) { f32x2_t v = {lo, hi}; bf16x2_t b = __builtin_convertvector(v, bf16x2_t); return __builtin_bit_cast(unsigned, b); }
; __device__ __forceinline__ float bflo(unsigned v) { return __uint_as_float(v << 16); }
; __device__ __forceinline__ float bfhi(unsigned v) { return __uint_as_float(v & 0xffff0000u); }
; __device__ __forceinline__ float fexp(float x) { return __builtin_amdgcn_exp2f(x * 1.44269504088896f); }
; __device__ void rwkv_prep_item(const Params& p, char* lds_, int item, PrepRaw& raw, int next_item) {
;     ...
;     auto ldshift = [&](int col, float (&o)[8], const u32x4 cur) {
;       u32x4 prv; prv.x = prv.y = prv.z = prv.w = 0u;
;       if (hasprev) prv = *(const u32x4*)(prow - PBW + col);
;       const f32x4 m0 = *(const f32x4*)(p.shift_mu + col), m1 = *(const f32x4*)(p.shift_mu + col + 4);
;       const unsigned cw[4] = {cur.x, cur.y, cur.z, cur.w}, pw[4] = {prv.x, prv.y, prv.z, prv.w};
; #pragma unroll
;       for (int q = 0; q < 4; ++q) {
;         const float c0 = bflo(cw[q]), c1 = bfhi(cw[q]), p0 = bflo(pw[q]), p1 = bfhi(pw[q]);
;         const float mu0 = (q < 2) ? m0[2 * q] : m1[2 * q - 4], mu1 = (q < 2) ? m0[2 * q + 1] : m1[2 * q - 3];
;         o[2 * q] = c0 + (p0 - c0) * mu0;
;         o[2 * q + 1] = c1 + (p1 - c1) * mu1;
;       }
;     };
;     ldshift(hd * 64 + cg8, rr, raw.cur[0]);
;     ldshift(512 + hd * 64 + cg8, kk_, raw.cur[1]);
;     ldshift(1024 + hd * 64 + cg8, vv, raw.cur[2]);
;     float wd[8], ad[8];
;     ldshift(1536 + cg8, wd, raw.cur[3]);
;     ldshift(1600 + cg8, ad, raw.cur[4]);
;     u32x4 w;
;     float th[8];
; #pragma unroll
;     for (int e = 0; e < 8; ++e) th[e] = 1.f - 2.f * __builtin_amdgcn_rcpf(1.f + fexp(2.f * wd[e]));
;     w.x = pk2(th[0], th[1]); w.y = pk2(th[2], th[3]); w.z = pk2(th[4], th[5]); w.w = pk2(th[6], th[7]);
;     *(u32x4*)(TW + t * LD + cg8) = w;
;     w.x = pk2(ad[0], ad[1]); w.y = pk2(ad[2], ad[3]); w.z = pk2(ad[4], ad[5]); w.w = pk2(ad[6], ad[7]);
;     *(u32x4*)(AD + t * LD + cg8) = w;
;     *(u32x4*)(DUs + t * LD + cg8) = *(const u32x4*)(p.DUt + (size_t)(hd * 64 + t) * 64 + cg8);
;     *(u32x4*)(IUs + t * LD + cg8) = *(const u32x4*)(p.IUt + (size_t)(hd * 64 + t) * 64 + cg8);
.LBB0_291:
	s_or_b64 exec, exec, s[56:57]
	s_waitcnt vmcnt(19)
	v_lshlrev_b32_e32 v118, 16, v10
	v_and_b32_e32 v155, 0xffff0000, v10
	s_waitcnt vmcnt(2)
	v_lshlrev_b32_e32 v156, 16, v102
	v_and_b32_e32 v102, 0xffff0000, v102
	v_sub_f32_e32 v156, v156, v118
	v_sub_f32_e32 v102, v102, v155
	s_waitcnt vmcnt(0)
	v_fmac_f32_e32 v118, v110, v156
	v_fmac_f32_e32 v155, v111, v102
	v_lshlrev_b32_e32 v110, 16, v11
	v_lshlrev_b32_e32 v102, 16, v103
	v_and_b32_e32 v111, 0xffff0000, v11
	v_and_b32_e32 v103, 0xffff0000, v103
	v_sub_f32_e32 v102, v102, v110
	v_fmac_f32_e32 v110, v112, v102
	v_sub_f32_e32 v102, v103, v111
	v_fmac_f32_e32 v111, v113, v102
	v_lshlrev_b32_e32 v112, 16, v12
	v_lshlrev_b32_e32 v102, 16, v104
	v_and_b32_e32 v113, 0xffff0000, v12
	v_and_b32_e32 v103, 0xffff0000, v104
	v_sub_f32_e32 v102, v102, v112
	v_fmac_f32_e32 v112, v106, v102
	v_sub_f32_e32 v102, v103, v113
	v_fmac_f32_e32 v113, v107, v102
	v_and_b32_e32 v102, 0xffff0000, v105
	v_and_b32_e32 v156, 0xffff0000, v13
	v_sub_f32_e32 v102, v102, v156
	v_lshlrev_b32_e32 v103, 16, v105
	v_lshlrev_b32_e32 v157, 16, v13
	v_fmac_f32_e32 v156, v109, v102
	v_and_b32_e32 v104, 0xffff0000, v2
	v_lshlrev_b32_e32 v102, 16, v90
	v_and_b32_e32 v90, 0xffff0000, v90
	v_sub_f32_e32 v103, v103, v157
	v_lshlrev_b32_e32 v105, 16, v2
	v_sub_f32_e32 v90, v90, v104
	v_fmac_f32_e32 v157, v108, v103
	v_sub_f32_e32 v102, v102, v105
	v_fmac_f32_e32 v104, v99, v90
	v_lshlrev_b32_e32 v103, 16, v3
	v_lshlrev_b32_e32 v90, 16, v91
	v_fmac_f32_e32 v105, v98, v102
	v_and_b32_e32 v102, 0xffff0000, v3
	v_and_b32_e32 v91, 0xffff0000, v91
	v_sub_f32_e32 v90, v90, v103
	v_fmac_f32_e32 v103, v100, v90
	v_sub_f32_e32 v90, v91, v102
	v_fmac_f32_e32 v102, v101, v90
	v_lshlrev_b32_e32 v99, 16, v4
	v_lshlrev_b32_e32 v90, 16, v92
	v_and_b32_e32 v98, 0xffff0000, v4
	v_and_b32_e32 v91, 0xffff0000, v92
	v_sub_f32_e32 v90, v90, v99
	v_fmac_f32_e32 v99, v94, v90
	v_sub_f32_e32 v90, v91, v98
	v_fmac_f32_e32 v98, v95, v90
	v_and_b32_e32 v90, 0xffff0000, v93
	v_and_b32_e32 v92, 0xffff0000, v5
	v_lshlrev_b32_e32 v91, 16, v93
	v_lshlrev_b32_e32 v93, 16, v5
	v_sub_f32_e32 v90, v90, v92
	v_sub_f32_e32 v91, v91, v93
	v_fmac_f32_e32 v92, v97, v90
	v_and_b32_e32 v90, 0xffff0000, v6
	v_lshlrev_b32_e32 v94, 16, v78
	v_and_b32_e32 v78, 0xffff0000, v78
	v_fmac_f32_e32 v93, v96, v91
	v_lshlrev_b32_e32 v91, 16, v6
	v_sub_f32_e32 v78, v78, v90
	v_sub_f32_e32 v94, v94, v91
	v_fmac_f32_e32 v90, v87, v78
	v_lshlrev_b32_e32 v87, 16, v7
	v_lshlrev_b32_e32 v78, 16, v79
	v_fmac_f32_e32 v91, v86, v94
	v_and_b32_e32 v86, 0xffff0000, v7
	v_and_b32_e32 v79, 0xffff0000, v79
	v_sub_f32_e32 v78, v78, v87
	v_fmac_f32_e32 v87, v88, v78
	v_sub_f32_e32 v78, v79, v86
	v_fmac_f32_e32 v86, v89, v78
	v_lshlrev_b32_e32 v89, 16, v8
	v_lshlrev_b32_e32 v78, 16, v80
	v_and_b32_e32 v88, 0xffff0000, v8
	v_and_b32_e32 v79, 0xffff0000, v80
	v_sub_f32_e32 v78, v78, v89
	v_fmac_f32_e32 v89, v78, v82
	v_sub_f32_e32 v78, v79, v88
	v_fmac_f32_e32 v88, v78, v83
	v_and_b32_e32 v78, 0xffff0000, v81
	v_lshlrev_b32_e32 v79, 16, v81
	v_and_b32_e32 v82, 0xffff0000, v9
	v_lshlrev_b32_e32 v83, 16, v9
	v_sub_f32_e32 v79, v79, v83
	v_sub_f32_e32 v78, v78, v82
	v_fmac_f32_e32 v83, v79, v84
	v_fmac_f32_e32 v82, v78, v85
	global_load_dwordx4 v[78:81], v[132:133], off offset:16
	global_load_dwordx4 v[94:97], v[132:133], off
	v_add_f32_e32 v84, v118, v118
	v_add_f32_e32 v85, v155, v155
	v_add_f32_e32 v100, v110, v110
	v_add_f32_e32 v101, v111, v111
	v_add_f32_e32 v106, v112, v112
	v_add_f32_e32 v107, v113, v113
	v_add_f32_e32 v108, v157, v157
	v_add_f32_e32 v109, v156, v156
	v_mul_f32_e32 v84, 0x3fb8aa3b, v84
	v_mul_f32_e32 v85, 0x3fb8aa3b, v85
	v_mul_f32_e32 v100, 0x3fb8aa3b, v100
	v_mul_f32_e32 v101, 0x3fb8aa3b, v101
	v_mul_f32_e32 v106, 0x3fb8aa3b, v106
	v_mul_f32_e32 v107, 0x3fb8aa3b, v107
	v_mul_f32_e32 v108, 0x3fb8aa3b, v108
	v_mul_f32_e32 v109, 0x3fb8aa3b, v109
	v_exp_f32_e32 v84, v84
	v_exp_f32_e32 v85, v85
	v_exp_f32_e32 v100, v100
	v_exp_f32_e32 v101, v101
	v_exp_f32_e32 v106, v106
	v_exp_f32_e32 v107, v107
	v_exp_f32_e32 v108, v108
	v_exp_f32_e32 v109, v109
	v_lshlrev_b32_e32 v110, 16, v14
	v_and_b32_e32 v111, 0xffff0000, v14
	v_lshlrev_b32_e32 v112, 16, v74
	v_and_b32_e32 v113, 0xffff0000, v74
	v_pk_add_f32 v[112:113], v[112:113], v[110:111] neg_lo:[0,1] neg_hi:[0,1]
	v_add_f32_e32 v84, 1.0, v84
	v_add_f32_e32 v85, 1.0, v85
	v_add_f32_e32 v100, 1.0, v100
	v_add_f32_e32 v101, 1.0, v101
	v_add_f32_e32 v106, 1.0, v106
	v_add_f32_e32 v107, 1.0, v107
	v_add_f32_e32 v108, 1.0, v108
	v_add_f32_e32 v109, 1.0, v109
	v_lshlrev_b32_e32 v74, 16, v75
	v_and_b32_e32 v75, 0xffff0000, v75
	v_rcp_f32_e32 v84, v84
	v_rcp_f32_e32 v85, v85
	v_rcp_f32_e32 v100, v100
	v_rcp_f32_e32 v101, v101
	v_rcp_f32_e32 v106, v106
	v_rcp_f32_e32 v107, v107
	v_rcp_f32_e32 v108, v108
	v_rcp_f32_e32 v109, v109
	v_pk_fma_f32 v[84:85], v[84:85], 2.0, 1.0 op_sel_hi:[1,0,0] neg_lo:[1,0,0] neg_hi:[1,0,0]
	v_pk_fma_f32 v[100:101], v[100:101], 2.0, 1.0 op_sel_hi:[1,0,0] neg_lo:[1,0,0] neg_hi:[1,0,0]
	v_pk_fma_f32 v[106:107], v[106:107], 2.0, 1.0 op_sel_hi:[1,0,0] neg_lo:[1,0,0] neg_hi:[1,0,0]
	v_pk_fma_f32 v[108:109], v[108:109], 2.0, 1.0 op_sel_hi:[1,0,0] neg_lo:[1,0,0] neg_hi:[1,0,0]
	v_add_lshl_u32 v118, s55, v240, 7
	v_mul_f32_e32 v67, v67, v104
	v_mul_f32_e32 v66, v66, v105
	v_mul_f32_e32 v68, v68, v103
	v_mul_f32_e32 v69, v69, v102
	s_add_i32 s90, s54, s50
	s_waitcnt vmcnt(0)
	v_pk_fma_f32 v[94:95], v[94:95], v[112:113], v[110:111]
	v_lshlrev_b32_e32 v110, 16, v15
	v_and_b32_e32 v111, 0xffff0000, v15
	v_pk_add_f32 v[74:75], v[74:75], v[110:111] neg_lo:[0,1] neg_hi:[0,1]
	s_nop 0
	v_pk_fma_f32 v[96:97], v[96:97], v[74:75], v[110:111]
	v_lshlrev_b32_e32 v74, 16, v16
	v_and_b32_e32 v75, 0xffff0000, v16
	v_lshlrev_b32_e32 v110, 16, v76
	v_and_b32_e32 v111, 0xffff0000, v76
	v_pk_add_f32 v[110:111], v[110:111], v[74:75] neg_lo:[0,1] neg_hi:[0,1]
	v_lshlrev_b32_e32 v76, 16, v17
	v_pk_fma_f32 v[78:79], v[78:79], v[110:111], v[74:75]
	v_lshlrev_b32_e32 v74, 16, v77
	v_and_b32_e32 v75, 0xffff0000, v77
	v_and_b32_e32 v77, 0xffff0000, v17
	v_pk_add_f32 v[74:75], v[74:75], v[76:77] neg_lo:[0,1] neg_hi:[0,1]
	s_nop 0
	v_pk_fma_f32 v[80:81], v[80:81], v[74:75], v[76:77]
	v_cvt_pk_bf16_f32 v74, v84, v85
	v_cvt_pk_bf16_f32 v75, v100, v101
	v_cvt_pk_bf16_f32 v76, v106, v107
	v_cvt_pk_bf16_f32 v77, v108, v109
	ds_write_b128 v117, v[74:77]
	v_cvt_pk_bf16_f32 v74, v94, v95
	v_cvt_pk_bf16_f32 v75, v96, v97
	v_cvt_pk_bf16_f32 v76, v78, v79
	v_cvt_pk_bf16_f32 v77, v80, v81
	ds_write_b128 v159, v[74:77]
	v_lshl_add_u64 v[74:75], v[134:135], 0, v[118:119]
	global_load_dwordx4 v[74:77], v[74:75], off
	v_mul_f32_e32 v85, v67, v67
	v_fmac_f32_e32 v85, v66, v66
	v_fmac_f32_e32 v85, v68, v68
	v_fmac_f32_e32 v85, v69, v69
	s_waitcnt vmcnt(0)
	ds_write_b128 v160, v[74:77]
	ds_write_b128 v161, v[192:195]
	s_waitcnt lgkmcnt(0)
	s_barrier
; __device__ __forceinline__ float fsigmoid(float x) { return __builtin_amdgcn_rcpf(1.f + fexp(-x)); }
; __device__ void rwkv_prep_item(const Params& p, char* lds_, int item, PrepRaw& raw, int next_item) {
;     ...
;   {
;     f32x4 a1[2], a2[2]; zero2(a1); zero2(a2);
;     mm_nt(TW, DUs, a1, wave, lane);
;     mm_nt(AD, IUs, a2, wave, lane);
; #pragma unroll
;     for (int jj = 0; jj < 2; ++jj) {
;       *(f32x4*)(Zw + mi * 68 + (jt0 + jj) * 16 + 4 * mg) = a1[jj];
;       *(f32x4*)(Za + mi * 68 + (jt0 + jj) * 16 + 4 * mg) = a2[jj];
;     }
;   }
;   __syncthreads();
;   float av[8], bv[8], k2[8], lw[8];
;   float bon;
;   {
;     float ss = 0.f; bon = 0.f;
;     float kk[8], ai[8];
; #pragma unroll
;     for (int e = 0; e < 8; ++e) {
;       const float zw = Zw[t * 68 + cg8 + e] + pdb[e >> 2][e & 3];
;       const float za = Za[t * 68 + cg8 + e] + pib[e >> 2][e & 3];
;       lw[e] = -0.6065306597126334f * fsigmoid(zw);
;       ai[e] = fsigmoid(za);
;       kk[e] = kk_[e] * pkk[e >> 2][e & 3];
;       k2[e] = kk_[e] * (1.f + (ai[e] - 1.f) * pka[e >> 2][e & 3]);
;       ss += kk[e] * kk[e];
;       bon += rr[e] * k2[e] * prk[e >> 2][e & 3];
;     }
;     ss += __shfl_xor(ss, 1); ss += __shfl_xor(ss, 2); ss += __shfl_xor(ss, 4);
;     bon += __shfl_xor(bon, 1); bon += __shfl_xor(bon, 2); bon += __shfl_xor(bon, 4);
;     const float inv = __builtin_amdgcn_rsqf(fmaxf(ss, 1e-24f));
; #pragma unroll
;     for (int e = 0; e < 8; ++e) { const float kn = kk[e] * inv; av[e] = -kn; bv[e] = kn * ai[e]; }
;   }
;   __builtin_amdgcn_sched_barrier(0);
;   if (next_item < 4096) prep_load(p, next_item, raw);
	ds_read_b128 v[74:77], v162
	ds_read_b128 v[78:81], v163
	ds_read_b128 v[94:97], v163 offset:2304
	s_waitcnt lgkmcnt(1)
	v_mfma_f32_16x16x32_bf16 v[78:81], v[78:81], v[74:77], 0
	s_waitcnt lgkmcnt(0)
	v_mfma_f32_16x16x32_bf16 v[74:77], v[94:97], v[74:77], 0
	ds_read_b128 v[94:97], v162 offset:64
	ds_read_b128 v[106:109], v164
	s_waitcnt lgkmcnt(0)
	v_mfma_f32_16x16x32_bf16 v[78:81], v[106:109], v[94:97], v[78:81]
	ds_read_b128 v[106:109], v165 offset:2304
	s_waitcnt lgkmcnt(0)
	v_mfma_f32_16x16x32_bf16 v[74:77], v[106:109], v[94:97], v[74:77]
	ds_read_b128 v[94:97], v166
	ds_read_b128 v[106:109], v167
	ds_read_b128 v[110:113], v167 offset:2304
	s_waitcnt lgkmcnt(1)
	v_mfma_f32_16x16x32_bf16 v[106:109], v[106:109], v[94:97], 0
	s_waitcnt lgkmcnt(0)
	v_mfma_f32_16x16x32_bf16 v[94:97], v[110:113], v[94:97], 0
	ds_read_b128 v[110:113], v166 offset:64
	ds_read_b128 v[192:195], v168
	s_waitcnt lgkmcnt(0)
	v_mfma_f32_16x16x32_bf16 v[106:109], v[192:195], v[110:113], v[106:109]
	ds_read_b128 v[192:195], v169 offset:2304
	s_waitcnt lgkmcnt(0)
	v_mfma_f32_16x16x32_bf16 v[94:97], v[192:195], v[110:113], v[94:97]
	ds_write_b128 v170, v[78:81]
	s_nop 3
	ds_write_b128 v171, v[106:109]
	ds_write_b128 v170, v[74:77] offset:64
	s_nop 0
	ds_write_b128 v171, v[94:97] offset:64
	s_waitcnt lgkmcnt(0)
	s_barrier
	ds_read_b128 v[74:77], v172
	ds_read_b128 v[78:81], v173
	s_waitcnt lgkmcnt(0)
	v_add_f32_e32 v70, v70, v78
	v_mul_f32_e32 v70, 0xbfb8aa3b, v70
	v_exp_f32_e32 v70, v70
	s_nop 0
	v_add_f32_e32 v70, 1.0, v70
	v_rcp_f32_e32 v70, v70
	s_nop 0
	v_add_f32_e32 v78, -1.0, v70
	v_fma_f32 v62, v62, v78, 1.0
	v_mul_f32_e32 v62, v105, v62
	v_mul_f32_e32 v78, v91, v62
	v_fma_f32 v84, v58, v78, 0
	v_add_f32_e32 v58, v71, v79
	v_mul_f32_e32 v58, 0xbfb8aa3b, v58
	v_exp_f32_e32 v58, v58
	s_nop 0
	v_add_f32_e32 v58, 1.0, v58
	v_rcp_f32_e32 v71, v58
	s_nop 0
	v_add_f32_e32 v58, -1.0, v71
	v_fma_f32 v58, v63, v58, 1.0
	v_mul_f32_e32 v63, v104, v58
	v_mul_f32_e32 v58, v90, v63
	v_fmac_f32_e32 v84, v59, v58
	v_add_f32_e32 v58, v72, v80
	v_mul_f32_e32 v58, 0xbfb8aa3b, v58
	v_exp_f32_e32 v58, v58
	s_nop 0
	v_add_f32_e32 v58, 1.0, v58
	v_rcp_f32_e32 v72, v58
	s_nop 0
	v_add_f32_e32 v58, -1.0, v72
	v_fma_f32 v58, v64, v58, 1.0
	v_mul_f32_e32 v64, v103, v58
	v_mul_f32_e32 v58, v87, v64
	v_fmac_f32_e32 v84, v60, v58
	v_add_f32_e32 v58, v73, v81
	v_mul_f32_e32 v58, 0xbfb8aa3b, v58
	v_exp_f32_e32 v58, v58
	s_nop 0
	v_add_f32_e32 v58, 1.0, v58
	v_rcp_f32_e32 v73, v58
	s_nop 0
	v_add_f32_e32 v58, -1.0, v73
	v_fma_f32 v58, v65, v58, 1.0
	v_mul_f32_e32 v65, v102, v58
	v_mul_f32_e32 v58, v86, v65
	v_fmac_f32_e32 v84, v61, v58
	ds_read_b128 v[58:61], v176
	ds_read_b128 v[78:81], v177
	s_waitcnt lgkmcnt(0)
	v_add_f32_e32 v54, v54, v78
	v_mul_f32_e32 v54, 0xbfb8aa3b, v54
	v_exp_f32_e32 v54, v54
	v_mul_f32_e32 v78, v46, v99
	v_fmac_f32_e32 v85, v78, v78
	v_add_f32_e32 v54, 1.0, v54
	v_rcp_f32_e32 v54, v54
	s_nop 0
	v_add_f32_e32 v46, -1.0, v54
	v_fma_f32 v46, v50, v46, 1.0
	v_mul_f32_e32 v46, v99, v46
	v_mul_f32_e32 v50, v89, v46
	v_fmac_f32_e32 v84, v42, v50
	v_add_f32_e32 v42, v55, v79
	v_mul_f32_e32 v42, 0xbfb8aa3b, v42
	v_exp_f32_e32 v42, v42
	v_mul_f32_e32 v55, v47, v98
	v_fmac_f32_e32 v85, v55, v55
	v_mul_f32_e32 v79, v49, v92
	v_add_f32_e32 v42, 1.0, v42
	v_rcp_f32_e32 v50, v42
	s_nop 0
	v_add_f32_e32 v42, -1.0, v50
	v_fma_f32 v42, v51, v42, 1.0
	v_mul_f32_e32 v47, v98, v42
	v_mul_f32_e32 v42, v88, v47
	v_fmac_f32_e32 v84, v43, v42
	v_add_f32_e32 v42, v56, v80
	v_mul_f32_e32 v42, 0xbfb8aa3b, v42
	v_exp_f32_e32 v42, v42
	v_mul_f32_e32 v56, v48, v93
	v_fmac_f32_e32 v85, v56, v56
	v_fmac_f32_e32 v85, v79, v79
	v_add_f32_e32 v42, 1.0, v42
	v_rcp_f32_e32 v51, v42
	s_nop 0
	v_add_f32_e32 v42, -1.0, v51
	v_fma_f32 v42, v52, v42, 1.0
	v_mul_f32_e32 v52, v93, v42
	v_mul_f32_e32 v42, v83, v52
	v_fmac_f32_e32 v84, v44, v42
	v_add_f32_e32 v42, v57, v81
	v_mul_f32_e32 v42, 0xbfb8aa3b, v42
	v_exp_f32_e32 v42, v42
	s_nop 0
	v_add_f32_e32 v42, 1.0, v42
	v_rcp_f32_e32 v57, v42
	s_nop 0
	v_add_f32_e32 v42, -1.0, v57
	v_fma_f32 v42, v53, v42, 1.0
	v_mul_f32_e32 v53, v92, v42
	v_mul_f32_e32 v42, v82, v53
	v_fmac_f32_e32 v84, v45, v42
	ds_bpermute_b32 v42, v178, v85
	s_waitcnt lgkmcnt(0)
	v_add_f32_e32 v42, v85, v42
	ds_bpermute_b32 v43, v179, v42
	s_waitcnt lgkmcnt(0)
	v_add_f32_e32 v80, v42, v43
	ds_bpermute_b32 v42, v178, v84
	ds_bpermute_b32 v81, v180, v80
	s_waitcnt lgkmcnt(1)
	v_add_f32_e32 v42, v84, v42
	ds_bpermute_b32 v43, v179, v42
	s_waitcnt lgkmcnt(0)
	v_add_f32_e32 v48, v42, v43
	ds_bpermute_b32 v49, v180, v48
	s_cmpk_gt_i32 s90, 0xfff
	s_cselect_b64 s[56:57], -1, 0
	v_mov_b64_e32 v[44:45], v[20:21]
	s_and_b64 vcc, exec, s[56:57]
	v_mov_b64_e32 v[42:43], v[18:19]
	s_cbranch_vccnz .LBB0_293
	s_ashr_i32 s58, s90, 9
	s_lshl_b32 s74, s90, 6
	s_ashr_i32 s59, s58, 31
	s_and_b32 s74, s74, 0xfc0
	s_lshl_b64 s[58:59], s[58:59], 12
	v_add_u32_e32 v118, s74, v240
	v_lshl_add_u64 v[2:3], s[58:59], 0, v[118:119]
	v_mov_b64_e32 v[4:5], s[78:79]
	s_and_b32 s55, s90, 0x1c0
	v_mad_u64_u32 v[10:11], s[58:59], v2, s53, v[4:5]
	v_mad_i32_i24 v11, v3, s53, v11
	s_lshl_b32 s74, s55, 1
	v_lshl_add_u64 v[2:3], v[10:11], 0, s[74:75]
	v_mov_b32_e32 v155, v119
	v_lshl_add_u64 v[12:13], v[2:3], 0, v[154:155]
	v_lshl_add_u64 v[14:15], v[10:11], 0, v[154:155]
	global_load_dwordx4 v[6:9], v[12:13], off
	global_load_dwordx4 v[2:5], v[12:13], off offset:1024
	global_load_dwordx4 v[42:45], v[12:13], off offset:2048
	s_nop 0
	global_load_dwordx4 v[10:13], v[14:15], off offset:3072
	s_nop 0
	global_load_dwordx4 v[14:17], v[14:15], off offset:3200

; __device__ __forceinline__ float fexp(float x) { return __builtin_amdgcn_exp2f(x * 1.44269504088896f); }
; __device__ void rwkv_prep_item(const Params& p, char* lds_, int item, PrepRaw& raw, int next_item) {
;     ...
;   {
;     const int d = tid & 63, seg = tid >> 6;
;     float pre = 0.f;
;     for (int q = 0; q < seg; ++q) pre += Za[q * 64 + d];
; #pragma unroll
;     for (int q = 0; q < 8; ++q) { pre += G[(seg * 8 + q) * 68 + d]; G[(seg * 8 + q) * 68 + d] = pre; }
;   }
;   __syncthreads();
;   {
;     float a_[8], b_[8], k_[8], r_[8];
; #pragma unroll
;     for (int e = 0; e < 8; ++e) {
;       const float g = G[t * 68 + cg8 + e];
;       const float eg = fexp(g), egm = fexp(g - lw[e]), ei = fexp(-g);
;       a_[e] = av[e] * egm; b_[e] = bv[e] * ei; k_[e] = k2[e] * ei; r_[e] = rr[e] * eg;
;       if (t == 63) gC[cg8 + e] = eg;
.LBB0_303:
	s_or_b64 exec, exec, s[58:59]
	ds_read2_b32 v[60:61], v252 offset1:68
	ds_read2_b32 v[74:75], v252 offset0:136 offset1:204
	ds_read2_b32 v[76:77], v58 offset0:16 offset1:84
	ds_read2_b32 v[84:85], v58 offset0:152 offset1:220
	s_waitcnt lgkmcnt(3)
	v_add_f32_e32 v59, v59, v60
	v_add_f32_e32 v60, v59, v61
	ds_write2_b32 v252, v59, v60 offset1:68
	s_waitcnt lgkmcnt(3)
	v_add_f32_e32 v59, v60, v74
	v_add_f32_e32 v60, v59, v75
	ds_write2_b32 v252, v59, v60 offset0:136 offset1:204
	s_waitcnt lgkmcnt(3)
	v_add_f32_e32 v59, v60, v76
	v_add_f32_e32 v60, v59, v77
	ds_write2_b32 v58, v59, v60 offset0:16 offset1:84
	s_waitcnt lgkmcnt(3)
	v_add_f32_e32 v59, v60, v84
	v_add_f32_e32 v60, v59, v85
	ds_write2_b32 v58, v59, v60 offset0:152 offset1:220
	s_waitcnt lgkmcnt(0)
	s_barrier
	ds_read_b32 v61, v181
	ds_read_b32 v60, v181 offset:4
	ds_read_b32 v77, v181 offset:8
	ds_read_b32 v76, v181 offset:12
	ds_read_b32 v93, v181 offset:16
	ds_read_b32 v92, v181 offset:20
	ds_read_b32 v97, v181 offset:24
	ds_read_b32 v96, v181 offset:28
	s_waitcnt lgkmcnt(7)
	v_mul_f32_e32 v58, 0x3fb8aa3b, v61
	v_exp_f32_e32 v59, v58
	s_waitcnt lgkmcnt(6)
	v_mul_f32_e32 v58, 0x3fb8aa3b, v60
	v_exp_f32_e32 v58, v58
	s_waitcnt lgkmcnt(5)
	v_mul_f32_e32 v74, 0x3fb8aa3b, v77
	v_exp_f32_e32 v75, v74
	s_waitcnt lgkmcnt(4)
	v_mul_f32_e32 v74, 0x3fb8aa3b, v76
	v_exp_f32_e32 v74, v74
	s_waitcnt lgkmcnt(3)
	v_mul_f32_e32 v84, 0x3fb8aa3b, v93
	v_exp_f32_e32 v85, v84
	s_waitcnt lgkmcnt(2)
	v_mul_f32_e32 v84, 0x3fb8aa3b, v92
	v_exp_f32_e32 v84, v84
	s_waitcnt lgkmcnt(1)
	v_mul_f32_e32 v94, 0x3fb8aa3b, v97
	v_exp_f32_e32 v95, v94
	s_waitcnt lgkmcnt(0)
	v_mul_f32_e32 v94, 0x3fb8aa3b, v96
	v_exp_f32_e32 v94, v94
	s_and_saveexec_b64 s[58:59], s[8:9]
	ds_write_b32 v183, v59
	ds_write_b32 v183, v58 offset:4
	ds_write_b32 v183, v75 offset:8
	ds_write_b32 v183, v74 offset:12
	ds_write_b32 v183, v85 offset:16
	ds_write_b32 v183, v84 offset:20
	ds_write_b32 v183, v95 offset:24
	ds_write_b32 v183, v94 offset:28
	s_or_b64 exec, exec, s[58:59]
	v_lshlrev_b32_e32 v98, 16, v18
	v_and_b32_e32 v99, 0xffff0000, v18
	v_lshlrev_b32_e32 v100, 16, v22
	v_and_b32_e32 v101, 0xffff0000, v22
	v_lshlrev_b32_e32 v18, 16, v19
	v_and_b32_e32 v19, 0xffff0000, v19
	v_lshlrev_b32_e32 v22, 16, v23
	v_and_b32_e32 v23, 0xffff0000, v23
	v_pk_add_f32 v[22:23], v[22:23], v[18:19] neg_lo:[0,1] neg_hi:[0,1]
	v_pk_add_f32 v[100:101], v[100:101], v[98:99] neg_lo:[0,1] neg_hi:[0,1]
	v_pk_fma_f32 v[18:19], v[32:33], v[22:23], v[18:19]
	v_lshlrev_b32_e32 v22, 16, v20
	v_and_b32_e32 v23, 0xffff0000, v20
	v_lshlrev_b32_e32 v32, 16, v24
	v_and_b32_e32 v33, 0xffff0000, v24
	v_lshlrev_b32_e32 v24, 16, v25
	v_and_b32_e32 v25, 0xffff0000, v25
	v_lshlrev_b32_e32 v20, 16, v21
	v_and_b32_e32 v21, 0xffff0000, v21
	v_pk_add_f32 v[32:33], v[32:33], v[22:23] neg_lo:[0,1] neg_hi:[0,1]
	v_pk_add_f32 v[24:25], v[24:25], v[20:21] neg_lo:[0,1] neg_hi:[0,1]
	v_pk_fma_f32 v[30:31], v[30:31], v[100:101], v[98:99]
	v_pk_fma_f32 v[22:23], v[26:27], v[32:33], v[22:23]
	v_pk_fma_f32 v[20:21], v[28:29], v[24:25], v[20:21]
	s_and_b64 vcc, exec, s[76:77]
	s_cbranch_vccz .LBB0_321
; __device__ __forceinline__ unsigned pk2(float lo, float hi) { f32x2_t v = {lo, hi}; bf16x2_t b = __builtin_convertvector(v, bf16x2_t); return __builtin_bit_cast(unsigned, b); }
; __device__ __forceinline__ float fexp(float x) { return __builtin_amdgcn_exp2f(x * 1.44269504088896f); }
; __device__ void rwkv_prep_item(const Params& p, char* lds_, int item, PrepRaw& raw, int next_item) {
;     ...
;     const float inv = __builtin_amdgcn_rsqf(fmaxf(ss, 1e-24f));
; #pragma unroll
;     for (int e = 0; e < 8; ++e) { const float kn = kk[e] * inv; av[e] = -kn; bv[e] = kn * ai[e]; }
;   }
;   __builtin_amdgcn_sched_barrier(0);
;   if (next_item < 4096) prep_load(p, next_item, raw);
;   __builtin_amdgcn_sched_barrier(0);
;   __syncthreads();
; #pragma unroll
;   for (int e = 0; e < 8; ++e) G[t * 68 + cg8 + e] = lw[e];
;   __syncthreads();
;   {
;     const int d = tid & 63, seg = tid >> 6;
;     float s = 0.f;
; #pragma unroll
;     for (int q = 0; q < 8; ++q) s += G[(seg * 8 + q) * 68 + d];
;     Za[seg * 64 + d] = s;
;   }
;   __syncthreads();
;   {
;     const int d = tid & 63, seg = tid >> 6;
;     float pre = 0.f;
;     for (int q = 0; q < seg; ++q) pre += Za[q * 64 + d];
; #pragma unroll
;     for (int q = 0; q < 8; ++q) { pre += G[(seg * 8 + q) * 68 + d]; G[(seg * 8 + q) * 68 + d] = pre; }
;   }
;   __syncthreads();
;   {
;     float a_[8], b_[8], k_[8], r_[8];
; #pragma unroll
;     for (int e = 0; e < 8; ++e) {
;       const float g = G[t * 68 + cg8 + e];
;       const float eg = fexp(g), egm = fexp(g - lw[e]), ei = fexp(-g);
;       a_[e] = av[e] * egm; b_[e] = bv[e] * ei; k_[e] = k2[e] * ei; r_[e] = rr[e] * eg;
;       if (t == 63) gC[cg8 + e] = eg;
;     }
;     auto put = [&](u16* rowm, u16* trans, const float (&f)[8]) {
;       const unsigned wv[4] = {pk2(f[0], f[1]), pk2(f[2], f[3]), pk2(f[4], f[5]), pk2(f[6], f[7])};
;       if (rowm) { u32x4 w4; w4.x = wv[0]; w4.y = wv[1]; w4.z = wv[2]; w4.w = wv[3]; *(u32x4*)(rowm + t * LD + cg8) = w4; }
;       if (trans) {
; #pragma unroll
;         for (int e = 0; e < 8; ++e) trans[(cg8 + e) * LD + (((t >> 3) ^ (cg8 >> 3)) << 3) + (t & 7)] = (u16)((e & 1) ? (wv[e >> 1] >> 16) : (wv[e >> 1] & 0xffffu));
;       }
;     };
;     put(At, AT, a_); put(Bt, BT, b_); put(Kt, KT, k_); put(Rt, nullptr, r_); put(nullptr, VT, vv);
	v_add_f32_e32 v24, v80, v81
	v_max_f32_e32 v24, 0x179abe15, v24
	v_rsq_f32_e32 v24, v24
	v_sub_f32_e32 v25, v97, v40
	v_mul_f32_e32 v26, 0xbfb8aa3b, v97
	v_mul_f32_e32 v25, 0x3fb8aa3b, v25
	v_exp_f32_e32 v26, v26
	v_exp_f32_e32 v25, v25
	v_mul_f32_e32 v27, v56, v24
	v_mul_f32_e32 v28, v51, v27
	v_mul_f32_e32 v28, v28, v26
	v_mul_f32_e32 v29, v52, v26
	v_sub_f32_e32 v26, v96, v41
	v_mul_f32_e64 v25, v25, -v27
	v_mul_f32_e32 v26, 0x3fb8aa3b, v26
	v_mul_f32_e32 v27, 0xbfb8aa3b, v96
	v_exp_f32_e32 v26, v26
	v_exp_f32_e32 v27, v27
	v_mul_f32_e32 v33, v79, v24
	v_mul_f32_e32 v40, v57, v33
	v_mul_f32_e64 v26, v26, -v33
	v_mul_f32_e32 v33, v40, v27
	v_mul_f32_e32 v40, v53, v27
	v_sub_f32_e32 v27, v93, v38
	v_mul_f32_e32 v27, 0x3fb8aa3b, v27
	v_exp_f32_e32 v27, v27
	v_mul_f32_e32 v51, v78, v24
	v_mul_f32_e32 v52, v54, v51
	v_mul_f32_e32 v53, v55, v24
	v_mul_f32_e64 v51, v27, -v51
	v_sub_f32_e32 v27, v92, v39
	v_mul_f32_e32 v27, 0x3fb8aa3b, v27
	v_exp_f32_e32 v27, v27
	v_mul_f32_e32 v50, v50, v53
	v_mul_f32_e32 v54, v68, v24
	v_mul_f32_e32 v55, v72, v54
	v_mul_f32_e64 v53, v27, -v53
	v_sub_f32_e32 v27, v77, v36
	v_mul_f32_e32 v27, 0x3fb8aa3b, v27
	v_exp_f32_e32 v27, v27
	v_mul_f32_e32 v36, 0xbfb8aa3b, v77
	v_exp_f32_e32 v36, v36
	v_mul_f32_e32 v57, v69, v24
	v_mul_f32_e64 v54, v27, -v54
	v_sub_f32_e32 v27, v76, v37
	v_mul_f32_e32 v27, 0x3fb8aa3b, v27
	v_exp_f32_e32 v27, v27
	v_mul_f32_e32 v55, v55, v36
	v_mul_f32_e32 v36, v64, v36
	v_mul_f32_e32 v64, v73, v57
	v_mul_f32_e64 v57, v27, -v57
	v_sub_f32_e32 v27, v61, v34
	v_mul_f32_e32 v27, 0x3fb8aa3b, v27
	v_exp_f32_e32 v27, v27
	v_mul_f32_e32 v34, 0xbfb8aa3b, v61
	v_mul_f32_e32 v61, v66, v24
	v_mul_f32_e32 v66, v70, v61
	v_mul_f32_e64 v61, v27, -v61
	v_sub_f32_e32 v27, v60, v35
	v_mul_f32_e32 v27, 0x3fb8aa3b, v27
	v_mul_f32_e32 v38, 0xbfb8aa3b, v93
	v_mul_f32_e32 v39, 0xbfb8aa3b, v92
	v_mul_f32_e32 v37, 0xbfb8aa3b, v76
	v_exp_f32_e32 v27, v27
	v_mul_f32_e32 v35, 0xbfb8aa3b, v60
	v_exp_f32_e32 v38, v38
	v_exp_f32_e32 v39, v39
	v_exp_f32_e32 v37, v37
	v_exp_f32_e32 v34, v34
	v_exp_f32_e32 v35, v35
	v_mul_f32_e32 v24, v67, v24
	v_mul_f32_e32 v60, v71, v24
	v_mul_f32_e64 v24, v27, -v24
	v_mul_f32_e32 v52, v52, v38
	v_mul_f32_e32 v50, v50, v39
	v_mul_f32_e32 v64, v64, v37
	v_mul_f32_e32 v66, v66, v34
	v_mul_f32_e32 v60, v60, v35
	v_cvt_pk_bf16_f32 v27, v25, v26
	v_cvt_pk_bf16_f32 v26, v51, v53
	v_cvt_pk_bf16_f32 v25, v54, v57
	v_cvt_pk_bf16_f32 v24, v61, v24
	v_mul_f32_e32 v38, v46, v38
	v_mul_f32_e32 v39, v47, v39
	v_mul_f32_e32 v37, v65, v37
	v_mul_f32_e32 v34, v62, v34
	v_mul_f32_e32 v35, v63, v35
	ds_write_b128 v184, v[24:27] offset:256
	ds_write_b16 v185, v24 offset:37120
	ds_write_b16_d16_hi v185, v24 offset:37264
	ds_write_b16 v185, v25 offset:37408
	ds_write_b16_d16_hi v185, v25 offset:37552
	ds_write_b16 v185, v26 offset:37696
	ds_write_b16_d16_hi v185, v26 offset:37840
	ds_write_b16 v185, v27 offset:37984
	ds_write_b16_d16_hi v185, v27 offset:38128
	v_cvt_pk_bf16_f32 v24, v66, v60
	v_cvt_pk_bf16_f32 v25, v55, v64
	v_cvt_pk_bf16_f32 v26, v52, v50
	v_cvt_pk_bf16_f32 v27, v28, v33
	v_mul_f32_e32 v32, v83, v95
	v_mul_f32_e32 v41, v82, v94
	v_mul_f32_e32 v46, v89, v85
	v_mul_f32_e32 v47, v88, v84
	v_mul_f32_e32 v56, v87, v75
	v_mul_f32_e32 v65, v86, v74
	v_mul_f32_e32 v59, v91, v59
	v_mul_f32_e32 v58, v90, v58
	ds_write_b128 v184, v[24:27] offset:9472
	ds_write_b16 v185, v24 offset:46336
	ds_write_b16_d16_hi v185, v24 offset:46480
	ds_write_b16 v185, v25 offset:46624
	ds_write_b16_d16_hi v185, v25 offset:46768
	ds_write_b16 v185, v26 offset:46912
	ds_write_b16_d16_hi v185, v26 offset:47056
	ds_write_b16 v185, v27 offset:47200
	ds_write_b16_d16_hi v185, v27 offset:47344
	v_cvt_pk_bf16_f32 v27, v29, v40
	v_cvt_pk_bf16_f32 v26, v38, v39
	v_cvt_pk_bf16_f32 v25, v36, v37
	v_cvt_pk_bf16_f32 v24, v34, v35
	ds_write_b128 v184, v[24:27] offset:18688
	ds_write_b16 v185, v24 offset:55552
	ds_write_b16_d16_hi v185, v24 offset:55696
	ds_write_b16 v185, v25 offset:55840
	ds_write_b16_d16_hi v185, v25 offset:55984
	ds_write_b16 v185, v26 offset:56128
	ds_write_b16_d16_hi v185, v26 offset:56272
	ds_write_b16 v185, v27 offset:56416
	ds_write_b16_d16_hi v185, v27 offset:56560
	v_cvt_pk_bf16_f32 v24, v59, v58
	v_cvt_pk_bf16_f32 v25, v56, v65
	v_cvt_pk_bf16_f32 v26, v46, v47
	v_cvt_pk_bf16_f32 v27, v32, v41
	ds_write_b128 v184, v[24:27] offset:27904
	v_cvt_pk_bf16_f32 v27, v30, v31
	v_cvt_pk_bf16_f32 v24, v20, v21
	v_cvt_pk_bf16_f32 v25, v22, v23
	v_cvt_pk_bf16_f32 v26, v18, v19
	ds_write_b16 v185, v27 offset:64768
	ds_write_b16_d16_hi v185, v27 offset:64912
	ds_write_b16 v185, v26 offset:65056
	ds_write_b16_d16_hi v185, v26 offset:65200
	ds_write_b16 v185, v25 offset:65344
	ds_write_b16_d16_hi v185, v25 offset:65488
	ds_write_b16 v186, v24 offset:864
	ds_write_b16_d16_hi v186, v24 offset:1008

; __device__ __forceinline__ float bflo(unsigned v) { return __uint_as_float(v << 16); }
; __device__ __forceinline__ float bfhi(unsigned v) { return __uint_as_float(v & 0xffff0000u); }
; __device__ void phase_rwkv_out(const Params& p, int bid, int nb) {
;     ...
;   for (int it2 = bid; it2 < 2048; it2 += nb) {
;     const int item = it2 * 2 + (wave >> 2);
;     const int b = item >> 9, hd = (item >> 6) & 7, c = item & 63;
;     const int tl = wq * 16 + r;
;     const u16* ryp = p.Ry + (size_t)item * 4096 + tl * 64;
;     const u16* hsp = p.Hs + (size_t)item * 4096;
;     f32x4 acc[4];
; #pragma unroll
;     for (int jt = 0; jt < 4; ++jt) { const u32x2 yw = *(const u32x2*)(p.Y0 + (size_t)item * 4096 + tl * 64 + jt * 16 + 4 * g); acc[jt][0] = bflo(yw.x); acc[jt][1] = bfhi(yw.x); acc[jt][2] = bflo(yw.y); acc[jt][3] = bfhi(yw.y); }
; #pragma unroll
;     for (int ks = 0; ks < 2; ++ks) {
;       const bf16x8 bfr = *(const bf16x8*)(ryp + ks * 32 + g * 8);
; #pragma unroll
;       for (int jt = 0; jt < 4; ++jt) {
;         const bf16x8 afr = *(const bf16x8*)(hsp + (jt * 16 + r) * 64 + ks * 32 + g * 8);
;     ...
;         acc[jt] = __builtin_amdgcn_mfma_f32_16x16x32_bf16(afr, bfr, acc[jt], 0, 0, 0);
;     ...
;       }
;     }
;     ...
; #pragma unroll
;     for (int jt = 0; jt < 4; ++jt) {
;       const int v = jt * 16 + 4 * g, cc = hd * 64 + v;
;       const f32x4 gg = *(const f32x4*)(p.gn_gain + cc), gb = *(const f32x4*)(p.gn_bias + cc);
;       const u32x2 bvw = *(const u32x2*)(p.BV + (size_t)item * 4096 + tl * 64 + v);
;       const u32x2 gw = *(const u32x2*)(p.GB + tok * 512 + cc);
.LBB0_498:
	v_ashrrev_i32_e32 v15, 31, v14
	v_ashrrev_i32_e32 v22, 9, v14
	v_and_or_b32 v4, v14, s15, v114
	v_lshlrev_b64 v[36:37], 13, v[14:15]
	v_ashrrev_i32_e32 v23, 31, v22
	v_lshlrev_b32_e32 v15, 2, v4
	v_lshl_add_u64 v[38:39], v[6:7], 0, v[36:37]
	v_lshl_add_u64 v[44:45], v[8:9], 0, v[36:37]
	v_lshl_add_u64 v[46:47], v[10:11], 0, v[36:37]
	v_lshlrev_b64 v[76:77], 12, v[22:23]
	s_waitcnt lgkmcnt(0)
	global_load_dwordx4 v[28:31], v15, s[4:5]
	global_load_dwordx4 v[32:35], v15, s[6:7]
	v_lshl_add_u64 v[22:23], v[12:13], 0, v[36:37]
	global_load_dwordx2 v[78:79], v[38:39], off
	global_load_dwordx2 v[82:83], v[38:39], off offset:32
	global_load_dwordx2 v[84:85], v[38:39], off offset:64
	global_load_dwordx2 v[86:87], v[38:39], off offset:96
	s_nop 0
	global_load_dwordx4 v[36:39], v[44:45], off
	global_load_dwordx4 v[40:43], v[44:45], off offset:64
	v_lshl_add_u64 v[68:69], v[46:47], 0, v[16:17]
	v_lshl_add_u64 v[70:71], v[46:47], 0, v[18:19]
	v_lshl_add_u64 v[72:73], v[46:47], 0, v[20:21]
	v_lshl_add_u64 v[74:75], v[46:47], 0, 64
	global_load_dwordx2 v[88:89], v[22:23], off
	global_load_dwordx4 v[44:47], v[68:69], off
	global_load_dwordx4 v[48:51], v[68:69], off offset:2048
	global_load_dwordx4 v[52:55], v[70:71], off
	global_load_dwordx4 v[56:59], v[72:73], off
	global_load_dwordx4 v[60:63], v[68:69], off offset:64
	global_load_dwordx4 v[64:67], v[68:69], off offset:2112
	v_lshl_add_u64 v[80:81], v[74:75], 0, v[18:19]
	v_lshl_add_u64 v[90:91], v[74:75], 0, v[20:21]
	global_load_dwordx4 v[68:71], v[80:81], off
	global_load_dwordx4 v[72:75], v[90:91], off
	v_and_or_b32 v27, v25, s14, v76
	v_or_b32_e32 v76, v27, v2
	v_lshlrev_b64 v[80:81], 10, v[76:77]
	v_lshlrev_b64 v[90:91], 11, v[76:77]
	v_lshl_add_u64 v[92:93], s[8:9], 0, v[80:81]
	v_lshlrev_b32_e32 v4, 1, v4
	v_lshl_add_u64 v[176:177], v[92:93], 0, v[4:5]
	global_load_dwordx2 v[120:121], v[22:23], off offset:32
	global_load_dwordx4 v[124:127], v15, s[4:5] offset:64
	global_load_dwordx4 v[128:131], v15, s[6:7] offset:64
	global_load_dwordx2 v[122:123], v[176:177], off offset:32
	global_load_dwordx2 v[132:133], v[22:23], off offset:64
	global_load_dwordx4 v[136:139], v15, s[4:5] offset:128
	global_load_dwordx4 v[140:143], v15, s[6:7] offset:128
	global_load_dwordx2 v[134:135], v[176:177], off offset:64
	global_load_dwordx2 v[144:145], v[22:23], off offset:96
	global_load_dwordx4 v[148:151], v15, s[4:5] offset:192
	global_load_dwordx4 v[152:155], v15, s[6:7] offset:192
	global_load_dwordx2 v[146:147], v[176:177], off offset:96
	s_add_i32 s16, s16, s50
	v_add_u32_e32 v14, s13, v14
	s_cmpk_lt_i32 s16, 0x800
	v_add_u32_e32 v25, s12, v25
	s_waitcnt vmcnt(26)
	v_lshlrev_b32_e32 v76, 16, v78
	v_and_b32_e32 v77, 0xffff0000, v78
	v_lshlrev_b32_e32 v78, 16, v79
	v_and_b32_e32 v79, 0xffff0000, v79
	s_waitcnt vmcnt(25)
	v_lshlrev_b32_e32 v80, 16, v82
	v_and_b32_e32 v81, 0xffff0000, v82
	s_waitcnt vmcnt(19)
	v_mfma_f32_16x16x32_bf16 v[44:47], v[44:47], v[36:39], v[76:79]
	v_lshlrev_b32_e32 v82, 16, v83
	v_and_b32_e32 v83, 0xffff0000, v83
	s_nop 0
	v_lshlrev_b32_e32 v76, 16, v84
	v_and_b32_e32 v77, 0xffff0000, v84
	s_waitcnt vmcnt(18)
	v_mfma_f32_16x16x32_bf16 v[48:51], v[48:51], v[36:39], v[80:83]
	v_lshlrev_b32_e32 v78, 16, v85
	v_and_b32_e32 v79, 0xffff0000, v85
	s_nop 0
	v_lshlrev_b32_e32 v80, 16, v86
	v_and_b32_e32 v81, 0xffff0000, v86
	v_lshlrev_b32_e32 v82, 16, v87
	v_and_b32_e32 v83, 0xffff0000, v87
	s_waitcnt vmcnt(17)
	v_mfma_f32_16x16x32_bf16 v[52:55], v[52:55], v[36:39], v[76:79]
	s_waitcnt vmcnt(16)
	v_mfma_f32_16x16x32_bf16 v[36:39], v[56:59], v[36:39], v[80:83]
	v_lshl_add_u64 v[58:59], v[92:93], 0, v[4:5]
	v_lshl_add_u64 v[56:57], s[10:11], 0, v[90:91]
	v_lshl_add_u64 v[56:57], v[56:57], 0, v[4:5]
	s_waitcnt vmcnt(15)
	v_mfma_f32_16x16x32_bf16 v[44:47], v[60:63], v[40:43], v[44:47]
	global_load_dwordx2 v[60:61], v[58:59], off
	v_lshlrev_b32_e32 v62, 16, v89
	v_and_b32_e32 v63, 0xffff0000, v89
	s_waitcnt vmcnt(15)
	v_mfma_f32_16x16x32_bf16 v[48:51], v[64:67], v[40:43], v[48:51]
	v_lshlrev_b32_e32 v64, 16, v88
	s_nop 1
	v_add_f32_e32 v4, 0, v44
	v_add_f32_e32 v4, v45, v4
	v_add_f32_e32 v4, v46, v4
	v_add_f32_e32 v4, v47, v4
	s_waitcnt vmcnt(14)
	v_mfma_f32_16x16x32_bf16 v[52:55], v[68:71], v[40:43], v[52:55]
	v_add_f32_e32 v4, v48, v4
	v_add_f32_e32 v4, v49, v4
	v_add_f32_e32 v4, v50, v4
	v_add_f32_e32 v4, v51, v4
	s_waitcnt vmcnt(13)
	v_mfma_f32_16x16x32_bf16 v[36:39], v[72:75], v[40:43], v[36:39]
	s_nop 1
	v_add_f32_e32 v4, v52, v4
	v_add_f32_e32 v4, v53, v4
	v_add_f32_e32 v4, v54, v4
	v_add_f32_e32 v4, v55, v4
	v_and_b32_e32 v65, 0xffff0000, v88
	s_nop 0
	v_add_f32_e32 v4, v36, v4
	v_add_f32_e32 v4, v37, v4
	v_add_f32_e32 v4, v38, v4
	v_add_f32_e32 v4, v39, v4
	ds_bpermute_b32 v27, v3, v4
	s_waitcnt lgkmcnt(0)
	v_add_f32_e32 v4, v4, v27
	ds_bpermute_b32 v27, v24, v4
	s_waitcnt lgkmcnt(0)
; __device__ __forceinline__ unsigned pk2(float lo, float hi) { f32x2_t v = {lo, hi}; bf16x2_t b = __builtin_convertvector(v, bf16x2_t); return __builtin_bit_cast(unsigned, b); }
; __device__ __forceinline__ float bflo(unsigned v) { return __uint_as_float(v << 16); }
; __device__ __forceinline__ float bfhi(unsigned v) { return __uint_as_float(v & 0xffff0000u); }
; __device__ void phase_rwkv_out(const Params& p, int bid, int nb) {
;     ...
;     float s = 0.f;
; #pragma unroll
;     for (int jt = 0; jt < 4; ++jt)
; #pragma unroll
;       for (int e = 0; e < 4; ++e) s += acc[jt][e];
;     s += __shfl_xor(s, 16); s += __shfl_xor(s, 32);
;     const float mu = s * (1.f / 64.f);
;     float vs = 0.f;
; #pragma unroll
;     for (int jt = 0; jt < 4; ++jt)
; #pragma unroll
;       for (int e = 0; e < 4; ++e) { const float d = acc[jt][e] - mu; vs += d * d; }
;     vs += __shfl_xor(vs, 16); vs += __shfl_xor(vs, 32);
;     const float rstd = __builtin_amdgcn_rsqf(vs * (1.f / 64.f) + 64e-5f);
;     const size_t tok = (size_t)b * SEQ + c * 64 + tl;
; #pragma unroll
;     for (int jt = 0; jt < 4; ++jt) {
;       const int v = jt * 16 + 4 * g, cc = hd * 64 + v;
;       const f32x4 gg = *(const f32x4*)(p.gn_gain + cc), gb = *(const f32x4*)(p.gn_bias + cc);
;       const u32x2 bvw = *(const u32x2*)(p.BV + (size_t)item * 4096 + tl * 64 + v);
;       const u32x2 gw = *(const u32x2*)(p.GB + tok * 512 + cc);
;       float o[4];
;       const float bvf[4] = {bflo(bvw.x), bfhi(bvw.x), bflo(bvw.y), bfhi(bvw.y)};
;       const float gf[4] = {bflo(gw.x), bfhi(gw.x), bflo(gw.y), bfhi(gw.y)};
; #pragma unroll
;       for (int e = 0; e < 4; ++e) {
;     ...
;         o[e] = bvf[e] * gf[e];
;     ...
;         o[e] = ((acc[jt][e] - mu) * rstd * gg[e] + gb[e]) * gf[e];
;     ...
;         o[e] = ((acc[jt][e] - mu) * rstd * gg[e] + gb[e] + bvf[e]) * gf[e];
;     ...
;       }
;       u32x2 w; w.x = pk2(o[0], o[1]); w.y = pk2(o[2], o[3]);
;       *(u32x2*)(p.Ymix + tok * 1024 + 512 + cc) = w;
;     }
	v_add_f32_e32 v4, v4, v27
	v_mul_f32_e32 v4, 0x3c800000, v4
	v_pk_add_f32 v[44:45], v[44:45], v[4:5] op_sel_hi:[1,0] neg_lo:[0,1] neg_hi:[0,1]
	v_pk_add_f32 v[42:43], v[46:47], v[4:5] op_sel_hi:[1,0] neg_lo:[0,1] neg_hi:[0,1]
	v_pk_mul_f32 v[72:73], v[44:45], v[44:45]
	v_pk_add_f32 v[40:41], v[54:55], v[4:5] op_sel_hi:[1,0] neg_lo:[0,1] neg_hi:[0,1]
	v_pk_add_f32 v[36:37], v[36:37], v[4:5] op_sel_hi:[1,0] neg_lo:[0,1] neg_hi:[0,1]
	v_pk_add_f32 v[38:39], v[38:39], v[4:5] op_sel_hi:[1,0] neg_lo:[0,1] neg_hi:[0,1]
	v_pk_add_f32 v[46:47], v[50:51], v[4:5] op_sel_hi:[1,0] neg_lo:[0,1] neg_hi:[0,1]
	v_pk_add_f32 v[48:49], v[48:49], v[4:5] op_sel_hi:[1,0] neg_lo:[0,1] neg_hi:[0,1]
	v_pk_add_f32 v[50:51], v[52:53], v[4:5] op_sel_hi:[1,0] neg_lo:[0,1] neg_hi:[0,1]
	v_pk_mul_f32 v[70:71], v[42:43], v[42:43]
	v_add_f32_e32 v4, v72, v73
	v_add_f32_e32 v4, v70, v4
	v_pk_mul_f32 v[76:77], v[48:49], v[48:49]
	v_add_f32_e32 v4, v71, v4
	v_add_f32_e32 v4, v76, v4
	v_pk_mul_f32 v[74:75], v[46:47], v[46:47]
	v_add_f32_e32 v4, v77, v4
	v_add_f32_e32 v4, v74, v4
	v_pk_mul_f32 v[78:79], v[50:51], v[50:51]
	v_add_f32_e32 v4, v75, v4
	v_add_f32_e32 v4, v78, v4
	v_pk_mul_f32 v[52:53], v[40:41], v[40:41]
	v_add_f32_e32 v4, v79, v4
	v_add_f32_e32 v4, v52, v4
	v_pk_mul_f32 v[54:55], v[36:37], v[36:37]
	v_add_f32_e32 v4, v53, v4
	v_add_f32_e32 v4, v54, v4
	v_add_f32_e32 v4, v55, v4
	s_waitcnt vmcnt(0)
	v_lshlrev_b32_e32 v66, 16, v61
	v_and_b32_e32 v67, 0xffff0000, v61
	v_lshlrev_b32_e32 v68, 16, v60
	v_and_b32_e32 v69, 0xffff0000, v60
	v_pk_mul_f32 v[60:61], v[38:39], v[38:39]
	s_nop 0
	v_add_f32_e32 v4, v60, v4
	v_add_f32_e32 v4, v61, v4
	ds_bpermute_b32 v27, v3, v4
	s_waitcnt lgkmcnt(0)
	v_add_f32_e32 v4, v4, v27
	ds_bpermute_b32 v27, v24, v4
	s_waitcnt lgkmcnt(0)
	v_add_f32_e32 v4, v4, v27
	v_fmamk_f32 v4, v4, 0x3c800000, v26
	v_rsq_f32_e32 v4, v4
	s_nop 0
	v_pk_mul_f32 v[44:45], v[44:45], v[4:5] op_sel_hi:[1,0]
	v_pk_mul_f32 v[42:43], v[42:43], v[4:5] op_sel_hi:[1,0]
	v_pk_fma_f32 v[28:29], v[28:29], v[44:45], v[32:33]
	v_pk_fma_f32 v[30:31], v[30:31], v[42:43], v[34:35]
	v_pk_add_f32 v[28:29], v[28:29], v[64:65]
	v_pk_add_f32 v[30:31], v[30:31], v[62:63]
	v_pk_mul_f32 v[28:29], v[28:29], v[68:69]
	v_pk_mul_f32 v[30:31], v[30:31], v[66:67]
	v_cvt_pk_bf16_f32 v28, v28, v29
	v_cvt_pk_bf16_f32 v29, v30, v31
	global_store_dwordx2 v[56:57], v[28:29], off offset:1024
	v_pk_mul_f32 v[48:49], v[48:49], v[4:5] op_sel_hi:[1,0]
	v_pk_mul_f32 v[46:47], v[46:47], v[4:5] op_sel_hi:[1,0]
	v_pk_mul_f32 v[40:41], v[40:41], v[4:5] op_sel_hi:[1,0]
	v_lshlrev_b32_e32 v52, 16, v120
	v_and_b32_e32 v53, 0xffff0000, v120
	v_lshlrev_b32_e32 v120, 16, v121
	v_and_b32_e32 v121, 0xffff0000, v121
	v_pk_fma_f32 v[124:125], v[124:125], v[48:49], v[128:129]
	v_pk_fma_f32 v[126:127], v[126:127], v[46:47], v[130:131]
	v_lshlrev_b32_e32 v54, 16, v122
	v_and_b32_e32 v55, 0xffff0000, v122
	v_lshlrev_b32_e32 v122, 16, v123
	v_and_b32_e32 v123, 0xffff0000, v123
	v_pk_add_f32 v[124:125], v[124:125], v[52:53]
	v_pk_add_f32 v[126:127], v[126:127], v[120:121]
	v_pk_mul_f32 v[124:125], v[124:125], v[54:55]
	v_pk_mul_f32 v[126:127], v[126:127], v[122:123]
	v_cvt_pk_bf16_f32 v124, v124, v125
	v_cvt_pk_bf16_f32 v125, v126, v127
	global_store_dwordx2 v[56:57], v[124:125], off offset:1056
	v_pk_mul_f32 v[46:47], v[50:51], v[4:5] op_sel_hi:[1,0]
	v_lshlrev_b32_e32 v48, 16, v132
	v_and_b32_e32 v49, 0xffff0000, v132
	v_pk_fma_f32 v[136:137], v[136:137], v[46:47], v[140:141]
	v_lshlrev_b32_e32 v140, 16, v133
	v_and_b32_e32 v141, 0xffff0000, v133
	v_pk_fma_f32 v[138:139], v[138:139], v[40:41], v[142:143]
	v_lshlrev_b32_e32 v50, 16, v134
	v_and_b32_e32 v51, 0xffff0000, v134
	v_lshlrev_b32_e32 v132, 16, v135
	v_and_b32_e32 v133, 0xffff0000, v135
	v_pk_add_f32 v[136:137], v[136:137], v[48:49]
	v_pk_add_f32 v[138:139], v[138:139], v[140:141]
	v_pk_mul_f32 v[136:137], v[136:137], v[50:51]
	v_pk_mul_f32 v[138:139], v[138:139], v[132:133]
	v_cvt_pk_bf16_f32 v136, v136, v137
	v_cvt_pk_bf16_f32 v137, v138, v139
	global_store_dwordx2 v[56:57], v[136:137], off offset:1088
	v_pk_mul_f32 v[22:23], v[36:37], v[4:5] op_sel_hi:[1,0]
	v_pk_mul_f32 v[36:37], v[38:39], v[4:5] op_sel_hi:[1,0]
	v_lshlrev_b32_e32 v38, 16, v144
	v_and_b32_e32 v39, 0xffff0000, v144
	v_pk_fma_f32 v[22:23], v[148:149], v[22:23], v[152:153]
	v_lshlrev_b32_e32 v148, 16, v145
	v_and_b32_e32 v149, 0xffff0000, v145
	v_pk_fma_f32 v[150:151], v[150:151], v[36:37], v[154:155]
	v_lshlrev_b32_e32 v44, 16, v146
	v_and_b32_e32 v45, 0xffff0000, v146
	v_lshlrev_b32_e32 v152, 16, v147
	v_and_b32_e32 v153, 0xffff0000, v147
	v_pk_add_f32 v[22:23], v[22:23], v[38:39]
	v_pk_add_f32 v[148:149], v[150:151], v[148:149]
	v_pk_mul_f32 v[22:23], v[22:23], v[44:45]
	v_pk_mul_f32 v[148:149], v[148:149], v[152:153]
	v_cvt_pk_bf16_f32 v22, v22, v23
	v_cvt_pk_bf16_f32 v23, v148, v149
	global_store_dwordx2 v[56:57], v[22:23], off offset:1120
	s_cbranch_scc1 .LBB0_498

;     ...
;   const int srow = tid >> 3, skc = tid & 7;
;   const u16* Ag = A + (size_t)(m0 + srow) * K + skc * 8;
;   const u16* Bg[4];
; #pragma unroll
;   for (int i = 0; i < 4; ++i) { int n = n0 + srow + 64 * i; n = n < nmax ? n : nmax - 1; Bg[i] = Bt + (size_t)n * K + skc * 8; }
;   const int nk = nk_override ? nk_override : K / 64;
; #pragma unroll
;   for (int i = 0; i < 4; ++i) { ra[i] = *(const u32x4*)(Ag + (size_t)(64 * i) * K); rb[i] = *(const u32x4*)(Bg[i]); }
; #pragma unroll
;   for (int i = 0; i < 4; ++i) { *(u32x4*)(As0 + (srow + 64 * i) * LD + skc * 8) = ra[i]; *(u32x4*)(Bs0 + (srow + 64 * i) * LD + skc * 8) = rb[i]; }
;   if (nk > 1) {
; #pragma unroll
;     for (int i = 0; i < 4; ++i) { ra[i] = *(const u32x4*)(Ag + (size_t)(64 * i) * K + 64); rb[i] = *(const u32x4*)(Bg[i] + 64); }
;   }
.LBB0_554:
	s_ashr_i32 s4, s3, 31
	s_lshr_b32 s4, s4, 30
	s_add_i32 s4, s3, s4
	s_and_b32 s5, s4, 0xfffffc
	s_sub_i32 s5, s3, s5
	v_mov_b32_e32 v66, v223
	s_lshl_b32 s34, s5, 8
	s_lshl_b32 s4, s4, 6
	v_ashrrev_i32_e32 v40, 3, v66
	v_add_u32_e32 v8, s34, v40
	s_and_b32 s38, s4, 0xffffff00
	v_lshlrev_b32_e32 v4, 4, v66
	v_min_i32_e32 v6, 0x3ff, v8
	s_add_i32 s38, s38, s44
	v_and_b32_e32 v150, 0x70, v4
	v_ashrrev_i32_e32 v7, 31, v6
	v_add_u32_e32 v2, s38, v40
	s_waitcnt lgkmcnt(0)
	v_lshl_add_u64 v[4:5], s[22:23], 0, v[150:151]
	v_lshlrev_b64 v[6:7], 11, v[6:7]
	v_ashrrev_i32_e32 v3, 31, v2
	v_lshl_add_u64 v[130:131], v[4:5], 0, v[6:7]
	v_min_i32_e32 v6, 0x3bf, v8
	v_lshlrev_b64 v[2:3], 11, v[2:3]
	v_ashrrev_i32_e32 v7, 31, v6
	v_lshlrev_b64 v[6:7], 11, v[6:7]
	v_lshl_add_u64 v[2:3], s[16:17], 0, v[2:3]
	v_lshl_add_u64 v[34:35], v[4:5], 0, v[6:7]
	v_min_i32_e32 v6, 0x37f, v8
	v_lshl_add_u64 v[132:133], v[2:3], 0, v[150:151]
	v_ashrrev_i32_e32 v7, 31, v6
	v_add_co_u32_e32 v134, vcc, s45, v132
	v_lshlrev_b64 v[6:7], 11, v[6:7]
	s_nop 0
	v_addc_co_u32_e32 v135, vcc, 0, v133, vcc
	v_lshl_add_u64 v[36:37], v[4:5], 0, v[6:7]
	v_min_i32_e32 v6, 0x33f, v8
	v_add_co_u32_e32 v14, vcc, s45, v34
	v_ashrrev_i32_e32 v7, 31, v6
	s_nop 0
	v_addc_co_u32_e32 v15, vcc, 0, v35, vcc
	v_lshlrev_b64 v[6:7], 11, v[6:7]
	v_add_co_u32_e32 v136, vcc, s46, v132
	v_lshl_add_u64 v[38:39], v[4:5], 0, v[6:7]
	global_load_dwordx4 v[2:5], v[132:133], off
	global_load_dwordx4 v[6:9], v[130:131], off
	v_addc_co_u32_e32 v137, vcc, 0, v133, vcc
	v_add_co_u32_e32 v22, vcc, s46, v36
	global_load_dwordx4 v[10:13], v[134:135], off
	global_load_dwordx4 v[18:21], v[136:137], off
	v_addc_co_u32_e32 v23, vcc, 0, v37, vcc
	global_load_dwordx4 v[14:17], v[14:15], off
	v_add_co_u32_e32 v138, vcc, s47, v132
	global_load_dwordx4 v[22:25], v[22:23], off
	s_nop 0
	v_addc_co_u32_e32 v139, vcc, 0, v133, vcc
	v_add_co_u32_e32 v30, vcc, s47, v38
	global_load_dwordx4 v[26:29], v[138:139], off
	s_nop 0
	v_addc_co_u32_e32 v31, vcc, 0, v39, vcc
	global_load_dwordx4 v[30:33], v[30:31], off
	v_mul_lo_u32 v40, v40, s52
	v_add3_u32 v149, 0, v150, v40
	v_lshl_add_u64 v[144:145], v[38:39], 0, s[30:31]
	v_add3_u32 v152, s51, v150, v40
	v_lshl_add_u64 v[140:141], v[34:35], 0, s[26:27]
	v_lshl_add_u64 v[142:143], v[36:37], 0, s[28:29]
	global_load_dwordx4 v[34:37], v[132:133], off offset:128
	global_load_dwordx4 v[38:41], v[130:131], off offset:128
	global_load_dwordx4 v[42:45], v[134:135], off offset:128
	global_load_dwordx4 v[46:49], v[136:137], off offset:128
	global_load_dwordx4 v[50:53], v[140:141], off offset:128
	global_load_dwordx4 v[54:57], v[142:143], off offset:128
	global_load_dwordx4 v[58:61], v[138:139], off offset:128
	global_load_dwordx4 v[62:65], v[144:145], off offset:128
	v_readfirstlane_b32 s5, v66
	s_and_b32 s4, s5, 0xc0
	s_ashr_i32 s5, s5, 1
	v_and_b32_e32 v146, 31, v66
	s_and_b32 s5, s5, 0xffffff80
	v_bfe_u32 v159, v66, 5, 1
	v_lshlrev_b32_e32 v150, 4, v159
	s_waitcnt vmcnt(15)
	ds_write_b128 v149, v[2:5]
	s_waitcnt vmcnt(14)
	ds_write_b128 v152, v[6:9]
	s_waitcnt vmcnt(13)
	ds_write_b128 v149, v[10:13] offset:9216
	s_waitcnt vmcnt(11)
	ds_write_b128 v152, v[14:17] offset:9216
	ds_write_b128 v149, v[18:21] offset:18432
	s_waitcnt vmcnt(10)
	ds_write_b128 v152, v[22:25] offset:18432
	s_waitcnt vmcnt(9)
	ds_write_b128 v149, v[26:29] offset:27648
	s_waitcnt vmcnt(8)
	ds_write_b128 v152, v[30:33] offset:27648
	s_waitcnt lgkmcnt(0)
	s_barrier
	v_or_b32_e32 v2, s5, v146
	v_mul_lo_u32 v2, v2, s52
	v_add3_u32 v147, 0, v2, v150
	v_or_b32_e32 v2, s4, v146
	v_mul_u32_u24_e32 v2, 0x90, v2
	v_add3_u32 v148, s51, v2, v150
	v_lshrrev_b32_e32 v153, 3, v223
	v_lshlrev_b32_e32 v153, 11, v153
	v_lshlrev_b32_e32 v2, 4, v223
	v_and_b32_e32 v2, 0x70, v2
	v_or_b32_e32 v153, v153, v2
	s_lshl_b32 s53, s38, 11
	s_add_u32 s74, s16, s53
	s_addc_u32 s75, s17, 0
	s_add_u32 s76, s74, 0x20000
	s_addc_u32 s77, s75, 0
	s_add_u32 s78, s74, 0x40000
	s_addc_u32 s79, s75, 0
	s_add_u32 s80, s74, 0x60000
	s_addc_u32 s81, s75, 0
	s_lshl_b32 s53, s34, 11
	s_add_u32 s82, s22, s53
	s_addc_u32 s83, s23, 0
	s_add_u32 s84, s82, 0x20000
	s_addc_u32 s85, s83, 0
	s_add_u32 s86, s82, 0x40000
	s_addc_u32 s87, s83, 0
	s_add_u32 s92, s82, 0x60000
	s_addc_u32 s93, s83, 0
	global_load_dwordx4 v[130:133], v153, s[74:75] offset:256
	global_load_dwordx4 v[176:179], v153, s[82:83] offset:256
	global_load_dwordx4 v[134:137], v153, s[76:77] offset:256
	global_load_dwordx4 v[180:183], v153, s[84:85] offset:256
	global_load_dwordx4 v[138:141], v153, s[78:79] offset:256
	global_load_dwordx4 v[184:187], v153, s[86:87] offset:256
	global_load_dwordx4 v[142:145], v153, s[80:81] offset:256
	global_load_dwordx4 v[188:191], v153, s[92:93] offset:256
	global_load_dwordx4 v[160:163], v153, s[74:75] offset:384
	global_load_dwordx4 v[192:195], v153, s[82:83] offset:384
	global_load_dwordx4 v[164:167], v153, s[76:77] offset:384
	global_load_dwordx4 v[196:199], v153, s[84:85] offset:384
	global_load_dwordx4 v[168:171], v153, s[78:79] offset:384
	global_load_dwordx4 v[200:203], v153, s[86:87] offset:384
	global_load_dwordx4 v[172:175], v153, s[80:81] offset:384
	global_load_dwordx4 v[204:207], v153, s[92:93] offset:384
	s_waitcnt vmcnt(23)
	ds_write_b128 v149, v[34:37] offset:36864
	s_waitcnt vmcnt(22)
	ds_write_b128 v152, v[38:41] offset:36864
	s_waitcnt vmcnt(21)
	ds_write_b128 v149, v[42:45] offset:46080
	s_waitcnt vmcnt(20)
	ds_write_b128 v149, v[46:49] offset:55296
	s_waitcnt vmcnt(19)
	ds_write_b128 v152, v[50:53] offset:46080
	s_waitcnt vmcnt(18)
	ds_write_b128 v152, v[54:57] offset:55296
	s_waitcnt vmcnt(17)
	ds_write_b128 v149, v[58:61] offset:64512
	s_waitcnt vmcnt(16)
;     ...
;   for (int kt = 0; kt < nk; ++kt) {
;     __syncthreads();
;     if (kt + 1 < nk) {
;       u16* aw = As0 + ((kt + 1) & 1) * 256 * LD;
;       u16* bw = Bs0 + ((kt + 1) & 1) * 256 * LD;
; #pragma unroll
;       for (int i = 0; i < 4; ++i) { *(u32x4*)(aw + (srow + 64 * i) * LD + skc * 8) = ra[i]; *(u32x4*)(bw + (srow + 64 * i) * LD + skc * 8) = rb[i]; }
;     }
;     if (kt + 2 < nk) {
; #pragma unroll
;       for (int i = 0; i < 4; ++i) { ra[i] = *(const u32x4*)(Ag + (size_t)(64 * i) * K + (kt + 2) * 64); rb[i] = *(const u32x4*)(Bg[i] + (kt + 2) * 64); }
;     }
;     __builtin_amdgcn_sched_barrier(0);
;     const u16* as = As0 + (kt & 1) * 256 * LD + (wr * 128 + l31) * LD + h * 8;
;     const u16* bs = Bs0 + (kt & 1) * 256 * LD + (wc * 64 + l31) * LD + h * 8;
;     if (domma)
; #pragma unroll
;     for (int ks = 0; ks < 4; ++ks) {
;       bf16x8 wf[2], xf[4];
; #pragma unroll
;       for (int ct = 0; ct < 2; ++ct) wf[ct] = *(const bf16x8*)(bs + ct * 32 * LD + ks * 16);
; #pragma unroll
;       for (int tt = 0; tt < 4; ++tt) xf[tt] = *(const bf16x8*)(as + tt * 32 * LD + ks * 16);
; #pragma unroll
;       for (int ct = 0; ct < 2; ++ct)
; #pragma unroll
;         for (int tt = 0; tt < 4; ++tt) acc[ct][tt] = __builtin_amdgcn_mfma_f32_32x32x16_bf16(wf[ct], xf[tt], acc[ct][tt], 0, 0, 0);
;     }
	ds_write_b128 v152, v[62:65] offset:64512
	ds_read_b128 v[208:211], v148
	ds_read_b128 v[228:231], v147
	ds_read_b128 v[212:215], v148 offset:4608
	ds_read_b128 v[232:235], v147 offset:4608
	ds_read_b128 v[236:239], v147 offset:9216
	ds_read_b128 v[240:243], v147 offset:13824
	s_waitcnt lgkmcnt(4)
	v_mfma_f32_32x32x16_bf16 v[98:113], v[208:211], v[228:231], 0
	ds_read_b128 v[216:219], v148 offset:32
	s_waitcnt lgkmcnt(4)
	v_mfma_f32_32x32x16_bf16 v[114:129], v[212:215], v[228:231], 0
	ds_read_b128 v[244:247], v147 offset:32
	s_waitcnt lgkmcnt(4)
	v_mfma_f32_32x32x16_bf16 v[82:97], v[208:211], v[232:235], 0
	ds_read_b128 v[224:227], v148 offset:4640
	v_mfma_f32_32x32x16_bf16 v[66:81], v[212:215], v[232:235], 0
	ds_read_b128 v[228:231], v147 offset:4640
	s_waitcnt lgkmcnt(5)
	v_mfma_f32_32x32x16_bf16 v[50:65], v[208:211], v[236:239], 0
	ds_read_b128 v[232:235], v147 offset:9248
	v_mfma_f32_32x32x16_bf16 v[34:49], v[212:215], v[236:239], 0
	s_waitcnt lgkmcnt(5)
	v_mfma_f32_32x32x16_bf16 v[18:33], v[208:211], v[240:243], 0
	ds_read_b128 v[236:239], v147 offset:13856
	v_mfma_f32_32x32x16_bf16 v[2:17], v[212:215], v[240:243], 0
	s_waitcnt lgkmcnt(4)
	v_mfma_f32_32x32x16_bf16 v[98:113], v[216:219], v[244:247], v[98:113]
	ds_read_b128 v[208:211], v148 offset:64
	s_waitcnt lgkmcnt(4)
	v_mfma_f32_32x32x16_bf16 v[114:129], v[224:227], v[244:247], v[114:129]
	ds_read_b128 v[240:243], v147 offset:64
	s_waitcnt lgkmcnt(4)
	v_mfma_f32_32x32x16_bf16 v[82:97], v[216:219], v[228:231], v[82:97]
	ds_read_b128 v[212:215], v148 offset:4672
	v_mfma_f32_32x32x16_bf16 v[66:81], v[224:227], v[228:231], v[66:81]
	ds_read_b128 v[244:247], v147 offset:4672
	s_waitcnt lgkmcnt(5)
	v_mfma_f32_32x32x16_bf16 v[50:65], v[216:219], v[232:235], v[50:65]
	ds_read_b128 v[228:231], v147 offset:9280
	v_mfma_f32_32x32x16_bf16 v[34:49], v[224:227], v[232:235], v[34:49]
	s_waitcnt lgkmcnt(5)
	v_mfma_f32_32x32x16_bf16 v[18:33], v[216:219], v[236:239], v[18:33]
	ds_read_b128 v[232:235], v147 offset:13888
	v_mfma_f32_32x32x16_bf16 v[2:17], v[224:227], v[236:239], v[2:17]
	s_waitcnt lgkmcnt(4)
	v_mfma_f32_32x32x16_bf16 v[98:113], v[208:211], v[240:243], v[98:113]
	ds_read_b128 v[216:219], v148 offset:96
	s_waitcnt lgkmcnt(4)
	v_mfma_f32_32x32x16_bf16 v[114:129], v[212:215], v[240:243], v[114:129]
	ds_read_b128 v[236:239], v147 offset:96
	s_waitcnt lgkmcnt(4)
	v_mfma_f32_32x32x16_bf16 v[82:97], v[208:211], v[244:247], v[82:97]
	ds_read_b128 v[224:227], v148 offset:4704
	v_mfma_f32_32x32x16_bf16 v[66:81], v[212:215], v[244:247], v[66:81]
	ds_read_b128 v[240:243], v147 offset:4704
	s_waitcnt lgkmcnt(5)
	v_mfma_f32_32x32x16_bf16 v[50:65], v[208:211], v[228:231], v[50:65]
	ds_read_b128 v[244:247], v147 offset:9312
	v_mfma_f32_32x32x16_bf16 v[34:49], v[212:215], v[228:231], v[34:49]
	s_waitcnt lgkmcnt(5)
	v_mfma_f32_32x32x16_bf16 v[18:33], v[208:211], v[232:235], v[18:33]
	ds_read_b128 v[228:231], v147 offset:13920
	v_mfma_f32_32x32x16_bf16 v[2:17], v[212:215], v[232:235], v[2:17]
	s_waitcnt lgkmcnt(4)
	v_mfma_f32_32x32x16_bf16 v[98:113], v[216:219], v[236:239], v[98:113]
	s_waitcnt lgkmcnt(3)
	v_mfma_f32_32x32x16_bf16 v[114:129], v[224:227], v[236:239], v[114:129]
	s_waitcnt lgkmcnt(2)
	v_mfma_f32_32x32x16_bf16 v[82:97], v[216:219], v[240:243], v[82:97]
	v_mfma_f32_32x32x16_bf16 v[66:81], v[224:227], v[240:243], v[66:81]
	s_waitcnt lgkmcnt(1)
	v_mfma_f32_32x32x16_bf16 v[50:65], v[216:219], v[244:247], v[50:65]
	v_mfma_f32_32x32x16_bf16 v[34:49], v[224:227], v[244:247], v[34:49]
	s_waitcnt lgkmcnt(0)
	v_mfma_f32_32x32x16_bf16 v[18:33], v[216:219], v[228:231], v[18:33]
	v_mfma_f32_32x32x16_bf16 v[2:17], v[224:227], v[228:231], v[2:17]
	s_barrier
	ds_read_b128 v[208:211], v148 offset:36864
	ds_read_b128 v[228:231], v147 offset:36864
	ds_read_b128 v[212:215], v148 offset:41472
	ds_read_b128 v[232:235], v147 offset:41472
	ds_read_b128 v[236:239], v147 offset:46080
	ds_read_b128 v[240:243], v147 offset:50688
	s_waitcnt lgkmcnt(4)
	v_mfma_f32_32x32x16_bf16 v[98:113], v[208:211], v[228:231], v[98:113]
	ds_read_b128 v[216:219], v148 offset:36896
	s_waitcnt lgkmcnt(4)
	v_mfma_f32_32x32x16_bf16 v[114:129], v[212:215], v[228:231], v[114:129]
	ds_read_b128 v[244:247], v147 offset:36896
	s_waitcnt lgkmcnt(4)
	v_mfma_f32_32x32x16_bf16 v[82:97], v[208:211], v[232:235], v[82:97]
	ds_read_b128 v[224:227], v148 offset:41504
	v_mfma_f32_32x32x16_bf16 v[66:81], v[212:215], v[232:235], v[66:81]
	ds_read_b128 v[228:231], v147 offset:41504
	s_waitcnt vmcnt(15)
	ds_write_b128 v149, v[130:133]
	s_waitcnt lgkmcnt(6)
	v_mfma_f32_32x32x16_bf16 v[50:65], v[208:211], v[236:239], v[50:65]
	ds_read_b128 v[232:235], v147 offset:46112
	v_mfma_f32_32x32x16_bf16 v[34:49], v[212:215], v[236:239], v[34:49]
	global_load_dwordx4 v[130:133], v153, s[74:75] offset:512
	s_waitcnt lgkmcnt(6)
	v_mfma_f32_32x32x16_bf16 v[18:33], v[208:211], v[240:243], v[18:33]
	ds_read_b128 v[236:239], v147 offset:50720
	s_waitcnt vmcnt(15)
	ds_write_b128 v152, v[176:179]
	v_mfma_f32_32x32x16_bf16 v[2:17], v[212:215], v[240:243], v[2:17]
	s_waitcnt lgkmcnt(6)
	v_mfma_f32_32x32x16_bf16 v[98:113], v[216:219], v[244:247], v[98:113]
	ds_read_b128 v[208:211], v148 offset:36928
	global_load_dwordx4 v[176:179], v153, s[82:83] offset:512
	s_waitcnt lgkmcnt(6)
	v_mfma_f32_32x32x16_bf16 v[114:129], v[224:227], v[244:247], v[114:129]
	ds_read_b128 v[240:243], v147 offset:36928
	s_waitcnt vmcnt(15)
	ds_write_b128 v149, v[134:137] offset:9216
	s_waitcnt lgkmcnt(7)
	v_mfma_f32_32x32x16_bf16 v[82:97], v[216:219], v[228:231], v[82:97]
	ds_read_b128 v[212:215], v148 offset:41536
	v_mfma_f32_32x32x16_bf16 v[66:81], v[224:227], v[228:231], v[66:81]
	ds_read_b128 v[244:247], v147 offset:41536
	global_load_dwordx4 v[134:137], v153, s[76:77] offset:512
	s_waitcnt lgkmcnt(7)
;     ...
;   for (int kt = 0; kt < nk; ++kt) {
;     __syncthreads();
;     if (kt + 1 < nk) {
;       u16* aw = As0 + ((kt + 1) & 1) * 256 * LD;
;       u16* bw = Bs0 + ((kt + 1) & 1) * 256 * LD;
; #pragma unroll
;       for (int i = 0; i < 4; ++i) { *(u32x4*)(aw + (srow + 64 * i) * LD + skc * 8) = ra[i]; *(u32x4*)(bw + (srow + 64 * i) * LD + skc * 8) = rb[i]; }
;     }
;     if (kt + 2 < nk) {
; #pragma unroll
;       for (int i = 0; i < 4; ++i) { ra[i] = *(const u32x4*)(Ag + (size_t)(64 * i) * K + (kt + 2) * 64); rb[i] = *(const u32x4*)(Bg[i] + (kt + 2) * 64); }
;     }
;     __builtin_amdgcn_sched_barrier(0);
;     const u16* as = As0 + (kt & 1) * 256 * LD + (wr * 128 + l31) * LD + h * 8;
;     const u16* bs = Bs0 + (kt & 1) * 256 * LD + (wc * 64 + l31) * LD + h * 8;
;     if (domma)
; #pragma unroll
;     for (int ks = 0; ks < 4; ++ks) {
;       bf16x8 wf[2], xf[4];
; #pragma unroll
;       for (int ct = 0; ct < 2; ++ct) wf[ct] = *(const bf16x8*)(bs + ct * 32 * LD + ks * 16);
; #pragma unroll
;       for (int tt = 0; tt < 4; ++tt) xf[tt] = *(const bf16x8*)(as + tt * 32 * LD + ks * 16);
; #pragma unroll
;       for (int ct = 0; ct < 2; ++ct)
; #pragma unroll
;         for (int tt = 0; tt < 4; ++tt) acc[ct][tt] = __builtin_amdgcn_mfma_f32_32x32x16_bf16(wf[ct], xf[tt], acc[ct][tt], 0, 0, 0);
;     }
;     __builtin_amdgcn_sched_barrier(0);
;   }
	v_mfma_f32_32x32x16_bf16 v[50:65], v[216:219], v[232:235], v[50:65]
	ds_read_b128 v[228:231], v147 offset:46144
	s_waitcnt vmcnt(15)
	ds_write_b128 v152, v[180:183] offset:9216
	v_mfma_f32_32x32x16_bf16 v[34:49], v[224:227], v[232:235], v[34:49]
	s_waitcnt lgkmcnt(8)
	v_mfma_f32_32x32x16_bf16 v[18:33], v[216:219], v[236:239], v[18:33]
	ds_read_b128 v[232:235], v147 offset:50752
	global_load_dwordx4 v[180:183], v153, s[84:85] offset:512
	v_mfma_f32_32x32x16_bf16 v[2:17], v[224:227], v[236:239], v[2:17]
	s_waitcnt vmcnt(15)
	ds_write_b128 v149, v[138:141] offset:18432
	s_waitcnt lgkmcnt(7)
	v_mfma_f32_32x32x16_bf16 v[98:113], v[208:211], v[240:243], v[98:113]
	ds_read_b128 v[216:219], v148 offset:36960
	s_waitcnt lgkmcnt(6)
	v_mfma_f32_32x32x16_bf16 v[114:129], v[212:215], v[240:243], v[114:129]
	ds_read_b128 v[236:239], v147 offset:36960
	global_load_dwordx4 v[138:141], v153, s[78:79] offset:512
	s_waitcnt lgkmcnt(6)
	v_mfma_f32_32x32x16_bf16 v[82:97], v[208:211], v[244:247], v[82:97]
	ds_read_b128 v[224:227], v148 offset:41568
	s_waitcnt vmcnt(15)
	ds_write_b128 v152, v[184:187] offset:18432
	v_mfma_f32_32x32x16_bf16 v[66:81], v[212:215], v[244:247], v[66:81]
	ds_read_b128 v[240:243], v147 offset:41568
	s_waitcnt lgkmcnt(8)
	v_mfma_f32_32x32x16_bf16 v[50:65], v[208:211], v[228:231], v[50:65]
	ds_read_b128 v[244:247], v147 offset:46176
	global_load_dwordx4 v[184:187], v153, s[86:87] offset:512
	v_mfma_f32_32x32x16_bf16 v[34:49], v[212:215], v[228:231], v[34:49]
	s_waitcnt vmcnt(15)
	ds_write_b128 v149, v[142:145] offset:27648
	s_waitcnt lgkmcnt(8)
	v_mfma_f32_32x32x16_bf16 v[18:33], v[208:211], v[232:235], v[18:33]
	ds_read_b128 v[228:231], v147 offset:50784
	v_mfma_f32_32x32x16_bf16 v[2:17], v[212:215], v[232:235], v[2:17]
	global_load_dwordx4 v[142:145], v153, s[80:81] offset:512
	s_waitcnt lgkmcnt(6)
	v_mfma_f32_32x32x16_bf16 v[98:113], v[216:219], v[236:239], v[98:113]
	s_waitcnt vmcnt(15)
	ds_write_b128 v152, v[188:191] offset:27648
	s_waitcnt lgkmcnt(6)
	v_mfma_f32_32x32x16_bf16 v[114:129], v[224:227], v[236:239], v[114:129]
	s_waitcnt lgkmcnt(4)
	v_mfma_f32_32x32x16_bf16 v[82:97], v[216:219], v[240:243], v[82:97]
	global_load_dwordx4 v[188:191], v153, s[92:93] offset:512
	v_mfma_f32_32x32x16_bf16 v[66:81], v[224:227], v[240:243], v[66:81]
	s_waitcnt lgkmcnt(3)
	v_mfma_f32_32x32x16_bf16 v[50:65], v[216:219], v[244:247], v[50:65]
	v_mfma_f32_32x32x16_bf16 v[34:49], v[224:227], v[244:247], v[34:49]
	s_waitcnt lgkmcnt(1)
	v_mfma_f32_32x32x16_bf16 v[18:33], v[216:219], v[228:231], v[18:33]
	v_mfma_f32_32x32x16_bf16 v[2:17], v[224:227], v[228:231], v[2:17]
	s_waitcnt lgkmcnt(0)
	s_barrier
	ds_read_b128 v[208:211], v148
	ds_read_b128 v[228:231], v147
	ds_read_b128 v[212:215], v148 offset:4608
	ds_read_b128 v[232:235], v147 offset:4608
	ds_read_b128 v[236:239], v147 offset:9216
	ds_read_b128 v[240:243], v147 offset:13824
	s_waitcnt lgkmcnt(4)
	v_mfma_f32_32x32x16_bf16 v[98:113], v[208:211], v[228:231], v[98:113]
	ds_read_b128 v[216:219], v148 offset:32
	s_waitcnt lgkmcnt(4)
	v_mfma_f32_32x32x16_bf16 v[114:129], v[212:215], v[228:231], v[114:129]
	ds_read_b128 v[244:247], v147 offset:32
	s_waitcnt lgkmcnt(4)
	v_mfma_f32_32x32x16_bf16 v[82:97], v[208:211], v[232:235], v[82:97]
	ds_read_b128 v[224:227], v148 offset:4640
	v_mfma_f32_32x32x16_bf16 v[66:81], v[212:215], v[232:235], v[66:81]
	ds_read_b128 v[228:231], v147 offset:4640
	s_waitcnt vmcnt(15)
	ds_write_b128 v149, v[160:163] offset:36864
	s_waitcnt lgkmcnt(6)
	v_mfma_f32_32x32x16_bf16 v[50:65], v[208:211], v[236:239], v[50:65]
	ds_read_b128 v[232:235], v147 offset:9248
	v_mfma_f32_32x32x16_bf16 v[34:49], v[212:215], v[236:239], v[34:49]
	global_load_dwordx4 v[160:163], v153, s[74:75] offset:640
	s_waitcnt lgkmcnt(6)
	v_mfma_f32_32x32x16_bf16 v[18:33], v[208:211], v[240:243], v[18:33]
	ds_read_b128 v[236:239], v147 offset:13856
	s_waitcnt vmcnt(15)
	ds_write_b128 v152, v[192:195] offset:36864
	v_mfma_f32_32x32x16_bf16 v[2:17], v[212:215], v[240:243], v[2:17]
	s_waitcnt lgkmcnt(6)
	v_mfma_f32_32x32x16_bf16 v[98:113], v[216:219], v[244:247], v[98:113]
	ds_read_b128 v[208:211], v148 offset:64
	global_load_dwordx4 v[192:195], v153, s[82:83] offset:640
	s_waitcnt lgkmcnt(6)
	v_mfma_f32_32x32x16_bf16 v[114:129], v[224:227], v[244:247], v[114:129]
	ds_read_b128 v[240:243], v147 offset:64
	s_waitcnt vmcnt(15)
	ds_write_b128 v149, v[164:167] offset:46080
	s_waitcnt lgkmcnt(7)
	v_mfma_f32_32x32x16_bf16 v[82:97], v[216:219], v[228:231], v[82:97]
	ds_read_b128 v[212:215], v148 offset:4672
	v_mfma_f32_32x32x16_bf16 v[66:81], v[224:227], v[228:231], v[66:81]
	ds_read_b128 v[244:247], v147 offset:4672
	global_load_dwordx4 v[164:167], v153, s[76:77] offset:640
	s_waitcnt lgkmcnt(7)
	v_mfma_f32_32x32x16_bf16 v[50:65], v[216:219], v[232:235], v[50:65]
	ds_read_b128 v[228:231], v147 offset:9280
	s_waitcnt vmcnt(15)
	ds_write_b128 v152, v[196:199] offset:46080
	v_mfma_f32_32x32x16_bf16 v[34:49], v[224:227], v[232:235], v[34:49]
	s_waitcnt lgkmcnt(8)
	v_mfma_f32_32x32x16_bf16 v[18:33], v[216:219], v[236:239], v[18:33]
	ds_read_b128 v[232:235], v147 offset:13888
	global_load_dwordx4 v[196:199], v153, s[84:85] offset:640
	v_mfma_f32_32x32x16_bf16 v[2:17], v[224:227], v[236:239], v[2:17]
	s_waitcnt vmcnt(15)
	ds_write_b128 v149, v[168:171] offset:55296
	s_waitcnt lgkmcnt(7)
	v_mfma_f32_32x32x16_bf16 v[98:113], v[208:211], v[240:243], v[98:113]
	ds_read_b128 v[216:219], v148 offset:96
	s_waitcnt lgkmcnt(6)
	v_mfma_f32_32x32x16_bf16 v[114:129], v[212:215], v[240:243], v[114:129]
	ds_read_b128 v[236:239], v147 offset:96
	global_load_dwordx4 v[168:171], v153, s[78:79] offset:640
	s_waitcnt lgkmcnt(6)
;     ...
;   for (int kt = 0; kt < nk; ++kt) {
;     __syncthreads();
;     if (kt + 1 < nk) {
;       u16* aw = As0 + ((kt + 1) & 1) * 256 * LD;
;       u16* bw = Bs0 + ((kt + 1) & 1) * 256 * LD;
; #pragma unroll
;       for (int i = 0; i < 4; ++i) { *(u32x4*)(aw + (srow + 64 * i) * LD + skc * 8) = ra[i]; *(u32x4*)(bw + (srow + 64 * i) * LD + skc * 8) = rb[i]; }
;     }
;     if (kt + 2 < nk) {
; #pragma unroll
;       for (int i = 0; i < 4; ++i) { ra[i] = *(const u32x4*)(Ag + (size_t)(64 * i) * K + (kt + 2) * 64); rb[i] = *(const u32x4*)(Bg[i] + (kt + 2) * 64); }
;     }
;     __builtin_amdgcn_sched_barrier(0);
;     const u16* as = As0 + (kt & 1) * 256 * LD + (wr * 128 + l31) * LD + h * 8;
;     const u16* bs = Bs0 + (kt & 1) * 256 * LD + (wc * 64 + l31) * LD + h * 8;
;     if (domma)
; #pragma unroll
;     for (int ks = 0; ks < 4; ++ks) {
;       bf16x8 wf[2], xf[4];
; #pragma unroll
;       for (int ct = 0; ct < 2; ++ct) wf[ct] = *(const bf16x8*)(bs + ct * 32 * LD + ks * 16);
; #pragma unroll
;       for (int tt = 0; tt < 4; ++tt) xf[tt] = *(const bf16x8*)(as + tt * 32 * LD + ks * 16);
; #pragma unroll
;       for (int ct = 0; ct < 2; ++ct)
; #pragma unroll
;         for (int tt = 0; tt < 4; ++tt) acc[ct][tt] = __builtin_amdgcn_mfma_f32_32x32x16_bf16(wf[ct], xf[tt], acc[ct][tt], 0, 0, 0);
;     }
;     __builtin_amdgcn_sched_barrier(0);
;   }
	v_mfma_f32_32x32x16_bf16 v[82:97], v[208:211], v[244:247], v[82:97]
	ds_read_b128 v[224:227], v148 offset:4704
	s_waitcnt vmcnt(15)
	ds_write_b128 v152, v[200:203] offset:55296
	v_mfma_f32_32x32x16_bf16 v[66:81], v[212:215], v[244:247], v[66:81]
	ds_read_b128 v[240:243], v147 offset:4704
	s_waitcnt lgkmcnt(8)
	v_mfma_f32_32x32x16_bf16 v[50:65], v[208:211], v[228:231], v[50:65]
	ds_read_b128 v[244:247], v147 offset:9312
	global_load_dwordx4 v[200:203], v153, s[86:87] offset:640
	v_mfma_f32_32x32x16_bf16 v[34:49], v[212:215], v[228:231], v[34:49]
	s_waitcnt vmcnt(15)
	ds_write_b128 v149, v[172:175] offset:64512
	s_waitcnt lgkmcnt(8)
	v_mfma_f32_32x32x16_bf16 v[18:33], v[208:211], v[232:235], v[18:33]
	ds_read_b128 v[228:231], v147 offset:13920
	v_mfma_f32_32x32x16_bf16 v[2:17], v[212:215], v[232:235], v[2:17]
	global_load_dwordx4 v[172:175], v153, s[80:81] offset:640
	s_waitcnt lgkmcnt(6)
	v_mfma_f32_32x32x16_bf16 v[98:113], v[216:219], v[236:239], v[98:113]
	s_waitcnt vmcnt(15)
	ds_write_b128 v152, v[204:207] offset:64512
	s_waitcnt lgkmcnt(6)
	v_mfma_f32_32x32x16_bf16 v[114:129], v[224:227], v[236:239], v[114:129]
	s_waitcnt lgkmcnt(4)
	v_mfma_f32_32x32x16_bf16 v[82:97], v[216:219], v[240:243], v[82:97]
	global_load_dwordx4 v[204:207], v153, s[92:93] offset:640
	v_mfma_f32_32x32x16_bf16 v[66:81], v[224:227], v[240:243], v[66:81]
	s_waitcnt lgkmcnt(3)
	v_mfma_f32_32x32x16_bf16 v[50:65], v[216:219], v[244:247], v[50:65]
	v_mfma_f32_32x32x16_bf16 v[34:49], v[224:227], v[244:247], v[34:49]
	s_waitcnt lgkmcnt(1)
	v_mfma_f32_32x32x16_bf16 v[18:33], v[216:219], v[228:231], v[18:33]
	v_mfma_f32_32x32x16_bf16 v[2:17], v[224:227], v[228:231], v[2:17]
	s_waitcnt lgkmcnt(0)
	s_barrier
	ds_read_b128 v[208:211], v148 offset:36864
	ds_read_b128 v[228:231], v147 offset:36864
	ds_read_b128 v[212:215], v148 offset:41472
	ds_read_b128 v[232:235], v147 offset:41472
	ds_read_b128 v[236:239], v147 offset:46080
	ds_read_b128 v[240:243], v147 offset:50688
	s_waitcnt lgkmcnt(4)
	v_mfma_f32_32x32x16_bf16 v[98:113], v[208:211], v[228:231], v[98:113]
	ds_read_b128 v[216:219], v148 offset:36896
	s_waitcnt lgkmcnt(4)
	v_mfma_f32_32x32x16_bf16 v[114:129], v[212:215], v[228:231], v[114:129]
	ds_read_b128 v[244:247], v147 offset:36896
	s_waitcnt lgkmcnt(4)
	v_mfma_f32_32x32x16_bf16 v[82:97], v[208:211], v[232:235], v[82:97]
	ds_read_b128 v[224:227], v148 offset:41504
	v_mfma_f32_32x32x16_bf16 v[66:81], v[212:215], v[232:235], v[66:81]
	ds_read_b128 v[228:231], v147 offset:41504
	s_waitcnt vmcnt(15)
	ds_write_b128 v149, v[130:133]
	s_waitcnt lgkmcnt(6)
	v_mfma_f32_32x32x16_bf16 v[50:65], v[208:211], v[236:239], v[50:65]
	ds_read_b128 v[232:235], v147 offset:46112
	v_mfma_f32_32x32x16_bf16 v[34:49], v[212:215], v[236:239], v[34:49]
	global_load_dwordx4 v[130:133], v153, s[74:75] offset:768
	s_waitcnt lgkmcnt(6)
	v_mfma_f32_32x32x16_bf16 v[18:33], v[208:211], v[240:243], v[18:33]
	ds_read_b128 v[236:239], v147 offset:50720
	s_waitcnt vmcnt(15)
	ds_write_b128 v152, v[176:179]
	v_mfma_f32_32x32x16_bf16 v[2:17], v[212:215], v[240:243], v[2:17]
	s_waitcnt lgkmcnt(6)
	v_mfma_f32_32x32x16_bf16 v[98:113], v[216:219], v[244:247], v[98:113]
	ds_read_b128 v[208:211], v148 offset:36928
	global_load_dwordx4 v[176:179], v153, s[82:83] offset:768
	s_waitcnt lgkmcnt(6)
	v_mfma_f32_32x32x16_bf16 v[114:129], v[224:227], v[244:247], v[114:129]
	ds_read_b128 v[240:243], v147 offset:36928
	s_waitcnt vmcnt(15)
	ds_write_b128 v149, v[134:137] offset:9216
	s_waitcnt lgkmcnt(7)
	v_mfma_f32_32x32x16_bf16 v[82:97], v[216:219], v[228:231], v[82:97]
	ds_read_b128 v[212:215], v148 offset:41536
	v_mfma_f32_32x32x16_bf16 v[66:81], v[224:227], v[228:231], v[66:81]
	ds_read_b128 v[244:247], v147 offset:41536
	global_load_dwordx4 v[134:137], v153, s[76:77] offset:768
	s_waitcnt lgkmcnt(7)
	v_mfma_f32_32x32x16_bf16 v[50:65], v[216:219], v[232:235], v[50:65]
	ds_read_b128 v[228:231], v147 offset:46144
	s_waitcnt vmcnt(15)
	ds_write_b128 v152, v[180:183] offset:9216
	v_mfma_f32_32x32x16_bf16 v[34:49], v[224:227], v[232:235], v[34:49]
	s_waitcnt lgkmcnt(8)
	v_mfma_f32_32x32x16_bf16 v[18:33], v[216:219], v[236:239], v[18:33]
	ds_read_b128 v[232:235], v147 offset:50752
	global_load_dwordx4 v[180:183], v153, s[84:85] offset:768
	v_mfma_f32_32x32x16_bf16 v[2:17], v[224:227], v[236:239], v[2:17]
	s_waitcnt vmcnt(15)
	ds_write_b128 v149, v[138:141] offset:18432
	s_waitcnt lgkmcnt(7)
	v_mfma_f32_32x32x16_bf16 v[98:113], v[208:211], v[240:243], v[98:113]
	ds_read_b128 v[216:219], v148 offset:36960
	s_waitcnt lgkmcnt(6)
	v_mfma_f32_32x32x16_bf16 v[114:129], v[212:215], v[240:243], v[114:129]
	ds_read_b128 v[236:239], v147 offset:36960
	global_load_dwordx4 v[138:141], v153, s[78:79] offset:768
	s_waitcnt lgkmcnt(6)
	v_mfma_f32_32x32x16_bf16 v[82:97], v[208:211], v[244:247], v[82:97]
	ds_read_b128 v[224:227], v148 offset:41568
	s_waitcnt vmcnt(15)
	ds_write_b128 v152, v[184:187] offset:18432
	v_mfma_f32_32x32x16_bf16 v[66:81], v[212:215], v[244:247], v[66:81]
	ds_read_b128 v[240:243], v147 offset:41568
	s_waitcnt lgkmcnt(8)
	v_mfma_f32_32x32x16_bf16 v[50:65], v[208:211], v[228:231], v[50:65]
	ds_read_b128 v[244:247], v147 offset:46176
	global_load_dwordx4 v[184:187], v153, s[86:87] offset:768
	v_mfma_f32_32x32x16_bf16 v[34:49], v[212:215], v[228:231], v[34:49]
	s_waitcnt vmcnt(15)
	ds_write_b128 v149, v[142:145] offset:27648
	s_waitcnt lgkmcnt(8)
	v_mfma_f32_32x32x16_bf16 v[18:33], v[208:211], v[232:235], v[18:33]
	ds_read_b128 v[228:231], v147 offset:50784
	v_mfma_f32_32x32x16_bf16 v[2:17], v[212:215], v[232:235], v[2:17]
	global_load_dwordx4 v[142:145], v153, s[80:81] offset:768
	s_waitcnt lgkmcnt(6)
	v_mfma_f32_32x32x16_bf16 v[98:113], v[216:219], v[236:239], v[98:113]
	s_waitcnt vmcnt(15)
	ds_write_b128 v152, v[188:191] offset:27648
	s_waitcnt lgkmcnt(6)
	v_mfma_f32_32x32x16_bf16 v[114:129], v[224:227], v[236:239], v[114:129]
	s_waitcnt lgkmcnt(4)
	v_mfma_f32_32x32x16_bf16 v[82:97], v[216:219], v[240:243], v[82:97]
	global_load_dwordx4 v[188:191], v153, s[92:93] offset:768
	v_mfma_f32_32x32x16_bf16 v[66:81], v[224:227], v[240:243], v[66:81]
	s_waitcnt lgkmcnt(3)
	v_mfma_f32_32x32x16_bf16 v[50:65], v[216:219], v[244:247], v[50:65]
	v_mfma_f32_32x32x16_bf16 v[34:49], v[224:227], v[244:247], v[34:49]
	s_waitcnt lgkmcnt(1)
	v_mfma_f32_32x32x16_bf16 v[18:33], v[216:219], v[228:231], v[18:33]
	v_mfma_f32_32x32x16_bf16 v[2:17], v[224:227], v[228:231], v[2:17]
	s_waitcnt lgkmcnt(0)
	s_barrier
;     ...
;   for (int kt = 0; kt < nk; ++kt) {
;     __syncthreads();
;     if (kt + 1 < nk) {
;       u16* aw = As0 + ((kt + 1) & 1) * 256 * LD;
;       u16* bw = Bs0 + ((kt + 1) & 1) * 256 * LD;
; #pragma unroll
;       for (int i = 0; i < 4; ++i) { *(u32x4*)(aw + (srow + 64 * i) * LD + skc * 8) = ra[i]; *(u32x4*)(bw + (srow + 64 * i) * LD + skc * 8) = rb[i]; }
;     }
;     if (kt + 2 < nk) {
; #pragma unroll
;       for (int i = 0; i < 4; ++i) { ra[i] = *(const u32x4*)(Ag + (size_t)(64 * i) * K + (kt + 2) * 64); rb[i] = *(const u32x4*)(Bg[i] + (kt + 2) * 64); }
;     }
;     __builtin_amdgcn_sched_barrier(0);
;     const u16* as = As0 + (kt & 1) * 256 * LD + (wr * 128 + l31) * LD + h * 8;
;     const u16* bs = Bs0 + (kt & 1) * 256 * LD + (wc * 64 + l31) * LD + h * 8;
;     if (domma)
; #pragma unroll
;     for (int ks = 0; ks < 4; ++ks) {
;       bf16x8 wf[2], xf[4];
; #pragma unroll
;       for (int ct = 0; ct < 2; ++ct) wf[ct] = *(const bf16x8*)(bs + ct * 32 * LD + ks * 16);
; #pragma unroll
;       for (int tt = 0; tt < 4; ++tt) xf[tt] = *(const bf16x8*)(as + tt * 32 * LD + ks * 16);
; #pragma unroll
;       for (int ct = 0; ct < 2; ++ct)
; #pragma unroll
;         for (int tt = 0; tt < 4; ++tt) acc[ct][tt] = __builtin_amdgcn_mfma_f32_32x32x16_bf16(wf[ct], xf[tt], acc[ct][tt], 0, 0, 0);
;     }
;     __builtin_amdgcn_sched_barrier(0);
;   }
	ds_read_b128 v[208:211], v148
	ds_read_b128 v[228:231], v147
	ds_read_b128 v[212:215], v148 offset:4608
	ds_read_b128 v[232:235], v147 offset:4608
	ds_read_b128 v[236:239], v147 offset:9216
	ds_read_b128 v[240:243], v147 offset:13824
	s_waitcnt lgkmcnt(4)
	v_mfma_f32_32x32x16_bf16 v[98:113], v[208:211], v[228:231], v[98:113]
	ds_read_b128 v[216:219], v148 offset:32
	s_waitcnt lgkmcnt(4)
	v_mfma_f32_32x32x16_bf16 v[114:129], v[212:215], v[228:231], v[114:129]
	ds_read_b128 v[244:247], v147 offset:32
	s_waitcnt lgkmcnt(4)
	v_mfma_f32_32x32x16_bf16 v[82:97], v[208:211], v[232:235], v[82:97]
	ds_read_b128 v[224:227], v148 offset:4640
	v_mfma_f32_32x32x16_bf16 v[66:81], v[212:215], v[232:235], v[66:81]
	ds_read_b128 v[228:231], v147 offset:4640
	s_waitcnt vmcnt(15)
	ds_write_b128 v149, v[160:163] offset:36864
	s_waitcnt lgkmcnt(6)
	v_mfma_f32_32x32x16_bf16 v[50:65], v[208:211], v[236:239], v[50:65]
	ds_read_b128 v[232:235], v147 offset:9248
	v_mfma_f32_32x32x16_bf16 v[34:49], v[212:215], v[236:239], v[34:49]
	global_load_dwordx4 v[160:163], v153, s[74:75] offset:896
	s_waitcnt lgkmcnt(6)
	v_mfma_f32_32x32x16_bf16 v[18:33], v[208:211], v[240:243], v[18:33]
	ds_read_b128 v[236:239], v147 offset:13856
	s_waitcnt vmcnt(15)
	ds_write_b128 v152, v[192:195] offset:36864
	v_mfma_f32_32x32x16_bf16 v[2:17], v[212:215], v[240:243], v[2:17]
	s_waitcnt lgkmcnt(6)
	v_mfma_f32_32x32x16_bf16 v[98:113], v[216:219], v[244:247], v[98:113]
	ds_read_b128 v[208:211], v148 offset:64
	global_load_dwordx4 v[192:195], v153, s[82:83] offset:896
	s_waitcnt lgkmcnt(6)
	v_mfma_f32_32x32x16_bf16 v[114:129], v[224:227], v[244:247], v[114:129]
	ds_read_b128 v[240:243], v147 offset:64
	s_waitcnt vmcnt(15)
	ds_write_b128 v149, v[164:167] offset:46080
	s_waitcnt lgkmcnt(7)
	v_mfma_f32_32x32x16_bf16 v[82:97], v[216:219], v[228:231], v[82:97]
	ds_read_b128 v[212:215], v148 offset:4672
	v_mfma_f32_32x32x16_bf16 v[66:81], v[224:227], v[228:231], v[66:81]
	ds_read_b128 v[244:247], v147 offset:4672
	global_load_dwordx4 v[164:167], v153, s[76:77] offset:896
	s_waitcnt lgkmcnt(7)
	v_mfma_f32_32x32x16_bf16 v[50:65], v[216:219], v[232:235], v[50:65]
	ds_read_b128 v[228:231], v147 offset:9280
	s_waitcnt vmcnt(15)
	ds_write_b128 v152, v[196:199] offset:46080
	v_mfma_f32_32x32x16_bf16 v[34:49], v[224:227], v[232:235], v[34:49]
	s_waitcnt lgkmcnt(8)
	v_mfma_f32_32x32x16_bf16 v[18:33], v[216:219], v[236:239], v[18:33]
	ds_read_b128 v[232:235], v147 offset:13888
	global_load_dwordx4 v[196:199], v153, s[84:85] offset:896
	v_mfma_f32_32x32x16_bf16 v[2:17], v[224:227], v[236:239], v[2:17]
	s_waitcnt vmcnt(15)
	ds_write_b128 v149, v[168:171] offset:55296
	s_waitcnt lgkmcnt(7)
	v_mfma_f32_32x32x16_bf16 v[98:113], v[208:211], v[240:243], v[98:113]
	ds_read_b128 v[216:219], v148 offset:96
	s_waitcnt lgkmcnt(6)
	v_mfma_f32_32x32x16_bf16 v[114:129], v[212:215], v[240:243], v[114:129]
	ds_read_b128 v[236:239], v147 offset:96
	global_load_dwordx4 v[168:171], v153, s[78:79] offset:896
	s_waitcnt lgkmcnt(6)
	v_mfma_f32_32x32x16_bf16 v[82:97], v[208:211], v[244:247], v[82:97]
	ds_read_b128 v[224:227], v148 offset:4704
	s_waitcnt vmcnt(15)
	ds_write_b128 v152, v[200:203] offset:55296
	v_mfma_f32_32x32x16_bf16 v[66:81], v[212:215], v[244:247], v[66:81]
	ds_read_b128 v[240:243], v147 offset:4704
	s_waitcnt lgkmcnt(8)
	v_mfma_f32_32x32x16_bf16 v[50:65], v[208:211], v[228:231], v[50:65]
	ds_read_b128 v[244:247], v147 offset:9312
	global_load_dwordx4 v[200:203], v153, s[86:87] offset:896
	v_mfma_f32_32x32x16_bf16 v[34:49], v[212:215], v[228:231], v[34:49]
	s_waitcnt vmcnt(15)
	ds_write_b128 v149, v[172:175] offset:64512
	s_waitcnt lgkmcnt(8)
	v_mfma_f32_32x32x16_bf16 v[18:33], v[208:211], v[232:235], v[18:33]
	ds_read_b128 v[228:231], v147 offset:13920
	v_mfma_f32_32x32x16_bf16 v[2:17], v[212:215], v[232:235], v[2:17]
	global_load_dwordx4 v[172:175], v153, s[80:81] offset:896
	s_waitcnt lgkmcnt(6)
	v_mfma_f32_32x32x16_bf16 v[98:113], v[216:219], v[236:239], v[98:113]
	s_waitcnt vmcnt(15)
	ds_write_b128 v152, v[204:207] offset:64512
	s_waitcnt lgkmcnt(6)
	v_mfma_f32_32x32x16_bf16 v[114:129], v[224:227], v[236:239], v[114:129]
	s_waitcnt lgkmcnt(4)
	v_mfma_f32_32x32x16_bf16 v[82:97], v[216:219], v[240:243], v[82:97]
	global_load_dwordx4 v[204:207], v153, s[92:93] offset:896
	v_mfma_f32_32x32x16_bf16 v[66:81], v[224:227], v[240:243], v[66:81]
	s_waitcnt lgkmcnt(3)
	v_mfma_f32_32x32x16_bf16 v[50:65], v[216:219], v[244:247], v[50:65]
	v_mfma_f32_32x32x16_bf16 v[34:49], v[224:227], v[244:247], v[34:49]
	s_waitcnt lgkmcnt(1)
	v_mfma_f32_32x32x16_bf16 v[18:33], v[216:219], v[228:231], v[18:33]
	v_mfma_f32_32x32x16_bf16 v[2:17], v[224:227], v[228:231], v[2:17]
	s_waitcnt lgkmcnt(0)
	s_barrier
;     ...
;   for (int kt = 0; kt < nk; ++kt) {
;     __syncthreads();
;     if (kt + 1 < nk) {
;       u16* aw = As0 + ((kt + 1) & 1) * 256 * LD;
;       u16* bw = Bs0 + ((kt + 1) & 1) * 256 * LD;
; #pragma unroll
;       for (int i = 0; i < 4; ++i) { *(u32x4*)(aw + (srow + 64 * i) * LD + skc * 8) = ra[i]; *(u32x4*)(bw + (srow + 64 * i) * LD + skc * 8) = rb[i]; }
;     }
;     if (kt + 2 < nk) {
; #pragma unroll
;       for (int i = 0; i < 4; ++i) { ra[i] = *(const u32x4*)(Ag + (size_t)(64 * i) * K + (kt + 2) * 64); rb[i] = *(const u32x4*)(Bg[i] + (kt + 2) * 64); }
;     }
;     __builtin_amdgcn_sched_barrier(0);
;     const u16* as = As0 + (kt & 1) * 256 * LD + (wr * 128 + l31) * LD + h * 8;
;     const u16* bs = Bs0 + (kt & 1) * 256 * LD + (wc * 64 + l31) * LD + h * 8;
;     if (domma)
; #pragma unroll
;     for (int ks = 0; ks < 4; ++ks) {
;       bf16x8 wf[2], xf[4];
; #pragma unroll
;       for (int ct = 0; ct < 2; ++ct) wf[ct] = *(const bf16x8*)(bs + ct * 32 * LD + ks * 16);
; #pragma unroll
;       for (int tt = 0; tt < 4; ++tt) xf[tt] = *(const bf16x8*)(as + tt * 32 * LD + ks * 16);
; #pragma unroll
;       for (int ct = 0; ct < 2; ++ct)
; #pragma unroll
;         for (int tt = 0; tt < 4; ++tt) acc[ct][tt] = __builtin_amdgcn_mfma_f32_32x32x16_bf16(wf[ct], xf[tt], acc[ct][tt], 0, 0, 0);
;     }
;     __builtin_amdgcn_sched_barrier(0);
;   }
	ds_read_b128 v[208:211], v148 offset:36864
	ds_read_b128 v[228:231], v147 offset:36864
	ds_read_b128 v[212:215], v148 offset:41472
	ds_read_b128 v[232:235], v147 offset:41472
	ds_read_b128 v[236:239], v147 offset:46080
	ds_read_b128 v[240:243], v147 offset:50688
	s_waitcnt lgkmcnt(4)
	v_mfma_f32_32x32x16_bf16 v[98:113], v[208:211], v[228:231], v[98:113]
	ds_read_b128 v[216:219], v148 offset:36896
	s_waitcnt lgkmcnt(4)
	v_mfma_f32_32x32x16_bf16 v[114:129], v[212:215], v[228:231], v[114:129]
	ds_read_b128 v[244:247], v147 offset:36896
	s_waitcnt lgkmcnt(4)
	v_mfma_f32_32x32x16_bf16 v[82:97], v[208:211], v[232:235], v[82:97]
	ds_read_b128 v[224:227], v148 offset:41504
	v_mfma_f32_32x32x16_bf16 v[66:81], v[212:215], v[232:235], v[66:81]
	ds_read_b128 v[228:231], v147 offset:41504
	s_waitcnt vmcnt(15)
	ds_write_b128 v149, v[130:133]
	s_waitcnt lgkmcnt(6)
	v_mfma_f32_32x32x16_bf16 v[50:65], v[208:211], v[236:239], v[50:65]
	ds_read_b128 v[232:235], v147 offset:46112
	v_mfma_f32_32x32x16_bf16 v[34:49], v[212:215], v[236:239], v[34:49]
	global_load_dwordx4 v[130:133], v153, s[74:75] offset:1024
	s_waitcnt lgkmcnt(6)
	v_mfma_f32_32x32x16_bf16 v[18:33], v[208:211], v[240:243], v[18:33]
	ds_read_b128 v[236:239], v147 offset:50720
	s_waitcnt vmcnt(15)
	ds_write_b128 v152, v[176:179]
	v_mfma_f32_32x32x16_bf16 v[2:17], v[212:215], v[240:243], v[2:17]
	s_waitcnt lgkmcnt(6)
	v_mfma_f32_32x32x16_bf16 v[98:113], v[216:219], v[244:247], v[98:113]
	ds_read_b128 v[208:211], v148 offset:36928
	global_load_dwordx4 v[176:179], v153, s[82:83] offset:1024
	s_waitcnt lgkmcnt(6)
	v_mfma_f32_32x32x16_bf16 v[114:129], v[224:227], v[244:247], v[114:129]
	ds_read_b128 v[240:243], v147 offset:36928
	s_waitcnt vmcnt(15)
	ds_write_b128 v149, v[134:137] offset:9216
	s_waitcnt lgkmcnt(7)
	v_mfma_f32_32x32x16_bf16 v[82:97], v[216:219], v[228:231], v[82:97]
	ds_read_b128 v[212:215], v148 offset:41536
	v_mfma_f32_32x32x16_bf16 v[66:81], v[224:227], v[228:231], v[66:81]
	ds_read_b128 v[244:247], v147 offset:41536
	global_load_dwordx4 v[134:137], v153, s[76:77] offset:1024
	s_waitcnt lgkmcnt(7)
	v_mfma_f32_32x32x16_bf16 v[50:65], v[216:219], v[232:235], v[50:65]
	ds_read_b128 v[228:231], v147 offset:46144
	s_waitcnt vmcnt(15)
	ds_write_b128 v152, v[180:183] offset:9216
	v_mfma_f32_32x32x16_bf16 v[34:49], v[224:227], v[232:235], v[34:49]
	s_waitcnt lgkmcnt(8)
	v_mfma_f32_32x32x16_bf16 v[18:33], v[216:219], v[236:239], v[18:33]
	ds_read_b128 v[232:235], v147 offset:50752
	global_load_dwordx4 v[180:183], v153, s[84:85] offset:1024
	v_mfma_f32_32x32x16_bf16 v[2:17], v[224:227], v[236:239], v[2:17]
	s_waitcnt vmcnt(15)
	ds_write_b128 v149, v[138:141] offset:18432
	s_waitcnt lgkmcnt(7)
	v_mfma_f32_32x32x16_bf16 v[98:113], v[208:211], v[240:243], v[98:113]
	ds_read_b128 v[216:219], v148 offset:36960
	s_waitcnt lgkmcnt(6)
	v_mfma_f32_32x32x16_bf16 v[114:129], v[212:215], v[240:243], v[114:129]
	ds_read_b128 v[236:239], v147 offset:36960
	global_load_dwordx4 v[138:141], v153, s[78:79] offset:1024
	s_waitcnt lgkmcnt(6)
	v_mfma_f32_32x32x16_bf16 v[82:97], v[208:211], v[244:247], v[82:97]
	ds_read_b128 v[224:227], v148 offset:41568
	s_waitcnt vmcnt(15)
	ds_write_b128 v152, v[184:187] offset:18432
	v_mfma_f32_32x32x16_bf16 v[66:81], v[212:215], v[244:247], v[66:81]
	ds_read_b128 v[240:243], v147 offset:41568
	s_waitcnt lgkmcnt(8)
	v_mfma_f32_32x32x16_bf16 v[50:65], v[208:211], v[228:231], v[50:65]
	ds_read_b128 v[244:247], v147 offset:46176
	global_load_dwordx4 v[184:187], v153, s[86:87] offset:1024
	v_mfma_f32_32x32x16_bf16 v[34:49], v[212:215], v[228:231], v[34:49]
	s_waitcnt vmcnt(15)
	ds_write_b128 v149, v[142:145] offset:27648
	s_waitcnt lgkmcnt(8)
	v_mfma_f32_32x32x16_bf16 v[18:33], v[208:211], v[232:235], v[18:33]
	ds_read_b128 v[228:231], v147 offset:50784
	v_mfma_f32_32x32x16_bf16 v[2:17], v[212:215], v[232:235], v[2:17]
	global_load_dwordx4 v[142:145], v153, s[80:81] offset:1024
	s_waitcnt lgkmcnt(6)
	v_mfma_f32_32x32x16_bf16 v[98:113], v[216:219], v[236:239], v[98:113]
	s_waitcnt vmcnt(15)
	ds_write_b128 v152, v[188:191] offset:27648
	s_waitcnt lgkmcnt(6)
	v_mfma_f32_32x32x16_bf16 v[114:129], v[224:227], v[236:239], v[114:129]
	s_waitcnt lgkmcnt(4)
	v_mfma_f32_32x32x16_bf16 v[82:97], v[216:219], v[240:243], v[82:97]
	global_load_dwordx4 v[188:191], v153, s[92:93] offset:1024
	v_mfma_f32_32x32x16_bf16 v[66:81], v[224:227], v[240:243], v[66:81]
	s_waitcnt lgkmcnt(3)
	v_mfma_f32_32x32x16_bf16 v[50:65], v[216:219], v[244:247], v[50:65]
	v_mfma_f32_32x32x16_bf16 v[34:49], v[224:227], v[244:247], v[34:49]
	s_waitcnt lgkmcnt(1)
	v_mfma_f32_32x32x16_bf16 v[18:33], v[216:219], v[228:231], v[18:33]
	v_mfma_f32_32x32x16_bf16 v[2:17], v[224:227], v[228:231], v[2:17]
	s_waitcnt lgkmcnt(0)
	s_barrier
;     ...
;   for (int kt = 0; kt < nk; ++kt) {
;     __syncthreads();
;     if (kt + 1 < nk) {
;       u16* aw = As0 + ((kt + 1) & 1) * 256 * LD;
;       u16* bw = Bs0 + ((kt + 1) & 1) * 256 * LD;
; #pragma unroll
;       for (int i = 0; i < 4; ++i) { *(u32x4*)(aw + (srow + 64 * i) * LD + skc * 8) = ra[i]; *(u32x4*)(bw + (srow + 64 * i) * LD + skc * 8) = rb[i]; }
;     }
;     if (kt + 2 < nk) {
; #pragma unroll
;       for (int i = 0; i < 4; ++i) { ra[i] = *(const u32x4*)(Ag + (size_t)(64 * i) * K + (kt + 2) * 64); rb[i] = *(const u32x4*)(Bg[i] + (kt + 2) * 64); }
;     }
;     __builtin_amdgcn_sched_barrier(0);
;     const u16* as = As0 + (kt & 1) * 256 * LD + (wr * 128 + l31) * LD + h * 8;
;     const u16* bs = Bs0 + (kt & 1) * 256 * LD + (wc * 64 + l31) * LD + h * 8;
;     if (domma)
; #pragma unroll
;     for (int ks = 0; ks < 4; ++ks) {
;       bf16x8 wf[2], xf[4];
; #pragma unroll
;       for (int ct = 0; ct < 2; ++ct) wf[ct] = *(const bf16x8*)(bs + ct * 32 * LD + ks * 16);
; #pragma unroll
;       for (int tt = 0; tt < 4; ++tt) xf[tt] = *(const bf16x8*)(as + tt * 32 * LD + ks * 16);
; #pragma unroll
;       for (int ct = 0; ct < 2; ++ct)
; #pragma unroll
;         for (int tt = 0; tt < 4; ++tt) acc[ct][tt] = __builtin_amdgcn_mfma_f32_32x32x16_bf16(wf[ct], xf[tt], acc[ct][tt], 0, 0, 0);
;     }
;     __builtin_amdgcn_sched_barrier(0);
;   }
	ds_read_b128 v[208:211], v148
	ds_read_b128 v[228:231], v147
	ds_read_b128 v[212:215], v148 offset:4608
	ds_read_b128 v[232:235], v147 offset:4608
	ds_read_b128 v[236:239], v147 offset:9216
	ds_read_b128 v[240:243], v147 offset:13824
	s_waitcnt lgkmcnt(4)
	v_mfma_f32_32x32x16_bf16 v[98:113], v[208:211], v[228:231], v[98:113]
	ds_read_b128 v[216:219], v148 offset:32
	s_waitcnt lgkmcnt(4)
	v_mfma_f32_32x32x16_bf16 v[114:129], v[212:215], v[228:231], v[114:129]
	ds_read_b128 v[244:247], v147 offset:32
	s_waitcnt lgkmcnt(4)
	v_mfma_f32_32x32x16_bf16 v[82:97], v[208:211], v[232:235], v[82:97]
	ds_read_b128 v[224:227], v148 offset:4640
	v_mfma_f32_32x32x16_bf16 v[66:81], v[212:215], v[232:235], v[66:81]
	ds_read_b128 v[228:231], v147 offset:4640
	s_waitcnt vmcnt(15)
	ds_write_b128 v149, v[160:163] offset:36864
	s_waitcnt lgkmcnt(6)
	v_mfma_f32_32x32x16_bf16 v[50:65], v[208:211], v[236:239], v[50:65]
	ds_read_b128 v[232:235], v147 offset:9248
	v_mfma_f32_32x32x16_bf16 v[34:49], v[212:215], v[236:239], v[34:49]
	global_load_dwordx4 v[160:163], v153, s[74:75] offset:1152
	s_waitcnt lgkmcnt(6)
	v_mfma_f32_32x32x16_bf16 v[18:33], v[208:211], v[240:243], v[18:33]
	ds_read_b128 v[236:239], v147 offset:13856
	s_waitcnt vmcnt(15)
	ds_write_b128 v152, v[192:195] offset:36864
	v_mfma_f32_32x32x16_bf16 v[2:17], v[212:215], v[240:243], v[2:17]
	s_waitcnt lgkmcnt(6)
	v_mfma_f32_32x32x16_bf16 v[98:113], v[216:219], v[244:247], v[98:113]
	ds_read_b128 v[208:211], v148 offset:64
	global_load_dwordx4 v[192:195], v153, s[82:83] offset:1152
	s_waitcnt lgkmcnt(6)
	v_mfma_f32_32x32x16_bf16 v[114:129], v[224:227], v[244:247], v[114:129]
	ds_read_b128 v[240:243], v147 offset:64
	s_waitcnt vmcnt(15)
	ds_write_b128 v149, v[164:167] offset:46080
	s_waitcnt lgkmcnt(7)
	v_mfma_f32_32x32x16_bf16 v[82:97], v[216:219], v[228:231], v[82:97]
	ds_read_b128 v[212:215], v148 offset:4672
	v_mfma_f32_32x32x16_bf16 v[66:81], v[224:227], v[228:231], v[66:81]
	ds_read_b128 v[244:247], v147 offset:4672
	global_load_dwordx4 v[164:167], v153, s[76:77] offset:1152
	s_waitcnt lgkmcnt(7)
	v_mfma_f32_32x32x16_bf16 v[50:65], v[216:219], v[232:235], v[50:65]
	ds_read_b128 v[228:231], v147 offset:9280
	s_waitcnt vmcnt(15)
	ds_write_b128 v152, v[196:199] offset:46080
	v_mfma_f32_32x32x16_bf16 v[34:49], v[224:227], v[232:235], v[34:49]
	s_waitcnt lgkmcnt(8)
	v_mfma_f32_32x32x16_bf16 v[18:33], v[216:219], v[236:239], v[18:33]
	ds_read_b128 v[232:235], v147 offset:13888
	global_load_dwordx4 v[196:199], v153, s[84:85] offset:1152
	v_mfma_f32_32x32x16_bf16 v[2:17], v[224:227], v[236:239], v[2:17]
	s_waitcnt vmcnt(15)
	ds_write_b128 v149, v[168:171] offset:55296
	s_waitcnt lgkmcnt(7)
	v_mfma_f32_32x32x16_bf16 v[98:113], v[208:211], v[240:243], v[98:113]
	ds_read_b128 v[216:219], v148 offset:96
	s_waitcnt lgkmcnt(6)
	v_mfma_f32_32x32x16_bf16 v[114:129], v[212:215], v[240:243], v[114:129]
	ds_read_b128 v[236:239], v147 offset:96
	global_load_dwordx4 v[168:171], v153, s[78:79] offset:1152
	s_waitcnt lgkmcnt(6)
	v_mfma_f32_32x32x16_bf16 v[82:97], v[208:211], v[244:247], v[82:97]
	ds_read_b128 v[224:227], v148 offset:4704
	s_waitcnt vmcnt(15)
	ds_write_b128 v152, v[200:203] offset:55296
	v_mfma_f32_32x32x16_bf16 v[66:81], v[212:215], v[244:247], v[66:81]
	ds_read_b128 v[240:243], v147 offset:4704
	s_waitcnt lgkmcnt(8)
	v_mfma_f32_32x32x16_bf16 v[50:65], v[208:211], v[228:231], v[50:65]
	ds_read_b128 v[244:247], v147 offset:9312
	global_load_dwordx4 v[200:203], v153, s[86:87] offset:1152
	v_mfma_f32_32x32x16_bf16 v[34:49], v[212:215], v[228:231], v[34:49]
	s_waitcnt vmcnt(15)
	ds_write_b128 v149, v[172:175] offset:64512
	s_waitcnt lgkmcnt(8)
	v_mfma_f32_32x32x16_bf16 v[18:33], v[208:211], v[232:235], v[18:33]
	ds_read_b128 v[228:231], v147 offset:13920
	v_mfma_f32_32x32x16_bf16 v[2:17], v[212:215], v[232:235], v[2:17]
	global_load_dwordx4 v[172:175], v153, s[80:81] offset:1152
	s_waitcnt lgkmcnt(6)
	v_mfma_f32_32x32x16_bf16 v[98:113], v[216:219], v[236:239], v[98:113]
	s_waitcnt vmcnt(15)
	ds_write_b128 v152, v[204:207] offset:64512
	s_waitcnt lgkmcnt(6)
	v_mfma_f32_32x32x16_bf16 v[114:129], v[224:227], v[236:239], v[114:129]
	s_waitcnt lgkmcnt(4)
	v_mfma_f32_32x32x16_bf16 v[82:97], v[216:219], v[240:243], v[82:97]
	global_load_dwordx4 v[204:207], v153, s[92:93] offset:1152
	v_mfma_f32_32x32x16_bf16 v[66:81], v[224:227], v[240:243], v[66:81]
	s_waitcnt lgkmcnt(3)
	v_mfma_f32_32x32x16_bf16 v[50:65], v[216:219], v[244:247], v[50:65]
	v_mfma_f32_32x32x16_bf16 v[34:49], v[224:227], v[244:247], v[34:49]
	s_waitcnt lgkmcnt(1)
	v_mfma_f32_32x32x16_bf16 v[18:33], v[216:219], v[228:231], v[18:33]
	v_mfma_f32_32x32x16_bf16 v[2:17], v[224:227], v[228:231], v[2:17]
	s_waitcnt lgkmcnt(0)
	s_barrier
;     ...
;   for (int kt = 0; kt < nk; ++kt) {
;     __syncthreads();
;     if (kt + 1 < nk) {
;       u16* aw = As0 + ((kt + 1) & 1) * 256 * LD;
;       u16* bw = Bs0 + ((kt + 1) & 1) * 256 * LD;
; #pragma unroll
;       for (int i = 0; i < 4; ++i) { *(u32x4*)(aw + (srow + 64 * i) * LD + skc * 8) = ra[i]; *(u32x4*)(bw + (srow + 64 * i) * LD + skc * 8) = rb[i]; }
;     }
;     if (kt + 2 < nk) {
; #pragma unroll
;       for (int i = 0; i < 4; ++i) { ra[i] = *(const u32x4*)(Ag + (size_t)(64 * i) * K + (kt + 2) * 64); rb[i] = *(const u32x4*)(Bg[i] + (kt + 2) * 64); }
;     }
;     __builtin_amdgcn_sched_barrier(0);
;     const u16* as = As0 + (kt & 1) * 256 * LD + (wr * 128 + l31) * LD + h * 8;
;     const u16* bs = Bs0 + (kt & 1) * 256 * LD + (wc * 64 + l31) * LD + h * 8;
;     if (domma)
; #pragma unroll
;     for (int ks = 0; ks < 4; ++ks) {
;       bf16x8 wf[2], xf[4];
; #pragma unroll
;       for (int ct = 0; ct < 2; ++ct) wf[ct] = *(const bf16x8*)(bs + ct * 32 * LD + ks * 16);
; #pragma unroll
;       for (int tt = 0; tt < 4; ++tt) xf[tt] = *(const bf16x8*)(as + tt * 32 * LD + ks * 16);
; #pragma unroll
;       for (int ct = 0; ct < 2; ++ct)
; #pragma unroll
;         for (int tt = 0; tt < 4; ++tt) acc[ct][tt] = __builtin_amdgcn_mfma_f32_32x32x16_bf16(wf[ct], xf[tt], acc[ct][tt], 0, 0, 0);
;     }
;     __builtin_amdgcn_sched_barrier(0);
;   }
	ds_read_b128 v[208:211], v148 offset:36864
	ds_read_b128 v[228:231], v147 offset:36864
	ds_read_b128 v[212:215], v148 offset:41472
	ds_read_b128 v[232:235], v147 offset:41472
	ds_read_b128 v[236:239], v147 offset:46080
	ds_read_b128 v[240:243], v147 offset:50688
	s_waitcnt lgkmcnt(4)
	v_mfma_f32_32x32x16_bf16 v[98:113], v[208:211], v[228:231], v[98:113]
	ds_read_b128 v[216:219], v148 offset:36896
	s_waitcnt lgkmcnt(4)
	v_mfma_f32_32x32x16_bf16 v[114:129], v[212:215], v[228:231], v[114:129]
	ds_read_b128 v[244:247], v147 offset:36896
	s_waitcnt lgkmcnt(4)
	v_mfma_f32_32x32x16_bf16 v[82:97], v[208:211], v[232:235], v[82:97]
	ds_read_b128 v[224:227], v148 offset:41504
	v_mfma_f32_32x32x16_bf16 v[66:81], v[212:215], v[232:235], v[66:81]
	ds_read_b128 v[228:231], v147 offset:41504
	s_waitcnt vmcnt(15)
	ds_write_b128 v149, v[130:133]
	s_waitcnt lgkmcnt(6)
	v_mfma_f32_32x32x16_bf16 v[50:65], v[208:211], v[236:239], v[50:65]
	ds_read_b128 v[232:235], v147 offset:46112
	v_mfma_f32_32x32x16_bf16 v[34:49], v[212:215], v[236:239], v[34:49]
	global_load_dwordx4 v[130:133], v153, s[74:75] offset:1280
	s_waitcnt lgkmcnt(6)
	v_mfma_f32_32x32x16_bf16 v[18:33], v[208:211], v[240:243], v[18:33]
	ds_read_b128 v[236:239], v147 offset:50720
	s_waitcnt vmcnt(15)
	ds_write_b128 v152, v[176:179]
	v_mfma_f32_32x32x16_bf16 v[2:17], v[212:215], v[240:243], v[2:17]
	s_waitcnt lgkmcnt(6)
	v_mfma_f32_32x32x16_bf16 v[98:113], v[216:219], v[244:247], v[98:113]
	ds_read_b128 v[208:211], v148 offset:36928
	global_load_dwordx4 v[176:179], v153, s[82:83] offset:1280
	s_waitcnt lgkmcnt(6)
	v_mfma_f32_32x32x16_bf16 v[114:129], v[224:227], v[244:247], v[114:129]
	ds_read_b128 v[240:243], v147 offset:36928
	s_waitcnt vmcnt(15)
	ds_write_b128 v149, v[134:137] offset:9216
	s_waitcnt lgkmcnt(7)
	v_mfma_f32_32x32x16_bf16 v[82:97], v[216:219], v[228:231], v[82:97]
	ds_read_b128 v[212:215], v148 offset:41536
	v_mfma_f32_32x32x16_bf16 v[66:81], v[224:227], v[228:231], v[66:81]
	ds_read_b128 v[244:247], v147 offset:41536
	global_load_dwordx4 v[134:137], v153, s[76:77] offset:1280
	s_waitcnt lgkmcnt(7)
	v_mfma_f32_32x32x16_bf16 v[50:65], v[216:219], v[232:235], v[50:65]
	ds_read_b128 v[228:231], v147 offset:46144
	s_waitcnt vmcnt(15)
	ds_write_b128 v152, v[180:183] offset:9216
	v_mfma_f32_32x32x16_bf16 v[34:49], v[224:227], v[232:235], v[34:49]
	s_waitcnt lgkmcnt(8)
	v_mfma_f32_32x32x16_bf16 v[18:33], v[216:219], v[236:239], v[18:33]
	ds_read_b128 v[232:235], v147 offset:50752
	global_load_dwordx4 v[180:183], v153, s[84:85] offset:1280
	v_mfma_f32_32x32x16_bf16 v[2:17], v[224:227], v[236:239], v[2:17]
	s_waitcnt vmcnt(15)
	ds_write_b128 v149, v[138:141] offset:18432
	s_waitcnt lgkmcnt(7)
	v_mfma_f32_32x32x16_bf16 v[98:113], v[208:211], v[240:243], v[98:113]
	ds_read_b128 v[216:219], v148 offset:36960
	s_waitcnt lgkmcnt(6)
	v_mfma_f32_32x32x16_bf16 v[114:129], v[212:215], v[240:243], v[114:129]
	ds_read_b128 v[236:239], v147 offset:36960
	global_load_dwordx4 v[138:141], v153, s[78:79] offset:1280
	s_waitcnt lgkmcnt(6)
	v_mfma_f32_32x32x16_bf16 v[82:97], v[208:211], v[244:247], v[82:97]
	ds_read_b128 v[224:227], v148 offset:41568
	s_waitcnt vmcnt(15)
	ds_write_b128 v152, v[184:187] offset:18432
	v_mfma_f32_32x32x16_bf16 v[66:81], v[212:215], v[244:247], v[66:81]
	ds_read_b128 v[240:243], v147 offset:41568
	s_waitcnt lgkmcnt(8)
	v_mfma_f32_32x32x16_bf16 v[50:65], v[208:211], v[228:231], v[50:65]
	ds_read_b128 v[244:247], v147 offset:46176
	global_load_dwordx4 v[184:187], v153, s[86:87] offset:1280
	v_mfma_f32_32x32x16_bf16 v[34:49], v[212:215], v[228:231], v[34:49]
	s_waitcnt vmcnt(15)
	ds_write_b128 v149, v[142:145] offset:27648
	s_waitcnt lgkmcnt(8)
	v_mfma_f32_32x32x16_bf16 v[18:33], v[208:211], v[232:235], v[18:33]
	ds_read_b128 v[228:231], v147 offset:50784
	v_mfma_f32_32x32x16_bf16 v[2:17], v[212:215], v[232:235], v[2:17]
	global_load_dwordx4 v[142:145], v153, s[80:81] offset:1280
	s_waitcnt lgkmcnt(6)
	v_mfma_f32_32x32x16_bf16 v[98:113], v[216:219], v[236:239], v[98:113]
	s_waitcnt vmcnt(15)
	ds_write_b128 v152, v[188:191] offset:27648
	s_waitcnt lgkmcnt(6)
	v_mfma_f32_32x32x16_bf16 v[114:129], v[224:227], v[236:239], v[114:129]
	s_waitcnt lgkmcnt(4)
	v_mfma_f32_32x32x16_bf16 v[82:97], v[216:219], v[240:243], v[82:97]
	global_load_dwordx4 v[188:191], v153, s[92:93] offset:1280
	v_mfma_f32_32x32x16_bf16 v[66:81], v[224:227], v[240:243], v[66:81]
	s_waitcnt lgkmcnt(3)
	v_mfma_f32_32x32x16_bf16 v[50:65], v[216:219], v[244:247], v[50:65]
	v_mfma_f32_32x32x16_bf16 v[34:49], v[224:227], v[244:247], v[34:49]
	s_waitcnt lgkmcnt(1)
	v_mfma_f32_32x32x16_bf16 v[18:33], v[216:219], v[228:231], v[18:33]
	v_mfma_f32_32x32x16_bf16 v[2:17], v[224:227], v[228:231], v[2:17]
	s_waitcnt lgkmcnt(0)
	s_barrier
;     ...
;   for (int kt = 0; kt < nk; ++kt) {
;     __syncthreads();
;     if (kt + 1 < nk) {
;       u16* aw = As0 + ((kt + 1) & 1) * 256 * LD;
;       u16* bw = Bs0 + ((kt + 1) & 1) * 256 * LD;
; #pragma unroll
;       for (int i = 0; i < 4; ++i) { *(u32x4*)(aw + (srow + 64 * i) * LD + skc * 8) = ra[i]; *(u32x4*)(bw + (srow + 64 * i) * LD + skc * 8) = rb[i]; }
;     }
;     if (kt + 2 < nk) {
; #pragma unroll
;       for (int i = 0; i < 4; ++i) { ra[i] = *(const u32x4*)(Ag + (size_t)(64 * i) * K + (kt + 2) * 64); rb[i] = *(const u32x4*)(Bg[i] + (kt + 2) * 64); }
;     }
;     __builtin_amdgcn_sched_barrier(0);
;     const u16* as = As0 + (kt & 1) * 256 * LD + (wr * 128 + l31) * LD + h * 8;
;     const u16* bs = Bs0 + (kt & 1) * 256 * LD + (wc * 64 + l31) * LD + h * 8;
;     if (domma)
; #pragma unroll
;     for (int ks = 0; ks < 4; ++ks) {
;       bf16x8 wf[2], xf[4];
; #pragma unroll
;       for (int ct = 0; ct < 2; ++ct) wf[ct] = *(const bf16x8*)(bs + ct * 32 * LD + ks * 16);
; #pragma unroll
;       for (int tt = 0; tt < 4; ++tt) xf[tt] = *(const bf16x8*)(as + tt * 32 * LD + ks * 16);
; #pragma unroll
;       for (int ct = 0; ct < 2; ++ct)
; #pragma unroll
;         for (int tt = 0; tt < 4; ++tt) acc[ct][tt] = __builtin_amdgcn_mfma_f32_32x32x16_bf16(wf[ct], xf[tt], acc[ct][tt], 0, 0, 0);
;     }
;     __builtin_amdgcn_sched_barrier(0);
;   }
	ds_read_b128 v[208:211], v148
	ds_read_b128 v[228:231], v147
	ds_read_b128 v[212:215], v148 offset:4608
	ds_read_b128 v[232:235], v147 offset:4608
	ds_read_b128 v[236:239], v147 offset:9216
	ds_read_b128 v[240:243], v147 offset:13824
	s_waitcnt lgkmcnt(4)
	v_mfma_f32_32x32x16_bf16 v[98:113], v[208:211], v[228:231], v[98:113]
	ds_read_b128 v[216:219], v148 offset:32
	s_waitcnt lgkmcnt(4)
	v_mfma_f32_32x32x16_bf16 v[114:129], v[212:215], v[228:231], v[114:129]
	ds_read_b128 v[244:247], v147 offset:32
	s_waitcnt lgkmcnt(4)
	v_mfma_f32_32x32x16_bf16 v[82:97], v[208:211], v[232:235], v[82:97]
	ds_read_b128 v[224:227], v148 offset:4640
	v_mfma_f32_32x32x16_bf16 v[66:81], v[212:215], v[232:235], v[66:81]
	ds_read_b128 v[228:231], v147 offset:4640
	s_waitcnt vmcnt(15)
	ds_write_b128 v149, v[160:163] offset:36864
	s_waitcnt lgkmcnt(6)
	v_mfma_f32_32x32x16_bf16 v[50:65], v[208:211], v[236:239], v[50:65]
	ds_read_b128 v[232:235], v147 offset:9248
	v_mfma_f32_32x32x16_bf16 v[34:49], v[212:215], v[236:239], v[34:49]
	global_load_dwordx4 v[160:163], v153, s[74:75] offset:1408
	s_waitcnt lgkmcnt(6)
	v_mfma_f32_32x32x16_bf16 v[18:33], v[208:211], v[240:243], v[18:33]
	ds_read_b128 v[236:239], v147 offset:13856
	s_waitcnt vmcnt(15)
	ds_write_b128 v152, v[192:195] offset:36864
	v_mfma_f32_32x32x16_bf16 v[2:17], v[212:215], v[240:243], v[2:17]
	s_waitcnt lgkmcnt(6)
	v_mfma_f32_32x32x16_bf16 v[98:113], v[216:219], v[244:247], v[98:113]
	ds_read_b128 v[208:211], v148 offset:64
	global_load_dwordx4 v[192:195], v153, s[82:83] offset:1408
	s_waitcnt lgkmcnt(6)
	v_mfma_f32_32x32x16_bf16 v[114:129], v[224:227], v[244:247], v[114:129]
	ds_read_b128 v[240:243], v147 offset:64
	s_waitcnt vmcnt(15)
	ds_write_b128 v149, v[164:167] offset:46080
	s_waitcnt lgkmcnt(7)
	v_mfma_f32_32x32x16_bf16 v[82:97], v[216:219], v[228:231], v[82:97]
	ds_read_b128 v[212:215], v148 offset:4672
	v_mfma_f32_32x32x16_bf16 v[66:81], v[224:227], v[228:231], v[66:81]
	ds_read_b128 v[244:247], v147 offset:4672
	global_load_dwordx4 v[164:167], v153, s[76:77] offset:1408
	s_waitcnt lgkmcnt(7)
	v_mfma_f32_32x32x16_bf16 v[50:65], v[216:219], v[232:235], v[50:65]
	ds_read_b128 v[228:231], v147 offset:9280
	s_waitcnt vmcnt(15)
	ds_write_b128 v152, v[196:199] offset:46080
	v_mfma_f32_32x32x16_bf16 v[34:49], v[224:227], v[232:235], v[34:49]
	s_waitcnt lgkmcnt(8)
	v_mfma_f32_32x32x16_bf16 v[18:33], v[216:219], v[236:239], v[18:33]
	ds_read_b128 v[232:235], v147 offset:13888
	global_load_dwordx4 v[196:199], v153, s[84:85] offset:1408
	v_mfma_f32_32x32x16_bf16 v[2:17], v[224:227], v[236:239], v[2:17]
	s_waitcnt vmcnt(15)
	ds_write_b128 v149, v[168:171] offset:55296
	s_waitcnt lgkmcnt(7)
	v_mfma_f32_32x32x16_bf16 v[98:113], v[208:211], v[240:243], v[98:113]
	ds_read_b128 v[216:219], v148 offset:96
	s_waitcnt lgkmcnt(6)
	v_mfma_f32_32x32x16_bf16 v[114:129], v[212:215], v[240:243], v[114:129]
	ds_read_b128 v[236:239], v147 offset:96
	global_load_dwordx4 v[168:171], v153, s[78:79] offset:1408
	s_waitcnt lgkmcnt(6)
	v_mfma_f32_32x32x16_bf16 v[82:97], v[208:211], v[244:247], v[82:97]
	ds_read_b128 v[224:227], v148 offset:4704
	s_waitcnt vmcnt(15)
	ds_write_b128 v152, v[200:203] offset:55296
	v_mfma_f32_32x32x16_bf16 v[66:81], v[212:215], v[244:247], v[66:81]
	ds_read_b128 v[240:243], v147 offset:4704
	s_waitcnt lgkmcnt(8)
	v_mfma_f32_32x32x16_bf16 v[50:65], v[208:211], v[228:231], v[50:65]
	ds_read_b128 v[244:247], v147 offset:9312
	global_load_dwordx4 v[200:203], v153, s[86:87] offset:1408
	v_mfma_f32_32x32x16_bf16 v[34:49], v[212:215], v[228:231], v[34:49]
	s_waitcnt vmcnt(15)
	ds_write_b128 v149, v[172:175] offset:64512
	s_waitcnt lgkmcnt(8)
	v_mfma_f32_32x32x16_bf16 v[18:33], v[208:211], v[232:235], v[18:33]
	ds_read_b128 v[228:231], v147 offset:13920
	v_mfma_f32_32x32x16_bf16 v[2:17], v[212:215], v[232:235], v[2:17]
	global_load_dwordx4 v[172:175], v153, s[80:81] offset:1408
	s_waitcnt lgkmcnt(6)
	v_mfma_f32_32x32x16_bf16 v[98:113], v[216:219], v[236:239], v[98:113]
	s_waitcnt vmcnt(15)
	ds_write_b128 v152, v[204:207] offset:64512
	s_waitcnt lgkmcnt(6)
	v_mfma_f32_32x32x16_bf16 v[114:129], v[224:227], v[236:239], v[114:129]
	s_waitcnt lgkmcnt(4)
	v_mfma_f32_32x32x16_bf16 v[82:97], v[216:219], v[240:243], v[82:97]
	global_load_dwordx4 v[204:207], v153, s[92:93] offset:1408
	v_mfma_f32_32x32x16_bf16 v[66:81], v[224:227], v[240:243], v[66:81]
	s_waitcnt lgkmcnt(3)
	v_mfma_f32_32x32x16_bf16 v[50:65], v[216:219], v[244:247], v[50:65]
	v_mfma_f32_32x32x16_bf16 v[34:49], v[224:227], v[244:247], v[34:49]
	s_waitcnt lgkmcnt(1)
	v_mfma_f32_32x32x16_bf16 v[18:33], v[216:219], v[228:231], v[18:33]
	v_mfma_f32_32x32x16_bf16 v[2:17], v[224:227], v[228:231], v[2:17]
	s_waitcnt lgkmcnt(0)
	s_barrier
;     ...
;   for (int kt = 0; kt < nk; ++kt) {
;     __syncthreads();
;     if (kt + 1 < nk) {
;       u16* aw = As0 + ((kt + 1) & 1) * 256 * LD;
;       u16* bw = Bs0 + ((kt + 1) & 1) * 256 * LD;
; #pragma unroll
;       for (int i = 0; i < 4; ++i) { *(u32x4*)(aw + (srow + 64 * i) * LD + skc * 8) = ra[i]; *(u32x4*)(bw + (srow + 64 * i) * LD + skc * 8) = rb[i]; }
;     }
;     if (kt + 2 < nk) {
; #pragma unroll
;       for (int i = 0; i < 4; ++i) { ra[i] = *(const u32x4*)(Ag + (size_t)(64 * i) * K + (kt + 2) * 64); rb[i] = *(const u32x4*)(Bg[i] + (kt + 2) * 64); }
;     }
;     __builtin_amdgcn_sched_barrier(0);
;     const u16* as = As0 + (kt & 1) * 256 * LD + (wr * 128 + l31) * LD + h * 8;
;     const u16* bs = Bs0 + (kt & 1) * 256 * LD + (wc * 64 + l31) * LD + h * 8;
;     if (domma)
; #pragma unroll
;     for (int ks = 0; ks < 4; ++ks) {
;       bf16x8 wf[2], xf[4];
; #pragma unroll
;       for (int ct = 0; ct < 2; ++ct) wf[ct] = *(const bf16x8*)(bs + ct * 32 * LD + ks * 16);
; #pragma unroll
;       for (int tt = 0; tt < 4; ++tt) xf[tt] = *(const bf16x8*)(as + tt * 32 * LD + ks * 16);
; #pragma unroll
;       for (int ct = 0; ct < 2; ++ct)
; #pragma unroll
;         for (int tt = 0; tt < 4; ++tt) acc[ct][tt] = __builtin_amdgcn_mfma_f32_32x32x16_bf16(wf[ct], xf[tt], acc[ct][tt], 0, 0, 0);
;     }
;     __builtin_amdgcn_sched_barrier(0);
;   }
	ds_read_b128 v[208:211], v148 offset:36864
	ds_read_b128 v[228:231], v147 offset:36864
	ds_read_b128 v[212:215], v148 offset:41472
	ds_read_b128 v[232:235], v147 offset:41472
	ds_read_b128 v[236:239], v147 offset:46080
	ds_read_b128 v[240:243], v147 offset:50688
	s_waitcnt lgkmcnt(4)
	v_mfma_f32_32x32x16_bf16 v[98:113], v[208:211], v[228:231], v[98:113]
	ds_read_b128 v[216:219], v148 offset:36896
	s_waitcnt lgkmcnt(4)
	v_mfma_f32_32x32x16_bf16 v[114:129], v[212:215], v[228:231], v[114:129]
	ds_read_b128 v[244:247], v147 offset:36896
	s_waitcnt lgkmcnt(4)
	v_mfma_f32_32x32x16_bf16 v[82:97], v[208:211], v[232:235], v[82:97]
	ds_read_b128 v[224:227], v148 offset:41504
	v_mfma_f32_32x32x16_bf16 v[66:81], v[212:215], v[232:235], v[66:81]
	ds_read_b128 v[228:231], v147 offset:41504
	s_waitcnt vmcnt(15)
	ds_write_b128 v149, v[130:133]
	s_waitcnt lgkmcnt(6)
	v_mfma_f32_32x32x16_bf16 v[50:65], v[208:211], v[236:239], v[50:65]
	ds_read_b128 v[232:235], v147 offset:46112
	v_mfma_f32_32x32x16_bf16 v[34:49], v[212:215], v[236:239], v[34:49]
	global_load_dwordx4 v[130:133], v153, s[74:75] offset:1536
	s_waitcnt lgkmcnt(6)
	v_mfma_f32_32x32x16_bf16 v[18:33], v[208:211], v[240:243], v[18:33]
	ds_read_b128 v[236:239], v147 offset:50720
	s_waitcnt vmcnt(15)
	ds_write_b128 v152, v[176:179]
	v_mfma_f32_32x32x16_bf16 v[2:17], v[212:215], v[240:243], v[2:17]
	s_waitcnt lgkmcnt(6)
	v_mfma_f32_32x32x16_bf16 v[98:113], v[216:219], v[244:247], v[98:113]
	ds_read_b128 v[208:211], v148 offset:36928
	global_load_dwordx4 v[176:179], v153, s[82:83] offset:1536
	s_waitcnt lgkmcnt(6)
	v_mfma_f32_32x32x16_bf16 v[114:129], v[224:227], v[244:247], v[114:129]
	ds_read_b128 v[240:243], v147 offset:36928
	s_waitcnt vmcnt(15)
	ds_write_b128 v149, v[134:137] offset:9216
	s_waitcnt lgkmcnt(7)
	v_mfma_f32_32x32x16_bf16 v[82:97], v[216:219], v[228:231], v[82:97]
	ds_read_b128 v[212:215], v148 offset:41536
	v_mfma_f32_32x32x16_bf16 v[66:81], v[224:227], v[228:231], v[66:81]
	ds_read_b128 v[244:247], v147 offset:41536
	global_load_dwordx4 v[134:137], v153, s[76:77] offset:1536
	s_waitcnt lgkmcnt(7)
	v_mfma_f32_32x32x16_bf16 v[50:65], v[216:219], v[232:235], v[50:65]
	ds_read_b128 v[228:231], v147 offset:46144
	s_waitcnt vmcnt(15)
	ds_write_b128 v152, v[180:183] offset:9216
	v_mfma_f32_32x32x16_bf16 v[34:49], v[224:227], v[232:235], v[34:49]
	s_waitcnt lgkmcnt(8)
	v_mfma_f32_32x32x16_bf16 v[18:33], v[216:219], v[236:239], v[18:33]
	ds_read_b128 v[232:235], v147 offset:50752
	global_load_dwordx4 v[180:183], v153, s[84:85] offset:1536
	v_mfma_f32_32x32x16_bf16 v[2:17], v[224:227], v[236:239], v[2:17]
	s_waitcnt vmcnt(15)
	ds_write_b128 v149, v[138:141] offset:18432
	s_waitcnt lgkmcnt(7)
	v_mfma_f32_32x32x16_bf16 v[98:113], v[208:211], v[240:243], v[98:113]
	ds_read_b128 v[216:219], v148 offset:36960
	s_waitcnt lgkmcnt(6)
	v_mfma_f32_32x32x16_bf16 v[114:129], v[212:215], v[240:243], v[114:129]
	ds_read_b128 v[236:239], v147 offset:36960
	global_load_dwordx4 v[138:141], v153, s[78:79] offset:1536
	s_waitcnt lgkmcnt(6)
	v_mfma_f32_32x32x16_bf16 v[82:97], v[208:211], v[244:247], v[82:97]
	ds_read_b128 v[224:227], v148 offset:41568
	s_waitcnt vmcnt(15)
	ds_write_b128 v152, v[184:187] offset:18432
	v_mfma_f32_32x32x16_bf16 v[66:81], v[212:215], v[244:247], v[66:81]
	ds_read_b128 v[240:243], v147 offset:41568
	s_waitcnt lgkmcnt(8)
	v_mfma_f32_32x32x16_bf16 v[50:65], v[208:211], v[228:231], v[50:65]
	ds_read_b128 v[244:247], v147 offset:46176
	global_load_dwordx4 v[184:187], v153, s[86:87] offset:1536
	v_mfma_f32_32x32x16_bf16 v[34:49], v[212:215], v[228:231], v[34:49]
	s_waitcnt vmcnt(15)
	ds_write_b128 v149, v[142:145] offset:27648
	s_waitcnt lgkmcnt(8)
	v_mfma_f32_32x32x16_bf16 v[18:33], v[208:211], v[232:235], v[18:33]
	ds_read_b128 v[228:231], v147 offset:50784
	v_mfma_f32_32x32x16_bf16 v[2:17], v[212:215], v[232:235], v[2:17]
	global_load_dwordx4 v[142:145], v153, s[80:81] offset:1536
	s_waitcnt lgkmcnt(6)
	v_mfma_f32_32x32x16_bf16 v[98:113], v[216:219], v[236:239], v[98:113]
	s_waitcnt vmcnt(15)
	ds_write_b128 v152, v[188:191] offset:27648
	s_waitcnt lgkmcnt(6)
	v_mfma_f32_32x32x16_bf16 v[114:129], v[224:227], v[236:239], v[114:129]
	s_waitcnt lgkmcnt(4)
	v_mfma_f32_32x32x16_bf16 v[82:97], v[216:219], v[240:243], v[82:97]
	global_load_dwordx4 v[188:191], v153, s[92:93] offset:1536
	v_mfma_f32_32x32x16_bf16 v[66:81], v[224:227], v[240:243], v[66:81]
	s_waitcnt lgkmcnt(3)
	v_mfma_f32_32x32x16_bf16 v[50:65], v[216:219], v[244:247], v[50:65]
	v_mfma_f32_32x32x16_bf16 v[34:49], v[224:227], v[244:247], v[34:49]
	s_waitcnt lgkmcnt(1)
	v_mfma_f32_32x32x16_bf16 v[18:33], v[216:219], v[228:231], v[18:33]
	v_mfma_f32_32x32x16_bf16 v[2:17], v[224:227], v[228:231], v[2:17]
	s_waitcnt lgkmcnt(0)
	s_barrier
;     ...
;   for (int kt = 0; kt < nk; ++kt) {
;     __syncthreads();
;     if (kt + 1 < nk) {
;       u16* aw = As0 + ((kt + 1) & 1) * 256 * LD;
;       u16* bw = Bs0 + ((kt + 1) & 1) * 256 * LD;
; #pragma unroll
;       for (int i = 0; i < 4; ++i) { *(u32x4*)(aw + (srow + 64 * i) * LD + skc * 8) = ra[i]; *(u32x4*)(bw + (srow + 64 * i) * LD + skc * 8) = rb[i]; }
;     }
;     if (kt + 2 < nk) {
; #pragma unroll
;       for (int i = 0; i < 4; ++i) { ra[i] = *(const u32x4*)(Ag + (size_t)(64 * i) * K + (kt + 2) * 64); rb[i] = *(const u32x4*)(Bg[i] + (kt + 2) * 64); }
;     }
;     __builtin_amdgcn_sched_barrier(0);
;     const u16* as = As0 + (kt & 1) * 256 * LD + (wr * 128 + l31) * LD + h * 8;
;     const u16* bs = Bs0 + (kt & 1) * 256 * LD + (wc * 64 + l31) * LD + h * 8;
;     if (domma)
; #pragma unroll
;     for (int ks = 0; ks < 4; ++ks) {
;       bf16x8 wf[2], xf[4];
; #pragma unroll
;       for (int ct = 0; ct < 2; ++ct) wf[ct] = *(const bf16x8*)(bs + ct * 32 * LD + ks * 16);
; #pragma unroll
;       for (int tt = 0; tt < 4; ++tt) xf[tt] = *(const bf16x8*)(as + tt * 32 * LD + ks * 16);
; #pragma unroll
;       for (int ct = 0; ct < 2; ++ct)
; #pragma unroll
;         for (int tt = 0; tt < 4; ++tt) acc[ct][tt] = __builtin_amdgcn_mfma_f32_32x32x16_bf16(wf[ct], xf[tt], acc[ct][tt], 0, 0, 0);
;     }
;     __builtin_amdgcn_sched_barrier(0);
;   }
	ds_read_b128 v[208:211], v148
	ds_read_b128 v[228:231], v147
	ds_read_b128 v[212:215], v148 offset:4608
	ds_read_b128 v[232:235], v147 offset:4608
	ds_read_b128 v[236:239], v147 offset:9216
	ds_read_b128 v[240:243], v147 offset:13824
	s_waitcnt lgkmcnt(4)
	v_mfma_f32_32x32x16_bf16 v[98:113], v[208:211], v[228:231], v[98:113]
	ds_read_b128 v[216:219], v148 offset:32
	s_waitcnt lgkmcnt(4)
	v_mfma_f32_32x32x16_bf16 v[114:129], v[212:215], v[228:231], v[114:129]
	ds_read_b128 v[244:247], v147 offset:32
	s_waitcnt lgkmcnt(4)
	v_mfma_f32_32x32x16_bf16 v[82:97], v[208:211], v[232:235], v[82:97]
	ds_read_b128 v[224:227], v148 offset:4640
	v_mfma_f32_32x32x16_bf16 v[66:81], v[212:215], v[232:235], v[66:81]
	ds_read_b128 v[228:231], v147 offset:4640
	s_waitcnt vmcnt(15)
	ds_write_b128 v149, v[160:163] offset:36864
	s_waitcnt lgkmcnt(6)
	v_mfma_f32_32x32x16_bf16 v[50:65], v[208:211], v[236:239], v[50:65]
	ds_read_b128 v[232:235], v147 offset:9248
	v_mfma_f32_32x32x16_bf16 v[34:49], v[212:215], v[236:239], v[34:49]
	global_load_dwordx4 v[160:163], v153, s[74:75] offset:1664
	s_waitcnt lgkmcnt(6)
	v_mfma_f32_32x32x16_bf16 v[18:33], v[208:211], v[240:243], v[18:33]
	ds_read_b128 v[236:239], v147 offset:13856
	s_waitcnt vmcnt(15)
	ds_write_b128 v152, v[192:195] offset:36864
	v_mfma_f32_32x32x16_bf16 v[2:17], v[212:215], v[240:243], v[2:17]
	s_waitcnt lgkmcnt(6)
	v_mfma_f32_32x32x16_bf16 v[98:113], v[216:219], v[244:247], v[98:113]
	ds_read_b128 v[208:211], v148 offset:64
	global_load_dwordx4 v[192:195], v153, s[82:83] offset:1664
	s_waitcnt lgkmcnt(6)
	v_mfma_f32_32x32x16_bf16 v[114:129], v[224:227], v[244:247], v[114:129]
	ds_read_b128 v[240:243], v147 offset:64
	s_waitcnt vmcnt(15)
	ds_write_b128 v149, v[164:167] offset:46080
	s_waitcnt lgkmcnt(7)
	v_mfma_f32_32x32x16_bf16 v[82:97], v[216:219], v[228:231], v[82:97]
	ds_read_b128 v[212:215], v148 offset:4672
	v_mfma_f32_32x32x16_bf16 v[66:81], v[224:227], v[228:231], v[66:81]
	ds_read_b128 v[244:247], v147 offset:4672
	global_load_dwordx4 v[164:167], v153, s[76:77] offset:1664
	s_waitcnt lgkmcnt(7)
	v_mfma_f32_32x32x16_bf16 v[50:65], v[216:219], v[232:235], v[50:65]
	ds_read_b128 v[228:231], v147 offset:9280
	s_waitcnt vmcnt(15)
	ds_write_b128 v152, v[196:199] offset:46080
	v_mfma_f32_32x32x16_bf16 v[34:49], v[224:227], v[232:235], v[34:49]
	s_waitcnt lgkmcnt(8)
	v_mfma_f32_32x32x16_bf16 v[18:33], v[216:219], v[236:239], v[18:33]
	ds_read_b128 v[232:235], v147 offset:13888
	global_load_dwordx4 v[196:199], v153, s[84:85] offset:1664
	v_mfma_f32_32x32x16_bf16 v[2:17], v[224:227], v[236:239], v[2:17]
	s_waitcnt vmcnt(15)
	ds_write_b128 v149, v[168:171] offset:55296
	s_waitcnt lgkmcnt(7)
	v_mfma_f32_32x32x16_bf16 v[98:113], v[208:211], v[240:243], v[98:113]
	ds_read_b128 v[216:219], v148 offset:96
	s_waitcnt lgkmcnt(6)
	v_mfma_f32_32x32x16_bf16 v[114:129], v[212:215], v[240:243], v[114:129]
	ds_read_b128 v[236:239], v147 offset:96
	global_load_dwordx4 v[168:171], v153, s[78:79] offset:1664
	s_waitcnt lgkmcnt(6)
	v_mfma_f32_32x32x16_bf16 v[82:97], v[208:211], v[244:247], v[82:97]
	ds_read_b128 v[224:227], v148 offset:4704
	s_waitcnt vmcnt(15)
	ds_write_b128 v152, v[200:203] offset:55296
	v_mfma_f32_32x32x16_bf16 v[66:81], v[212:215], v[244:247], v[66:81]
	ds_read_b128 v[240:243], v147 offset:4704
	s_waitcnt lgkmcnt(8)
	v_mfma_f32_32x32x16_bf16 v[50:65], v[208:211], v[228:231], v[50:65]
	ds_read_b128 v[244:247], v147 offset:9312
	global_load_dwordx4 v[200:203], v153, s[86:87] offset:1664
	v_mfma_f32_32x32x16_bf16 v[34:49], v[212:215], v[228:231], v[34:49]
	s_waitcnt vmcnt(15)
	ds_write_b128 v149, v[172:175] offset:64512
	s_waitcnt lgkmcnt(8)
	v_mfma_f32_32x32x16_bf16 v[18:33], v[208:211], v[232:235], v[18:33]
	ds_read_b128 v[228:231], v147 offset:13920
	v_mfma_f32_32x32x16_bf16 v[2:17], v[212:215], v[232:235], v[2:17]
	global_load_dwordx4 v[172:175], v153, s[80:81] offset:1664
	s_waitcnt lgkmcnt(6)
	v_mfma_f32_32x32x16_bf16 v[98:113], v[216:219], v[236:239], v[98:113]
	s_waitcnt vmcnt(15)
	ds_write_b128 v152, v[204:207] offset:64512
	s_waitcnt lgkmcnt(6)
	v_mfma_f32_32x32x16_bf16 v[114:129], v[224:227], v[236:239], v[114:129]
	s_waitcnt lgkmcnt(4)
	v_mfma_f32_32x32x16_bf16 v[82:97], v[216:219], v[240:243], v[82:97]
	global_load_dwordx4 v[204:207], v153, s[92:93] offset:1664
	v_mfma_f32_32x32x16_bf16 v[66:81], v[224:227], v[240:243], v[66:81]
	s_waitcnt lgkmcnt(3)
	v_mfma_f32_32x32x16_bf16 v[50:65], v[216:219], v[244:247], v[50:65]
	v_mfma_f32_32x32x16_bf16 v[34:49], v[224:227], v[244:247], v[34:49]
	s_waitcnt lgkmcnt(1)
	v_mfma_f32_32x32x16_bf16 v[18:33], v[216:219], v[228:231], v[18:33]
	v_mfma_f32_32x32x16_bf16 v[2:17], v[224:227], v[228:231], v[2:17]
	s_waitcnt lgkmcnt(0)
	s_barrier
;     ...
;   for (int kt = 0; kt < nk; ++kt) {
;     __syncthreads();
;     if (kt + 1 < nk) {
;       u16* aw = As0 + ((kt + 1) & 1) * 256 * LD;
;       u16* bw = Bs0 + ((kt + 1) & 1) * 256 * LD;
; #pragma unroll
;       for (int i = 0; i < 4; ++i) { *(u32x4*)(aw + (srow + 64 * i) * LD + skc * 8) = ra[i]; *(u32x4*)(bw + (srow + 64 * i) * LD + skc * 8) = rb[i]; }
;     }
;     if (kt + 2 < nk) {
; #pragma unroll
;       for (int i = 0; i < 4; ++i) { ra[i] = *(const u32x4*)(Ag + (size_t)(64 * i) * K + (kt + 2) * 64); rb[i] = *(const u32x4*)(Bg[i] + (kt + 2) * 64); }
;     }
;     __builtin_amdgcn_sched_barrier(0);
;     const u16* as = As0 + (kt & 1) * 256 * LD + (wr * 128 + l31) * LD + h * 8;
;     const u16* bs = Bs0 + (kt & 1) * 256 * LD + (wc * 64 + l31) * LD + h * 8;
;     if (domma)
; #pragma unroll
;     for (int ks = 0; ks < 4; ++ks) {
;       bf16x8 wf[2], xf[4];
; #pragma unroll
;       for (int ct = 0; ct < 2; ++ct) wf[ct] = *(const bf16x8*)(bs + ct * 32 * LD + ks * 16);
; #pragma unroll
;       for (int tt = 0; tt < 4; ++tt) xf[tt] = *(const bf16x8*)(as + tt * 32 * LD + ks * 16);
; #pragma unroll
;       for (int ct = 0; ct < 2; ++ct)
; #pragma unroll
;         for (int tt = 0; tt < 4; ++tt) acc[ct][tt] = __builtin_amdgcn_mfma_f32_32x32x16_bf16(wf[ct], xf[tt], acc[ct][tt], 0, 0, 0);
;     }
;     __builtin_amdgcn_sched_barrier(0);
;   }
	ds_read_b128 v[208:211], v148 offset:36864
	ds_read_b128 v[228:231], v147 offset:36864
	ds_read_b128 v[212:215], v148 offset:41472
	ds_read_b128 v[232:235], v147 offset:41472
	ds_read_b128 v[236:239], v147 offset:46080
	ds_read_b128 v[240:243], v147 offset:50688
	s_waitcnt lgkmcnt(4)
	v_mfma_f32_32x32x16_bf16 v[98:113], v[208:211], v[228:231], v[98:113]
	ds_read_b128 v[216:219], v148 offset:36896
	s_waitcnt lgkmcnt(4)
	v_mfma_f32_32x32x16_bf16 v[114:129], v[212:215], v[228:231], v[114:129]
	ds_read_b128 v[244:247], v147 offset:36896
	s_waitcnt lgkmcnt(4)
	v_mfma_f32_32x32x16_bf16 v[82:97], v[208:211], v[232:235], v[82:97]
	ds_read_b128 v[224:227], v148 offset:41504
	v_mfma_f32_32x32x16_bf16 v[66:81], v[212:215], v[232:235], v[66:81]
	ds_read_b128 v[228:231], v147 offset:41504
	s_waitcnt vmcnt(15)
	ds_write_b128 v149, v[130:133]
	s_waitcnt lgkmcnt(6)
	v_mfma_f32_32x32x16_bf16 v[50:65], v[208:211], v[236:239], v[50:65]
	ds_read_b128 v[232:235], v147 offset:46112
	v_mfma_f32_32x32x16_bf16 v[34:49], v[212:215], v[236:239], v[34:49]
	global_load_dwordx4 v[130:133], v153, s[74:75] offset:1792
	s_waitcnt lgkmcnt(6)
	v_mfma_f32_32x32x16_bf16 v[18:33], v[208:211], v[240:243], v[18:33]
	ds_read_b128 v[236:239], v147 offset:50720
	s_waitcnt vmcnt(15)
	ds_write_b128 v152, v[176:179]
	v_mfma_f32_32x32x16_bf16 v[2:17], v[212:215], v[240:243], v[2:17]
	s_waitcnt lgkmcnt(6)
	v_mfma_f32_32x32x16_bf16 v[98:113], v[216:219], v[244:247], v[98:113]
	ds_read_b128 v[208:211], v148 offset:36928
	global_load_dwordx4 v[176:179], v153, s[82:83] offset:1792
	s_waitcnt lgkmcnt(6)
	v_mfma_f32_32x32x16_bf16 v[114:129], v[224:227], v[244:247], v[114:129]
	ds_read_b128 v[240:243], v147 offset:36928
	s_waitcnt vmcnt(15)
	ds_write_b128 v149, v[134:137] offset:9216
	s_waitcnt lgkmcnt(7)
	v_mfma_f32_32x32x16_bf16 v[82:97], v[216:219], v[228:231], v[82:97]
	ds_read_b128 v[212:215], v148 offset:41536
	v_mfma_f32_32x32x16_bf16 v[66:81], v[224:227], v[228:231], v[66:81]
	ds_read_b128 v[244:247], v147 offset:41536
	global_load_dwordx4 v[134:137], v153, s[76:77] offset:1792
	s_waitcnt lgkmcnt(7)
	v_mfma_f32_32x32x16_bf16 v[50:65], v[216:219], v[232:235], v[50:65]
	ds_read_b128 v[228:231], v147 offset:46144
	s_waitcnt vmcnt(15)
	ds_write_b128 v152, v[180:183] offset:9216
	v_mfma_f32_32x32x16_bf16 v[34:49], v[224:227], v[232:235], v[34:49]
	s_waitcnt lgkmcnt(8)
	v_mfma_f32_32x32x16_bf16 v[18:33], v[216:219], v[236:239], v[18:33]
	ds_read_b128 v[232:235], v147 offset:50752
	global_load_dwordx4 v[180:183], v153, s[84:85] offset:1792
	v_mfma_f32_32x32x16_bf16 v[2:17], v[224:227], v[236:239], v[2:17]
	s_waitcnt vmcnt(15)
	ds_write_b128 v149, v[138:141] offset:18432
	s_waitcnt lgkmcnt(7)
	v_mfma_f32_32x32x16_bf16 v[98:113], v[208:211], v[240:243], v[98:113]
	ds_read_b128 v[216:219], v148 offset:36960
	s_waitcnt lgkmcnt(6)
	v_mfma_f32_32x32x16_bf16 v[114:129], v[212:215], v[240:243], v[114:129]
	ds_read_b128 v[236:239], v147 offset:36960
	global_load_dwordx4 v[138:141], v153, s[78:79] offset:1792
	s_waitcnt lgkmcnt(6)
	v_mfma_f32_32x32x16_bf16 v[82:97], v[208:211], v[244:247], v[82:97]
	ds_read_b128 v[224:227], v148 offset:41568
	s_waitcnt vmcnt(15)
	ds_write_b128 v152, v[184:187] offset:18432
	v_mfma_f32_32x32x16_bf16 v[66:81], v[212:215], v[244:247], v[66:81]
	ds_read_b128 v[240:243], v147 offset:41568
	s_waitcnt lgkmcnt(8)
	v_mfma_f32_32x32x16_bf16 v[50:65], v[208:211], v[228:231], v[50:65]
	ds_read_b128 v[244:247], v147 offset:46176
	global_load_dwordx4 v[184:187], v153, s[86:87] offset:1792
	v_mfma_f32_32x32x16_bf16 v[34:49], v[212:215], v[228:231], v[34:49]
	s_waitcnt vmcnt(15)
	ds_write_b128 v149, v[142:145] offset:27648
	s_waitcnt lgkmcnt(8)
	v_mfma_f32_32x32x16_bf16 v[18:33], v[208:211], v[232:235], v[18:33]
	ds_read_b128 v[228:231], v147 offset:50784
	v_mfma_f32_32x32x16_bf16 v[2:17], v[212:215], v[232:235], v[2:17]
	global_load_dwordx4 v[142:145], v153, s[80:81] offset:1792
	s_waitcnt lgkmcnt(6)
	v_mfma_f32_32x32x16_bf16 v[98:113], v[216:219], v[236:239], v[98:113]
	s_waitcnt vmcnt(15)
	ds_write_b128 v152, v[188:191] offset:27648
	s_waitcnt lgkmcnt(6)
	v_mfma_f32_32x32x16_bf16 v[114:129], v[224:227], v[236:239], v[114:129]
	s_waitcnt lgkmcnt(4)
	v_mfma_f32_32x32x16_bf16 v[82:97], v[216:219], v[240:243], v[82:97]
	global_load_dwordx4 v[188:191], v153, s[92:93] offset:1792
	v_mfma_f32_32x32x16_bf16 v[66:81], v[224:227], v[240:243], v[66:81]
	s_waitcnt lgkmcnt(3)
	v_mfma_f32_32x32x16_bf16 v[50:65], v[216:219], v[244:247], v[50:65]
	v_mfma_f32_32x32x16_bf16 v[34:49], v[224:227], v[244:247], v[34:49]
	s_waitcnt lgkmcnt(1)
	v_mfma_f32_32x32x16_bf16 v[18:33], v[216:219], v[228:231], v[18:33]
	v_mfma_f32_32x32x16_bf16 v[2:17], v[224:227], v[228:231], v[2:17]
	s_waitcnt lgkmcnt(0)
	s_barrier
;     ...
;   for (int kt = 0; kt < nk; ++kt) {
;     __syncthreads();
;     if (kt + 1 < nk) {
;       u16* aw = As0 + ((kt + 1) & 1) * 256 * LD;
;       u16* bw = Bs0 + ((kt + 1) & 1) * 256 * LD;
; #pragma unroll
;       for (int i = 0; i < 4; ++i) { *(u32x4*)(aw + (srow + 64 * i) * LD + skc * 8) = ra[i]; *(u32x4*)(bw + (srow + 64 * i) * LD + skc * 8) = rb[i]; }
;     }
;     if (kt + 2 < nk) {
; #pragma unroll
;       for (int i = 0; i < 4; ++i) { ra[i] = *(const u32x4*)(Ag + (size_t)(64 * i) * K + (kt + 2) * 64); rb[i] = *(const u32x4*)(Bg[i] + (kt + 2) * 64); }
;     }
;     __builtin_amdgcn_sched_barrier(0);
;     const u16* as = As0 + (kt & 1) * 256 * LD + (wr * 128 + l31) * LD + h * 8;
;     const u16* bs = Bs0 + (kt & 1) * 256 * LD + (wc * 64 + l31) * LD + h * 8;
;     if (domma)
; #pragma unroll
;     for (int ks = 0; ks < 4; ++ks) {
;       bf16x8 wf[2], xf[4];
; #pragma unroll
;       for (int ct = 0; ct < 2; ++ct) wf[ct] = *(const bf16x8*)(bs + ct * 32 * LD + ks * 16);
; #pragma unroll
;       for (int tt = 0; tt < 4; ++tt) xf[tt] = *(const bf16x8*)(as + tt * 32 * LD + ks * 16);
; #pragma unroll
;       for (int ct = 0; ct < 2; ++ct)
; #pragma unroll
;         for (int tt = 0; tt < 4; ++tt) acc[ct][tt] = __builtin_amdgcn_mfma_f32_32x32x16_bf16(wf[ct], xf[tt], acc[ct][tt], 0, 0, 0);
;     }
;     __builtin_amdgcn_sched_barrier(0);
;   }
	ds_read_b128 v[208:211], v148
	ds_read_b128 v[228:231], v147
	ds_read_b128 v[212:215], v148 offset:4608
	ds_read_b128 v[232:235], v147 offset:4608
	ds_read_b128 v[236:239], v147 offset:9216
	ds_read_b128 v[240:243], v147 offset:13824
	s_waitcnt lgkmcnt(4)
	v_mfma_f32_32x32x16_bf16 v[98:113], v[208:211], v[228:231], v[98:113]
	ds_read_b128 v[216:219], v148 offset:32
	s_waitcnt lgkmcnt(4)
	v_mfma_f32_32x32x16_bf16 v[114:129], v[212:215], v[228:231], v[114:129]
	ds_read_b128 v[244:247], v147 offset:32
	s_waitcnt lgkmcnt(4)
	v_mfma_f32_32x32x16_bf16 v[82:97], v[208:211], v[232:235], v[82:97]
	ds_read_b128 v[224:227], v148 offset:4640
	v_mfma_f32_32x32x16_bf16 v[66:81], v[212:215], v[232:235], v[66:81]
	ds_read_b128 v[228:231], v147 offset:4640
	s_waitcnt vmcnt(15)
	ds_write_b128 v149, v[160:163] offset:36864
	s_waitcnt lgkmcnt(6)
	v_mfma_f32_32x32x16_bf16 v[50:65], v[208:211], v[236:239], v[50:65]
	ds_read_b128 v[232:235], v147 offset:9248
	v_mfma_f32_32x32x16_bf16 v[34:49], v[212:215], v[236:239], v[34:49]
	global_load_dwordx4 v[160:163], v153, s[74:75] offset:1920
	s_waitcnt lgkmcnt(6)
	v_mfma_f32_32x32x16_bf16 v[18:33], v[208:211], v[240:243], v[18:33]
	ds_read_b128 v[236:239], v147 offset:13856
	s_waitcnt vmcnt(15)
	ds_write_b128 v152, v[192:195] offset:36864
	v_mfma_f32_32x32x16_bf16 v[2:17], v[212:215], v[240:243], v[2:17]
	s_waitcnt lgkmcnt(6)
	v_mfma_f32_32x32x16_bf16 v[98:113], v[216:219], v[244:247], v[98:113]
	ds_read_b128 v[208:211], v148 offset:64
	global_load_dwordx4 v[192:195], v153, s[82:83] offset:1920
	s_waitcnt lgkmcnt(6)
	v_mfma_f32_32x32x16_bf16 v[114:129], v[224:227], v[244:247], v[114:129]
	ds_read_b128 v[240:243], v147 offset:64
	s_waitcnt vmcnt(15)
	ds_write_b128 v149, v[164:167] offset:46080
	s_waitcnt lgkmcnt(7)
	v_mfma_f32_32x32x16_bf16 v[82:97], v[216:219], v[228:231], v[82:97]
	ds_read_b128 v[212:215], v148 offset:4672
	v_mfma_f32_32x32x16_bf16 v[66:81], v[224:227], v[228:231], v[66:81]
	ds_read_b128 v[244:247], v147 offset:4672
	global_load_dwordx4 v[164:167], v153, s[76:77] offset:1920
	s_waitcnt lgkmcnt(7)
	v_mfma_f32_32x32x16_bf16 v[50:65], v[216:219], v[232:235], v[50:65]
	ds_read_b128 v[228:231], v147 offset:9280
	s_waitcnt vmcnt(15)
	ds_write_b128 v152, v[196:199] offset:46080
	v_mfma_f32_32x32x16_bf16 v[34:49], v[224:227], v[232:235], v[34:49]
	s_waitcnt lgkmcnt(8)
	v_mfma_f32_32x32x16_bf16 v[18:33], v[216:219], v[236:239], v[18:33]
	ds_read_b128 v[232:235], v147 offset:13888
	global_load_dwordx4 v[196:199], v153, s[84:85] offset:1920
	v_mfma_f32_32x32x16_bf16 v[2:17], v[224:227], v[236:239], v[2:17]
	s_waitcnt vmcnt(15)
	ds_write_b128 v149, v[168:171] offset:55296
	s_waitcnt lgkmcnt(7)
	v_mfma_f32_32x32x16_bf16 v[98:113], v[208:211], v[240:243], v[98:113]
	ds_read_b128 v[216:219], v148 offset:96
	s_waitcnt lgkmcnt(6)
	v_mfma_f32_32x32x16_bf16 v[114:129], v[212:215], v[240:243], v[114:129]
	ds_read_b128 v[236:239], v147 offset:96
	global_load_dwordx4 v[168:171], v153, s[78:79] offset:1920
	s_waitcnt lgkmcnt(6)
	v_mfma_f32_32x32x16_bf16 v[82:97], v[208:211], v[244:247], v[82:97]
	ds_read_b128 v[224:227], v148 offset:4704
	s_waitcnt vmcnt(15)
	ds_write_b128 v152, v[200:203] offset:55296
	v_mfma_f32_32x32x16_bf16 v[66:81], v[212:215], v[244:247], v[66:81]
	ds_read_b128 v[240:243], v147 offset:4704
	s_waitcnt lgkmcnt(8)
	v_mfma_f32_32x32x16_bf16 v[50:65], v[208:211], v[228:231], v[50:65]
	ds_read_b128 v[244:247], v147 offset:9312
	global_load_dwordx4 v[200:203], v153, s[86:87] offset:1920
	v_mfma_f32_32x32x16_bf16 v[34:49], v[212:215], v[228:231], v[34:49]
	s_waitcnt vmcnt(15)
	ds_write_b128 v149, v[172:175] offset:64512
	s_waitcnt lgkmcnt(8)
	v_mfma_f32_32x32x16_bf16 v[18:33], v[208:211], v[232:235], v[18:33]
	ds_read_b128 v[228:231], v147 offset:13920
	v_mfma_f32_32x32x16_bf16 v[2:17], v[212:215], v[232:235], v[2:17]
	global_load_dwordx4 v[172:175], v153, s[80:81] offset:1920
	s_waitcnt lgkmcnt(6)
	v_mfma_f32_32x32x16_bf16 v[98:113], v[216:219], v[236:239], v[98:113]
	s_waitcnt vmcnt(15)
	ds_write_b128 v152, v[204:207] offset:64512
	s_waitcnt lgkmcnt(6)
	v_mfma_f32_32x32x16_bf16 v[114:129], v[224:227], v[236:239], v[114:129]
	s_waitcnt lgkmcnt(4)
	v_mfma_f32_32x32x16_bf16 v[82:97], v[216:219], v[240:243], v[82:97]
	global_load_dwordx4 v[204:207], v153, s[92:93] offset:1920
	v_mfma_f32_32x32x16_bf16 v[66:81], v[224:227], v[240:243], v[66:81]
	s_waitcnt lgkmcnt(3)
	v_mfma_f32_32x32x16_bf16 v[50:65], v[216:219], v[244:247], v[50:65]
	v_mfma_f32_32x32x16_bf16 v[34:49], v[224:227], v[244:247], v[34:49]
	s_waitcnt lgkmcnt(1)
	v_mfma_f32_32x32x16_bf16 v[18:33], v[216:219], v[228:231], v[18:33]
	v_mfma_f32_32x32x16_bf16 v[2:17], v[224:227], v[228:231], v[2:17]
	s_waitcnt lgkmcnt(0)
	s_barrier
;     ...
;   for (int kt = 0; kt < nk; ++kt) {
;     __syncthreads();
;     if (kt + 1 < nk) {
;       u16* aw = As0 + ((kt + 1) & 1) * 256 * LD;
;       u16* bw = Bs0 + ((kt + 1) & 1) * 256 * LD;
; #pragma unroll
;       for (int i = 0; i < 4; ++i) { *(u32x4*)(aw + (srow + 64 * i) * LD + skc * 8) = ra[i]; *(u32x4*)(bw + (srow + 64 * i) * LD + skc * 8) = rb[i]; }
;     }
;     if (kt + 2 < nk) {
; #pragma unroll
;       for (int i = 0; i < 4; ++i) { ra[i] = *(const u32x4*)(Ag + (size_t)(64 * i) * K + (kt + 2) * 64); rb[i] = *(const u32x4*)(Bg[i] + (kt + 2) * 64); }
;     }
;     __builtin_amdgcn_sched_barrier(0);
;     const u16* as = As0 + (kt & 1) * 256 * LD + (wr * 128 + l31) * LD + h * 8;
;     const u16* bs = Bs0 + (kt & 1) * 256 * LD + (wc * 64 + l31) * LD + h * 8;
;     if (domma)
; #pragma unroll
;     for (int ks = 0; ks < 4; ++ks) {
;       bf16x8 wf[2], xf[4];
; #pragma unroll
;       for (int ct = 0; ct < 2; ++ct) wf[ct] = *(const bf16x8*)(bs + ct * 32 * LD + ks * 16);
; #pragma unroll
;       for (int tt = 0; tt < 4; ++tt) xf[tt] = *(const bf16x8*)(as + tt * 32 * LD + ks * 16);
; #pragma unroll
;       for (int ct = 0; ct < 2; ++ct)
; #pragma unroll
;         for (int tt = 0; tt < 4; ++tt) acc[ct][tt] = __builtin_amdgcn_mfma_f32_32x32x16_bf16(wf[ct], xf[tt], acc[ct][tt], 0, 0, 0);
;     }
;     __builtin_amdgcn_sched_barrier(0);
;   }
	ds_read_b128 v[208:211], v148 offset:36864
	ds_read_b128 v[228:231], v147 offset:36864
	ds_read_b128 v[212:215], v148 offset:41472
	ds_read_b128 v[232:235], v147 offset:41472
	ds_read_b128 v[236:239], v147 offset:46080
	ds_read_b128 v[240:243], v147 offset:50688
	s_waitcnt lgkmcnt(4)
	v_mfma_f32_32x32x16_bf16 v[98:113], v[208:211], v[228:231], v[98:113]
	ds_read_b128 v[216:219], v148 offset:36896
	s_waitcnt lgkmcnt(4)
	v_mfma_f32_32x32x16_bf16 v[114:129], v[212:215], v[228:231], v[114:129]
	ds_read_b128 v[244:247], v147 offset:36896
	s_waitcnt lgkmcnt(4)
	v_mfma_f32_32x32x16_bf16 v[82:97], v[208:211], v[232:235], v[82:97]
	ds_read_b128 v[224:227], v148 offset:41504
	v_mfma_f32_32x32x16_bf16 v[66:81], v[212:215], v[232:235], v[66:81]
	ds_read_b128 v[228:231], v147 offset:41504
	s_waitcnt vmcnt(15)
	ds_write_b128 v149, v[130:133]
	s_waitcnt lgkmcnt(6)
	v_mfma_f32_32x32x16_bf16 v[50:65], v[208:211], v[236:239], v[50:65]
	ds_read_b128 v[232:235], v147 offset:46112
	v_mfma_f32_32x32x16_bf16 v[34:49], v[212:215], v[236:239], v[34:49]
	s_waitcnt lgkmcnt(6)
	v_mfma_f32_32x32x16_bf16 v[18:33], v[208:211], v[240:243], v[18:33]
	ds_read_b128 v[236:239], v147 offset:50720
	s_waitcnt vmcnt(14)
	ds_write_b128 v152, v[176:179]
	v_mfma_f32_32x32x16_bf16 v[2:17], v[212:215], v[240:243], v[2:17]
	s_waitcnt lgkmcnt(6)
	v_mfma_f32_32x32x16_bf16 v[98:113], v[216:219], v[244:247], v[98:113]
	ds_read_b128 v[208:211], v148 offset:36928
	s_waitcnt lgkmcnt(6)
	v_mfma_f32_32x32x16_bf16 v[114:129], v[224:227], v[244:247], v[114:129]
	ds_read_b128 v[240:243], v147 offset:36928
	s_waitcnt vmcnt(13)
	ds_write_b128 v149, v[134:137] offset:9216
	s_waitcnt lgkmcnt(7)
	v_mfma_f32_32x32x16_bf16 v[82:97], v[216:219], v[228:231], v[82:97]
	ds_read_b128 v[212:215], v148 offset:41536
	v_mfma_f32_32x32x16_bf16 v[66:81], v[224:227], v[228:231], v[66:81]
	ds_read_b128 v[244:247], v147 offset:41536
	s_waitcnt lgkmcnt(7)
	v_mfma_f32_32x32x16_bf16 v[50:65], v[216:219], v[232:235], v[50:65]
	ds_read_b128 v[228:231], v147 offset:46144
	s_waitcnt vmcnt(12)
	ds_write_b128 v152, v[180:183] offset:9216
	v_mfma_f32_32x32x16_bf16 v[34:49], v[224:227], v[232:235], v[34:49]
	s_waitcnt lgkmcnt(8)
	v_mfma_f32_32x32x16_bf16 v[18:33], v[216:219], v[236:239], v[18:33]
	ds_read_b128 v[232:235], v147 offset:50752
	v_mfma_f32_32x32x16_bf16 v[2:17], v[224:227], v[236:239], v[2:17]
	s_waitcnt vmcnt(11)
	ds_write_b128 v149, v[138:141] offset:18432
	s_waitcnt lgkmcnt(7)
	v_mfma_f32_32x32x16_bf16 v[98:113], v[208:211], v[240:243], v[98:113]
	ds_read_b128 v[216:219], v148 offset:36960
	s_waitcnt lgkmcnt(6)
	v_mfma_f32_32x32x16_bf16 v[114:129], v[212:215], v[240:243], v[114:129]
	ds_read_b128 v[236:239], v147 offset:36960
	s_waitcnt lgkmcnt(6)
	v_mfma_f32_32x32x16_bf16 v[82:97], v[208:211], v[244:247], v[82:97]
	ds_read_b128 v[224:227], v148 offset:41568
	s_waitcnt vmcnt(10)
	ds_write_b128 v152, v[184:187] offset:18432
	v_mfma_f32_32x32x16_bf16 v[66:81], v[212:215], v[244:247], v[66:81]
	ds_read_b128 v[240:243], v147 offset:41568
	s_waitcnt lgkmcnt(8)
	v_mfma_f32_32x32x16_bf16 v[50:65], v[208:211], v[228:231], v[50:65]
	ds_read_b128 v[244:247], v147 offset:46176
	v_mfma_f32_32x32x16_bf16 v[34:49], v[212:215], v[228:231], v[34:49]
	s_waitcnt vmcnt(9)
	ds_write_b128 v149, v[142:145] offset:27648
	s_waitcnt lgkmcnt(8)
	v_mfma_f32_32x32x16_bf16 v[18:33], v[208:211], v[232:235], v[18:33]
	ds_read_b128 v[228:231], v147 offset:50784
	v_mfma_f32_32x32x16_bf16 v[2:17], v[212:215], v[232:235], v[2:17]
	s_waitcnt lgkmcnt(6)
	v_mfma_f32_32x32x16_bf16 v[98:113], v[216:219], v[236:239], v[98:113]
	s_waitcnt vmcnt(8)
	ds_write_b128 v152, v[188:191] offset:27648
	s_waitcnt lgkmcnt(6)
	v_mfma_f32_32x32x16_bf16 v[114:129], v[224:227], v[236:239], v[114:129]
	s_waitcnt lgkmcnt(4)
	v_mfma_f32_32x32x16_bf16 v[82:97], v[216:219], v[240:243], v[82:97]
	v_mfma_f32_32x32x16_bf16 v[66:81], v[224:227], v[240:243], v[66:81]
	s_waitcnt lgkmcnt(3)
	v_mfma_f32_32x32x16_bf16 v[50:65], v[216:219], v[244:247], v[50:65]
	v_mfma_f32_32x32x16_bf16 v[34:49], v[224:227], v[244:247], v[34:49]
	s_waitcnt lgkmcnt(1)
	v_mfma_f32_32x32x16_bf16 v[18:33], v[216:219], v[228:231], v[18:33]
	v_mfma_f32_32x32x16_bf16 v[2:17], v[224:227], v[228:231], v[2:17]
	s_waitcnt lgkmcnt(0)
	s_barrier
;     ...
;   for (int kt = 0; kt < nk; ++kt) {
;     __syncthreads();
;     if (kt + 1 < nk) {
;       u16* aw = As0 + ((kt + 1) & 1) * 256 * LD;
;       u16* bw = Bs0 + ((kt + 1) & 1) * 256 * LD;
; #pragma unroll
;       for (int i = 0; i < 4; ++i) { *(u32x4*)(aw + (srow + 64 * i) * LD + skc * 8) = ra[i]; *(u32x4*)(bw + (srow + 64 * i) * LD + skc * 8) = rb[i]; }
;     }
;     if (kt + 2 < nk) {
; #pragma unroll
;       for (int i = 0; i < 4; ++i) { ra[i] = *(const u32x4*)(Ag + (size_t)(64 * i) * K + (kt + 2) * 64); rb[i] = *(const u32x4*)(Bg[i] + (kt + 2) * 64); }
;     }
;     __builtin_amdgcn_sched_barrier(0);
;     const u16* as = As0 + (kt & 1) * 256 * LD + (wr * 128 + l31) * LD + h * 8;
;     const u16* bs = Bs0 + (kt & 1) * 256 * LD + (wc * 64 + l31) * LD + h * 8;
;     if (domma)
; #pragma unroll
;     for (int ks = 0; ks < 4; ++ks) {
;       bf16x8 wf[2], xf[4];
; #pragma unroll
;       for (int ct = 0; ct < 2; ++ct) wf[ct] = *(const bf16x8*)(bs + ct * 32 * LD + ks * 16);
; #pragma unroll
;       for (int tt = 0; tt < 4; ++tt) xf[tt] = *(const bf16x8*)(as + tt * 32 * LD + ks * 16);
; #pragma unroll
;       for (int ct = 0; ct < 2; ++ct)
; #pragma unroll
;         for (int tt = 0; tt < 4; ++tt) acc[ct][tt] = __builtin_amdgcn_mfma_f32_32x32x16_bf16(wf[ct], xf[tt], acc[ct][tt], 0, 0, 0);
;     }
;     __builtin_amdgcn_sched_barrier(0);
;   }
	ds_read_b128 v[208:211], v148
	ds_read_b128 v[228:231], v147
	ds_read_b128 v[212:215], v148 offset:4608
	ds_read_b128 v[232:235], v147 offset:4608
	ds_read_b128 v[236:239], v147 offset:9216
	ds_read_b128 v[240:243], v147 offset:13824
	s_waitcnt lgkmcnt(4)
	v_mfma_f32_32x32x16_bf16 v[98:113], v[208:211], v[228:231], v[98:113]
	ds_read_b128 v[216:219], v148 offset:32
	s_waitcnt lgkmcnt(4)
	v_mfma_f32_32x32x16_bf16 v[114:129], v[212:215], v[228:231], v[114:129]
	ds_read_b128 v[244:247], v147 offset:32
	s_waitcnt lgkmcnt(4)
	v_mfma_f32_32x32x16_bf16 v[82:97], v[208:211], v[232:235], v[82:97]
	ds_read_b128 v[224:227], v148 offset:4640
	v_mfma_f32_32x32x16_bf16 v[66:81], v[212:215], v[232:235], v[66:81]
	ds_read_b128 v[228:231], v147 offset:4640
	s_waitcnt vmcnt(7)
	ds_write_b128 v149, v[160:163] offset:36864
	s_waitcnt lgkmcnt(6)
	v_mfma_f32_32x32x16_bf16 v[50:65], v[208:211], v[236:239], v[50:65]
	ds_read_b128 v[232:235], v147 offset:9248
	v_mfma_f32_32x32x16_bf16 v[34:49], v[212:215], v[236:239], v[34:49]
	s_waitcnt lgkmcnt(6)
	v_mfma_f32_32x32x16_bf16 v[18:33], v[208:211], v[240:243], v[18:33]
	ds_read_b128 v[236:239], v147 offset:13856
	s_waitcnt vmcnt(6)
	ds_write_b128 v152, v[192:195] offset:36864
	v_mfma_f32_32x32x16_bf16 v[2:17], v[212:215], v[240:243], v[2:17]
	s_waitcnt lgkmcnt(6)
	v_mfma_f32_32x32x16_bf16 v[98:113], v[216:219], v[244:247], v[98:113]
	ds_read_b128 v[208:211], v148 offset:64
	s_waitcnt lgkmcnt(6)
	v_mfma_f32_32x32x16_bf16 v[114:129], v[224:227], v[244:247], v[114:129]
	ds_read_b128 v[240:243], v147 offset:64
	s_waitcnt vmcnt(5)
	ds_write_b128 v149, v[164:167] offset:46080
	s_waitcnt lgkmcnt(7)
	v_mfma_f32_32x32x16_bf16 v[82:97], v[216:219], v[228:231], v[82:97]
	ds_read_b128 v[212:215], v148 offset:4672
	v_mfma_f32_32x32x16_bf16 v[66:81], v[224:227], v[228:231], v[66:81]
	ds_read_b128 v[244:247], v147 offset:4672
	s_waitcnt lgkmcnt(7)
	v_mfma_f32_32x32x16_bf16 v[50:65], v[216:219], v[232:235], v[50:65]
	ds_read_b128 v[228:231], v147 offset:9280
	s_waitcnt vmcnt(4)
	ds_write_b128 v152, v[196:199] offset:46080
	v_mfma_f32_32x32x16_bf16 v[34:49], v[224:227], v[232:235], v[34:49]
	s_waitcnt lgkmcnt(8)
	v_mfma_f32_32x32x16_bf16 v[18:33], v[216:219], v[236:239], v[18:33]
	ds_read_b128 v[232:235], v147 offset:13888
	v_mfma_f32_32x32x16_bf16 v[2:17], v[224:227], v[236:239], v[2:17]
	s_waitcnt vmcnt(3)
	ds_write_b128 v149, v[168:171] offset:55296
	s_waitcnt lgkmcnt(7)
	v_mfma_f32_32x32x16_bf16 v[98:113], v[208:211], v[240:243], v[98:113]
	ds_read_b128 v[216:219], v148 offset:96
	s_waitcnt lgkmcnt(6)
	v_mfma_f32_32x32x16_bf16 v[114:129], v[212:215], v[240:243], v[114:129]
	ds_read_b128 v[236:239], v147 offset:96
	s_waitcnt lgkmcnt(6)
	v_mfma_f32_32x32x16_bf16 v[82:97], v[208:211], v[244:247], v[82:97]
	ds_read_b128 v[224:227], v148 offset:4704
	s_waitcnt vmcnt(2)
	ds_write_b128 v152, v[200:203] offset:55296
	v_mfma_f32_32x32x16_bf16 v[66:81], v[212:215], v[244:247], v[66:81]
	ds_read_b128 v[240:243], v147 offset:4704
	s_waitcnt lgkmcnt(8)
	v_mfma_f32_32x32x16_bf16 v[50:65], v[208:211], v[228:231], v[50:65]
	ds_read_b128 v[244:247], v147 offset:9312
	v_mfma_f32_32x32x16_bf16 v[34:49], v[212:215], v[228:231], v[34:49]
	s_waitcnt vmcnt(1)
	ds_write_b128 v149, v[172:175] offset:64512
	s_waitcnt lgkmcnt(8)
	v_mfma_f32_32x32x16_bf16 v[18:33], v[208:211], v[232:235], v[18:33]
	ds_read_b128 v[228:231], v147 offset:13920
	v_mfma_f32_32x32x16_bf16 v[2:17], v[212:215], v[232:235], v[2:17]
	s_waitcnt lgkmcnt(6)
	v_mfma_f32_32x32x16_bf16 v[98:113], v[216:219], v[236:239], v[98:113]
	s_waitcnt vmcnt(0)
	ds_write_b128 v152, v[204:207] offset:64512
	s_waitcnt lgkmcnt(6)
	v_mfma_f32_32x32x16_bf16 v[114:129], v[224:227], v[236:239], v[114:129]
	s_waitcnt lgkmcnt(4)
	v_mfma_f32_32x32x16_bf16 v[82:97], v[216:219], v[240:243], v[82:97]
	v_mfma_f32_32x32x16_bf16 v[66:81], v[224:227], v[240:243], v[66:81]
	s_waitcnt lgkmcnt(3)
	v_mfma_f32_32x32x16_bf16 v[50:65], v[216:219], v[244:247], v[50:65]
	v_mfma_f32_32x32x16_bf16 v[34:49], v[224:227], v[244:247], v[34:49]
	s_waitcnt lgkmcnt(1)
	v_mfma_f32_32x32x16_bf16 v[18:33], v[216:219], v[228:231], v[18:33]
	v_mfma_f32_32x32x16_bf16 v[2:17], v[224:227], v[228:231], v[2:17]
	s_waitcnt lgkmcnt(0)
	s_barrier
	ds_read_b128 v[208:211], v148 offset:36864
	ds_read_b128 v[228:231], v147 offset:36864
	ds_read_b128 v[212:215], v148 offset:41472
	ds_read_b128 v[232:235], v147 offset:41472
	ds_read_b128 v[236:239], v147 offset:46080
	ds_read_b128 v[240:243], v147 offset:50688
	s_waitcnt lgkmcnt(4)
	v_mfma_f32_32x32x16_bf16 v[98:113], v[208:211], v[228:231], v[98:113]
	ds_read_b128 v[216:219], v148 offset:36896
	s_waitcnt lgkmcnt(4)
	v_mfma_f32_32x32x16_bf16 v[114:129], v[212:215], v[228:231], v[114:129]
	ds_read_b128 v[244:247], v147 offset:36896
	s_waitcnt lgkmcnt(4)
	v_mfma_f32_32x32x16_bf16 v[82:97], v[208:211], v[232:235], v[82:97]
	ds_read_b128 v[224:227], v148 offset:41504
	v_mfma_f32_32x32x16_bf16 v[66:81], v[212:215], v[232:235], v[66:81]
	ds_read_b128 v[228:231], v147 offset:41504
	s_waitcnt lgkmcnt(5)
	v_mfma_f32_32x32x16_bf16 v[50:65], v[208:211], v[236:239], v[50:65]
	ds_read_b128 v[232:235], v147 offset:46112
	v_mfma_f32_32x32x16_bf16 v[34:49], v[212:215], v[236:239], v[34:49]
	s_waitcnt lgkmcnt(5)
	v_mfma_f32_32x32x16_bf16 v[18:33], v[208:211], v[240:243], v[18:33]
	ds_read_b128 v[236:239], v147 offset:50720
	v_mfma_f32_32x32x16_bf16 v[2:17], v[212:215], v[240:243], v[2:17]
	s_waitcnt lgkmcnt(4)
	v_mfma_f32_32x32x16_bf16 v[98:113], v[216:219], v[244:247], v[98:113]
	ds_read_b128 v[208:211], v148 offset:36928
	s_waitcnt lgkmcnt(4)
	v_mfma_f32_32x32x16_bf16 v[114:129], v[224:227], v[244:247], v[114:129]
	ds_read_b128 v[240:243], v147 offset:36928
	s_waitcnt lgkmcnt(4)
;     ...
;   for (int kt = 0; kt < nk; ++kt) {
;     __syncthreads();
;     if (kt + 1 < nk) {
;       u16* aw = As0 + ((kt + 1) & 1) * 256 * LD;
;       u16* bw = Bs0 + ((kt + 1) & 1) * 256 * LD;
; #pragma unroll
;       for (int i = 0; i < 4; ++i) { *(u32x4*)(aw + (srow + 64 * i) * LD + skc * 8) = ra[i]; *(u32x4*)(bw + (srow + 64 * i) * LD + skc * 8) = rb[i]; }
;     }
;     if (kt + 2 < nk) {
; #pragma unroll
;       for (int i = 0; i < 4; ++i) { ra[i] = *(const u32x4*)(Ag + (size_t)(64 * i) * K + (kt + 2) * 64); rb[i] = *(const u32x4*)(Bg[i] + (kt + 2) * 64); }
;     }
;     __builtin_amdgcn_sched_barrier(0);
;     const u16* as = As0 + (kt & 1) * 256 * LD + (wr * 128 + l31) * LD + h * 8;
;     const u16* bs = Bs0 + (kt & 1) * 256 * LD + (wc * 64 + l31) * LD + h * 8;
;     if (domma)
; #pragma unroll
;     for (int ks = 0; ks < 4; ++ks) {
;       bf16x8 wf[2], xf[4];
; #pragma unroll
;       for (int ct = 0; ct < 2; ++ct) wf[ct] = *(const bf16x8*)(bs + ct * 32 * LD + ks * 16);
; #pragma unroll
;       for (int tt = 0; tt < 4; ++tt) xf[tt] = *(const bf16x8*)(as + tt * 32 * LD + ks * 16);
; #pragma unroll
;       for (int ct = 0; ct < 2; ++ct)
; #pragma unroll
;         for (int tt = 0; tt < 4; ++tt) acc[ct][tt] = __builtin_amdgcn_mfma_f32_32x32x16_bf16(wf[ct], xf[tt], acc[ct][tt], 0, 0, 0);
;     }
;     __builtin_amdgcn_sched_barrier(0);
;   }
;   __syncthreads();
;   epi(acc, m0, n0, wr, wc, l31, h);
; __device__ void phase_gemm2(const Params& p, char* lds, int bid, int nb, bool fused) {
;     ...
;     gemm_tile(p.Ymix, p.woutT, DM, mt * 256, nt * 256, DM, lds, [&](f32x16 (&acc)[2][4], int m0, int n0, int wr, int wc, int l31, int h) {
;       float olds[4];
; #pragma unroll
;       for (int tt = 0; tt < 4; ++tt) {
;         const int tok = m0 + wr * 128 + tt * 32 + l31;
;         const float* xr = p.x + (size_t)tok * DM + n0 + wc * 64;
;         float ss = 0.f;
; #pragma unroll
;         for (int ct = 0; ct < 2; ++ct)
; #pragma unroll
;           for (int rq = 0; rq < 4; ++rq) {
;             const f32x4 xv = *(const f32x4*)(xr + ct * 32 + 8 * rq + 4 * h);
; #pragma unroll
;             for (int e = 0; e < 4; ++e) { acc[ct][tt][rq * 4 + e] += xv[e]; ss += acc[ct][tt][rq * 4 + e] * acc[ct][tt][rq * 4 + e]; }
;           }
;         ss += __shfl_xor(ss, 32);
;         olds[tt] = 0.f;
;         if (h == 0) olds[tt] = atomicAdd(p.ssq + tok, ss);
;       }
	v_mfma_f32_32x32x16_bf16 v[82:97], v[216:219], v[228:231], v[82:97]
	ds_read_b128 v[212:215], v148 offset:41536
	v_mfma_f32_32x32x16_bf16 v[66:81], v[224:227], v[228:231], v[66:81]
	ds_read_b128 v[244:247], v147 offset:41536
	s_waitcnt lgkmcnt(5)
	v_mfma_f32_32x32x16_bf16 v[50:65], v[216:219], v[232:235], v[50:65]
	ds_read_b128 v[228:231], v147 offset:46144
	v_mfma_f32_32x32x16_bf16 v[34:49], v[224:227], v[232:235], v[34:49]
	s_waitcnt lgkmcnt(5)
	v_mfma_f32_32x32x16_bf16 v[18:33], v[216:219], v[236:239], v[18:33]
	ds_read_b128 v[232:235], v147 offset:50752
	v_mfma_f32_32x32x16_bf16 v[2:17], v[224:227], v[236:239], v[2:17]
	s_waitcnt lgkmcnt(4)
	v_mfma_f32_32x32x16_bf16 v[98:113], v[208:211], v[240:243], v[98:113]
	ds_read_b128 v[216:219], v148 offset:36960
	s_waitcnt lgkmcnt(4)
	v_mfma_f32_32x32x16_bf16 v[114:129], v[212:215], v[240:243], v[114:129]
	ds_read_b128 v[236:239], v147 offset:36960
	s_waitcnt lgkmcnt(4)
	v_mfma_f32_32x32x16_bf16 v[82:97], v[208:211], v[244:247], v[82:97]
	ds_read_b128 v[224:227], v148 offset:41568
	v_mfma_f32_32x32x16_bf16 v[66:81], v[212:215], v[244:247], v[66:81]
	ds_read_b128 v[240:243], v147 offset:41568
	s_waitcnt lgkmcnt(5)
	v_mfma_f32_32x32x16_bf16 v[50:65], v[208:211], v[228:231], v[50:65]
	ds_read_b128 v[244:247], v147 offset:46176
	v_mfma_f32_32x32x16_bf16 v[34:49], v[212:215], v[228:231], v[34:49]
	s_waitcnt lgkmcnt(5)
	v_mfma_f32_32x32x16_bf16 v[18:33], v[208:211], v[232:235], v[18:33]
	ds_read_b128 v[228:231], v147 offset:50784
	v_mfma_f32_32x32x16_bf16 v[2:17], v[212:215], v[232:235], v[2:17]
	s_waitcnt lgkmcnt(4)
	v_mfma_f32_32x32x16_bf16 v[98:113], v[216:219], v[236:239], v[98:113]
	s_waitcnt lgkmcnt(3)
	v_mfma_f32_32x32x16_bf16 v[114:129], v[224:227], v[236:239], v[114:129]
	s_waitcnt lgkmcnt(2)
	v_mfma_f32_32x32x16_bf16 v[82:97], v[216:219], v[240:243], v[82:97]
	v_mfma_f32_32x32x16_bf16 v[66:81], v[224:227], v[240:243], v[66:81]
	s_waitcnt lgkmcnt(1)
	v_mfma_f32_32x32x16_bf16 v[50:65], v[216:219], v[244:247], v[50:65]
	v_mfma_f32_32x32x16_bf16 v[34:49], v[224:227], v[244:247], v[34:49]
	s_waitcnt lgkmcnt(0)
	v_mfma_f32_32x32x16_bf16 v[18:33], v[216:219], v[228:231], v[18:33]
	v_mfma_f32_32x32x16_bf16 v[2:17], v[224:227], v[228:231], v[2:17]
	s_andn2_b64 vcc, exec, s[12:13]
	s_cbranch_vccnz .Lp5_slow
	v_or_b32_e32 v130, s38, v146
	v_add_u32_e32 v152, s5, v130
	s_lshl_b32 s14, s4, 2
	s_lshl_b32 s36, s34, 2
	s_add_i32 s36, s36, s14
	v_lshl_add_u32 v162, v152, 12, v150
	v_lshlrev_b32_e32 v163, 2, v152
	s_add_u32 s54, s24, s36
	s_addc_u32 s55, s25, 0
	s_add_u32 s56, s54, 0x20000
	s_addc_u32 s57, s55, 0
	s_add_u32 s58, s54, 0x40000
	s_addc_u32 s59, s55, 0
	s_add_u32 s60, s54, 0x60000
	s_addc_u32 s61, s55, 0
	global_load_dwordx4 v[164:167], v162, s[54:55]
	global_load_dwordx4 v[168:171], v162, s[54:55] offset:32
	global_load_dwordx4 v[172:175], v162, s[54:55] offset:64
	global_load_dwordx4 v[176:179], v162, s[54:55] offset:96
	global_load_dwordx4 v[180:183], v162, s[54:55] offset:128
	global_load_dwordx4 v[184:187], v162, s[54:55] offset:160
	global_load_dwordx4 v[188:191], v162, s[54:55] offset:192
	global_load_dwordx4 v[192:195], v162, s[54:55] offset:224
	global_load_dwordx4 v[224:227], v162, s[56:57]
	global_load_dwordx4 v[228:231], v162, s[56:57] offset:32
	global_load_dwordx4 v[232:235], v162, s[56:57] offset:64
	global_load_dwordx4 v[236:239], v162, s[56:57] offset:96
	global_load_dwordx4 v[240:243], v162, s[56:57] offset:128
	global_load_dwordx4 v[244:247], v162, s[56:57] offset:160
	global_load_dwordx4 v[248:251], v162, s[56:57] offset:192
	global_load_dwordx4 v[252:255], v162, s[56:57] offset:224
	global_load_dwordx4 v[196:199], v162, s[58:59]
	global_load_dwordx4 v[200:203], v162, s[58:59] offset:32
	global_load_dwordx4 v[204:207], v162, s[58:59] offset:64
	global_load_dwordx4 v[208:211], v162, s[58:59] offset:96
	global_load_dwordx4 v[212:215], v162, s[58:59] offset:128
	global_load_dwordx4 v[216:219], v162, s[58:59] offset:160
	global_load_dwordx4 v[130:133], v162, s[58:59] offset:192
	global_load_dwordx4 v[134:137], v162, s[58:59] offset:224
	v_mbcnt_lo_u32_b32 v160, -1, 0
	v_mbcnt_hi_u32_b32 v160, -1, v160
	v_xor_b32_e32 v160, 32, v160
	v_lshlrev_b32_e32 v160, 2, v160
	v_cmp_eq_u32_e64 s[62:63], 0, v159
	s_add_u32 s66, s8, s36
	s_addc_u32 s67, s9, 0
	s_waitcnt vmcnt(16)
	v_pk_add_f32 v[98:99], v[98:99], v[164:165]
	v_pk_add_f32 v[100:101], v[100:101], v[166:167]
	v_pk_add_f32 v[102:103], v[102:103], v[168:169]
	v_pk_add_f32 v[104:105], v[104:105], v[170:171]
	v_pk_add_f32 v[106:107], v[106:107], v[172:173]
	v_pk_add_f32 v[108:109], v[108:109], v[174:175]
	v_pk_add_f32 v[110:111], v[110:111], v[176:177]
	v_pk_add_f32 v[112:113], v[112:113], v[178:179]
	v_pk_add_f32 v[114:115], v[114:115], v[180:181]
	v_pk_add_f32 v[116:117], v[116:117], v[182:183]
	v_pk_add_f32 v[118:119], v[118:119], v[184:185]
	v_pk_add_f32 v[120:121], v[120:121], v[186:187]
	v_pk_add_f32 v[122:123], v[122:123], v[188:189]
	v_pk_add_f32 v[124:125], v[124:125], v[190:191]
	v_pk_add_f32 v[126:127], v[126:127], v[192:193]
	v_pk_add_f32 v[128:129], v[128:129], v[194:195]
	v_pk_mul_f32 v[146:147], v[98:99], v[98:99]
	v_add_f32_e32 v161, v146, v147
	v_pk_mul_f32 v[148:149], v[100:101], v[100:101]
	v_add_f32_e32 v161, v148, v161
	v_add_f32_e32 v161, v149, v161
	v_pk_mul_f32 v[146:147], v[102:103], v[102:103]
	v_add_f32_e32 v161, v146, v161
	v_add_f32_e32 v161, v147, v161
	v_pk_mul_f32 v[148:149], v[104:105], v[104:105]
	v_add_f32_e32 v161, v148, v161
	v_add_f32_e32 v161, v149, v161
	v_pk_mul_f32 v[146:147], v[106:107], v[106:107]
	v_add_f32_e32 v161, v146, v161
	v_add_f32_e32 v161, v147, v161
	v_pk_mul_f32 v[148:149], v[108:109], v[108:109]
	v_add_f32_e32 v161, v148, v161
	v_add_f32_e32 v161, v149, v161
	v_pk_mul_f32 v[146:147], v[110:111], v[110:111]
	v_add_f32_e32 v161, v146, v161
	v_add_f32_e32 v161, v147, v161
	v_pk_mul_f32 v[148:149], v[112:113], v[112:113]
	v_add_f32_e32 v161, v148, v161
	v_add_f32_e32 v161, v149, v161
	v_pk_mul_f32 v[146:147], v[114:115], v[114:115]
	v_add_f32_e32 v161, v146, v161
	v_add_f32_e32 v161, v147, v161
	v_pk_mul_f32 v[148:149], v[116:117], v[116:117]
	v_add_f32_e32 v161, v148, v161
	v_add_f32_e32 v161, v149, v161
	v_pk_mul_f32 v[146:147], v[118:119], v[118:119]
	v_add_f32_e32 v161, v146, v161
	v_add_f32_e32 v161, v147, v161
	v_pk_mul_f32 v[148:149], v[120:121], v[120:121]
	v_add_f32_e32 v161, v148, v161
	v_add_f32_e32 v161, v149, v161
	v_pk_mul_f32 v[146:147], v[122:123], v[122:123]
	v_add_f32_e32 v161, v146, v161
	v_add_f32_e32 v161, v147, v161
	v_pk_mul_f32 v[148:149], v[124:125], v[124:125]
	v_add_f32_e32 v161, v148, v161
	v_add_f32_e32 v161, v149, v161
	v_pk_mul_f32 v[146:147], v[126:127], v[126:127]
	v_add_f32_e32 v161, v146, v161
	v_add_f32_e32 v161, v147, v161
	v_pk_mul_f32 v[148:149], v[128:129], v[128:129]
	v_add_f32_e32 v161, v148, v161
	v_add_f32_e32 v161, v149, v161
	ds_bpermute_b32 v146, v160, v161
	s_waitcnt lgkmcnt(0)
; __device__ void phase_gemm2(const Params& p, char* lds, int bid, int nb, bool fused) {
;     ...
;       for (int tt = 0; tt < 4; ++tt) {
;         const int tok = m0 + wr * 128 + tt * 32 + l31;
;         const float* xr = p.x + (size_t)tok * DM + n0 + wc * 64;
;         float ss = 0.f;
; #pragma unroll
;         for (int ct = 0; ct < 2; ++ct)
; #pragma unroll
;           for (int rq = 0; rq < 4; ++rq) {
;             const f32x4 xv = *(const f32x4*)(xr + ct * 32 + 8 * rq + 4 * h);
; #pragma unroll
;             for (int e = 0; e < 4; ++e) { acc[ct][tt][rq * 4 + e] += xv[e]; ss += acc[ct][tt][rq * 4 + e] * acc[ct][tt][rq * 4 + e]; }
;           }
;         ss += __shfl_xor(ss, 32);
;         olds[tt] = 0.f;
;         if (h == 0) olds[tt] = atomicAdd(p.ssq + tok, ss);
;       }
	v_add_f32_e32 v161, v161, v146
	s_and_saveexec_b64 s[64:65], s[62:63]
	global_atomic_add_f32 v139, v163, v161, s[18:19] sc0
	s_or_b64 exec, exec, s[64:65]
	global_load_dwordx4 v[164:167], v162, s[60:61]
	global_load_dwordx4 v[168:171], v162, s[60:61] offset:32
	global_load_dwordx4 v[172:175], v162, s[60:61] offset:64
	global_load_dwordx4 v[176:179], v162, s[60:61] offset:96
	global_load_dwordx4 v[180:183], v162, s[60:61] offset:128
	global_load_dwordx4 v[184:187], v162, s[60:61] offset:160
	global_load_dwordx4 v[188:191], v162, s[60:61] offset:192
	global_load_dwordx4 v[192:195], v162, s[60:61] offset:224
	s_waitcnt vmcnt(17)
	v_pk_add_f32 v[82:83], v[82:83], v[224:225]
	v_pk_add_f32 v[84:85], v[84:85], v[226:227]
	v_pk_add_f32 v[86:87], v[86:87], v[228:229]
	v_pk_add_f32 v[88:89], v[88:89], v[230:231]
	v_pk_add_f32 v[90:91], v[90:91], v[232:233]
	v_pk_add_f32 v[92:93], v[92:93], v[234:235]
	v_pk_add_f32 v[94:95], v[94:95], v[236:237]
	v_pk_add_f32 v[96:97], v[96:97], v[238:239]
	v_pk_add_f32 v[66:67], v[66:67], v[240:241]
	v_pk_add_f32 v[68:69], v[68:69], v[242:243]
	v_pk_add_f32 v[70:71], v[70:71], v[244:245]
	v_pk_add_f32 v[72:73], v[72:73], v[246:247]
	v_pk_add_f32 v[74:75], v[74:75], v[248:249]
	v_pk_add_f32 v[76:77], v[76:77], v[250:251]
	v_pk_add_f32 v[78:79], v[78:79], v[252:253]
	v_pk_add_f32 v[80:81], v[80:81], v[254:255]
	v_pk_mul_f32 v[146:147], v[82:83], v[82:83]
	v_add_f32_e32 v220, v146, v147
	v_pk_mul_f32 v[148:149], v[84:85], v[84:85]
	v_add_f32_e32 v220, v148, v220
	v_add_f32_e32 v220, v149, v220
	v_pk_mul_f32 v[146:147], v[86:87], v[86:87]
	v_add_f32_e32 v220, v146, v220
	v_add_f32_e32 v220, v147, v220
	v_pk_mul_f32 v[148:149], v[88:89], v[88:89]
	v_add_f32_e32 v220, v148, v220
	v_add_f32_e32 v220, v149, v220
	v_pk_mul_f32 v[146:147], v[90:91], v[90:91]
	v_add_f32_e32 v220, v146, v220
	v_add_f32_e32 v220, v147, v220
	v_pk_mul_f32 v[148:149], v[92:93], v[92:93]
	v_add_f32_e32 v220, v148, v220
	v_add_f32_e32 v220, v149, v220
	v_pk_mul_f32 v[146:147], v[94:95], v[94:95]
	v_add_f32_e32 v220, v146, v220
	v_add_f32_e32 v220, v147, v220
	v_pk_mul_f32 v[148:149], v[96:97], v[96:97]
	v_add_f32_e32 v220, v148, v220
	v_add_f32_e32 v220, v149, v220
	v_pk_mul_f32 v[146:147], v[66:67], v[66:67]
	v_add_f32_e32 v220, v146, v220
	v_add_f32_e32 v220, v147, v220
	v_pk_mul_f32 v[148:149], v[68:69], v[68:69]
	v_add_f32_e32 v220, v148, v220
	v_add_f32_e32 v220, v149, v220
	v_pk_mul_f32 v[146:147], v[70:71], v[70:71]
	v_add_f32_e32 v220, v146, v220
	v_add_f32_e32 v220, v147, v220
	v_pk_mul_f32 v[148:149], v[72:73], v[72:73]
	v_add_f32_e32 v220, v148, v220
	v_add_f32_e32 v220, v149, v220
	v_pk_mul_f32 v[146:147], v[74:75], v[74:75]
	v_add_f32_e32 v220, v146, v220
	v_add_f32_e32 v220, v147, v220
	v_pk_mul_f32 v[148:149], v[76:77], v[76:77]
	v_add_f32_e32 v220, v148, v220
	v_add_f32_e32 v220, v149, v220
	v_pk_mul_f32 v[146:147], v[78:79], v[78:79]
	v_add_f32_e32 v220, v146, v220
	v_add_f32_e32 v220, v147, v220
	v_pk_mul_f32 v[148:149], v[80:81], v[80:81]
	v_add_f32_e32 v220, v148, v220
	v_add_f32_e32 v220, v149, v220
	ds_bpermute_b32 v146, v160, v220
	s_waitcnt lgkmcnt(0)
	v_add_f32_e32 v220, v220, v146
	s_and_saveexec_b64 s[64:65], s[62:63]
	global_atomic_add_f32 v141, v163, v220, s[18:19] offset:128 sc0
	s_or_b64 exec, exec, s[64:65]
	global_load_dwordx4 v[224:227], v150, s[66:67]
	global_load_dwordx4 v[228:231], v150, s[66:67] offset:32
	global_load_dwordx4 v[232:235], v150, s[66:67] offset:64
	global_load_dwordx4 v[236:239], v150, s[66:67] offset:96
	global_load_dwordx4 v[240:243], v150, s[66:67] offset:128
	global_load_dwordx4 v[244:247], v150, s[66:67] offset:160
	global_load_dwordx4 v[248:251], v150, s[66:67] offset:192
	global_load_dwordx4 v[252:255], v150, s[66:67] offset:224
	s_waitcnt vmcnt(18)
; __device__ void phase_gemm2(const Params& p, char* lds, int bid, int nb, bool fused) {
;     ...
;       for (int tt = 0; tt < 4; ++tt) {
;         const int tok = m0 + wr * 128 + tt * 32 + l31;
;         const float* xr = p.x + (size_t)tok * DM + n0 + wc * 64;
;         float ss = 0.f;
; #pragma unroll
;         for (int ct = 0; ct < 2; ++ct)
; #pragma unroll
;           for (int rq = 0; rq < 4; ++rq) {
;             const f32x4 xv = *(const f32x4*)(xr + ct * 32 + 8 * rq + 4 * h);
; #pragma unroll
;             for (int e = 0; e < 4; ++e) { acc[ct][tt][rq * 4 + e] += xv[e]; ss += acc[ct][tt][rq * 4 + e] * acc[ct][tt][rq * 4 + e]; }
;           }
;         ss += __shfl_xor(ss, 32);
;         olds[tt] = 0.f;
;         if (h == 0) olds[tt] = atomicAdd(p.ssq + tok, ss);
;       }
;       asm volatile("" :: "v"(olds[0]), "v"(olds[1]), "v"(olds[2]), "v"(olds[3]));
;       if (fused) {
;         __syncthreads();
;         if (threadIdx.x == 0) {
;           __hip_atomic_fetch_add(p.pcnt + (m0 >> 8), 1, __ATOMIC_RELAXED, __HIP_MEMORY_SCOPE_AGENT);
;           while (__hip_atomic_load(p.pcnt + (m0 >> 8), __ATOMIC_RELAXED, __HIP_MEMORY_SCOPE_AGENT) < NNT) __builtin_amdgcn_s_sleep(2);
	v_pk_add_f32 v[50:51], v[50:51], v[196:197]
	v_pk_add_f32 v[52:53], v[52:53], v[198:199]
	v_pk_add_f32 v[54:55], v[54:55], v[200:201]
	v_pk_add_f32 v[56:57], v[56:57], v[202:203]
	v_pk_add_f32 v[58:59], v[58:59], v[204:205]
	v_pk_add_f32 v[60:61], v[60:61], v[206:207]
	v_pk_add_f32 v[62:63], v[62:63], v[208:209]
	v_pk_add_f32 v[64:65], v[64:65], v[210:211]
	v_pk_add_f32 v[34:35], v[34:35], v[212:213]
	v_pk_add_f32 v[36:37], v[36:37], v[214:215]
	v_pk_add_f32 v[38:39], v[38:39], v[216:217]
	v_pk_add_f32 v[40:41], v[40:41], v[218:219]
	v_pk_add_f32 v[42:43], v[42:43], v[130:131]
	v_pk_add_f32 v[44:45], v[44:45], v[132:133]
	v_pk_add_f32 v[46:47], v[46:47], v[134:135]
	v_pk_add_f32 v[48:49], v[48:49], v[136:137]
	v_pk_mul_f32 v[146:147], v[50:51], v[50:51]
	v_add_f32_e32 v221, v146, v147
	v_pk_mul_f32 v[148:149], v[52:53], v[52:53]
	v_add_f32_e32 v221, v148, v221
	v_add_f32_e32 v221, v149, v221
	v_pk_mul_f32 v[146:147], v[54:55], v[54:55]
	v_add_f32_e32 v221, v146, v221
	v_add_f32_e32 v221, v147, v221
	v_pk_mul_f32 v[148:149], v[56:57], v[56:57]
	v_add_f32_e32 v221, v148, v221
	v_add_f32_e32 v221, v149, v221
	v_pk_mul_f32 v[146:147], v[58:59], v[58:59]
	v_add_f32_e32 v221, v146, v221
	v_add_f32_e32 v221, v147, v221
	v_pk_mul_f32 v[148:149], v[60:61], v[60:61]
	v_add_f32_e32 v221, v148, v221
	v_add_f32_e32 v221, v149, v221
	v_pk_mul_f32 v[146:147], v[62:63], v[62:63]
	v_add_f32_e32 v221, v146, v221
	v_add_f32_e32 v221, v147, v221
	v_pk_mul_f32 v[148:149], v[64:65], v[64:65]
	v_add_f32_e32 v221, v148, v221
	v_add_f32_e32 v221, v149, v221
	v_pk_mul_f32 v[146:147], v[34:35], v[34:35]
	v_add_f32_e32 v221, v146, v221
	v_add_f32_e32 v221, v147, v221
	v_pk_mul_f32 v[148:149], v[36:37], v[36:37]
	v_add_f32_e32 v221, v148, v221
	v_add_f32_e32 v221, v149, v221
	v_pk_mul_f32 v[146:147], v[38:39], v[38:39]
	v_add_f32_e32 v221, v146, v221
	v_add_f32_e32 v221, v147, v221
	v_pk_mul_f32 v[148:149], v[40:41], v[40:41]
	v_add_f32_e32 v221, v148, v221
	v_add_f32_e32 v221, v149, v221
	v_pk_mul_f32 v[146:147], v[42:43], v[42:43]
	v_add_f32_e32 v221, v146, v221
	v_add_f32_e32 v221, v147, v221
	v_pk_mul_f32 v[148:149], v[44:45], v[44:45]
	v_add_f32_e32 v221, v148, v221
	v_add_f32_e32 v221, v149, v221
	v_pk_mul_f32 v[146:147], v[46:47], v[46:47]
	v_add_f32_e32 v221, v146, v221
	v_add_f32_e32 v221, v147, v221
	v_pk_mul_f32 v[148:149], v[48:49], v[48:49]
	v_add_f32_e32 v221, v148, v221
	v_add_f32_e32 v221, v149, v221
	ds_bpermute_b32 v146, v160, v221
	s_waitcnt lgkmcnt(0)
	v_add_f32_e32 v221, v221, v146
	s_and_saveexec_b64 s[64:65], s[62:63]
	global_atomic_add_f32 v143, v163, v221, s[18:19] offset:256 sc0
	s_or_b64 exec, exec, s[64:65]
	s_waitcnt vmcnt(10)
	v_pk_add_f32 v[18:19], v[18:19], v[164:165]
	v_pk_add_f32 v[20:21], v[20:21], v[166:167]
	v_pk_add_f32 v[22:23], v[22:23], v[168:169]
	v_pk_add_f32 v[24:25], v[24:25], v[170:171]
	v_pk_add_f32 v[26:27], v[26:27], v[172:173]
	v_pk_add_f32 v[28:29], v[28:29], v[174:175]
	v_pk_add_f32 v[30:31], v[30:31], v[176:177]
	v_pk_add_f32 v[32:33], v[32:33], v[178:179]
	v_pk_add_f32 v[2:3], v[2:3], v[180:181]
	v_pk_add_f32 v[4:5], v[4:5], v[182:183]
	v_pk_add_f32 v[6:7], v[6:7], v[184:185]
	v_pk_add_f32 v[8:9], v[8:9], v[186:187]
	v_pk_add_f32 v[10:11], v[10:11], v[188:189]
	v_pk_add_f32 v[12:13], v[12:13], v[190:191]
	v_pk_add_f32 v[14:15], v[14:15], v[192:193]
	v_pk_add_f32 v[16:17], v[16:17], v[194:195]
	v_pk_mul_f32 v[146:147], v[18:19], v[18:19]
	v_add_f32_e32 v222, v146, v147
	v_pk_mul_f32 v[148:149], v[20:21], v[20:21]
	v_add_f32_e32 v222, v148, v222
	v_add_f32_e32 v222, v149, v222
	v_pk_mul_f32 v[146:147], v[22:23], v[22:23]
	v_add_f32_e32 v222, v146, v222
	v_add_f32_e32 v222, v147, v222
	v_pk_mul_f32 v[148:149], v[24:25], v[24:25]
	v_add_f32_e32 v222, v148, v222
	v_add_f32_e32 v222, v149, v222
	v_pk_mul_f32 v[146:147], v[26:27], v[26:27]
	v_add_f32_e32 v222, v146, v222
	v_add_f32_e32 v222, v147, v222
	v_pk_mul_f32 v[148:149], v[28:29], v[28:29]
	v_add_f32_e32 v222, v148, v222
	v_add_f32_e32 v222, v149, v222
	v_pk_mul_f32 v[146:147], v[30:31], v[30:31]
	v_add_f32_e32 v222, v146, v222
	v_add_f32_e32 v222, v147, v222
	v_pk_mul_f32 v[148:149], v[32:33], v[32:33]
	v_add_f32_e32 v222, v148, v222
	v_add_f32_e32 v222, v149, v222
	v_pk_mul_f32 v[146:147], v[2:3], v[2:3]
	v_add_f32_e32 v222, v146, v222
	v_add_f32_e32 v222, v147, v222
	v_pk_mul_f32 v[148:149], v[4:5], v[4:5]
	v_add_f32_e32 v222, v148, v222
	v_add_f32_e32 v222, v149, v222
	v_pk_mul_f32 v[146:147], v[6:7], v[6:7]
	v_add_f32_e32 v222, v146, v222
	v_add_f32_e32 v222, v147, v222
	v_pk_mul_f32 v[148:149], v[8:9], v[8:9]
	v_add_f32_e32 v222, v148, v222
	v_add_f32_e32 v222, v149, v222
	v_pk_mul_f32 v[146:147], v[10:11], v[10:11]
	v_add_f32_e32 v222, v146, v222
	v_add_f32_e32 v222, v147, v222
	v_pk_mul_f32 v[148:149], v[12:13], v[12:13]
	v_add_f32_e32 v222, v148, v222
	v_add_f32_e32 v222, v149, v222
	v_pk_mul_f32 v[146:147], v[14:15], v[14:15]
	v_add_f32_e32 v222, v146, v222
	v_add_f32_e32 v222, v147, v222
	v_pk_mul_f32 v[148:149], v[16:17], v[16:17]
	v_add_f32_e32 v222, v148, v222
	v_add_f32_e32 v222, v149, v222
	ds_bpermute_b32 v146, v160, v222
	s_waitcnt lgkmcnt(0)
	v_add_f32_e32 v222, v222, v146
	s_and_saveexec_b64 s[64:65], s[62:63]
	global_atomic_add_f32 v145, v163, v222, s[18:19] offset:384 sc0
	s_or_b64 exec, exec, s[64:65]
	s_waitcnt vmcnt(0)
	s_barrier
	s_and_saveexec_b64 s[64:65], s[48:49]
	s_cbranch_execz .Lp5_pollend
	s_ashr_i32 s38, s38, 8
	s_mov_b64 s[40:41], exec
	s_ashr_i32 s39, s38, 31
	s_lshl_b64 s[38:39], s[38:39], 2
	v_mbcnt_lo_u32_b32 v146, s40, 0
	s_add_u32 s38, s20, s38
	v_mbcnt_hi_u32_b32 v146, s41, v146
	s_addc_u32 s39, s21, s39
	v_cmp_eq_u32_e32 vcc, 0, v146
	s_and_saveexec_b64 s[42:43], vcc
	s_cbranch_execz .Lp5_noinc
	s_bcnt1_i32_b64 s40, s[40:41]
	v_mov_b32_e32 v146, s40
	global_atomic_add v151, v146, s[38:39]

; #define LAS __attribute__((address_space(3)))
; __global__ void __launch_bounds__(NT) fwd_mega(Params p) {
;   cg::grid_group grid = cg::this_grid();
;   const int bid = blockIdx.x, nb = gridDim.x;
;   volatile LAS unsigned* xst = (volatile LAS unsigned*)(dyn_lds + LDS_BYTES - 32);
;   if (threadIdx.x == 0) { xst[0] = 0u; xst[1] = 0u; }
;   __syncthreads();
;   const XcdBarrier xb = xcd_barrier_post(p.xbar, xst);
;   phase_prep(p, dyn_lds, bid, nb);
;   xcd_barrier(xb);
;     ...
;   phase_gemm1(p, dyn_lds, bid, nb, REP - 6);
;   xcd_barrier(xb);
;     ...
;   phase_gemm1(p, dyn_lds, bid, nb);
;     ...
;   xcd_barrier(xb);
;   phase_gemm1(p, dyn_lds, bid, nb);
;     ...
;   xcd_barrier(xb);
;   phase_mix(p, dyn_lds, bid, nb);
;     ...
;   __syncthreads();
;   phase_prep_only(p, dyn_lds, bid, nb);
;     ...
;   xcd_barrier(xb);
;   phase_scan(p, bid, nb);
;     ...
;   xcd_barrier(xb);
;     ...
;   phase_scan(p, bid, nb);
;   phase_scan(p, bid, nb);
;   phase_scan(p, bid, nb);
;   phase_scan(p, bid, nb);
;     ...
;   phase_attn_queue(p, dyn_lds, bid, nb);
;   xcd_barrier(xb);
;   phase_rwkv_out(p, bid, nb);
;   xcd_barrier(xb);
;   const bool fused = (nb & 31) == 0;
;   phase_gemm2(p, dyn_lds, bid, nb, fused);
;   if (!fused) {
;     grid.sync();
;     phase_final(p, bid, nb);
;   }
; }
	.amdhsa_kernel _Z8fwd_mega6Params
		.amdhsa_group_segment_fixed_size 0
		.amdhsa_private_segment_fixed_size 0
		.amdhsa_kernarg_size 592
		.amdhsa_user_sgpr_count 2
		.amdhsa_user_sgpr_dispatch_ptr 0
		.amdhsa_user_sgpr_queue_ptr 0
		.amdhsa_user_sgpr_kernarg_segment_ptr 1
		.amdhsa_user_sgpr_dispatch_id 0
		.amdhsa_user_sgpr_kernarg_preload_length 0
		.amdhsa_user_sgpr_kernarg_preload_offset 0
		.amdhsa_user_sgpr_private_segment_size 0
		.amdhsa_uses_dynamic_stack 0
		.amdhsa_enable_private_segment 0
		.amdhsa_system_sgpr_workgroup_id_x 1
		.amdhsa_system_sgpr_workgroup_id_y 0
		.amdhsa_system_sgpr_workgroup_id_z 0
		.amdhsa_system_sgpr_workgroup_info 0
		.amdhsa_system_vgpr_workitem_id 2
		.amdhsa_next_free_vgpr 256
		.amdhsa_next_free_sgpr 94
		.amdhsa_accum_offset 256
		.amdhsa_reserve_vcc 1
		.amdhsa_float_round_mode_32 0
		.amdhsa_float_round_mode_16_64 0
		.amdhsa_float_denorm_mode_32 3
		.amdhsa_float_denorm_mode_16_64 3
		.amdhsa_dx10_clamp 1
		.amdhsa_ieee_mode 1
		.amdhsa_fp16_overflow 0
		.amdhsa_tg_split 0
		.amdhsa_exception_fp_ieee_invalid_op 0
		.amdhsa_exception_fp_denorm_src 0
		.amdhsa_exception_fp_ieee_div_zero 0
		.amdhsa_exception_fp_ieee_overflow 0
		.amdhsa_exception_fp_ieee_underflow 0
		.amdhsa_exception_fp_ieee_inexact 0
		.amdhsa_exception_int_div_zero 0
	.end_amdhsa_kernel

; #define LAS __attribute__((address_space(3)))
; __global__ void __launch_bounds__(NT) fwd_mega(Params p) {
;   cg::grid_group grid = cg::this_grid();
;   const int bid = blockIdx.x, nb = gridDim.x;
;   volatile LAS unsigned* xst = (volatile LAS unsigned*)(dyn_lds + LDS_BYTES - 32);
;   if (threadIdx.x == 0) { xst[0] = 0u; xst[1] = 0u; }
;   __syncthreads();
;   const XcdBarrier xb = xcd_barrier_post(p.xbar, xst);
;   phase_prep(p, dyn_lds, bid, nb);
;   xcd_barrier(xb);
;     ...
;   phase_gemm1(p, dyn_lds, bid, nb, REP - 6);
;   xcd_barrier(xb);
;     ...
;   phase_gemm1(p, dyn_lds, bid, nb);
;     ...
;   xcd_barrier(xb);
;   phase_gemm1(p, dyn_lds, bid, nb);
;     ...
;   xcd_barrier(xb);
;   phase_mix(p, dyn_lds, bid, nb);
;     ...
;   __syncthreads();
;   phase_prep_only(p, dyn_lds, bid, nb);
;     ...
;   xcd_barrier(xb);
;   phase_scan(p, bid, nb);
;     ...
;   xcd_barrier(xb);
;     ...
;   phase_scan(p, bid, nb);
;   phase_scan(p, bid, nb);
;   phase_scan(p, bid, nb);
;   phase_scan(p, bid, nb);
;     ...
;   phase_attn_queue(p, dyn_lds, bid, nb);
;   xcd_barrier(xb);
;   phase_rwkv_out(p, bid, nb);
;   xcd_barrier(xb);
;   const bool fused = (nb & 31) == 0;
;   phase_gemm2(p, dyn_lds, bid, nb, fused);
;   if (!fused) {
;     grid.sync();
;     phase_final(p, bid, nb);
;   }
; }
amdhsa.kernels:
  - .agpr_count:     0
    .args:
      - .offset:         0
        .size:           336
        .value_kind:     by_value
      - .offset:         336
        .size:           4
        .value_kind:     hidden_block_count_x
      - .offset:         340
        .size:           4
        .value_kind:     hidden_block_count_y
      - .offset:         344
        .size:           4
        .value_kind:     hidden_block_count_z
      - .offset:         348
        .size:           2
        .value_kind:     hidden_group_size_x
      - .offset:         350
        .size:           2
        .value_kind:     hidden_group_size_y
      - .offset:         352
        .size:           2
        .value_kind:     hidden_group_size_z
      - .offset:         354
        .size:           2
        .value_kind:     hidden_remainder_x
      - .offset:         356
        .size:           2
        .value_kind:     hidden_remainder_y
      - .offset:         358
        .size:           2
        .value_kind:     hidden_remainder_z
      - .offset:         376
        .size:           8
        .value_kind:     hidden_global_offset_x
      - .offset:         384
        .size:           8
        .value_kind:     hidden_global_offset_y
      - .offset:         392
        .size:           8
        .value_kind:     hidden_global_offset_z
      - .offset:         400
        .size:           2
        .value_kind:     hidden_grid_dims
      - .offset:         424
        .size:           8
        .value_kind:     hidden_multigrid_sync_arg
      - .offset:         456
        .size:           4
        .value_kind:     hidden_dynamic_lds_size
    .group_segment_fixed_size: 0
    .kernarg_segment_align: 8
    .kernarg_segment_size: 592
    .language:       OpenCL C
    .language_version:
      - 2
      - 0
    .max_flat_workgroup_size: 512
    .name:           _Z8fwd_mega6Params
    .private_segment_fixed_size: 0
    .sgpr_count:     100
    .sgpr_spill_count: 0
    .symbol:         _Z8fwd_mega6Params.kd
    .uniform_work_group_size: 1
    .uses_dynamic_stack: false
    .vgpr_count:     256
    .vgpr_spill_count: 0
    .wavefront_size: 64
